# LDS-DMA 3-stage GEMM core rolled out to phases 6,8,10,12,15,17,19 mainloops (hipcc epilogues kept)
# speedup vs baseline: 1.0477x; 1.0445x over previous
; #define GA_LOAD(pr_) do { _Pragma("unroll") for (int i = 0; i < 4; ++i) ra[i] = *(const u32x4*)(Ab + (i * 32) * lda + (pr_) * 64); } while (0)
; #define GB_LOAD(kt_) do { const bfr* bk_ = Bb + (kt_) * NB * 32; \
;     _Pragma("unroll") for (int i = 0; i < 4; ++i) rb[i] = *(const u32x4*)(bk_ + (i * 64) * 32); } while (0)
; #define G_STORE(kt_) do { bfr* as_ = S0 + ((kt_) & 1) * GSTAGE; bfr* bs_ = as_ + 128 * 40; \
;     if (apar == ((kt_) & 1)) { _Pragma("unroll") for (int i = 0; i < 4; ++i) *(u32x4*)(as_ + asoff + i * 32 * 40) = ra[i]; } \
;     _Pragma("unroll") for (int i = 0; i < 4; ++i) *(u32x4*)(bs_ + bsoff + i * 64 * 40) = rb[i]; } while (0)
; template <int lda>
; DI void gemm_mainloop(const bfr* __restrict__ A, const bfr* __restrict__ Bt, int NB, int K, int m0, int n0, char* smem, f32x16 (&acc)[2][4]) {
;     ...
; #pragma unroll
;   for (int i = 0; i < 2; ++i)
; #pragma unroll
;     for (int j = 0; j < 4; ++j)
; #pragma unroll
;       for (int q = 0; q < 16; ++q) acc[i][j][q] = 0.f;
;   u32x4 ra[4], rb[4];
;   const int nk = K >> 5;
;   const int arow = tid >> 3, ac8 = tid & 7, apar = ac8 >> 2;
;   const bfr* Ab = A + (m0 + arow) * lda + ac8 * 8;
;   const int asoff = arow * 40 + (ac8 & 3) * 8;
;   const int brow = tid >> 2, bc4 = tid & 3;
;   const bfr* Bb = Bt + (n0 + brow) * 32 + bc4 * 8;
;   const int bsoff = brow * 40 + bc4 * 8;
;     ...
;   GA_LOAD(0);
;   GB_LOAD(0);
;   G_STORE(0);
;   GB_LOAD(1);
;   __syncthreads();
; template <bool FIRST, bool HAS_H>
; DI void phase_gemm_resid(const Params& p, const bfr* A, const bfr* Wt, const float* gnext, float* ss, char* smem) {
;     ...
;   for (int t0 = blockIdx.x; t0 < 128 * 4; t0 += gridDim.x) {
;     const int t = ((gridDim.x & 7) == 0) ? xcd_tile(t0, 4) : t0;
;     const int mt = t >> 2, nt = t & 3, m0 = mt * 128, n0 = nt * 256;
;     f32x16 acc[2][4];
;     gemm_mainloop<1024>(A, Wt, 1024, 1024, m0, n0, smem, acc);
.LBB0_843:
	s_lshl_b32 s5, s4, 5
	s_and_b32 s40, s5, 0xffffff80
	s_lshl_b32 s4, s4, 8
	s_and_b32 s39, s4, 0x300
	s_mov_b32 s41, 0
	s_mov_b64 s[24:25], 0
	s_lshl_b32 s98, s40, 11
	s_add_u32 s98, s12, s98
	s_addc_u32 s99, s13, 0
	s_lshl_b32 s100, s39, 6
	s_add_u32 s100, s6, s100
	s_addc_u32 s101, s7, 0
	v_writelane_b32 v187, s64, 0
	v_writelane_b32 v187, s65, 1
	v_writelane_b32 v187, s66, 2
	v_writelane_b32 v187, s67, 3
	v_writelane_b32 v187, s68, 4
	v_writelane_b32 v187, s69, 5
	v_writelane_b32 v187, s70, 6
	v_writelane_b32 v187, s71, 7
	v_writelane_b32 v187, s72, 8
	v_writelane_b32 v187, s73, 9
	v_writelane_b32 v187, s74, 10
	v_writelane_b32 v187, s75, 11
	v_writelane_b32 v187, s76, 12
	v_writelane_b32 v187, s77, 13
	v_writelane_b32 v187, s78, 14
	v_writelane_b32 v187, s79, 15
	v_lshrrev_b32_e32 v188, 6, v196
	v_and_b32_e32 v190, 63, v196
	v_readfirstlane_b32 s73, v188
	v_lshrrev_b32_e32 v191, 2, v190
	v_bfe_u32 v192, v190, 4, 2
	v_and_b32_e32 v188, 3, v190
	v_xor_b32_e32 v188, v188, v192
	v_lshlrev_b32_e32 v188, 4, v188
	v_lshl_add_u32 v176, v191, 11, v188
	v_add_u32_e32 v177, 0x8000, v176
	v_lshl_add_u32 v178, v191, 6, v188
	v_and_b32_e32 v191, 31, v190
	v_lshrrev_b32_e32 v192, 5, v190
	v_bfe_u32 v188, v190, 2, 2
	v_xor_b32_e32 v188, v188, v192
	v_lshlrev_b32_e32 v188, 4, v188
	v_lshl_add_u32 v179, v191, 6, v188
	s_lshr_b32 s74, s73, 1
	s_lshl_b32 s74, s74, 12
	s_and_b32 s75, s73, 1
	s_lshl_b32 s75, s75, 13
	v_add_u32_e32 v181, s75, v179
	v_add_u32_e32 v179, s74, v179
	v_xor_b32_e32 v182, 32, v181
	v_xor_b32_e32 v180, 32, v179
	s_lshl_b32 s74, s73, 16
	s_add_u32 s64, s98, s74
	s_addc_u32 s65, s99, 0
	s_lshl_b32 s74, s73, 12
	s_add_u32 s66, s100, s74
	s_addc_u32 s67, s101, 0
	s_lshl_b32 s68, s73, 11
	s_lshl_b32 s69, s73, 12
	s_mov_b32 s70, 0
	s_mov_b32 s71, 0
	s_mov_b32 s72, 0
	s_waitcnt lgkmcnt(0)
	s_barrier
	s_mul_i32 s74, s70, 0x6000
	s_add_u32 s75, s74, s68
	s_mov_b32 m0, s75
	s_add_u32 s76, s74, 0x2000
	s_cmp_eq_u32 s70, 2
	s_cselect_b32 s76, 0x10000, s76
	global_load_lds_dwordx4 v176, s[64:65]
	s_add_u32 m0, s75, 0x400
	s_add_u32 s76, s76, s69
	global_load_lds_dwordx4 v177, s[64:65]
	s_mov_b32 m0, s76
	s_add_u32 s64, s64, 64
	s_addc_u32 s65, s65, 0
	global_load_lds_dwordx4 v178, s[66:67]
	global_load_lds_dwordx4 v178, s[66:67] offset:1024
	global_load_lds_dwordx4 v178, s[66:67] offset:2048
	global_load_lds_dwordx4 v178, s[66:67] offset:3072
	s_add_u32 s66, s66, 0x10000
	s_addc_u32 s67, s67, 0
	s_add_u32 s70, s70, 1
	s_cmp_eq_u32 s70, 3
	s_cselect_b32 s70, 0, s70
	s_mul_i32 s74, s70, 0x6000
	s_add_u32 s75, s74, s68
	s_mov_b32 m0, s75
	s_add_u32 s76, s74, 0x2000
	s_cmp_eq_u32 s70, 2
	s_cselect_b32 s76, 0x10000, s76
	global_load_lds_dwordx4 v176, s[64:65]
	s_add_u32 m0, s75, 0x400
	s_add_u32 s76, s76, s69
	global_load_lds_dwordx4 v177, s[64:65]
	s_mov_b32 m0, s76
	s_add_u32 s64, s64, 64
	s_addc_u32 s65, s65, 0
	global_load_lds_dwordx4 v178, s[66:67]
	global_load_lds_dwordx4 v178, s[66:67] offset:1024
	global_load_lds_dwordx4 v178, s[66:67] offset:2048
	global_load_lds_dwordx4 v178, s[66:67] offset:3072
	s_add_u32 s66, s66, 0x10000
	s_addc_u32 s67, s67, 0
	s_add_u32 s70, s70, 1
	s_cmp_eq_u32 s70, 3
	s_cselect_b32 s70, 0, s70
	v_mov_b32_e32 v112, 0
	v_mov_b32_e32 v113, 0
	v_mov_b32_e32 v114, 0
	v_mov_b32_e32 v115, 0
	v_mov_b32_e32 v116, 0
	v_mov_b32_e32 v117, 0
	v_mov_b32_e32 v118, 0
	v_mov_b32_e32 v119, 0
	v_mov_b32_e32 v120, 0
	v_mov_b32_e32 v121, 0
	v_mov_b32_e32 v122, 0
	v_mov_b32_e32 v123, 0
	v_mov_b32_e32 v124, 0
	v_mov_b32_e32 v125, 0
	v_mov_b32_e32 v126, 0
	v_mov_b32_e32 v127, 0
	v_mov_b32_e32 v96, 0
	v_mov_b32_e32 v97, 0
	v_mov_b32_e32 v98, 0
	v_mov_b32_e32 v99, 0
	v_mov_b32_e32 v100, 0
	v_mov_b32_e32 v101, 0
	v_mov_b32_e32 v102, 0
	v_mov_b32_e32 v103, 0
	v_mov_b32_e32 v104, 0
	v_mov_b32_e32 v105, 0
	v_mov_b32_e32 v106, 0
	v_mov_b32_e32 v107, 0
	v_mov_b32_e32 v108, 0
	v_mov_b32_e32 v109, 0
	v_mov_b32_e32 v110, 0
	v_mov_b32_e32 v111, 0
	v_mov_b32_e32 v80, 0
	v_mov_b32_e32 v81, 0
	v_mov_b32_e32 v82, 0
	v_mov_b32_e32 v83, 0
	v_mov_b32_e32 v84, 0
	v_mov_b32_e32 v85, 0
	v_mov_b32_e32 v86, 0
	v_mov_b32_e32 v87, 0
	v_mov_b32_e32 v88, 0
	v_mov_b32_e32 v89, 0
	v_mov_b32_e32 v90, 0
	v_mov_b32_e32 v91, 0
	v_mov_b32_e32 v92, 0
	v_mov_b32_e32 v93, 0
	v_mov_b32_e32 v94, 0
	v_mov_b32_e32 v95, 0
	v_mov_b32_e32 v64, 0
	v_mov_b32_e32 v65, 0
	v_mov_b32_e32 v66, 0
	v_mov_b32_e32 v67, 0
	v_mov_b32_e32 v68, 0
	v_mov_b32_e32 v69, 0
	v_mov_b32_e32 v70, 0
	v_mov_b32_e32 v71, 0
	v_mov_b32_e32 v72, 0
	v_mov_b32_e32 v73, 0
	v_mov_b32_e32 v74, 0
	v_mov_b32_e32 v75, 0
	v_mov_b32_e32 v76, 0
	v_mov_b32_e32 v77, 0
	v_mov_b32_e32 v78, 0
	v_mov_b32_e32 v79, 0
	v_mov_b32_e32 v48, 0
	v_mov_b32_e32 v49, 0
	v_mov_b32_e32 v50, 0
	v_mov_b32_e32 v51, 0
	v_mov_b32_e32 v52, 0
	v_mov_b32_e32 v53, 0
	v_mov_b32_e32 v54, 0
	v_mov_b32_e32 v55, 0
	v_mov_b32_e32 v56, 0
	v_mov_b32_e32 v57, 0
	v_mov_b32_e32 v58, 0
	v_mov_b32_e32 v59, 0
	v_mov_b32_e32 v60, 0
	v_mov_b32_e32 v61, 0
	v_mov_b32_e32 v62, 0
	v_mov_b32_e32 v63, 0
	v_mov_b32_e32 v32, 0
	v_mov_b32_e32 v33, 0
	v_mov_b32_e32 v34, 0
	v_mov_b32_e32 v35, 0
	v_mov_b32_e32 v36, 0
	v_mov_b32_e32 v37, 0
	v_mov_b32_e32 v38, 0
	v_mov_b32_e32 v39, 0
	v_mov_b32_e32 v40, 0
	v_mov_b32_e32 v41, 0
	v_mov_b32_e32 v42, 0
	v_mov_b32_e32 v43, 0
	v_mov_b32_e32 v44, 0
	v_mov_b32_e32 v45, 0
	v_mov_b32_e32 v46, 0
	v_mov_b32_e32 v47, 0
	v_mov_b32_e32 v16, 0
	v_mov_b32_e32 v17, 0
	v_mov_b32_e32 v18, 0
	v_mov_b32_e32 v19, 0
	v_mov_b32_e32 v20, 0
	v_mov_b32_e32 v21, 0
	v_mov_b32_e32 v22, 0
	v_mov_b32_e32 v23, 0
	v_mov_b32_e32 v24, 0
	v_mov_b32_e32 v25, 0
	v_mov_b32_e32 v26, 0
	v_mov_b32_e32 v27, 0
	v_mov_b32_e32 v28, 0
	v_mov_b32_e32 v29, 0
	v_mov_b32_e32 v30, 0
	v_mov_b32_e32 v31, 0
	v_mov_b32_e32 v0, 0
	v_mov_b32_e32 v1, 0
	v_mov_b32_e32 v2, 0
	v_mov_b32_e32 v3, 0
	v_mov_b32_e32 v4, 0
	v_mov_b32_e32 v5, 0
	v_mov_b32_e32 v6, 0
	v_mov_b32_e32 v7, 0
	v_mov_b32_e32 v8, 0
	v_mov_b32_e32 v9, 0
	v_mov_b32_e32 v10, 0
	v_mov_b32_e32 v11, 0
	v_mov_b32_e32 v12, 0
	v_mov_b32_e32 v13, 0
	v_mov_b32_e32 v14, 0
	v_mov_b32_e32 v15, 0
; #define MFMA32(a, b, c) __builtin_amdgcn_mfma_f32_32x32x16_bf16((a), (b), (c), 0, 0, 0)
; #define GA_LOAD(pr_) do { _Pragma("unroll") for (int i = 0; i < 4; ++i) ra[i] = *(const u32x4*)(Ab + (i * 32) * lda + (pr_) * 64); } while (0)
; #define GB_LOAD(kt_) do { const bfr* bk_ = Bb + (kt_) * NB * 32; \
;     _Pragma("unroll") for (int i = 0; i < 4; ++i) rb[i] = *(const u32x4*)(bk_ + (i * 64) * 32); } while (0)
; #define G_STORE(kt_) do { bfr* as_ = S0 + ((kt_) & 1) * GSTAGE; bfr* bs_ = as_ + 128 * 40; \
;     if (apar == ((kt_) & 1)) { _Pragma("unroll") for (int i = 0; i < 4; ++i) *(u32x4*)(as_ + asoff + i * 32 * 40) = ra[i]; } \
;     _Pragma("unroll") for (int i = 0; i < 4; ++i) *(u32x4*)(bs_ + bsoff + i * 64 * 40) = rb[i]; } while (0)
; template <int lda>
; DI void gemm_mainloop(const bfr* __restrict__ A, const bfr* __restrict__ Bt, int NB, int K, int m0, int n0, char* smem, f32x16 (&acc)[2][4]) {
;     ...
;   for (int kt = 0; kt < nk; ++kt) {
;     if (kt + 1 < nk) G_STORE(kt + 1);
;     if (kt + 2 < nk) {
;       GB_LOAD(kt + 2);
;       if ((kt & 1) == 0) GA_LOAD((kt >> 1) + 1);
;     }
;     const bfr* As = S0 + (kt & 1) * GSTAGE;
;     const bfr* Bs = As + 128 * 40;
; #pragma unroll
;     for (int ks = 0; ks < 2; ++ks) {
;       bf16x8 af[2], bfg[4];
; #pragma unroll
;       for (int i = 0; i < 2; ++i) af[i] = *(const bf16x8*)(As + (wr * 64 + i * 32 + r) * 40 + ks * 16 + hl * 8);
; #pragma unroll
;       for (int j = 0; j < 4; ++j) bfg[j] = *(const bf16x8*)(Bs + (wc * 128 + j * 32 + r) * 40 + ks * 16 + hl * 8);
; #pragma unroll
;       for (int i = 0; i < 2; ++i)
; #pragma unroll
;         for (int j = 0; j < 4; ++j) acc[i][j] = MFMA32(af[i], bfg[j], acc[i][j]);
;     }
;     __syncthreads();
;   }
.Lp6_loop:
	s_waitcnt vmcnt(6)
	s_barrier
	s_mul_i32 s74, s70, 0x6000
	s_add_u32 s75, s74, s68
	s_mov_b32 m0, s75
	s_add_u32 s76, s74, 0x2000
	s_cmp_eq_u32 s70, 2
	s_cselect_b32 s76, 0x10000, s76
	global_load_lds_dwordx4 v176, s[64:65]
	s_add_u32 m0, s75, 0x400
	s_add_u32 s76, s76, s69
	global_load_lds_dwordx4 v177, s[64:65]
	s_mov_b32 m0, s76
	s_add_u32 s64, s64, 64
	s_addc_u32 s65, s65, 0
	global_load_lds_dwordx4 v178, s[66:67]
	global_load_lds_dwordx4 v178, s[66:67] offset:1024
	global_load_lds_dwordx4 v178, s[66:67] offset:2048
	global_load_lds_dwordx4 v178, s[66:67] offset:3072
	s_add_u32 s66, s66, 0x10000
	s_addc_u32 s67, s67, 0
	s_add_u32 s70, s70, 1
	s_cmp_eq_u32 s70, 3
	s_cselect_b32 s70, 0, s70
	s_mul_i32 s74, s71, 0x6000
	s_add_u32 s75, s74, 0x2000
	s_cmp_eq_u32 s71, 2
	s_cselect_b32 s75, 0x10000, s75
	v_add_u32_e32 v183, s74, v179
	v_add_u32_e32 v185, s75, v181
	v_add_u32_e32 v184, s74, v180
	v_add_u32_e32 v186, s75, v182
	ds_read_b128 v[128:131], v183
	ds_read_b128 v[144:147], v185
	ds_read_b128 v[148:151], v185 offset:2048
	ds_read_b128 v[152:155], v185 offset:4096
	ds_read_b128 v[156:159], v185 offset:6144
	ds_read_b128 v[132:135], v183 offset:2048
	ds_read_b128 v[136:139], v184
	ds_read_b128 v[160:163], v186
	ds_read_b128 v[164:167], v186 offset:2048
	ds_read_b128 v[168:171], v186 offset:4096
	ds_read_b128 v[172:175], v186 offset:6144
	ds_read_b128 v[140:143], v184 offset:2048
	s_add_u32 s71, s71, 1
	s_cmp_eq_u32 s71, 3
	s_cselect_b32 s71, 0, s71
	s_waitcnt lgkmcnt(10)
	v_mfma_f32_32x32x16_bf16 v[112:127], v[128:131], v[144:147], v[112:127]
	s_waitcnt lgkmcnt(9)
	v_mfma_f32_32x32x16_bf16 v[96:111], v[128:131], v[148:151], v[96:111]
	s_waitcnt lgkmcnt(8)
	v_mfma_f32_32x32x16_bf16 v[80:95], v[128:131], v[152:155], v[80:95]
	s_waitcnt lgkmcnt(7)
	v_mfma_f32_32x32x16_bf16 v[64:79], v[128:131], v[156:159], v[64:79]
	s_waitcnt lgkmcnt(6)
	v_mfma_f32_32x32x16_bf16 v[48:63], v[132:135], v[144:147], v[48:63]
	v_mfma_f32_32x32x16_bf16 v[32:47], v[132:135], v[148:151], v[32:47]
	v_mfma_f32_32x32x16_bf16 v[16:31], v[132:135], v[152:155], v[16:31]
	v_mfma_f32_32x32x16_bf16 v[0:15], v[132:135], v[156:159], v[0:15]
	s_waitcnt lgkmcnt(4)
	v_mfma_f32_32x32x16_bf16 v[112:127], v[136:139], v[160:163], v[112:127]
	s_waitcnt lgkmcnt(3)
	v_mfma_f32_32x32x16_bf16 v[96:111], v[136:139], v[164:167], v[96:111]
	s_waitcnt lgkmcnt(2)
	v_mfma_f32_32x32x16_bf16 v[80:95], v[136:139], v[168:171], v[80:95]
	s_waitcnt lgkmcnt(1)
	v_mfma_f32_32x32x16_bf16 v[64:79], v[136:139], v[172:175], v[64:79]
	s_waitcnt lgkmcnt(0)
	v_mfma_f32_32x32x16_bf16 v[48:63], v[140:143], v[160:163], v[48:63]
	v_mfma_f32_32x32x16_bf16 v[32:47], v[140:143], v[164:167], v[32:47]
	v_mfma_f32_32x32x16_bf16 v[16:31], v[140:143], v[168:171], v[16:31]
	v_mfma_f32_32x32x16_bf16 v[0:15], v[140:143], v[172:175], v[0:15]
	s_add_u32 s72, s72, 1
	s_cmp_lt_u32 s72, 30
	s_cbranch_scc1 .Lp6_loop
	s_waitcnt vmcnt(6)
	s_barrier
	s_mul_i32 s74, s71, 0x6000
	s_add_u32 s75, s74, 0x2000
	s_cmp_eq_u32 s71, 2
	s_cselect_b32 s75, 0x10000, s75
	v_add_u32_e32 v183, s74, v179
	v_add_u32_e32 v185, s75, v181
	v_add_u32_e32 v184, s74, v180
	v_add_u32_e32 v186, s75, v182
	ds_read_b128 v[128:131], v183
	ds_read_b128 v[144:147], v185
	ds_read_b128 v[148:151], v185 offset:2048
	ds_read_b128 v[152:155], v185 offset:4096
	ds_read_b128 v[156:159], v185 offset:6144
	ds_read_b128 v[132:135], v183 offset:2048
	ds_read_b128 v[136:139], v184
	ds_read_b128 v[160:163], v186
	ds_read_b128 v[164:167], v186 offset:2048
	ds_read_b128 v[168:171], v186 offset:4096
	ds_read_b128 v[172:175], v186 offset:6144
	ds_read_b128 v[140:143], v184 offset:2048
	s_add_u32 s71, s71, 1
	s_cmp_eq_u32 s71, 3
	s_cselect_b32 s71, 0, s71
	s_waitcnt lgkmcnt(10)
	v_mfma_f32_32x32x16_bf16 v[112:127], v[128:131], v[144:147], v[112:127]
	s_waitcnt lgkmcnt(9)
	v_mfma_f32_32x32x16_bf16 v[96:111], v[128:131], v[148:151], v[96:111]
	s_waitcnt lgkmcnt(8)
	v_mfma_f32_32x32x16_bf16 v[80:95], v[128:131], v[152:155], v[80:95]
	s_waitcnt lgkmcnt(7)
	v_mfma_f32_32x32x16_bf16 v[64:79], v[128:131], v[156:159], v[64:79]
	s_waitcnt lgkmcnt(6)
	v_mfma_f32_32x32x16_bf16 v[48:63], v[132:135], v[144:147], v[48:63]
	v_mfma_f32_32x32x16_bf16 v[32:47], v[132:135], v[148:151], v[32:47]
	v_mfma_f32_32x32x16_bf16 v[16:31], v[132:135], v[152:155], v[16:31]
	v_mfma_f32_32x32x16_bf16 v[0:15], v[132:135], v[156:159], v[0:15]
	s_waitcnt lgkmcnt(4)
	v_mfma_f32_32x32x16_bf16 v[112:127], v[136:139], v[160:163], v[112:127]
	s_waitcnt lgkmcnt(3)
	v_mfma_f32_32x32x16_bf16 v[96:111], v[136:139], v[164:167], v[96:111]
	s_waitcnt lgkmcnt(2)
	v_mfma_f32_32x32x16_bf16 v[80:95], v[136:139], v[168:171], v[80:95]
	s_waitcnt lgkmcnt(1)
	v_mfma_f32_32x32x16_bf16 v[64:79], v[136:139], v[172:175], v[64:79]
	s_waitcnt lgkmcnt(0)
	v_mfma_f32_32x32x16_bf16 v[48:63], v[140:143], v[160:163], v[48:63]
	v_mfma_f32_32x32x16_bf16 v[32:47], v[140:143], v[164:167], v[32:47]
	v_mfma_f32_32x32x16_bf16 v[16:31], v[140:143], v[168:171], v[16:31]
	v_mfma_f32_32x32x16_bf16 v[0:15], v[140:143], v[172:175], v[0:15]
	s_waitcnt vmcnt(0)
	s_barrier
; template <int lda>
; DI void gemm_mainloop(const bfr* __restrict__ A, const bfr* __restrict__ Bt, int NB, int K, int m0, int n0, char* smem, f32x16 (&acc)[2][4]) {
;     ...
;   for (int kt = 0; kt < nk; ++kt) {
;     if (kt + 1 < nk) G_STORE(kt + 1);
;     if (kt + 2 < nk) {
;       GB_LOAD(kt + 2);
;       if ((kt & 1) == 0) GA_LOAD((kt >> 1) + 1);
;     }
;     const bfr* As = S0 + (kt & 1) * GSTAGE;
;     const bfr* Bs = As + 128 * 40;
; #pragma unroll
;     for (int ks = 0; ks < 2; ++ks) {
;       bf16x8 af[2], bfg[4];
; #pragma unroll
;       for (int i = 0; i < 2; ++i) af[i] = *(const bf16x8*)(As + (wr * 64 + i * 32 + r) * 40 + ks * 16 + hl * 8);
; #pragma unroll
;       for (int j = 0; j < 4; ++j) bfg[j] = *(const bf16x8*)(Bs + (wc * 128 + j * 32 + r) * 40 + ks * 16 + hl * 8);
; #pragma unroll
;       for (int i = 0; i < 2; ++i)
; #pragma unroll
;         for (int j = 0; j < 4; ++j) acc[i][j] = MFMA32(af[i], bfg[j], acc[i][j]);
;     }
;     __syncthreads();
;   }
; template <bool FIRST, bool HAS_H>
; DI void phase_gemm_resid(const Params& p, const bfr* A, const bfr* Wt, const float* gnext, float* ss, char* smem) {
;     ...
;     int tid2 = threadIdx.x;
;     asm volatile("" : "+v"(tid2));
;     const int lane = tid2 & 63, wid = tid2 >> 6, wr = wid >> 1, wc = wid & 1, r = lane & 31, hl = lane >> 5;
;     const float* xsrc = FIRST ? p.x_prompt : X;
;     const int rbase = m0 + wr * 64 + 4 * hl, cbase = n0 + wc * 128 + r;
; #pragma unroll
;     for (int i = 0; i < 2; ++i) {
; #pragma unroll
;       for (int qh = 0; qh < 2; ++qh) {
;         float rs[8];
; #pragma unroll
;         for (int q = 0; q < 8; ++q) rs[q] = 0.f;
; #pragma unroll
;         for (int jh = 0; jh < 2; ++jh) {
;           float xo[2][8];
; #pragma unroll
;           for (int jj = 0; jj < 2; ++jj)
; #pragma unroll
;             for (int q = 0; q < 8; ++q)
;               xo[jj][q] = xsrc[(rbase + i * 32 + crow(qh * 8 + q, 0)) * 1024 + cbase + (jh * 2 + jj) * 32];
; #pragma unroll
;           for (int q = 0; q < 8; ++q) {
;             const int o = (rbase + i * 32 + crow(qh * 8 + q, 0)) * 1024 + cbase;
; #pragma unroll
;             for (int jj = 0; jj < 2; ++jj) {
;               const int j = jh * 2 + jj;
;               const float xn = xo[jj][q] + acc[i][j][qh * 8 + q];
;               X[o + j * 32] = xn;
;               if (HAS_H) Hn[o + j * 32] = f2bf(xn * gnext[cbase + j * 32]);
	s_mul_i32 s74, s71, 0x6000
	s_add_u32 s75, s74, 0x2000
	s_cmp_eq_u32 s71, 2
	s_cselect_b32 s75, 0x10000, s75
	v_add_u32_e32 v183, s74, v179
	v_add_u32_e32 v185, s75, v181
	v_add_u32_e32 v184, s74, v180
	v_add_u32_e32 v186, s75, v182
	ds_read_b128 v[128:131], v183
	ds_read_b128 v[144:147], v185
	ds_read_b128 v[148:151], v185 offset:2048
	ds_read_b128 v[152:155], v185 offset:4096
	ds_read_b128 v[156:159], v185 offset:6144
	ds_read_b128 v[132:135], v183 offset:2048
	ds_read_b128 v[136:139], v184
	ds_read_b128 v[160:163], v186
	ds_read_b128 v[164:167], v186 offset:2048
	ds_read_b128 v[168:171], v186 offset:4096
	ds_read_b128 v[172:175], v186 offset:6144
	ds_read_b128 v[140:143], v184 offset:2048
	s_add_u32 s71, s71, 1
	s_cmp_eq_u32 s71, 3
	s_cselect_b32 s71, 0, s71
	s_waitcnt lgkmcnt(10)
	v_mfma_f32_32x32x16_bf16 v[112:127], v[128:131], v[144:147], v[112:127]
	s_waitcnt lgkmcnt(9)
	v_mfma_f32_32x32x16_bf16 v[96:111], v[128:131], v[148:151], v[96:111]
	s_waitcnt lgkmcnt(8)
	v_mfma_f32_32x32x16_bf16 v[80:95], v[128:131], v[152:155], v[80:95]
	s_waitcnt lgkmcnt(7)
	v_mfma_f32_32x32x16_bf16 v[64:79], v[128:131], v[156:159], v[64:79]
	s_waitcnt lgkmcnt(6)
	v_mfma_f32_32x32x16_bf16 v[48:63], v[132:135], v[144:147], v[48:63]
	v_mfma_f32_32x32x16_bf16 v[32:47], v[132:135], v[148:151], v[32:47]
	v_mfma_f32_32x32x16_bf16 v[16:31], v[132:135], v[152:155], v[16:31]
	v_mfma_f32_32x32x16_bf16 v[0:15], v[132:135], v[156:159], v[0:15]
	s_waitcnt lgkmcnt(4)
	v_mfma_f32_32x32x16_bf16 v[112:127], v[136:139], v[160:163], v[112:127]
	s_waitcnt lgkmcnt(3)
	v_mfma_f32_32x32x16_bf16 v[96:111], v[136:139], v[164:167], v[96:111]
	s_waitcnt lgkmcnt(2)
	v_mfma_f32_32x32x16_bf16 v[80:95], v[136:139], v[168:171], v[80:95]
	s_waitcnt lgkmcnt(1)
	v_mfma_f32_32x32x16_bf16 v[64:79], v[136:139], v[172:175], v[64:79]
	s_waitcnt lgkmcnt(0)
	v_mfma_f32_32x32x16_bf16 v[48:63], v[140:143], v[160:163], v[48:63]
	v_mfma_f32_32x32x16_bf16 v[32:47], v[140:143], v[164:167], v[32:47]
	v_mfma_f32_32x32x16_bf16 v[16:31], v[140:143], v[168:171], v[16:31]
	v_mfma_f32_32x32x16_bf16 v[0:15], v[140:143], v[172:175], v[0:15]
	s_nop 7
	v_readlane_b32 s64, v187, 0
	v_readlane_b32 s65, v187, 1
	v_readlane_b32 s66, v187, 2
	v_readlane_b32 s67, v187, 3
	v_readlane_b32 s68, v187, 4
	v_readlane_b32 s69, v187, 5
	v_readlane_b32 s70, v187, 6
	v_readlane_b32 s71, v187, 7
	v_readlane_b32 s72, v187, 8
	v_readlane_b32 s73, v187, 9
	v_readlane_b32 s74, v187, 10
	v_readlane_b32 s75, v187, 11
	v_readlane_b32 s76, v187, 12
	v_readlane_b32 s77, v187, 13
	v_readlane_b32 s78, v187, 14
	v_readlane_b32 s79, v187, 15
	s_nop 7
	s_waitcnt vmcnt(1)
	s_nop 0
	s_nop 0
	s_nop 0
	s_waitcnt vmcnt(0)
	s_nop 0
	v_add_u32_e32 v136, v169, v171
	s_nop 0
	v_add_u32_e32 v188, v169, v170
	s_nop 0
	s_nop 0
	s_nop 0
	s_nop 0
	s_nop 0
	s_nop 0
	s_nop 0
	s_nop 0
	s_nop 0
	s_nop 0
	s_nop 0
	s_waitcnt lgkmcnt(0)
	s_nop 0
	s_nop 0
	s_nop 0
	s_nop 0
	s_nop 0
	s_nop 0
	s_nop 0
	s_nop 0
	s_nop 0
	s_nop 0
	s_nop 0
	s_nop 0
	s_nop 0
	s_nop 0
	s_nop 0
	s_nop 0
	s_nop 0
	s_nop 0
	v_mov_b32_e32 v188, v196
	s_waitcnt lgkmcnt(0)
	s_nop 0
	s_nop 0
	v_ashrrev_i32_e32 v190, 1, v188
	v_and_b32_e32 v190, 0xffffffc0, v190
	v_and_b32_e32 v225, 31, v188
	v_add_u32_e32 v190, s40, v190
	v_lshrrev_b32_e32 v191, 3, v188
	v_lshlrev_b32_e32 v188, 1, v188
	v_and_or_b32 v224, v191, 4, v190
	v_and_b32_e32 v188, 0x80, v188
	v_or3_b32 v197, s39, v188, v225
	v_lshlrev_b32_e32 v199, 10, v224
	v_or_b32_e32 v190, v199, v197
	v_ashrrev_i32_e32 v191, 31, v190
	v_lshlrev_b64 v[192:193], 2, v[190:191]
	s_nop 0
	v_lshl_add_u64 v[194:195], s[18:19], 0, v[192:193]
	global_load_dword v188, v[194:195], off
	v_or_b32_e32 v198, 32, v197
	v_or_b32_e32 v226, 0x2400, v199
	v_or_b32_e32 v228, 0x2800, v199
	v_or_b32_e32 v229, 0x2c00, v199
	v_lshl_add_u64 v[192:193], s[16:17], 0, v[192:193]
	s_nop 0
	v_or_b32_e32 v216, 0x400, v199
	v_or_b32_e32 v194, v216, v197
	v_ashrrev_i32_e32 v195, 31, v194
	v_or_b32_e32 v217, 0x800, v199
	v_lshl_add_u64 v[212:213], v[194:195], 2, s[18:19]
	v_or_b32_e32 v214, v217, v197
	v_ashrrev_i32_e32 v195, 31, v199
	v_mov_b32_e32 v194, v190
	v_ashrrev_i32_e32 v215, 31, v214
	v_lshl_add_u64 v[194:195], v[194:195], 2, s[18:19]
	global_load_dword v218, v[194:195], off offset:128
	v_lshl_add_u64 v[214:215], v[214:215], 2, s[18:19]
	global_load_dword v219, v[212:213], off
	global_load_dword v220, v[214:215], off
	v_or_b32_e32 v212, v216, v198
	v_ashrrev_i32_e32 v213, 31, v212
	v_lshl_add_u64 v[212:213], v[212:213], 2, s[18:19]
	global_load_dword v222, v[212:213], off
	s_nop 0
	v_or_b32_e32 v221, 0xc00, v199
	v_or_b32_e32 v223, 0x2000, v199
	v_or_b32_e32 v214, v223, v197
	v_ashrrev_i32_e32 v215, 31, v214
	v_lshl_add_u64 v[214:215], v[214:215], 2, s[18:19]
	v_cmp_eq_u32_e32 vcc, 31, v225
	v_ashrrev_i32_e32 v225, 31, v224
	s_nop 0
	s_nop 0
	s_nop 0
	v_or_b32_e32 v200, v217, v198
	v_ashrrev_i32_e32 v201, 31, v200
	v_lshl_add_u64 v[200:201], v[200:201], 2, s[18:19]
	global_load_dword v227, v[200:201], off
	v_or_b32_e32 v212, v221, v197
	v_or_b32_e32 v200, v226, v197
	v_or_b32_e32 v202, v228, v197
	s_nop 0
	v_ashrrev_i32_e32 v213, 31, v212
	v_ashrrev_i32_e32 v201, 31, v200
	v_ashrrev_i32_e32 v203, 31, v202
	v_lshl_add_u64 v[212:213], v[212:213], 2, s[18:19]
	v_lshl_add_u64 v[200:201], v[200:201], 2, s[18:19]
	v_lshl_add_u64 v[202:203], v[202:203], 2, s[18:19]
	s_nop 0
	s_nop 0
	s_nop 0
	s_nop 0
	v_or_b32_e32 v204, v229, v197
	v_ashrrev_i32_e32 v205, 31, v204
	v_lshl_add_u64 v[204:205], v[204:205], 2, s[18:19]
	v_or_b32_e32 v206, v228, v198
	v_ashrrev_i32_e32 v207, 31, v206
	v_lshl_add_u64 v[206:207], v[206:207], 2, s[18:19]
	s_waitcnt vmcnt(0)
; DI bfr f2bf(float a) { return (bfr)(pack2(a, 0.f) & 0xffffu); }
; DI int crow(int reg, int h) { return (reg & 3) + 8 * (reg >> 2) + 4 * h; }
; template <bool FIRST, bool HAS_H>
; DI void phase_gemm_resid(const Params& p, const bfr* A, const bfr* Wt, const float* gnext, float* ss, char* smem) {
;     ...
; #pragma unroll
;     for (int i = 0; i < 2; ++i) {
; #pragma unroll
;       for (int qh = 0; qh < 2; ++qh) {
;         float rs[8];
; #pragma unroll
;         for (int q = 0; q < 8; ++q) rs[q] = 0.f;
; #pragma unroll
;         for (int jh = 0; jh < 2; ++jh) {
;           float xo[2][8];
; #pragma unroll
;           for (int jj = 0; jj < 2; ++jj)
; #pragma unroll
;             for (int q = 0; q < 8; ++q)
;               xo[jj][q] = xsrc[(rbase + i * 32 + crow(qh * 8 + q, 0)) * 1024 + cbase + (jh * 2 + jj) * 32];
; #pragma unroll
;           for (int q = 0; q < 8; ++q) {
;             const int o = (rbase + i * 32 + crow(qh * 8 + q, 0)) * 1024 + cbase;
; #pragma unroll
;             for (int jj = 0; jj < 2; ++jj) {
;               const int j = jh * 2 + jj;
;               const float xn = xo[jj][q] + acc[i][j][qh * 8 + q];
;               X[o + j * 32] = xn;
;               if (HAS_H) Hn[o + j * 32] = f2bf(xn * gnext[cbase + j * 32]);
;               rs[q] += xn * xn;
;             }
;           }
;         }
	s_nop 3
	v_add_f32_e32 v98, v98, v227
	s_nop 0
	global_load_dword v210, v[212:213], off
	global_load_dword v211, v[214:215], off
	s_nop 0
	global_load_dword v212, v[200:201], off
	global_load_dword v213, v[202:203], off
	global_load_dword v214, v[204:205], off
	v_or_b32_e32 v200, v221, v198
	v_or_b32_e32 v202, v223, v198
	v_or_b32_e32 v204, v226, v198
	v_ashrrev_i32_e32 v201, 31, v200
	v_ashrrev_i32_e32 v203, 31, v202
	v_ashrrev_i32_e32 v205, 31, v204
	v_or_b32_e32 v208, v229, v198
	v_lshl_add_u64 v[200:201], v[200:201], 2, s[18:19]
	v_lshl_add_u64 v[202:203], v[202:203], 2, s[18:19]
	v_lshl_add_u64 v[204:205], v[204:205], 2, s[18:19]
	v_ashrrev_i32_e32 v209, 31, v208
	v_lshl_add_u64 v[208:209], v[208:209], 2, s[18:19]
	global_load_dword v200, v[200:201], off
	s_nop 0
	global_load_dword v201, v[202:203], off
	s_nop 0
	global_load_dword v202, v[204:205], off
	global_load_dword v203, v[206:207], off
	s_nop 0
	global_load_dword v204, v[208:209], off
	v_add_f32_e32 v205, v112, v188
	v_or_b32_e32 v112, 0x400, v190
	global_store_dword v[192:193], v205, off
	v_lshlrev_b32_e32 v188, 2, v197
	v_add_f32_e32 v207, v96, v218
	v_add_f32_e32 v209, v113, v219
	v_ashrrev_i32_e32 v113, 31, v112
	v_or_b32_e32 v96, 0x420, v190
	global_load_dword v206, v188, s[14:15]
	s_nop 0
	global_store_dword v[192:193], v207, off offset:128
	v_lshl_add_u64 v[112:113], v[112:113], 2, s[16:17]
	v_add_f32_e32 v185, v97, v222
	v_ashrrev_i32_e32 v97, 31, v96
	global_load_dword v208, v188, s[14:15] offset:128
	v_lshl_add_u64 v[96:97], v[96:97], 2, s[16:17]
	global_store_dword v[112:113], v209, off
	s_nop 0
	v_or_b32_e32 v172, 0x800, v190
	v_ashrrev_i32_e32 v173, 31, v172
	global_load_dword v184, v188, s[14:15]
	v_add_f32_e32 v177, v114, v220
	global_store_dword v[96:97], v185, off
	v_lshl_add_u64 v[96:97], v[172:173], 2, s[16:17]
	v_or_b32_e32 v174, 0x820, v190
	global_load_dword v176, v188, s[14:15] offset:128
	v_ashrrev_i32_e32 v175, 31, v174
	global_store_dword v[96:97], v177, off
	global_load_dword v178, v188, s[14:15]
	v_lshl_add_u64 v[96:97], v[174:175], 2, s[16:17]
	global_store_dword v[96:97], v98, off
	global_load_dword v179, v188, s[14:15] offset:128
	s_nop 0
	v_lshl_add_u64 v[158:159], v[172:173], 1, s[10:11]
	v_lshl_add_u64 v[96:97], v[224:225], 2, s[8:9]
	s_waitcnt vmcnt(21)
	v_add_f32_e32 v115, v115, v210
	s_nop 0
	s_waitcnt vmcnt(10)
	v_mul_f32_e32 v112, v205, v206
	s_nop 0
	v_cvt_pk_bf16_f32 v114, v112, s0
	v_lshl_add_u64 v[112:113], v[190:191], 1, s[10:11]
	global_store_short v[112:113], v114, off
	s_waitcnt vmcnt(9)
	v_mul_f32_e32 v114, v207, v208
	v_cvt_pk_bf16_f32 v114, v114, s0
	global_store_short v[112:113], v114, off offset:64
	s_nop 0
	v_or_b32_e32 v154, 0xc00, v190
	v_ashrrev_i32_e32 v155, 31, v154
	v_mul_f32_e32 v152, v98, v98
	s_waitcnt vmcnt(8)
	v_mul_f32_e32 v156, v209, v184
	v_cvt_pk_bf16_f32 v156, v156, s0
	global_store_short v[112:113], v156, off offset:2048
	v_mul_f32_e32 v114, v207, v207
	s_nop 0
	v_add_f32_e32 v169, v119, v214
	v_add_f32_e32 v171, v103, v204
	s_waitcnt vmcnt(5)
	v_mul_f32_e32 v157, v177, v178
	v_cvt_pk_bf16_f32 v157, v157, s0
	global_store_short v[158:159], v157, off
	s_waitcnt vmcnt(4)
	v_mul_f32_e32 v157, v98, v179
	v_cvt_pk_bf16_f32 v157, v157, s0
	v_lshl_add_u64 v[158:159], v[174:175], 1, s[10:11]
	s_nop 0
	global_store_short v[158:159], v157, off
	v_lshl_add_u64 v[158:159], v[154:155], 2, s[16:17]
	global_store_dword v[158:159], v115, off
	global_load_dword v153, v188, s[14:15]
	v_or_b32_e32 v158, 0xc20, v190
	v_ashrrev_i32_e32 v159, 31, v158
	v_add_f32_e32 v157, v99, v200
	v_lshl_add_u64 v[98:99], v[158:159], 2, s[16:17]
	global_store_dword v[98:99], v157, off
	s_nop 0
	global_load_dword v160, v188, s[14:15] offset:128
	v_add_f32_e32 v161, v100, v201
	v_add_f32_e32 v163, v117, v212
	v_add_f32_e32 v165, v118, v213
	v_add_f32_e32 v167, v102, v203
	v_mul_f32_e32 v156, v185, v176
	v_cvt_pk_bf16_f32 v156, v156, s0
	s_nop 0
	v_or_b32_e32 v148, 0x2000, v190
	v_ashrrev_i32_e32 v149, 31, v148
	v_add_f32_e32 v150, v116, v211
	v_lshl_add_u64 v[98:99], v[148:149], 2, s[16:17]
	global_store_dword v[98:99], v150, off
	global_load_dword v151, v188, s[14:15]
	v_or_b32_e32 v116, 0x2400, v190
	s_nop 0
	v_or_b32_e32 v140, 0x2020, v190
	v_ashrrev_i32_e32 v141, 31, v140
	v_lshl_add_u64 v[98:99], v[140:141], 2, s[16:17]
	global_store_dword v[98:99], v161, off
	global_load_dword v162, v188, s[14:15] offset:128
	v_ashrrev_i32_e32 v117, 31, v116
	v_lshl_add_u64 v[98:99], v[116:117], 2, s[16:17]
	v_or_b32_e32 v142, 0x2420, v190
	global_store_dword v[98:99], v163, off
	v_ashrrev_i32_e32 v143, 31, v142
	s_nop 0
	global_load_dword v146, v188, s[14:15]
	v_add_f32_e32 v147, v101, v202
	v_lshl_add_u64 v[98:99], v[142:143], 2, s[16:17]
	global_store_dword v[98:99], v147, off
	global_load_dword v164, v188, s[14:15] offset:128
	v_lshl_add_u64 v[116:117], v[116:117], 1, s[10:11]
	global_store_short v[112:113], v156, off offset:2112
	s_nop 0
	v_or_b32_e32 v136, 0x2800, v190
	v_ashrrev_i32_e32 v137, 31, v136
	v_lshl_add_u64 v[98:99], v[136:137], 2, s[16:17]
	global_store_dword v[98:99], v165, off
	global_load_dword v166, v188, s[14:15]
	v_mul_f32_e32 v156, v185, v185
	v_fmac_f32_e32 v114, v205, v205
	s_nop 0
	v_or_b32_e32 v128, 0x2820, v190
	v_ashrrev_i32_e32 v129, 31, v128
	v_lshl_add_u64 v[98:99], v[128:129], 2, s[16:17]
	global_store_dword v[98:99], v167, off
	global_load_dword v168, v188, s[14:15] offset:128
	v_or_b32_e32 v98, 0x2c00, v190
	v_ashrrev_i32_e32 v99, 31, v98
	v_lshl_add_u64 v[100:101], v[98:99], 2, s[16:17]
	global_store_dword v[100:101], v169, off
	global_load_dword v170, v188, s[14:15]
	v_or_b32_e32 v100, 0x2c20, v190
	v_ashrrev_i32_e32 v101, 31, v100
	v_lshl_add_u64 v[102:103], v[100:101], 2, s[16:17]
	global_store_dword v[102:103], v171, off
	v_or_b32_e32 v102, 64, v197
	v_or_b32_e32 v118, v216, v102
	v_or_b32_e32 v130, v217, v102
	v_or_b32_e32 v132, v221, v102
	v_or_b32_e32 v134, v223, v102
	v_ashrrev_i32_e32 v119, 31, v118
	v_ashrrev_i32_e32 v131, 31, v130
	v_ashrrev_i32_e32 v133, 31, v132
	v_ashrrev_i32_e32 v135, 31, v134
	v_or_b32_e32 v138, v226, v102
	v_or_b32_e32 v144, v228, v102
	v_lshl_add_u64 v[118:119], v[118:119], 2, s[18:19]
	v_lshl_add_u64 v[130:131], v[130:131], 2, s[18:19]
	v_lshl_add_u64 v[132:133], v[132:133], 2, s[18:19]
	v_lshl_add_u64 v[134:135], v[134:135], 2, s[18:19]
	v_ashrrev_i32_e32 v139, 31, v138
	v_ashrrev_i32_e32 v145, 31, v144
	s_waitcnt vmcnt(18)
; DI bfr f2bf(float a) { return (bfr)(pack2(a, 0.f) & 0xffffu); }
; DI int crow(int reg, int h) { return (reg & 3) + 8 * (reg >> 2) + 4 * h; }
; template <bool FIRST, bool HAS_H>
; DI void phase_gemm_resid(const Params& p, const bfr* A, const bfr* Wt, const float* gnext, float* ss, char* smem) {
;     ...
; #pragma unroll
;     for (int i = 0; i < 2; ++i) {
; #pragma unroll
;       for (int qh = 0; qh < 2; ++qh) {
;         float rs[8];
; #pragma unroll
;         for (int q = 0; q < 8; ++q) rs[q] = 0.f;
; #pragma unroll
;         for (int jh = 0; jh < 2; ++jh) {
;           float xo[2][8];
; #pragma unroll
;           for (int jj = 0; jj < 2; ++jj)
; #pragma unroll
;             for (int q = 0; q < 8; ++q)
;               xo[jj][q] = xsrc[(rbase + i * 32 + crow(qh * 8 + q, 0)) * 1024 + cbase + (jh * 2 + jj) * 32];
; #pragma unroll
;           for (int q = 0; q < 8; ++q) {
;             const int o = (rbase + i * 32 + crow(qh * 8 + q, 0)) * 1024 + cbase;
; #pragma unroll
;             for (int jj = 0; jj < 2; ++jj) {
;               const int j = jh * 2 + jj;
;               const float xn = xo[jj][q] + acc[i][j][qh * 8 + q];
;               X[o + j * 32] = xn;
;               if (HAS_H) Hn[o + j * 32] = f2bf(xn * gnext[cbase + j * 32]);
;               rs[q] += xn * xn;
;             }
;           }
;         }
	v_mul_f32_e32 v103, v115, v153
	v_lshl_add_u64 v[138:139], v[138:139], 2, s[18:19]
	v_lshl_add_u64 v[144:145], v[144:145], 2, s[18:19]
	global_load_dword v172, v[194:195], off offset:256
	global_load_dword v173, v[118:119], off
	s_nop 0
	global_load_dword v130, v[130:131], off
	s_nop 0
	global_load_dword v131, v[132:133], off
	s_nop 0
	global_load_dword v132, v[134:135], off
	global_load_dword v133, v[138:139], off
	s_nop 0
	global_load_dword v134, v[144:145], off
	global_load_dword v135, v[194:195], off offset:384
	v_cvt_pk_bf16_f32 v103, v103, s0
	v_lshl_add_u64 v[118:119], v[154:155], 1, s[10:11]
	global_store_short v[118:119], v103, off
	v_or_b32_e32 v103, 0x60, v197
	v_or_b32_e32 v118, v216, v103
	v_ashrrev_i32_e32 v119, 31, v118
	v_lshl_add_u64 v[118:119], v[118:119], 2, s[18:19]
	global_load_dword v138, v[118:119], off
	s_waitcnt vmcnt(26)
	v_mul_f32_e32 v118, v157, v160
	v_cvt_pk_bf16_f32 v139, v118, s0
	v_lshl_add_u64 v[118:119], v[158:159], 1, s[10:11]
	global_store_short v[118:119], v139, off
	v_or_b32_e32 v118, v217, v103
	v_mul_f32_e32 v139, v157, v157
	v_ashrrev_i32_e32 v119, 31, v118
	v_fmac_f32_e32 v139, v115, v115
	s_waitcnt vmcnt(25)
	v_mul_f32_e32 v115, v150, v151
	v_lshl_add_u64 v[118:119], v[118:119], 2, s[18:19]
	v_cvt_pk_bf16_f32 v115, v115, s0
	global_load_dword v144, v[118:119], off
	v_lshl_add_u64 v[118:119], v[148:149], 1, s[10:11]
	global_store_short v[118:119], v115, off
	s_waitcnt vmcnt(25)
	v_mul_f32_e32 v115, v161, v162
	v_cvt_pk_bf16_f32 v115, v115, s0
	v_lshl_add_u64 v[118:119], v[140:141], 1, s[10:11]
	global_store_short v[118:119], v115, off
	v_or_b32_e32 v118, v221, v103
	v_ashrrev_i32_e32 v119, 31, v118
	v_lshl_add_u64 v[118:119], v[118:119], 2, s[18:19]
	global_load_dword v140, v[118:119], off
	s_waitcnt vmcnt(25)
	v_mul_f32_e32 v118, v163, v146
	v_cvt_pk_bf16_f32 v118, v118, s0
	global_store_short v[116:117], v118, off
	s_waitcnt vmcnt(24)
	v_mul_f32_e32 v116, v147, v164
	v_cvt_pk_bf16_f32 v118, v116, s0
	v_lshl_add_u64 v[116:117], v[142:143], 1, s[10:11]
	global_store_short v[116:117], v118, off
	v_or_b32_e32 v116, v223, v103
	v_ashrrev_i32_e32 v117, 31, v116
	v_lshl_add_u64 v[116:117], v[116:117], 2, s[18:19]
	global_load_dword v141, v[116:117], off
	s_waitcnt vmcnt(23)
	v_mul_f32_e32 v116, v165, v166
	v_cvt_pk_bf16_f32 v118, v116, s0
	v_lshl_add_u64 v[116:117], v[136:137], 1, s[10:11]
	global_store_short v[116:117], v118, off
	v_mul_f32_e32 v142, v147, v147
	global_load_dword v145, v188, s[14:15] offset:128
	v_mul_f32_e32 v115, v161, v161
	v_fmac_f32_e32 v115, v150, v150
	s_waitcnt vmcnt(23)
	v_mul_f32_e32 v116, v167, v168
	v_cvt_pk_bf16_f32 v118, v116, s0
	v_or_b32_e32 v116, v226, v103
	v_ashrrev_i32_e32 v117, 31, v116
	v_lshl_add_u64 v[116:117], v[116:117], 2, s[18:19]
	global_load_dword v136, v[116:117], off
	v_lshl_add_u64 v[116:117], v[128:129], 1, s[10:11]
	global_store_short v[116:117], v118, off
	v_or_b32_e32 v118, v228, v103
	s_waitcnt vmcnt(23)
	v_mul_f32_e32 v116, v169, v170
	v_ashrrev_i32_e32 v119, 31, v118
	v_cvt_pk_bf16_f32 v143, v116, s0
	v_or_b32_e32 v116, v229, v102
	v_lshl_add_u64 v[118:119], v[118:119], 2, s[18:19]
	global_load_dword v146, v[118:119], off
	v_ashrrev_i32_e32 v117, 31, v116
	v_or_b32_e32 v118, v229, v103
	v_lshl_add_u64 v[116:117], v[116:117], 2, s[18:19]
	v_ashrrev_i32_e32 v119, 31, v118
	v_lshl_add_u64 v[118:119], v[118:119], 2, s[18:19]
	global_load_dword v147, v[116:117], off
	global_load_dword v148, v[118:119], off
	v_fmac_f32_e32 v142, v163, v163
	v_mul_f32_e32 v137, v167, v167
	s_waitcnt vmcnt(24)
	v_add_f32_e32 v149, v80, v172
	global_store_dword v[192:193], v149, off offset:256
	v_or_b32_e32 v80, 0x440, v190
	global_load_dword v150, v188, s[14:15] offset:256
	s_waitcnt vmcnt(25)
	v_add_f32_e32 v153, v81, v173
	v_ashrrev_i32_e32 v81, 31, v80
	v_lshl_add_u64 v[80:81], v[80:81], 2, s[16:17]
	s_waitcnt vmcnt(19)
	v_add_f32_e32 v135, v64, v135
	v_or_b32_e32 v64, 0x460, v190
	global_store_dword v[192:193], v135, off offset:384
	global_load_dword v151, v188, s[14:15] offset:384
	v_add_f32_e32 v157, v82, v130
	global_store_dword v[80:81], v153, off
	global_load_dword v154, v188, s[14:15] offset:256
	v_or_b32_e32 v82, 0xc40, v190
	s_waitcnt vmcnt(21)
	v_add_f32_e32 v138, v65, v138
	v_ashrrev_i32_e32 v65, 31, v64
	v_lshl_add_u64 v[64:65], v[64:65], 2, s[16:17]
	global_store_dword v[64:65], v138, off
	v_or_b32_e32 v64, 0x840, v190
	v_ashrrev_i32_e32 v65, 31, v64
	v_lshl_add_u64 v[80:81], v[64:65], 2, s[16:17]
	global_load_dword v155, v188, s[14:15] offset:384
	v_add_f32_e32 v160, v83, v131
	global_store_dword v[80:81], v157, off
	v_or_b32_e32 v80, 0x860, v190
	v_ashrrev_i32_e32 v81, 31, v80
	global_load_dword v158, v188, s[14:15] offset:256
	s_waitcnt vmcnt(23)
	v_add_f32_e32 v144, v66, v144
	v_lshl_add_u64 v[116:117], v[80:81], 2, s[16:17]
	v_ashrrev_i32_e32 v83, 31, v82
	v_or_b32_e32 v66, 0xc60, v190
	global_store_dword v[116:117], v144, off
	v_lshl_add_u64 v[116:117], v[82:83], 2, s[16:17]
	global_load_dword v159, v188, s[14:15] offset:384
	v_add_f32_e32 v163, v84, v132
	global_store_dword v[116:117], v160, off
	s_waitcnt vmcnt(23)
	v_add_f32_e32 v140, v67, v140
	v_ashrrev_i32_e32 v67, 31, v66
	v_lshl_add_u64 v[116:117], v[66:67], 2, s[16:17]
	global_load_dword v161, v188, s[14:15] offset:256
	v_or_b32_e32 v84, 0x2440, v190
	global_store_dword v[116:117], v140, off
	v_or_b32_e32 v116, 0x2040, v190
	v_ashrrev_i32_e32 v117, 31, v116
	v_lshl_add_u64 v[118:119], v[116:117], 2, s[16:17]
	global_load_dword v162, v188, s[14:15] offset:384
	v_add_f32_e32 v166, v85, v133
	global_store_dword v[118:119], v163, off
	v_or_b32_e32 v118, 0x2060, v190
	v_ashrrev_i32_e32 v119, 31, v118
	global_load_dword v164, v188, s[14:15] offset:256
	s_waitcnt vmcnt(25)
; DI bfr f2bf(float a) { return (bfr)(pack2(a, 0.f) & 0xffffu); }
; DI int crow(int reg, int h) { return (reg & 3) + 8 * (reg >> 2) + 4 * h; }
; template <bool FIRST, bool HAS_H>
; DI void phase_gemm_resid(const Params& p, const bfr* A, const bfr* Wt, const float* gnext, float* ss, char* smem) {
;     ...
; #pragma unroll
;     for (int i = 0; i < 2; ++i) {
; #pragma unroll
;       for (int qh = 0; qh < 2; ++qh) {
;         float rs[8];
; #pragma unroll
;         for (int q = 0; q < 8; ++q) rs[q] = 0.f;
; #pragma unroll
;         for (int jh = 0; jh < 2; ++jh) {
;           float xo[2][8];
; #pragma unroll
;           for (int jj = 0; jj < 2; ++jj)
; #pragma unroll
;             for (int q = 0; q < 8; ++q)
;               xo[jj][q] = xsrc[(rbase + i * 32 + crow(qh * 8 + q, 0)) * 1024 + cbase + (jh * 2 + jj) * 32];
; #pragma unroll
;           for (int q = 0; q < 8; ++q) {
;             const int o = (rbase + i * 32 + crow(qh * 8 + q, 0)) * 1024 + cbase;
; #pragma unroll
;             for (int jj = 0; jj < 2; ++jj) {
;               const int j = jh * 2 + jj;
;               const float xn = xo[jj][q] + acc[i][j][qh * 8 + q];
;               X[o + j * 32] = xn;
;               if (HAS_H) Hn[o + j * 32] = f2bf(xn * gnext[cbase + j * 32]);
;               rs[q] += xn * xn;
;             }
;           }
;         }
	v_add_f32_e32 v141, v68, v141
	v_lshl_add_u64 v[128:129], v[118:119], 2, s[16:17]
	v_ashrrev_i32_e32 v85, 31, v84
	v_or_b32_e32 v68, 0x2460, v190
	global_store_dword v[128:129], v141, off
	v_lshl_add_u64 v[128:129], v[84:85], 2, s[16:17]
	v_fmac_f32_e32 v137, v165, v165
	global_load_dword v165, v188, s[14:15] offset:384
	v_add_f32_e32 v134, v86, v134
	global_store_dword v[128:129], v166, off
	s_waitcnt vmcnt(25)
	v_add_f32_e32 v136, v69, v136
	v_ashrrev_i32_e32 v69, 31, v68
	v_lshl_add_u64 v[128:129], v[68:69], 2, s[16:17]
	global_load_dword v167, v188, s[14:15] offset:256
	v_or_b32_e32 v86, 0x2c40, v190
	global_store_dword v[128:129], v136, off
	v_or_b32_e32 v128, 0x2840, v190
	v_ashrrev_i32_e32 v129, 31, v128
	v_lshl_add_u64 v[130:131], v[128:129], 2, s[16:17]
	global_load_dword v168, v188, s[14:15] offset:384
	s_waitcnt vmcnt(26)
	v_add_f32_e32 v146, v70, v146
	global_store_dword v[130:131], v134, off
	v_or_b32_e32 v130, 0x2860, v190
	v_ashrrev_i32_e32 v131, 31, v130
	global_load_dword v170, v188, s[14:15] offset:256
	v_lshl_add_u64 v[132:133], v[130:131], 2, s[16:17]
	global_store_dword v[132:133], v146, off
	s_waitcnt vmcnt(28)
	v_add_f32_e32 v147, v87, v147
	v_ashrrev_i32_e32 v87, 31, v86
	global_load_dword v172, v188, s[14:15] offset:384
	v_lshl_add_u64 v[132:133], v[86:87], 2, s[16:17]
	v_or_b32_e32 v70, 0x2c60, v190
	global_store_dword v[132:133], v147, off
	s_waitcnt vmcnt(29)
	v_add_f32_e32 v148, v71, v148
	v_ashrrev_i32_e32 v71, 31, v70
	global_load_dword v173, v188, s[14:15] offset:256
	v_lshl_add_u64 v[132:133], v[70:71], 2, s[16:17]
	global_store_dword v[132:133], v148, off
	global_load_dword v132, v188, s[14:15] offset:384
	v_lshl_add_u64 v[98:99], v[98:99], 1, s[10:11]
	global_store_short v[98:99], v143, off
	v_mul_f32_e32 v98, v171, v145
	v_cvt_pk_bf16_f32 v133, v98, s0
	v_lshl_add_u64 v[98:99], v[100:101], 1, s[10:11]
	global_store_short v[98:99], v133, off
	s_waitcnt vmcnt(32)
	v_mul_f32_e32 v99, v149, v150
	v_cvt_pk_bf16_f32 v99, v99, s0
	global_store_short v[112:113], v99, off offset:128
	s_waitcnt vmcnt(31)
	v_mul_f32_e32 v99, v135, v151
	v_cvt_pk_bf16_f32 v99, v99, s0
	global_store_short v[112:113], v99, off offset:192
	s_waitcnt vmcnt(30)
	v_mul_f32_e32 v99, v153, v154
	v_cvt_pk_bf16_f32 v99, v99, s0
	global_store_short v[112:113], v99, off offset:2176
	s_waitcnt vmcnt(29)
	v_mul_f32_e32 v99, v138, v155
	v_cvt_pk_bf16_f32 v99, v99, s0
	global_store_short v[112:113], v99, off offset:2240
	s_waitcnt vmcnt(28)
	v_mul_f32_e32 v99, v157, v158
	v_cvt_pk_bf16_f32 v99, v99, s0
	v_lshl_add_u64 v[64:65], v[64:65], 1, s[10:11]
	global_store_short v[64:65], v99, off
	v_mul_f32_e32 v98, v171, v171
	s_waitcnt vmcnt(27)
	v_mul_f32_e32 v64, v144, v159
	v_cvt_pk_bf16_f32 v99, v64, s0
	v_lshl_add_u64 v[64:65], v[80:81], 1, s[10:11]
	global_store_short v[64:65], v99, off
	v_fmac_f32_e32 v156, v209, v209
	v_fmac_f32_e32 v152, v177, v177
	s_waitcnt vmcnt(26)
	v_mul_f32_e32 v64, v160, v161
	v_cvt_pk_bf16_f32 v80, v64, s0
	v_lshl_add_u64 v[64:65], v[82:83], 1, s[10:11]
	global_store_short v[64:65], v80, off
	v_fmac_f32_e32 v98, v169, v169
	v_fmac_f32_e32 v114, v149, v149
	s_waitcnt vmcnt(25)
	v_mul_f32_e32 v64, v140, v162
	v_cvt_pk_bf16_f32 v80, v64, s0
	v_lshl_add_u64 v[64:65], v[66:67], 1, s[10:11]
	global_store_short v[64:65], v80, off
	v_fmac_f32_e32 v156, v153, v153
	s_waitcnt vmcnt(24)
	v_mul_f32_e32 v64, v163, v164
	v_cvt_pk_bf16_f32 v66, v64, s0
	v_lshl_add_u64 v[64:65], v[116:117], 1, s[10:11]
	global_store_short v[64:65], v66, off
	v_fmac_f32_e32 v152, v157, v157
	v_fmac_f32_e32 v139, v160, v160
	v_fmac_f32_e32 v115, v163, v163
	v_fmac_f32_e32 v142, v166, v166
	s_waitcnt vmcnt(23)
	v_mul_f32_e32 v64, v141, v165
	v_cvt_pk_bf16_f32 v66, v64, s0
	v_lshl_add_u64 v[64:65], v[118:119], 1, s[10:11]
	global_store_short v[64:65], v66, off
	v_fmac_f32_e32 v137, v134, v134
	v_fmac_f32_e32 v98, v147, v147
	s_waitcnt vmcnt(22)
	v_mul_f32_e32 v64, v166, v167
	v_cvt_pk_bf16_f32 v66, v64, s0
	v_lshl_add_u64 v[64:65], v[84:85], 1, s[10:11]
	global_store_short v[64:65], v66, off
	v_fmac_f32_e32 v114, v135, v135
	v_fmac_f32_e32 v156, v138, v138
	s_waitcnt vmcnt(21)
	v_mul_f32_e32 v64, v136, v168
	v_cvt_pk_bf16_f32 v66, v64, s0
	v_lshl_add_u64 v[64:65], v[68:69], 1, s[10:11]
	global_store_short v[64:65], v66, off
	v_fmac_f32_e32 v152, v144, v144
	s_waitcnt vmcnt(20)
	v_mul_f32_e32 v64, v134, v170
	v_cvt_pk_bf16_f32 v66, v64, s0
	v_lshl_add_u64 v[64:65], v[128:129], 1, s[10:11]
	global_store_short v[64:65], v66, off
	v_fmac_f32_e32 v139, v140, v140
	s_waitcnt vmcnt(19)
; DI bfr f2bf(float a) { return (bfr)(pack2(a, 0.f) & 0xffffu); }
; DI int crow(int reg, int h) { return (reg & 3) + 8 * (reg >> 2) + 4 * h; }
; template <bool FIRST, bool HAS_H>
; DI void phase_gemm_resid(const Params& p, const bfr* A, const bfr* Wt, const float* gnext, float* ss, char* smem) {
;     ...
;               xo[jj][q] = xsrc[(rbase + i * 32 + crow(qh * 8 + q, 0)) * 1024 + cbase + (jh * 2 + jj) * 32];
; #pragma unroll
;           for (int q = 0; q < 8; ++q) {
;             const int o = (rbase + i * 32 + crow(qh * 8 + q, 0)) * 1024 + cbase;
; #pragma unroll
;             for (int jj = 0; jj < 2; ++jj) {
;               const int j = jh * 2 + jj;
;               const float xn = xo[jj][q] + acc[i][j][qh * 8 + q];
;               X[o + j * 32] = xn;
;               if (HAS_H) Hn[o + j * 32] = f2bf(xn * gnext[cbase + j * 32]);
;               rs[q] += xn * xn;
;             }
;           }
;         }
; #pragma unroll
;         for (int q = 0; q < 8; ++q) rs[q] = half32_sum_hi(rs[q]);
;         if (r == 31) {
; #pragma unroll
;           for (int q = 0; q < 8; ++q) unsafeAtomicAdd(ss + rbase + i * 32 + crow(qh * 8 + q, 0), rs[q]);
;         }
	v_mul_f32_e32 v64, v146, v172
	v_cvt_pk_bf16_f32 v66, v64, s0
	v_lshl_add_u64 v[64:65], v[130:131], 1, s[10:11]
	global_store_short v[64:65], v66, off
	v_fmac_f32_e32 v115, v141, v141
	v_fmac_f32_e32 v142, v136, v136
	s_waitcnt vmcnt(18)
	v_mul_f32_e32 v64, v147, v173
	v_cvt_pk_bf16_f32 v66, v64, s0
	v_lshl_add_u64 v[64:65], v[86:87], 1, s[10:11]
	global_store_short v[64:65], v66, off
	s_waitcnt vmcnt(17)
	v_mul_f32_e32 v64, v148, v132
	v_fmac_f32_e32 v137, v146, v146
	v_cvt_pk_bf16_f32 v66, v64, s0
	v_lshl_add_u64 v[64:65], v[70:71], 1, s[10:11]
	v_fmac_f32_e32 v98, v148, v148
	global_store_short v[64:65], v66, off
	v_add_f32_dpp v64, v114, v114 quad_perm:[1,0,3,2] row_mask:0xf bank_mask:0xf bound_ctrl:1
	v_add_f32_dpp v66, v156, v156 quad_perm:[1,0,3,2] row_mask:0xf bank_mask:0xf bound_ctrl:1
	v_add_f32_dpp v68, v152, v152 quad_perm:[1,0,3,2] row_mask:0xf bank_mask:0xf bound_ctrl:1
	v_add_f32_dpp v70, v139, v139 quad_perm:[1,0,3,2] row_mask:0xf bank_mask:0xf bound_ctrl:1
	v_add_f32_dpp v80, v115, v115 quad_perm:[1,0,3,2] row_mask:0xf bank_mask:0xf bound_ctrl:1
	v_add_f32_dpp v82, v142, v142 quad_perm:[1,0,3,2] row_mask:0xf bank_mask:0xf bound_ctrl:1
	v_add_f32_dpp v84, v137, v137 quad_perm:[1,0,3,2] row_mask:0xf bank_mask:0xf bound_ctrl:1
	v_add_f32_dpp v86, v98, v98 quad_perm:[1,0,3,2] row_mask:0xf bank_mask:0xf bound_ctrl:1
	v_add_f32_dpp v64, v64, v64 quad_perm:[2,3,0,1] row_mask:0xf bank_mask:0xf bound_ctrl:1
	v_add_f32_dpp v66, v66, v66 quad_perm:[2,3,0,1] row_mask:0xf bank_mask:0xf bound_ctrl:1
	v_add_f32_dpp v68, v68, v68 quad_perm:[2,3,0,1] row_mask:0xf bank_mask:0xf bound_ctrl:1
	v_add_f32_dpp v70, v70, v70 quad_perm:[2,3,0,1] row_mask:0xf bank_mask:0xf bound_ctrl:1
	v_add_f32_dpp v80, v80, v80 quad_perm:[2,3,0,1] row_mask:0xf bank_mask:0xf bound_ctrl:1
	v_add_f32_dpp v82, v82, v82 quad_perm:[2,3,0,1] row_mask:0xf bank_mask:0xf bound_ctrl:1
	v_add_f32_dpp v84, v84, v84 quad_perm:[2,3,0,1] row_mask:0xf bank_mask:0xf bound_ctrl:1
	v_add_f32_dpp v86, v86, v86 quad_perm:[2,3,0,1] row_mask:0xf bank_mask:0xf bound_ctrl:1
	v_add_f32_dpp v64, v64, v64 row_half_mirror row_mask:0xf bank_mask:0xf bound_ctrl:1
	v_add_f32_dpp v66, v66, v66 row_half_mirror row_mask:0xf bank_mask:0xf bound_ctrl:1
	v_add_f32_dpp v68, v68, v68 row_half_mirror row_mask:0xf bank_mask:0xf bound_ctrl:1
	v_add_f32_dpp v70, v70, v70 row_half_mirror row_mask:0xf bank_mask:0xf bound_ctrl:1
	v_add_f32_dpp v80, v80, v80 row_half_mirror row_mask:0xf bank_mask:0xf bound_ctrl:1
	v_add_f32_dpp v82, v82, v82 row_half_mirror row_mask:0xf bank_mask:0xf bound_ctrl:1
	v_add_f32_dpp v84, v84, v84 row_half_mirror row_mask:0xf bank_mask:0xf bound_ctrl:1
	v_add_f32_dpp v86, v86, v86 row_half_mirror row_mask:0xf bank_mask:0xf bound_ctrl:1
	v_add_f32_dpp v64, v64, v64 row_mirror row_mask:0xf bank_mask:0xf bound_ctrl:1
	v_mov_b32_e32 v65, 0
	v_add_f32_dpp v66, v66, v66 row_mirror row_mask:0xf bank_mask:0xf bound_ctrl:1
	v_mov_b32_e32 v67, 0
	v_add_f32_dpp v68, v68, v68 row_mirror row_mask:0xf bank_mask:0xf bound_ctrl:1
	v_mov_b32_e32 v69, 0
	v_add_f32_dpp v70, v70, v70 row_mirror row_mask:0xf bank_mask:0xf bound_ctrl:1
	v_mov_b32_e32 v71, 0
	v_add_f32_dpp v80, v80, v80 row_mirror row_mask:0xf bank_mask:0xf bound_ctrl:1
	v_mov_b32_e32 v81, 0
	v_add_f32_dpp v82, v82, v82 row_mirror row_mask:0xf bank_mask:0xf bound_ctrl:1
	v_mov_b32_e32 v83, 0
	v_add_f32_dpp v84, v84, v84 row_mirror row_mask:0xf bank_mask:0xf bound_ctrl:1
	v_mov_b32_e32 v85, 0
	v_add_f32_dpp v86, v86, v86 row_mirror row_mask:0xf bank_mask:0xf bound_ctrl:1
	v_mov_b32_e32 v87, 0
	v_mov_b32_dpp v65, v64 row_bcast:15 row_mask:0xa bank_mask:0xf
	v_mov_b32_dpp v67, v66 row_bcast:15 row_mask:0xa bank_mask:0xf
	v_mov_b32_dpp v69, v68 row_bcast:15 row_mask:0xa bank_mask:0xf
	v_mov_b32_dpp v71, v70 row_bcast:15 row_mask:0xa bank_mask:0xf
	v_mov_b32_dpp v81, v80 row_bcast:15 row_mask:0xa bank_mask:0xf
	v_mov_b32_dpp v83, v82 row_bcast:15 row_mask:0xa bank_mask:0xf
	v_mov_b32_dpp v85, v84 row_bcast:15 row_mask:0xa bank_mask:0xf
	v_mov_b32_dpp v87, v86 row_bcast:15 row_mask:0xa bank_mask:0xf
	s_and_saveexec_b64 s[4:5], vcc
	s_cbranch_execz .LBB0_856
	v_add_f32_e32 v64, v64, v65
	v_add_f32_e32 v86, v86, v87
	v_add_f32_e32 v84, v84, v85
	v_add_f32_e32 v82, v82, v83
	v_add_f32_e32 v80, v80, v81
	v_add_f32_e32 v70, v70, v71
	v_add_f32_e32 v68, v68, v69
	v_add_f32_e32 v66, v66, v67
	global_atomic_add_f32 v[96:97], v64, off
	global_atomic_add_f32 v[96:97], v66, off offset:4
	global_atomic_add_f32 v[96:97], v68, off offset:8
	global_atomic_add_f32 v[96:97], v70, off offset:12
	global_atomic_add_f32 v[96:97], v80, off offset:32
	global_atomic_add_f32 v[96:97], v82, off offset:36
	global_atomic_add_f32 v[96:97], v84, off offset:40
	global_atomic_add_f32 v[96:97], v86, off offset:44

; DI bfr f2bf(float a) { return (bfr)(pack2(a, 0.f) & 0xffffu); }
; DI int crow(int reg, int h) { return (reg & 3) + 8 * (reg >> 2) + 4 * h; }
; template <int lda, class Epi>
; DI void gemm_tile(const bfr* __restrict__ A, const bfr* __restrict__ Bt, int NB, int K, int m0, int n0, char* smem, Epi epi) {
;     ...
; #pragma unroll
;   for (int i = 0; i < 2; ++i)
; #pragma unroll
;     for (int j = 0; j < 4; ++j)
; #pragma unroll
;       for (int q = 0; q < 16; ++q) {
;         int row = m0 + wr * 64 + i * 32 + crow(q, hl);
;         int col = n0 + wc * 128 + j * 32 + r;
;         epi(row, col, acc[i][j][q]);
;       }
; DI void phase_gemm_bf16out(const Params& p, const bfr* A, const bfr* Wt, bfr* C, int N, const float* ss, char* smem) {
;     ...
;   for (int t0 = blockIdx.x; t0 < 128 * ntn; t0 += gridDim.x) {
;     const int t = ((gridDim.x & 7) == 0) ? xcd_tile(t0, ntn) : t0;
;     int mt = t / ntn, nt = t % ntn;
;     gemm_tile<1024>(A, Wt, N, 1024, mt * 128, nt * 256, smem,
;               [=](int row, int col, float v) {
;                 float inv = rsqrtf(ss[row] * (1.0f / 1024.0f) + EPSF);
;                 C[(size_t)row * N + col] = f2bf(v * inv);
;               });
.LBB0_922:
	s_nop 0
	s_waitcnt vmcnt(3)
	s_nop 0
	s_waitcnt vmcnt(2)
	s_nop 0
	s_waitcnt vmcnt(1)
	s_nop 0
	s_waitcnt vmcnt(0)
	s_nop 0
	v_add_u32_e32 v144, v169, v171
	s_nop 0
	v_add_u32_e32 v197, v169, v170
	s_nop 0
	s_nop 0
	s_nop 0
	s_nop 0
	s_nop 0
	s_nop 0
	s_nop 0
	s_nop 0
	s_nop 0
	s_nop 0
	s_nop 0
	s_waitcnt lgkmcnt(0)
	s_nop 0
	s_nop 0
	s_nop 0
	s_nop 0
	v_mov_b64_e32 v[204:205], s[18:19]
	s_add_i32 s28, s28, s34
	s_cmpk_lt_i32 s28, 0x200
	s_nop 0
	s_nop 0
	s_nop 0
	s_nop 0
	s_nop 0
	s_nop 0
	s_nop 0
	s_nop 0
	s_nop 0
	s_nop 0
	s_nop 0
	s_nop 0
	s_nop 0
	s_nop 0
	v_mov_b32_e32 v197, v196
	s_waitcnt lgkmcnt(0)
	s_nop 0
	s_nop 0
	v_ashrrev_i32_e32 v198, 1, v197
	v_and_b32_e32 v198, 0xffffffc0, v198
	s_nop 0
	v_lshrrev_b32_e32 v200, 3, v197
	v_add_u32_e32 v198, s30, v198
	v_and_or_b32 v200, v200, 4, v198
	v_ashrrev_i32_e32 v201, 31, v200
	v_lshl_add_u64 v[206:207], v[200:201], 2, s[8:9]
	global_load_dwordx4 v[226:229], v[206:207], off
	v_and_b32_e32 v198, 31, v197
	s_nop 0
	v_lshlrev_b32_e32 v197, 1, v197
	v_and_b32_e32 v197, 0x80, v197
	v_or3_b32 v202, v198, v197, s29
	v_or_b32_e32 v208, 1, v200
	v_or_b32_e32 v212, 2, v200
	v_ashrrev_i32_e32 v203, 31, v202
	v_ashrrev_i32_e32 v209, 31, v208
	s_nop 0
	global_load_dwordx4 v[218:221], v[206:207], off offset:32
	v_ashrrev_i32_e32 v213, 31, v212
	v_lshl_add_u64 v[202:203], v[202:203], 1, s[2:3]
	v_lshlrev_b64 v[208:209], 11, v[208:209]
	v_lshlrev_b64 v[222:223], 11, v[212:213]
	v_lshl_add_u64 v[212:213], v[202:203], 0, v[208:209]
	v_lshl_add_u64 v[208:209], v[202:203], 0, v[222:223]
	s_nop 0
	v_lshlrev_b64 v[210:211], 11, v[200:201]
	v_lshl_add_u64 v[210:211], v[202:203], 0, v[210:211]
	s_waitcnt vmcnt(1)
	v_fma_f32 v222, v226, s16, v204
	v_fma_f32 v223, v227, s16, v204
	s_nop 0
	v_mul_f32_e32 v197, 0x4b800000, v222
	v_cmp_gt_f32_e32 vcc, s27, v222
	v_mul_f32_e32 v198, 0x4b800000, v223
	v_cmp_gt_f32_e64 s[4:5], s27, v223
	v_cndmask_b32_e32 v197, v222, v197, vcc
	v_rsq_f32_e32 v197, v197
	v_cndmask_b32_e64 v198, v223, v198, s[4:5]
	s_nop 0
	v_fma_f32 v224, v228, s16, v204
	v_fma_f32 v225, v229, s16, v204
	v_rsq_f32_e32 v222, v198
	v_mul_f32_e32 v201, 0x4b800000, v224
	v_cmp_gt_f32_e64 s[6:7], s27, v224
	v_mul_f32_e32 v198, 0x45800000, v197
	v_mul_f32_e32 v223, 0x45800000, v222
	v_cndmask_b32_e64 v201, v224, v201, s[6:7]
	v_rsq_f32_e32 v201, v201
	v_cndmask_b32_e32 v198, v197, v198, vcc
	v_cndmask_b32_e64 v197, v222, v223, s[4:5]
	s_nop 0
	v_mul_f32_e32 v112, v112, v198
	v_mul_f32_e32 v113, v113, v197
	v_cvt_pk_bf16_f32 v112, v112, s0
	v_cvt_pk_bf16_f32 v113, v113, s0
	global_store_short v[210:211], v112, off
	global_store_short v[212:213], v113, off
	v_mul_f32_e32 v222, 0x45800000, v201
	s_nop 0
	v_cndmask_b32_e64 v201, v201, v222, s[6:7]
	v_mul_f32_e32 v222, 0x4b800000, v225
	v_cmp_gt_f32_e32 vcc, s27, v225
	v_mul_f32_e32 v114, v114, v201
	v_cvt_pk_bf16_f32 v114, v114, s0
	v_cndmask_b32_e32 v222, v225, v222, vcc
	v_rsq_f32_e32 v222, v222
	s_nop 0
	global_store_short v[208:209], v114, off
	v_or_b32_e32 v112, 3, v200
	v_mul_f32_e32 v114, 0x45800000, v222
	v_cndmask_b32_e32 v222, v222, v114, vcc
	v_ashrrev_i32_e32 v113, 31, v112
	v_mul_f32_e32 v114, v115, v222
	v_lshlrev_b64 v[112:113], 11, v[112:113]
	s_nop 0
	global_load_dwordx4 v[214:217], v[206:207], off offset:64
	v_cvt_pk_bf16_f32 v114, v114, s0
	v_lshl_add_u64 v[112:113], v[202:203], 0, v[112:113]
	global_store_short v[112:113], v114, off
	v_or_b32_e32 v114, 8, v200
	v_ashrrev_i32_e32 v115, 31, v114
	v_lshlrev_b64 v[114:115], 11, v[114:115]
	s_nop 0
	s_waitcnt vmcnt(5)
	v_fma_f32 v176, v218, s16, v204
	v_fma_f32 v177, v219, s16, v204
	v_lshl_add_u64 v[114:115], v[202:203], 0, v[114:115]
	v_mul_f32_e32 v178, 0x4b800000, v176
	v_cmp_gt_f32_e32 vcc, s27, v176
	s_nop 1
	v_cndmask_b32_e32 v176, v176, v178, vcc
	v_rsq_f32_e32 v176, v176
	s_nop 0
	v_or_b32_e32 v178, 9, v200
	v_ashrrev_i32_e32 v179, 31, v178
	v_mul_f32_e32 v188, 0x45800000, v176
	v_cndmask_b32_e32 v188, v176, v188, vcc
	v_mul_f32_e32 v176, 0x4b800000, v177
	v_cmp_gt_f32_e32 vcc, s27, v177
	v_mul_f32_e32 v116, v116, v188
	v_cvt_pk_bf16_f32 v116, v116, s0
	v_cndmask_b32_e32 v176, v177, v176, vcc
	v_rsq_f32_e32 v176, v176
	global_store_short v[114:115], v116, off
	s_nop 0
	v_or_b32_e32 v180, 11, v200
	v_mul_f32_e32 v116, 0x45800000, v176
	v_cndmask_b32_e32 v182, v176, v116, vcc
	v_mul_f32_e32 v116, v117, v182
	v_ashrrev_i32_e32 v181, 31, v180
	s_nop 0
	v_cvt_pk_bf16_f32 v172, v116, s0
	v_lshlrev_b64 v[116:117], 11, v[178:179]
	v_fma_f32 v178, v220, s16, v204
	v_fma_f32 v179, v221, s16, v204
	v_lshl_add_u64 v[116:117], v[202:203], 0, v[116:117]
	v_mul_f32_e32 v174, 0x4b800000, v178
	v_cmp_gt_f32_e32 vcc, s27, v178
	global_store_short v[116:117], v172, off
	s_nop 0
	v_cndmask_b32_e32 v174, v178, v174, vcc
	v_rsq_f32_e32 v174, v174
	v_or_b32_e32 v172, 10, v200
	v_ashrrev_i32_e32 v173, 31, v172
	v_lshlrev_b64 v[172:173], 11, v[172:173]
	v_mul_f32_e32 v175, 0x45800000, v174
	v_cndmask_b32_e32 v178, v174, v175, vcc
	global_load_dwordx4 v[174:177], v[206:207], off offset:96
	s_nop 0
	v_lshl_add_u64 v[172:173], v[202:203], 0, v[172:173]
	v_mul_f32_e32 v183, 0x4b800000, v179
	v_cmp_gt_f32_e32 vcc, s27, v179
	v_mul_f32_e32 v118, v118, v178
	v_cvt_pk_bf16_f32 v118, v118, s0
	v_cndmask_b32_e32 v179, v179, v183, vcc
	v_rsq_f32_e32 v179, v179
	s_nop 4
	v_mul_f32_e32 v80, v80, v198
	v_cvt_pk_bf16_f32 v80, v80, s0
	global_store_short v[210:211], v80, off offset:128
	v_mul_f32_e32 v80, v81, v197
	v_cvt_pk_bf16_f32 v80, v80, s0
	global_store_short v[212:213], v80, off offset:128
	v_mul_f32_e32 v80, v82, v201
	v_cvt_pk_bf16_f32 v80, v80, s0
	global_store_short v[208:209], v80, off offset:128
	v_mul_f32_e32 v80, v83, v222
	v_cvt_pk_bf16_f32 v80, v80, s0
	global_store_short v[112:113], v80, off offset:128
	v_mul_f32_e32 v80, v84, v188
	v_cvt_pk_bf16_f32 v80, v80, s0
	global_store_short v[114:115], v80, off offset:128
	v_mul_f32_e32 v80, v85, v182
	v_cvt_pk_bf16_f32 v80, v80, s0
	global_store_short v[116:117], v80, off offset:128
	v_mul_f32_e32 v80, v86, v178
	v_cvt_pk_bf16_f32 v80, v80, s0
	global_store_short v[172:173], v80, off offset:128
	global_load_dwordx4 v[80:83], v[206:207], off offset:128
	s_nop 0
	global_store_short v[172:173], v118, off
	v_mul_f32_e32 v118, 0x45800000, v179
	v_cndmask_b32_e32 v179, v179, v118, vcc
	v_mul_f32_e32 v118, v119, v179
	v_mul_f32_e32 v84, v87, v179
	v_cvt_pk_bf16_f32 v84, v84, s0
	s_nop 0
	s_nop 0
	v_cvt_pk_bf16_f32 v158, v118, s0
	v_lshlrev_b64 v[118:119], 11, v[180:181]
	v_lshl_add_u64 v[156:157], v[202:203], 0, v[118:119]
	v_or_b32_e32 v118, 16, v200
	v_ashrrev_i32_e32 v119, 31, v118
	v_lshlrev_b64 v[118:119], 11, v[118:119]
	global_store_short v[156:157], v158, off
	v_lshl_add_u64 v[158:159], v[202:203], 0, v[118:119]
	s_waitcnt vmcnt(14)
; DI bfr f2bf(float a) { return (bfr)(pack2(a, 0.f) & 0xffffu); }
; DI int crow(int reg, int h) { return (reg & 3) + 8 * (reg >> 2) + 4 * h; }
; template <int lda, class Epi>
; DI void gemm_tile(const bfr* __restrict__ A, const bfr* __restrict__ Bt, int NB, int K, int m0, int n0, char* smem, Epi epi) {
;     ...
; #pragma unroll
;   for (int i = 0; i < 2; ++i)
; #pragma unroll
;     for (int j = 0; j < 4; ++j)
; #pragma unroll
;       for (int q = 0; q < 16; ++q) {
;         int row = m0 + wr * 64 + i * 32 + crow(q, hl);
;         int col = n0 + wc * 128 + j * 32 + r;
;         epi(row, col, acc[i][j][q]);
;       }
; DI void phase_gemm_bf16out(const Params& p, const bfr* A, const bfr* Wt, bfr* C, int N, const float* ss, char* smem) {
;     ...
;   for (int t0 = blockIdx.x; t0 < 128 * ntn; t0 += gridDim.x) {
;     const int t = ((gridDim.x & 7) == 0) ? xcd_tile(t0, ntn) : t0;
;     int mt = t / ntn, nt = t % ntn;
;     gemm_tile<1024>(A, Wt, N, 1024, mt * 128, nt * 256, smem,
;               [=](int row, int col, float v) {
;                 float inv = rsqrtf(ss[row] * (1.0f / 1024.0f) + EPSF);
;                 C[(size_t)row * N + col] = f2bf(v * inv);
;               });
	v_pk_fma_f32 v[118:119], v[214:215], s[16:17], v[204:205] op_sel_hi:[1,0,0]
	s_nop 0
	v_mul_f32_e32 v164, 0x4b800000, v118
	v_cmp_gt_f32_e32 vcc, s27, v118
	v_mul_f32_e32 v64, v64, v198
	v_cvt_pk_bf16_f32 v64, v64, s0
	v_cndmask_b32_e32 v118, v118, v164, vcc
	v_rsq_f32_e32 v118, v118
	global_store_short v[210:211], v64, off offset:192
	v_mul_f32_e32 v64, v65, v197
	v_cvt_pk_bf16_f32 v64, v64, s0
	global_store_short v[212:213], v64, off offset:192
	v_mul_f32_e32 v64, v66, v201
	v_cvt_pk_bf16_f32 v64, v64, s0
	s_nop 0
	global_store_short v[208:209], v64, off offset:192
	v_mul_f32_e32 v64, v67, v222
	v_cvt_pk_bf16_f32 v64, v64, s0
	global_store_short v[112:113], v64, off offset:192
	v_mul_f32_e32 v64, v68, v188
	v_cvt_pk_bf16_f32 v64, v64, s0
	global_store_short v[114:115], v64, off offset:192
	s_nop 0
	v_mul_f32_e32 v152, 0x45800000, v118
	v_cndmask_b32_e32 v154, v118, v152, vcc
	v_mul_f32_e32 v118, v120, v154
	v_mul_f32_e32 v120, 0x4b800000, v119
	v_cmp_gt_f32_e32 vcc, s27, v119
	v_mul_f32_e32 v64, v69, v182
	v_cvt_pk_bf16_f32 v64, v64, s0
	s_nop 0
	v_cndmask_b32_e32 v119, v119, v120, vcc
	v_rsq_f32_e32 v119, v119
	global_store_short v[116:117], v64, off offset:192
	v_mul_f32_e32 v64, v70, v178
	v_cvt_pk_bf16_f32 v118, v118, s0
	v_cvt_pk_bf16_f32 v64, v64, s0
	global_store_short v[158:159], v118, off
	v_mul_f32_e32 v118, 0x45800000, v119
	v_pk_fma_f32 v[152:153], v[216:217], s[16:17], v[204:205] op_sel_hi:[1,0,0]
	global_store_short v[172:173], v64, off offset:192
	v_mul_f32_e32 v64, v71, v179
	global_load_dwordx4 v[68:71], v[206:207], off offset:160
	v_cndmask_b32_e32 v155, v119, v118, vcc
	v_mul_f32_e32 v160, 0x4b800000, v152
	v_cmp_gt_f32_e32 vcc, s27, v152
	s_nop 0
	v_or_b32_e32 v164, 17, v200
	v_cndmask_b32_e32 v140, v152, v160, vcc
	v_rsq_f32_e32 v142, v140
	v_ashrrev_i32_e32 v165, 31, v164
	v_mul_f32_e32 v118, v121, v155
	v_cvt_pk_bf16_f32 v120, v118, s0
	v_mul_f32_e32 v143, 0x45800000, v142
	v_lshlrev_b64 v[118:119], 11, v[164:165]
	v_cndmask_b32_e32 v142, v142, v143, vcc
	s_nop 0
	v_mul_f32_e32 v136, 0x4b800000, v153
	v_cmp_gt_f32_e32 vcc, s27, v153
	v_lshl_add_u64 v[118:119], v[202:203], 0, v[118:119]
	global_store_short v[118:119], v120, off
	v_cndmask_b32_e32 v136, v153, v136, vcc
	v_or_b32_e32 v120, 18, v200
	v_rsq_f32_e32 v136, v136
	v_ashrrev_i32_e32 v121, 31, v120
	v_lshlrev_b64 v[120:121], 11, v[120:121]
	v_mul_f32_e32 v122, v122, v142
	v_lshl_add_u64 v[120:121], v[202:203], 0, v[120:121]
	v_cvt_pk_bf16_f32 v122, v122, s0
	global_store_short v[120:121], v122, off
	v_mul_f32_e32 v122, 0x45800000, v136
	v_or_b32_e32 v140, 19, v200
	v_cndmask_b32_e32 v143, v136, v122, vcc
	v_ashrrev_i32_e32 v141, 31, v140
	v_mul_f32_e32 v122, v123, v143
	s_waitcnt vmcnt(21)
	v_pk_fma_f32 v[138:139], v[174:175], s[16:17], v[204:205] op_sel_hi:[1,0,0]
	v_cvt_pk_bf16_f32 v136, v122, s0
	v_lshlrev_b64 v[122:123], 11, v[140:141]
	v_mul_f32_e32 v140, 0x4b800000, v138
	v_cmp_gt_f32_e32 vcc, s27, v138
	s_nop 0
	v_lshl_add_u64 v[122:123], v[202:203], 0, v[122:123]
	v_cndmask_b32_e32 v138, v138, v140, vcc
	v_rsq_f32_e32 v132, v138
	global_store_short v[122:123], v136, off
	v_or_b32_e32 v136, 24, v200
	v_ashrrev_i32_e32 v137, 31, v136
	v_lshlrev_b64 v[136:137], 11, v[136:137]
	v_mul_f32_e32 v133, 0x45800000, v132
	s_nop 0
	global_store_short v[156:157], v84, off offset:128
	v_mul_f32_e32 v84, v88, v154
	v_cvt_pk_bf16_f32 v84, v84, s0
	v_cvt_pk_bf16_f32 v64, v64, s0
	global_store_short v[158:159], v84, off offset:128
	v_mul_f32_e32 v84, v89, v155
	global_store_short v[156:157], v64, off offset:192
	s_nop 0
	v_lshl_add_u64 v[128:129], v[202:203], 0, v[136:137]
	v_cndmask_b32_e32 v136, v132, v133, vcc
	v_mul_f32_e32 v132, 0x4b800000, v139
	v_cmp_gt_f32_e32 vcc, s27, v139
	v_mul_f32_e32 v124, v124, v136
	v_cvt_pk_bf16_f32 v124, v124, s0
	v_cndmask_b32_e32 v132, v139, v132, vcc
	v_rsq_f32_e32 v132, v132
	global_store_short v[128:129], v124, off
	v_or_b32_e32 v130, 25, v200
	v_ashrrev_i32_e32 v131, 31, v130
	v_mul_f32_e32 v124, 0x45800000, v132
	v_cndmask_b32_e32 v137, v132, v124, vcc
	v_mul_f32_e32 v124, v125, v137
	v_cvt_pk_bf16_f32 v132, v124, s0
	v_lshlrev_b64 v[124:125], 11, v[130:131]
	v_lshl_add_u64 v[124:125], v[202:203], 0, v[124:125]
	global_store_short v[124:125], v132, off
	v_pk_fma_f32 v[132:133], v[176:177], s[16:17], v[204:205] op_sel_hi:[1,0,0]
	v_mul_f32_e32 v64, v72, v154
	v_mul_f32_e32 v134, 0x4b800000, v132
	v_cmp_gt_f32_e32 vcc, s27, v132
	v_cvt_pk_bf16_f32 v84, v84, s0
	v_cvt_pk_bf16_f32 v64, v64, s0
	v_cndmask_b32_e32 v132, v132, v134, vcc
	v_rsq_f32_e32 v132, v132
	v_or_b32_e32 v130, 26, v200
	global_store_short v[118:119], v84, off offset:128
	v_mul_f32_e32 v84, v90, v142
	v_mul_f32_e32 v138, 0x45800000, v132
	v_cndmask_b32_e32 v132, v132, v138, vcc
	v_mul_f32_e32 v138, 0x4b800000, v133
	v_cmp_gt_f32_e32 vcc, s27, v133
	global_store_short v[158:159], v64, off offset:192
	v_mul_f32_e32 v64, v73, v155
	v_cndmask_b32_e32 v133, v133, v138, vcc
	v_rsq_f32_e32 v133, v133
	v_ashrrev_i32_e32 v131, 31, v130
	v_cvt_pk_bf16_f32 v84, v84, s0
	v_cvt_pk_bf16_f32 v64, v64, s0
	v_lshlrev_b64 v[130:131], 11, v[130:131]
	v_mul_f32_e32 v126, v126, v132
	global_store_short v[120:121], v84, off offset:128
	v_mul_f32_e32 v84, v91, v143
	global_store_short v[118:119], v64, off offset:192
	v_mul_f32_e32 v64, v74, v142
	v_lshl_add_u64 v[130:131], v[202:203], 0, v[130:131]
	v_cvt_pk_bf16_f32 v126, v126, s0
	v_cvt_pk_bf16_f32 v84, v84, s0
	v_cvt_pk_bf16_f32 v64, v64, s0
	global_store_short v[130:131], v126, off
	v_mul_f32_e32 v126, 0x45800000, v133
	global_store_short v[122:123], v84, off offset:128
	v_mul_f32_e32 v84, v92, v136
	global_store_short v[120:121], v64, off offset:192
	v_mul_f32_e32 v64, v75, v143
	s_waitcnt vmcnt(26)
; DI bfr f2bf(float a) { return (bfr)(pack2(a, 0.f) & 0xffffu); }
; DI int crow(int reg, int h) { return (reg & 3) + 8 * (reg >> 2) + 4 * h; }
; template <int lda, class Epi>
; DI void gemm_tile(const bfr* __restrict__ A, const bfr* __restrict__ Bt, int NB, int K, int m0, int n0, char* smem, Epi epi) {
;     ...
; #pragma unroll
;   for (int i = 0; i < 2; ++i)
; #pragma unroll
;     for (int j = 0; j < 4; ++j)
; #pragma unroll
;       for (int q = 0; q < 16; ++q) {
;         int row = m0 + wr * 64 + i * 32 + crow(q, hl);
;         int col = n0 + wc * 128 + j * 32 + r;
;         epi(row, col, acc[i][j][q]);
;       }
; DI void phase_gemm_bf16out(const Params& p, const bfr* A, const bfr* Wt, bfr* C, int N, const float* ss, char* smem) {
;     ...
;   for (int t0 = blockIdx.x; t0 < 128 * ntn; t0 += gridDim.x) {
;     const int t = ((gridDim.x & 7) == 0) ? xcd_tile(t0, ntn) : t0;
;     int mt = t / ntn, nt = t % ntn;
;     gemm_tile<1024>(A, Wt, N, 1024, mt * 128, nt * 256, smem,
;               [=](int row, int col, float v) {
;                 float inv = rsqrtf(ss[row] * (1.0f / 1024.0f) + EPSF);
;                 C[(size_t)row * N + col] = f2bf(v * inv);
;               });
	v_pk_fma_f32 v[66:67], v[80:81], s[16:17], v[204:205] op_sel_hi:[1,0,0]
	v_cndmask_b32_e32 v133, v133, v126, vcc
	v_cvt_pk_bf16_f32 v84, v84, s0
	v_cvt_pk_bf16_f32 v64, v64, s0
	v_mul_f32_e32 v72, 0x4b800000, v66
	v_cmp_gt_f32_e32 vcc, s27, v66
	global_store_short v[128:129], v84, off offset:128
	v_mul_f32_e32 v84, v93, v137
	global_store_short v[122:123], v64, off offset:192
	v_mul_f32_e32 v64, v76, v136
	v_cndmask_b32_e32 v66, v66, v72, vcc
	v_cvt_pk_bf16_f32 v84, v84, s0
	v_cvt_pk_bf16_f32 v64, v64, s0
	v_rsq_f32_e32 v66, v66
	v_or_b32_e32 v134, 27, v200
	global_store_short v[124:125], v84, off offset:128
	v_mul_f32_e32 v84, v94, v132
	global_store_short v[128:129], v64, off offset:192
	v_mul_f32_e32 v64, v77, v137
	v_ashrrev_i32_e32 v135, 31, v134
	v_mul_f32_e32 v126, v127, v133
	v_cvt_pk_bf16_f32 v84, v84, s0
	v_cvt_pk_bf16_f32 v64, v64, s0
	v_cvt_pk_bf16_f32 v138, v126, s0
	v_lshlrev_b64 v[126:127], 11, v[134:135]
	global_store_short v[130:131], v84, off offset:128
	v_mul_f32_e32 v84, v95, v133
	global_store_short v[124:125], v64, off offset:192
	v_mul_f32_e32 v64, v78, v132
	v_lshl_add_u64 v[126:127], v[202:203], 0, v[126:127]
	v_cvt_pk_bf16_f32 v84, v84, s0
	v_cvt_pk_bf16_f32 v64, v64, s0
	v_mul_f32_e32 v74, 0x45800000, v66
	global_store_short v[126:127], v84, off offset:128
	global_store_short v[130:131], v64, off offset:192
	v_mul_f32_e32 v64, v79, v133
	v_cndmask_b32_e32 v84, v66, v74, vcc
	v_mul_f32_e32 v66, 0x4b800000, v67
	v_cmp_gt_f32_e32 vcc, s27, v67
	v_cvt_pk_bf16_f32 v64, v64, s0
	global_store_short v[126:127], v64, off offset:192
	v_cndmask_b32_e32 v66, v67, v66, vcc
	v_or_b32_e32 v64, 32, v200
	v_rsq_f32_e32 v66, v66
	v_ashrrev_i32_e32 v65, 31, v64
	v_lshlrev_b64 v[64:65], 11, v[64:65]
	v_mul_f32_e32 v48, v48, v84
	v_lshl_add_u64 v[64:65], v[202:203], 0, v[64:65]
	v_cvt_pk_bf16_f32 v48, v48, s0
	global_store_short v[64:65], v48, off
	v_mul_f32_e32 v48, 0x45800000, v66
	v_pk_fma_f32 v[76:77], v[82:83], s[16:17], v[204:205] op_sel_hi:[1,0,0]
	v_cndmask_b32_e32 v85, v66, v48, vcc
	v_mul_f32_e32 v78, 0x4b800000, v76
	v_cmp_gt_f32_e32 vcc, s27, v76
	v_or_b32_e32 v72, 33, v200
	v_ashrrev_i32_e32 v73, 31, v72
	v_cndmask_b32_e32 v76, v76, v78, vcc
	v_mul_f32_e32 v48, v49, v85
	v_rsq_f32_e32 v76, v76
	v_cvt_pk_bf16_f32 v66, v48, s0
	v_lshlrev_b64 v[48:49], 11, v[72:73]
	global_load_dwordx4 v[72:75], v[206:207], off offset:192
	v_mul_f32_e32 v80, 0x45800000, v76
	v_cndmask_b32_e32 v86, v76, v80, vcc
	v_mul_f32_e32 v76, 0x4b800000, v77
	v_cmp_gt_f32_e32 vcc, s27, v77
	v_lshl_add_u64 v[48:49], v[202:203], 0, v[48:49]
	global_store_short v[48:49], v66, off
	v_cndmask_b32_e32 v76, v77, v76, vcc
	v_or_b32_e32 v66, 34, v200
	v_rsq_f32_e32 v76, v76
	v_ashrrev_i32_e32 v67, 31, v66
	v_lshlrev_b64 v[66:67], 11, v[66:67]
	v_mul_f32_e32 v50, v50, v86
	v_lshl_add_u64 v[66:67], v[202:203], 0, v[66:67]
	v_cvt_pk_bf16_f32 v50, v50, s0
	global_store_short v[66:67], v50, off
	v_mul_f32_e32 v50, 0x45800000, v76
	v_or_b32_e32 v78, 35, v200
	v_cndmask_b32_e32 v87, v76, v50, vcc
	v_ashrrev_i32_e32 v79, 31, v78
	v_mul_f32_e32 v50, v51, v87
	v_cvt_pk_bf16_f32 v76, v50, s0
	v_lshlrev_b64 v[50:51], 11, v[78:79]
	s_waitcnt vmcnt(28)
	v_pk_fma_f32 v[78:79], v[68:69], s[16:17], v[204:205] op_sel_hi:[1,0,0]
	v_lshl_add_u64 v[50:51], v[202:203], 0, v[50:51]
	v_mul_f32_e32 v68, 0x4b800000, v78
	v_cmp_gt_f32_e32 vcc, s27, v78
	global_store_short v[50:51], v76, off
	v_or_b32_e32 v76, 40, v200
	v_cndmask_b32_e32 v68, v78, v68, vcc
	v_rsq_f32_e32 v78, v68
	v_ashrrev_i32_e32 v77, 31, v76
	v_lshlrev_b64 v[76:77], 11, v[76:77]
	v_lshl_add_u64 v[68:69], v[202:203], 0, v[76:77]
	v_mul_f32_e32 v80, 0x45800000, v78
	v_cndmask_b32_e32 v88, v78, v80, vcc
	v_mul_f32_e32 v78, 0x4b800000, v79
	v_cmp_gt_f32_e32 vcc, s27, v79
	v_mul_f32_e32 v52, v52, v88
	v_cvt_pk_bf16_f32 v52, v52, s0
	v_cndmask_b32_e32 v78, v79, v78, vcc
	v_rsq_f32_e32 v78, v78
	global_store_short v[68:69], v52, off
	v_or_b32_e32 v76, 41, v200
	v_ashrrev_i32_e32 v77, 31, v76
	v_mul_f32_e32 v52, 0x45800000, v78
	v_cndmask_b32_e32 v89, v78, v52, vcc
	v_mul_f32_e32 v52, v53, v89
	v_cvt_pk_bf16_f32 v78, v52, s0
	v_lshlrev_b64 v[52:53], 11, v[76:77]
	v_or_b32_e32 v76, 42, v200
	v_lshl_add_u64 v[52:53], v[202:203], 0, v[52:53]
	v_ashrrev_i32_e32 v77, 31, v76
	global_store_short v[52:53], v78, off
	v_lshlrev_b64 v[80:81], 11, v[76:77]
	global_load_dwordx4 v[76:79], v[206:207], off offset:224
	v_pk_fma_f32 v[82:83], v[70:71], s[16:17], v[204:205] op_sel_hi:[1,0,0]
	v_mul_f32_e32 v96, v96, v198
	v_mul_f32_e32 v70, 0x4b800000, v82
	v_cmp_gt_f32_e32 vcc, s27, v82
	v_cvt_pk_bf16_f32 v96, v96, s0
	global_store_short v[210:211], v96, off offset:64
	v_cndmask_b32_e32 v70, v82, v70, vcc
	v_rsq_f32_e32 v82, v70
	v_lshl_add_u64 v[70:71], v[202:203], 0, v[80:81]
	v_or_b32_e32 v80, 43, v200
	v_ashrrev_i32_e32 v81, 31, v80
	v_mul_f32_e32 v90, 0x45800000, v82
	v_cndmask_b32_e32 v90, v82, v90, vcc
	v_mul_f32_e32 v82, 0x4b800000, v83
	v_cmp_gt_f32_e32 vcc, s27, v83
	v_mul_f32_e32 v54, v54, v90
	v_cvt_pk_bf16_f32 v54, v54, s0
	v_cndmask_b32_e32 v82, v83, v82, vcc
	v_rsq_f32_e32 v82, v82
	global_store_short v[70:71], v54, off
	v_mul_f32_e32 v96, v97, v197
	v_cvt_pk_bf16_f32 v96, v96, s0
	v_mul_f32_e32 v54, 0x45800000, v82
	v_cndmask_b32_e32 v91, v82, v54, vcc
	v_mul_f32_e32 v54, v55, v91
	v_cvt_pk_bf16_f32 v82, v54, s0
	v_lshlrev_b64 v[54:55], 11, v[80:81]
	v_lshl_add_u64 v[54:55], v[202:203], 0, v[54:55]
	s_waitcnt vmcnt(8)
; DI bfr f2bf(float a) { return (bfr)(pack2(a, 0.f) & 0xffffu); }
; DI int crow(int reg, int h) { return (reg & 3) + 8 * (reg >> 2) + 4 * h; }
; template <int lda, class Epi>
; DI void gemm_tile(const bfr* __restrict__ A, const bfr* __restrict__ Bt, int NB, int K, int m0, int n0, char* smem, Epi epi) {
;     ...
; #pragma unroll
;   for (int i = 0; i < 2; ++i)
; #pragma unroll
;     for (int j = 0; j < 4; ++j)
; #pragma unroll
;       for (int q = 0; q < 16; ++q) {
;         int row = m0 + wr * 64 + i * 32 + crow(q, hl);
;         int col = n0 + wc * 128 + j * 32 + r;
;         epi(row, col, acc[i][j][q]);
;       }
; DI void phase_gemm_bf16out(const Params& p, const bfr* A, const bfr* Wt, bfr* C, int N, const float* ss, char* smem) {
;     ...
;     gemm_tile<1024>(A, Wt, N, 1024, mt * 128, nt * 256, smem,
;               [=](int row, int col, float v) {
;                 float inv = rsqrtf(ss[row] * (1.0f / 1024.0f) + EPSF);
;                 C[(size_t)row * N + col] = f2bf(v * inv);
;               });
	v_pk_fma_f32 v[72:73], v[72:73], s[16:17], v[204:205] op_sel_hi:[1,0,0]
	global_store_short v[54:55], v82, off
	v_mul_f32_e32 v82, 0x4b800000, v72
	v_cmp_gt_f32_e32 vcc, s27, v72
	v_or_b32_e32 v80, 48, v200
	global_store_short v[212:213], v96, off offset:64
	v_cndmask_b32_e32 v72, v72, v82, vcc
	v_rsq_f32_e32 v72, v72
	v_mul_f32_e32 v96, v98, v201
	v_ashrrev_i32_e32 v81, 31, v80
	v_cvt_pk_bf16_f32 v96, v96, s0
	v_mul_f32_e32 v92, 0x45800000, v72
	v_cndmask_b32_e32 v92, v72, v92, vcc
	v_mul_f32_e32 v72, 0x4b800000, v73
	v_cmp_gt_f32_e32 vcc, s27, v73
	v_lshlrev_b64 v[80:81], 11, v[80:81]
	v_mul_f32_e32 v56, v56, v92
	v_cndmask_b32_e32 v72, v73, v72, vcc
	v_rsq_f32_e32 v72, v72
	global_store_short v[208:209], v96, off offset:64
	v_mul_f32_e32 v96, v99, v222
	v_lshl_add_u64 v[80:81], v[202:203], 0, v[80:81]
	v_cvt_pk_bf16_f32 v56, v56, s0
	v_cvt_pk_bf16_f32 v96, v96, s0
	global_store_short v[80:81], v56, off
	v_mul_f32_e32 v56, 0x45800000, v72
	global_store_short v[112:113], v96, off offset:64
	v_mul_f32_e32 v96, v100, v188
	v_or_b32_e32 v82, 49, v200
	v_cndmask_b32_e32 v93, v72, v56, vcc
	v_cvt_pk_bf16_f32 v96, v96, s0
	v_ashrrev_i32_e32 v83, 31, v82
	v_mul_f32_e32 v56, v57, v93
	v_pk_fma_f32 v[74:75], v[74:75], s[16:17], v[204:205] op_sel_hi:[1,0,0]
	global_store_short v[114:115], v96, off offset:64
	v_mul_f32_e32 v96, v101, v182
	v_cvt_pk_bf16_f32 v72, v56, s0
	v_lshlrev_b64 v[56:57], 11, v[82:83]
	v_mul_f32_e32 v82, 0x4b800000, v74
	v_cmp_gt_f32_e32 vcc, s27, v74
	v_cvt_pk_bf16_f32 v96, v96, s0
	global_store_short v[116:117], v96, off offset:64
	v_cndmask_b32_e32 v74, v74, v82, vcc
	v_mul_f32_e32 v96, v102, v178
	v_rsq_f32_e32 v74, v74
	v_cvt_pk_bf16_f32 v96, v96, s0
	global_store_short v[172:173], v96, off offset:64
	v_mul_f32_e32 v96, v103, v179
	v_cvt_pk_bf16_f32 v96, v96, s0
	global_store_short v[156:157], v96, off offset:64
	v_mul_f32_e32 v96, v104, v154
	v_mul_f32_e32 v94, 0x45800000, v74
	v_cvt_pk_bf16_f32 v96, v96, s0
	v_cndmask_b32_e32 v94, v74, v94, vcc
	v_mul_f32_e32 v74, 0x4b800000, v75
	v_cmp_gt_f32_e32 vcc, s27, v75
	global_store_short v[158:159], v96, off offset:64
	v_mul_f32_e32 v96, v105, v155
	v_lshl_add_u64 v[56:57], v[202:203], 0, v[56:57]
	v_cndmask_b32_e32 v74, v75, v74, vcc
	v_cvt_pk_bf16_f32 v96, v96, s0
	global_store_short v[56:57], v72, off
	v_or_b32_e32 v72, 50, v200
	v_rsq_f32_e32 v74, v74
	global_store_short v[118:119], v96, off offset:64
	v_mul_f32_e32 v96, v106, v142
	v_ashrrev_i32_e32 v73, 31, v72
	v_cvt_pk_bf16_f32 v96, v96, s0
	v_lshlrev_b64 v[72:73], 11, v[72:73]
	v_mul_f32_e32 v58, v58, v94
	global_store_short v[120:121], v96, off offset:64
	v_mul_f32_e32 v96, v107, v143
	v_lshl_add_u64 v[72:73], v[202:203], 0, v[72:73]
	v_cvt_pk_bf16_f32 v58, v58, s0
	v_cvt_pk_bf16_f32 v96, v96, s0
	global_store_short v[72:73], v58, off
	v_mul_f32_e32 v58, 0x45800000, v74
	global_store_short v[122:123], v96, off offset:64
	v_mul_f32_e32 v96, v108, v136
	v_or_b32_e32 v82, 51, v200
	v_cndmask_b32_e32 v95, v74, v58, vcc
	v_cvt_pk_bf16_f32 v96, v96, s0
	v_ashrrev_i32_e32 v83, 31, v82
	v_mul_f32_e32 v58, v59, v95
	s_waitcnt vmcnt(17)
	v_pk_fma_f32 v[76:77], v[76:77], s[16:17], v[204:205] op_sel_hi:[1,0,0]
	global_store_short v[128:129], v96, off offset:64
	v_mul_f32_e32 v96, v109, v137
	v_cvt_pk_bf16_f32 v74, v58, s0
	v_lshlrev_b64 v[58:59], 11, v[82:83]
	v_mul_f32_e32 v82, 0x4b800000, v76
	v_cmp_gt_f32_e32 vcc, s27, v76
	v_cvt_pk_bf16_f32 v96, v96, s0
	global_store_short v[124:125], v96, off offset:64
	v_cndmask_b32_e32 v76, v76, v82, vcc
	v_mul_f32_e32 v96, v110, v132
	v_rsq_f32_e32 v76, v76
	v_mul_f32_e32 v32, v32, v84
	v_mul_f32_e32 v16, v16, v84
	v_mul_f32_e32 v0, v0, v84
	v_cvt_pk_bf16_f32 v96, v96, s0
	v_cvt_pk_bf16_f32 v32, v32, s0
	v_cvt_pk_bf16_f32 v16, v16, s0
	v_cvt_pk_bf16_f32 v0, v0, s0
	global_store_short v[130:131], v96, off offset:64
	v_mul_f32_e32 v96, v111, v133
	global_store_short v[64:65], v32, off offset:64
	v_mul_f32_e32 v32, v33, v85
	global_store_short v[64:65], v16, off offset:128
	v_mul_f32_e32 v16, v17, v85
	global_store_short v[64:65], v0, off offset:192
	v_mul_f32_e32 v0, v1, v85
	v_cvt_pk_bf16_f32 v96, v96, s0
	v_cvt_pk_bf16_f32 v32, v32, s0
	v_cvt_pk_bf16_f32 v16, v16, s0
	v_cvt_pk_bf16_f32 v0, v0, s0
	global_store_short v[126:127], v96, off offset:64
	v_mul_f32_e32 v96, 0x45800000, v76
	global_store_short v[48:49], v32, off offset:64
	v_mul_f32_e32 v32, v34, v86
	global_store_short v[48:49], v16, off offset:128
	v_mul_f32_e32 v16, v18, v86
	global_store_short v[48:49], v0, off offset:192
	v_mul_f32_e32 v0, v2, v86
	v_cndmask_b32_e32 v96, v76, v96, vcc
	v_mul_f32_e32 v76, 0x4b800000, v77
	v_cmp_gt_f32_e32 vcc, s27, v77
	v_cvt_pk_bf16_f32 v32, v32, s0
	v_cvt_pk_bf16_f32 v16, v16, s0
	v_cvt_pk_bf16_f32 v0, v0, s0
	v_lshl_add_u64 v[58:59], v[202:203], 0, v[58:59]
	v_cndmask_b32_e32 v76, v77, v76, vcc
	global_store_short v[66:67], v32, off offset:64
	v_mul_f32_e32 v32, v35, v87
	global_store_short v[66:67], v16, off offset:128
	v_mul_f32_e32 v16, v19, v87
	global_store_short v[66:67], v0, off offset:192
	v_mul_f32_e32 v0, v3, v87
	global_store_short v[58:59], v74, off
	v_or_b32_e32 v74, 56, v200
	v_rsq_f32_e32 v76, v76
	v_cvt_pk_bf16_f32 v32, v32, s0
	v_cvt_pk_bf16_f32 v16, v16, s0
	v_cvt_pk_bf16_f32 v0, v0, s0
	v_ashrrev_i32_e32 v75, 31, v74
	global_store_short v[50:51], v32, off offset:64
	v_mul_f32_e32 v32, v36, v88
	global_store_short v[50:51], v16, off offset:128
	v_mul_f32_e32 v16, v20, v88
; DI bfr f2bf(float a) { return (bfr)(pack2(a, 0.f) & 0xffffu); }
; DI int crow(int reg, int h) { return (reg & 3) + 8 * (reg >> 2) + 4 * h; }
; template <int lda, class Epi>
; DI void gemm_tile(const bfr* __restrict__ A, const bfr* __restrict__ Bt, int NB, int K, int m0, int n0, char* smem, Epi epi) {
;     ...
; #pragma unroll
;   for (int i = 0; i < 2; ++i)
; #pragma unroll
;     for (int j = 0; j < 4; ++j)
; #pragma unroll
;       for (int q = 0; q < 16; ++q) {
;         int row = m0 + wr * 64 + i * 32 + crow(q, hl);
;         int col = n0 + wc * 128 + j * 32 + r;
;         epi(row, col, acc[i][j][q]);
;       }
; DI void phase_gemm_bf16out(const Params& p, const bfr* A, const bfr* Wt, bfr* C, int N, const float* ss, char* smem) {
;     ...
;     gemm_tile<1024>(A, Wt, N, 1024, mt * 128, nt * 256, smem,
;               [=](int row, int col, float v) {
;                 float inv = rsqrtf(ss[row] * (1.0f / 1024.0f) + EPSF);
;                 C[(size_t)row * N + col] = f2bf(v * inv);
;               });
	global_store_short v[50:51], v0, off offset:192
	v_mul_f32_e32 v0, v4, v88
	v_lshlrev_b64 v[74:75], 11, v[74:75]
	v_mul_f32_e32 v60, v60, v96
	v_cvt_pk_bf16_f32 v32, v32, s0
	v_cvt_pk_bf16_f32 v16, v16, s0
	v_cvt_pk_bf16_f32 v0, v0, s0
	v_lshl_add_u64 v[74:75], v[202:203], 0, v[74:75]
	v_cvt_pk_bf16_f32 v60, v60, s0
	global_store_short v[68:69], v32, off offset:64
	v_mul_f32_e32 v32, v37, v89
	global_store_short v[68:69], v16, off offset:128
	v_mul_f32_e32 v16, v21, v89
	global_store_short v[68:69], v0, off offset:192
	v_mul_f32_e32 v0, v5, v89
	global_store_short v[74:75], v60, off
	v_mul_f32_e32 v60, 0x45800000, v76
	v_cvt_pk_bf16_f32 v32, v32, s0
	v_cvt_pk_bf16_f32 v16, v16, s0
	v_cvt_pk_bf16_f32 v0, v0, s0
	v_or_b32_e32 v82, 57, v200
	v_cndmask_b32_e32 v97, v76, v60, vcc
	global_store_short v[52:53], v32, off offset:64
	v_mul_f32_e32 v32, v38, v90
	global_store_short v[52:53], v16, off offset:128
	v_mul_f32_e32 v16, v22, v90
	global_store_short v[52:53], v0, off offset:192
	v_mul_f32_e32 v0, v6, v90
	v_ashrrev_i32_e32 v83, 31, v82
	v_mul_f32_e32 v60, v61, v97
	v_pk_fma_f32 v[78:79], v[78:79], s[16:17], v[204:205] op_sel_hi:[1,0,0]
	v_cvt_pk_bf16_f32 v32, v32, s0
	v_cvt_pk_bf16_f32 v16, v16, s0
	v_cvt_pk_bf16_f32 v0, v0, s0
	v_cvt_pk_bf16_f32 v76, v60, s0
	v_lshlrev_b64 v[60:61], 11, v[82:83]
	v_mul_f32_e32 v82, 0x4b800000, v78
	v_cmp_gt_f32_e32 vcc, s27, v78
	global_store_short v[70:71], v32, off offset:64
	v_mul_f32_e32 v32, v39, v91
	global_store_short v[70:71], v16, off offset:128
	v_mul_f32_e32 v16, v23, v91
	global_store_short v[70:71], v0, off offset:192
	v_mul_f32_e32 v0, v7, v91
	v_cndmask_b32_e32 v78, v78, v82, vcc
	v_cvt_pk_bf16_f32 v32, v32, s0
	v_cvt_pk_bf16_f32 v16, v16, s0
	v_cvt_pk_bf16_f32 v0, v0, s0
	v_rsq_f32_e32 v78, v78
	global_store_short v[54:55], v32, off offset:64
	v_mul_f32_e32 v32, v40, v92
	global_store_short v[54:55], v16, off offset:128
	v_mul_f32_e32 v16, v24, v92
	global_store_short v[54:55], v0, off offset:192
	v_mul_f32_e32 v0, v8, v92
	v_cvt_pk_bf16_f32 v32, v32, s0
	v_cvt_pk_bf16_f32 v16, v16, s0
	v_cvt_pk_bf16_f32 v0, v0, s0
	global_store_short v[80:81], v32, off offset:64
	v_mul_f32_e32 v32, v41, v93
	global_store_short v[80:81], v16, off offset:128
	v_mul_f32_e32 v16, v25, v93
	global_store_short v[80:81], v0, off offset:192
	v_mul_f32_e32 v0, v9, v93
	v_cvt_pk_bf16_f32 v32, v32, s0
	v_cvt_pk_bf16_f32 v16, v16, s0
	v_cvt_pk_bf16_f32 v0, v0, s0
	v_mul_f32_e32 v98, 0x45800000, v78
	global_store_short v[56:57], v32, off offset:64
	v_mul_f32_e32 v32, v42, v94
	global_store_short v[56:57], v16, off offset:128
	v_mul_f32_e32 v16, v26, v94
	global_store_short v[56:57], v0, off offset:192
	v_mul_f32_e32 v0, v10, v94
	v_cndmask_b32_e32 v78, v78, v98, vcc
	v_mul_f32_e32 v98, 0x4b800000, v79
	v_cmp_gt_f32_e32 vcc, s27, v79
	v_cvt_pk_bf16_f32 v32, v32, s0
	v_cvt_pk_bf16_f32 v16, v16, s0
	v_cvt_pk_bf16_f32 v0, v0, s0
	v_lshl_add_u64 v[60:61], v[202:203], 0, v[60:61]
	v_cndmask_b32_e32 v79, v79, v98, vcc
	global_store_short v[72:73], v32, off offset:64
	v_mul_f32_e32 v32, v43, v95
	global_store_short v[72:73], v16, off offset:128
	v_mul_f32_e32 v16, v27, v95
	global_store_short v[72:73], v0, off offset:192
	v_mul_f32_e32 v0, v11, v95
	global_store_short v[60:61], v76, off
	v_or_b32_e32 v76, 58, v200
	v_rsq_f32_e32 v79, v79
	v_cvt_pk_bf16_f32 v32, v32, s0
	v_cvt_pk_bf16_f32 v16, v16, s0
	v_cvt_pk_bf16_f32 v0, v0, s0
	v_ashrrev_i32_e32 v77, 31, v76
	global_store_short v[58:59], v32, off offset:64
	v_mul_f32_e32 v32, v44, v96
	global_store_short v[58:59], v16, off offset:128
	v_mul_f32_e32 v16, v28, v96
	global_store_short v[58:59], v0, off offset:192
	v_mul_f32_e32 v0, v12, v96
	v_lshlrev_b64 v[76:77], 11, v[76:77]
	v_mul_f32_e32 v62, v62, v78
	v_cvt_pk_bf16_f32 v32, v32, s0
	v_cvt_pk_bf16_f32 v16, v16, s0
	v_cvt_pk_bf16_f32 v0, v0, s0
	v_lshl_add_u64 v[76:77], v[202:203], 0, v[76:77]
	v_cvt_pk_bf16_f32 v62, v62, s0
	global_store_short v[74:75], v32, off offset:64
	v_mul_f32_e32 v32, v45, v97
	global_store_short v[74:75], v16, off offset:128
	v_mul_f32_e32 v16, v29, v97
	global_store_short v[74:75], v0, off offset:192
	v_mul_f32_e32 v0, v13, v97
	global_store_short v[76:77], v62, off
	v_mul_f32_e32 v62, 0x45800000, v79
	v_cvt_pk_bf16_f32 v32, v32, s0
	v_cvt_pk_bf16_f32 v16, v16, s0
	v_cvt_pk_bf16_f32 v0, v0, s0
	v_or_b32_e32 v82, 59, v200
	v_cndmask_b32_e32 v79, v79, v62, vcc
	global_store_short v[60:61], v32, off offset:64
	v_mul_f32_e32 v32, v46, v78
	global_store_short v[60:61], v16, off offset:128
	v_mul_f32_e32 v16, v30, v78
	global_store_short v[60:61], v0, off offset:192
	v_mul_f32_e32 v0, v14, v78
	v_ashrrev_i32_e32 v83, 31, v82
	v_mul_f32_e32 v62, v63, v79
	v_cvt_pk_bf16_f32 v32, v32, s0
	v_cvt_pk_bf16_f32 v16, v16, s0
	v_cvt_pk_bf16_f32 v0, v0, s0
	v_cvt_pk_bf16_f32 v98, v62, s0
	v_lshlrev_b64 v[62:63], 11, v[82:83]
	global_store_short v[76:77], v32, off offset:64
	v_mul_f32_e32 v32, v47, v79
	global_store_short v[76:77], v16, off offset:128
	v_mul_f32_e32 v16, v31, v79
	global_store_short v[76:77], v0, off offset:192
	v_mul_f32_e32 v0, v15, v79
	v_lshl_add_u64 v[62:63], v[202:203], 0, v[62:63]
	v_cvt_pk_bf16_f32 v32, v32, s0
	v_cvt_pk_bf16_f32 v16, v16, s0
	v_cvt_pk_bf16_f32 v0, v0, s0
	global_store_short v[126:127], v138, off
	global_store_short v[62:63], v98, off
	global_store_short v[62:63], v32, off offset:64
	global_store_short v[62:63], v16, off offset:128
	global_store_short v[62:63], v0, off offset:192
	s_cbranch_scc0 .LBB0_936

; #define GA_LOAD(pr_) do { _Pragma("unroll") for (int i = 0; i < 4; ++i) ra[i] = *(const u32x4*)(Ab + (i * 32) * lda + (pr_) * 64); } while (0)
; #define GB_LOAD(kt_) do { const bfr* bk_ = Bb + (kt_) * NB * 32; \
;     _Pragma("unroll") for (int i = 0; i < 4; ++i) rb[i] = *(const u32x4*)(bk_ + (i * 64) * 32); } while (0)
; #define G_STORE(kt_) do { bfr* as_ = S0 + ((kt_) & 1) * GSTAGE; bfr* bs_ = as_ + 128 * 40; \
;     if (apar == ((kt_) & 1)) { _Pragma("unroll") for (int i = 0; i < 4; ++i) *(u32x4*)(as_ + asoff + i * 32 * 40) = ra[i]; } \
;     _Pragma("unroll") for (int i = 0; i < 4; ++i) *(u32x4*)(bs_ + bsoff + i * 64 * 40) = rb[i]; } while (0)
; template <int lda>
; DI void gemm_mainloop(const bfr* __restrict__ A, const bfr* __restrict__ Bt, int NB, int K, int m0, int n0, char* smem, f32x16 (&acc)[2][4]) {
;   bfr* S0 = (bfr*)smem;
;   int tid = threadIdx.x;
;   asm volatile("" : "+v"(tid));
;   const int lane = tid & 63, wid = tid >> 6, wr = wid >> 1, wc = wid & 1;
;   const int r = lane & 31, hl = lane >> 5;
; #pragma unroll
;   for (int i = 0; i < 2; ++i)
; #pragma unroll
;     for (int j = 0; j < 4; ++j)
; #pragma unroll
;       for (int q = 0; q < 16; ++q) acc[i][j][q] = 0.f;
;   u32x4 ra[4], rb[4];
;   const int nk = K >> 5;
;   const int arow = tid >> 3, ac8 = tid & 7, apar = ac8 >> 2;
;   const bfr* Ab = A + (m0 + arow) * lda + ac8 * 8;
;   const int asoff = arow * 40 + (ac8 & 3) * 8;
;   const int brow = tid >> 2, bc4 = tid & 3;
;   const bfr* Bb = Bt + (n0 + brow) * 32 + bc4 * 8;
;   const int bsoff = brow * 40 + bc4 * 8;
;     ...
;   GA_LOAD(0);
;   GB_LOAD(0);
;   G_STORE(0);
;   GB_LOAD(1);
;   __syncthreads();
; DI void phase_gemm_bf16out(const Params& p, const bfr* A, const bfr* Wt, bfr* C, int N, const float* ss, char* smem) {
;     ...
;   for (int t0 = blockIdx.x; t0 < 128 * ntn; t0 += gridDim.x) {
;     const int t = ((gridDim.x & 7) == 0) ? xcd_tile(t0, ntn) : t0;
;     int mt = t / ntn, nt = t % ntn;
;     gemm_tile<1024>(A, Wt, N, 1024, mt * 128, nt * 256, smem,
.LBB0_925:
	s_ashr_i32 s5, s4, 31
	s_lshr_b32 s5, s5, 30
	s_add_i32 s5, s4, s5
	s_and_b32 s6, s5, 0xfffffc
	s_lshl_b32 s5, s5, 5
	s_and_b32 s30, s5, 0xffffff80
	s_sub_i32 s4, s4, s6
	s_lshl_b32 s29, s4, 8
	s_mov_b32 s31, 0
	s_mov_b64 s[6:7], 0
	s_lshl_b32 s98, s30, 11
	s_add_u32 s98, s10, s98
	s_addc_u32 s99, s11, 0
	s_lshl_b32 s100, s29, 6
	s_add_u32 s100, s12, s100
	s_addc_u32 s101, s13, 0
	v_writelane_b32 v187, s64, 0
	v_writelane_b32 v187, s65, 1
	v_writelane_b32 v187, s66, 2
	v_writelane_b32 v187, s67, 3
	v_writelane_b32 v187, s68, 4
	v_writelane_b32 v187, s69, 5
	v_writelane_b32 v187, s70, 6
	v_writelane_b32 v187, s71, 7
	v_writelane_b32 v187, s72, 8
	v_writelane_b32 v187, s73, 9
	v_writelane_b32 v187, s74, 10
	v_writelane_b32 v187, s75, 11
	v_writelane_b32 v187, s76, 12
	v_writelane_b32 v187, s77, 13
	v_writelane_b32 v187, s78, 14
	v_writelane_b32 v187, s79, 15
	v_lshrrev_b32_e32 v188, 6, v196
	v_and_b32_e32 v189, 63, v196
	v_readfirstlane_b32 s73, v188
	v_lshrrev_b32_e32 v190, 2, v189
	v_bfe_u32 v191, v189, 4, 2
	v_and_b32_e32 v188, 3, v189
	v_xor_b32_e32 v188, v188, v191
	v_lshlrev_b32_e32 v188, 4, v188
	v_lshl_add_u32 v176, v190, 11, v188
	v_add_u32_e32 v177, 0x8000, v176
	v_lshl_add_u32 v178, v190, 6, v188
	v_and_b32_e32 v190, 31, v189
	v_lshrrev_b32_e32 v191, 5, v189
	v_bfe_u32 v188, v189, 2, 2
	v_xor_b32_e32 v188, v188, v191
	v_lshlrev_b32_e32 v188, 4, v188
	v_lshl_add_u32 v179, v190, 6, v188
	s_lshr_b32 s74, s73, 1
	s_lshl_b32 s74, s74, 12
	s_and_b32 s75, s73, 1
	s_lshl_b32 s75, s75, 13
	v_add_u32_e32 v181, s75, v179
	v_add_u32_e32 v179, s74, v179
	v_xor_b32_e32 v182, 32, v181
	v_xor_b32_e32 v180, 32, v179
	s_lshl_b32 s74, s73, 16
	s_add_u32 s64, s98, s74
	s_addc_u32 s65, s99, 0
	s_lshl_b32 s74, s73, 12
	s_add_u32 s66, s100, s74
	s_addc_u32 s67, s101, 0
	s_lshl_b32 s68, s73, 11
	s_lshl_b32 s69, s73, 12
	s_mov_b32 s70, 0
	s_mov_b32 s71, 0
	s_mov_b32 s72, 0
	s_waitcnt lgkmcnt(0)
	s_barrier
	s_mul_i32 s74, s70, 0x6000
	s_add_u32 s75, s74, s68
	s_mov_b32 m0, s75
	s_add_u32 s76, s74, 0x2000
	s_cmp_eq_u32 s70, 2
	s_cselect_b32 s76, 0x10000, s76
	global_load_lds_dwordx4 v176, s[64:65]
	s_add_u32 m0, s75, 0x400
	s_add_u32 s76, s76, s69
	global_load_lds_dwordx4 v177, s[64:65]
	s_mov_b32 m0, s76
	s_add_u32 s64, s64, 64
	s_addc_u32 s65, s65, 0
	global_load_lds_dwordx4 v178, s[66:67]
	global_load_lds_dwordx4 v178, s[66:67] offset:1024
	global_load_lds_dwordx4 v178, s[66:67] offset:2048
	global_load_lds_dwordx4 v178, s[66:67] offset:3072
	s_add_u32 s66, s66, 0x10000
	s_addc_u32 s67, s67, 0
	s_add_u32 s70, s70, 1
	s_cmp_eq_u32 s70, 3
	s_cselect_b32 s70, 0, s70
	s_mul_i32 s74, s70, 0x6000
	s_add_u32 s75, s74, s68
	s_mov_b32 m0, s75
	s_add_u32 s76, s74, 0x2000
	s_cmp_eq_u32 s70, 2
	s_cselect_b32 s76, 0x10000, s76
	global_load_lds_dwordx4 v176, s[64:65]
	s_add_u32 m0, s75, 0x400
	s_add_u32 s76, s76, s69
	global_load_lds_dwordx4 v177, s[64:65]
	s_mov_b32 m0, s76
	s_add_u32 s64, s64, 64
	s_addc_u32 s65, s65, 0
	global_load_lds_dwordx4 v178, s[66:67]
	global_load_lds_dwordx4 v178, s[66:67] offset:1024
	global_load_lds_dwordx4 v178, s[66:67] offset:2048
	global_load_lds_dwordx4 v178, s[66:67] offset:3072
	s_add_u32 s66, s66, 0x10000
	s_addc_u32 s67, s67, 0
	s_add_u32 s70, s70, 1
	s_cmp_eq_u32 s70, 3
	s_cselect_b32 s70, 0, s70
	v_mov_b32_e32 v112, 0
	v_mov_b32_e32 v113, 0
	v_mov_b32_e32 v114, 0
	v_mov_b32_e32 v115, 0
	v_mov_b32_e32 v116, 0
	v_mov_b32_e32 v117, 0
	v_mov_b32_e32 v118, 0
	v_mov_b32_e32 v119, 0
	v_mov_b32_e32 v120, 0
	v_mov_b32_e32 v121, 0
	v_mov_b32_e32 v122, 0
	v_mov_b32_e32 v123, 0
	v_mov_b32_e32 v124, 0
	v_mov_b32_e32 v125, 0
	v_mov_b32_e32 v126, 0
	v_mov_b32_e32 v127, 0
	v_mov_b32_e32 v96, 0
	v_mov_b32_e32 v97, 0
	v_mov_b32_e32 v98, 0
	v_mov_b32_e32 v99, 0
	v_mov_b32_e32 v100, 0
	v_mov_b32_e32 v101, 0
	v_mov_b32_e32 v102, 0
	v_mov_b32_e32 v103, 0
	v_mov_b32_e32 v104, 0
	v_mov_b32_e32 v105, 0
	v_mov_b32_e32 v106, 0
	v_mov_b32_e32 v107, 0
	v_mov_b32_e32 v108, 0
	v_mov_b32_e32 v109, 0
	v_mov_b32_e32 v110, 0
	v_mov_b32_e32 v111, 0
	v_mov_b32_e32 v80, 0
	v_mov_b32_e32 v81, 0
	v_mov_b32_e32 v82, 0
	v_mov_b32_e32 v83, 0
	v_mov_b32_e32 v84, 0
	v_mov_b32_e32 v85, 0
	v_mov_b32_e32 v86, 0
	v_mov_b32_e32 v87, 0
	v_mov_b32_e32 v88, 0
	v_mov_b32_e32 v89, 0
	v_mov_b32_e32 v90, 0
	v_mov_b32_e32 v91, 0
	v_mov_b32_e32 v92, 0
	v_mov_b32_e32 v93, 0
	v_mov_b32_e32 v94, 0
	v_mov_b32_e32 v95, 0
	v_mov_b32_e32 v64, 0
	v_mov_b32_e32 v65, 0
	v_mov_b32_e32 v66, 0
	v_mov_b32_e32 v67, 0
	v_mov_b32_e32 v68, 0
	v_mov_b32_e32 v69, 0
	v_mov_b32_e32 v70, 0
	v_mov_b32_e32 v71, 0
	v_mov_b32_e32 v72, 0
	v_mov_b32_e32 v73, 0
	v_mov_b32_e32 v74, 0
	v_mov_b32_e32 v75, 0
	v_mov_b32_e32 v76, 0
	v_mov_b32_e32 v77, 0
	v_mov_b32_e32 v78, 0
	v_mov_b32_e32 v79, 0
	v_mov_b32_e32 v48, 0
	v_mov_b32_e32 v49, 0
	v_mov_b32_e32 v50, 0
	v_mov_b32_e32 v51, 0
	v_mov_b32_e32 v52, 0
	v_mov_b32_e32 v53, 0
	v_mov_b32_e32 v54, 0
	v_mov_b32_e32 v55, 0
	v_mov_b32_e32 v56, 0
	v_mov_b32_e32 v57, 0
	v_mov_b32_e32 v58, 0
	v_mov_b32_e32 v59, 0
	v_mov_b32_e32 v60, 0
	v_mov_b32_e32 v61, 0
	v_mov_b32_e32 v62, 0
	v_mov_b32_e32 v63, 0
	v_mov_b32_e32 v32, 0
	v_mov_b32_e32 v33, 0
	v_mov_b32_e32 v34, 0
	v_mov_b32_e32 v35, 0
	v_mov_b32_e32 v36, 0
	v_mov_b32_e32 v37, 0
	v_mov_b32_e32 v38, 0
	v_mov_b32_e32 v39, 0
	v_mov_b32_e32 v40, 0
	v_mov_b32_e32 v41, 0
	v_mov_b32_e32 v42, 0
	v_mov_b32_e32 v43, 0
	v_mov_b32_e32 v44, 0
	v_mov_b32_e32 v45, 0
	v_mov_b32_e32 v46, 0
	v_mov_b32_e32 v47, 0
	v_mov_b32_e32 v16, 0
	v_mov_b32_e32 v17, 0
	v_mov_b32_e32 v18, 0
	v_mov_b32_e32 v19, 0
	v_mov_b32_e32 v20, 0
	v_mov_b32_e32 v21, 0
	v_mov_b32_e32 v22, 0
	v_mov_b32_e32 v23, 0
	v_mov_b32_e32 v24, 0
	v_mov_b32_e32 v25, 0
	v_mov_b32_e32 v26, 0
	v_mov_b32_e32 v27, 0
	v_mov_b32_e32 v28, 0
	v_mov_b32_e32 v29, 0
	v_mov_b32_e32 v30, 0
	v_mov_b32_e32 v31, 0
	v_mov_b32_e32 v0, 0
	v_mov_b32_e32 v1, 0
	v_mov_b32_e32 v2, 0
	v_mov_b32_e32 v3, 0
	v_mov_b32_e32 v4, 0
	v_mov_b32_e32 v5, 0
	v_mov_b32_e32 v6, 0
	v_mov_b32_e32 v7, 0
	v_mov_b32_e32 v8, 0
	v_mov_b32_e32 v9, 0
	v_mov_b32_e32 v10, 0
	v_mov_b32_e32 v11, 0
	v_mov_b32_e32 v12, 0
	v_mov_b32_e32 v13, 0
	v_mov_b32_e32 v14, 0
	v_mov_b32_e32 v15, 0

; #define GA_LOAD(pr_) do { _Pragma("unroll") for (int i = 0; i < 4; ++i) ra[i] = *(const u32x4*)(Ab + (i * 32) * lda + (pr_) * 64); } while (0)
; #define GB_LOAD(kt_) do { const bfr* bk_ = Bb + (kt_) * NB * 32; \
;     _Pragma("unroll") for (int i = 0; i < 4; ++i) rb[i] = *(const u32x4*)(bk_ + (i * 64) * 32); } while (0)
; #define G_STORE(kt_) do { bfr* as_ = S0 + ((kt_) & 1) * GSTAGE; bfr* bs_ = as_ + 128 * 40; \
;     if (apar == ((kt_) & 1)) { _Pragma("unroll") for (int i = 0; i < 4; ++i) *(u32x4*)(as_ + asoff + i * 32 * 40) = ra[i]; } \
;     _Pragma("unroll") for (int i = 0; i < 4; ++i) *(u32x4*)(bs_ + bsoff + i * 64 * 40) = rb[i]; } while (0)
; template <int lda>
; DI void gemm_mainloop(const bfr* __restrict__ A, const bfr* __restrict__ Bt, int NB, int K, int m0, int n0, char* smem, f32x16 (&acc)[2][4]) {
;   bfr* S0 = (bfr*)smem;
;   int tid = threadIdx.x;
;   asm volatile("" : "+v"(tid));
;   const int lane = tid & 63, wid = tid >> 6, wr = wid >> 1, wc = wid & 1;
;   const int r = lane & 31, hl = lane >> 5;
; #pragma unroll
;   for (int i = 0; i < 2; ++i)
; #pragma unroll
;     for (int j = 0; j < 4; ++j)
; #pragma unroll
;       for (int q = 0; q < 16; ++q) acc[i][j][q] = 0.f;
;   u32x4 ra[4], rb[4];
;   const int nk = K >> 5;
;   const int arow = tid >> 3, ac8 = tid & 7, apar = ac8 >> 2;
;   const bfr* Ab = A + (m0 + arow) * lda + ac8 * 8;
;   const int asoff = arow * 40 + (ac8 & 3) * 8;
;   const int brow = tid >> 2, bc4 = tid & 3;
;   const bfr* Bb = Bt + (n0 + brow) * 32 + bc4 * 8;
;   const int bsoff = brow * 40 + bc4 * 8;
;     ...
;   GA_LOAD(0);
;   GB_LOAD(0);
;   G_STORE(0);
;   GB_LOAD(1);
;   __syncthreads();
; template <bool FIRST, bool HAS_H>
; DI void phase_gemm_resid(const Params& p, const bfr* A, const bfr* Wt, const float* gnext, float* ss, char* smem) {
;     ...
;   for (int t0 = blockIdx.x; t0 < 128 * 4; t0 += gridDim.x) {
;     const int t = ((gridDim.x & 7) == 0) ? xcd_tile(t0, 4) : t0;
;     const int mt = t >> 2, nt = t & 3, m0 = mt * 128, n0 = nt * 256;
;     f32x16 acc[2][4];
;     gemm_mainloop<1024>(A, Wt, 1024, 1024, m0, n0, smem, acc);
.LBB0_1099:
	s_lshl_b32 s5, s4, 5
	s_and_b32 s36, s5, 0xffffff80
	s_lshl_b32 s4, s4, 8
	s_and_b32 s33, s4, 0x300
	s_mov_b32 s37, 0
	s_mov_b64 s[20:21], 0
	s_lshl_b32 s98, s36, 11
	s_add_u32 s98, s2, s98
	s_addc_u32 s99, s3, 0
	s_lshl_b32 s100, s33, 6
	s_add_u32 s100, s8, s100
	s_addc_u32 s101, s9, 0
	v_writelane_b32 v187, s64, 0
	v_writelane_b32 v187, s65, 1
	v_writelane_b32 v187, s66, 2
	v_writelane_b32 v187, s67, 3
	v_writelane_b32 v187, s68, 4
	v_writelane_b32 v187, s69, 5
	v_writelane_b32 v187, s70, 6
	v_writelane_b32 v187, s71, 7
	v_writelane_b32 v187, s72, 8
	v_writelane_b32 v187, s73, 9
	v_writelane_b32 v187, s74, 10
	v_writelane_b32 v187, s75, 11
	v_writelane_b32 v187, s76, 12
	v_writelane_b32 v187, s77, 13
	v_writelane_b32 v187, s78, 14
	v_writelane_b32 v187, s79, 15
	v_lshrrev_b32_e32 v188, 6, v196
	v_and_b32_e32 v189, 63, v196
	v_readfirstlane_b32 s73, v188
	v_lshrrev_b32_e32 v190, 2, v189
	v_bfe_u32 v191, v189, 4, 2
	v_and_b32_e32 v188, 3, v189
	v_xor_b32_e32 v188, v188, v191
	v_lshlrev_b32_e32 v188, 4, v188
	v_lshl_add_u32 v176, v190, 11, v188
	v_add_u32_e32 v177, 0x8000, v176
	v_lshl_add_u32 v178, v190, 6, v188
	v_and_b32_e32 v190, 31, v189
	v_lshrrev_b32_e32 v191, 5, v189
	v_bfe_u32 v188, v189, 2, 2
	v_xor_b32_e32 v188, v188, v191
	v_lshlrev_b32_e32 v188, 4, v188
	v_lshl_add_u32 v179, v190, 6, v188
	s_lshr_b32 s74, s73, 1
	s_lshl_b32 s74, s74, 12
	s_and_b32 s75, s73, 1
	s_lshl_b32 s75, s75, 13
	v_add_u32_e32 v181, s75, v179
	v_add_u32_e32 v179, s74, v179
	v_xor_b32_e32 v182, 32, v181
	v_xor_b32_e32 v180, 32, v179
	s_lshl_b32 s74, s73, 16
	s_add_u32 s64, s98, s74
	s_addc_u32 s65, s99, 0
	s_lshl_b32 s74, s73, 12
	s_add_u32 s66, s100, s74
	s_addc_u32 s67, s101, 0
	s_lshl_b32 s68, s73, 11
	s_lshl_b32 s69, s73, 12
	s_mov_b32 s70, 0
	s_mov_b32 s71, 0
	s_mov_b32 s72, 0
	s_waitcnt lgkmcnt(0)
	s_barrier
	s_mul_i32 s74, s70, 0x6000
	s_add_u32 s75, s74, s68
	s_mov_b32 m0, s75
	s_add_u32 s76, s74, 0x2000
	s_cmp_eq_u32 s70, 2
	s_cselect_b32 s76, 0x10000, s76
	global_load_lds_dwordx4 v176, s[64:65]
	s_add_u32 m0, s75, 0x400
	s_add_u32 s76, s76, s69
	global_load_lds_dwordx4 v177, s[64:65]
	s_mov_b32 m0, s76
	s_add_u32 s64, s64, 64
	s_addc_u32 s65, s65, 0
	global_load_lds_dwordx4 v178, s[66:67]
	global_load_lds_dwordx4 v178, s[66:67] offset:1024
	global_load_lds_dwordx4 v178, s[66:67] offset:2048
	global_load_lds_dwordx4 v178, s[66:67] offset:3072
	s_add_u32 s66, s66, 0x10000
	s_addc_u32 s67, s67, 0
	s_add_u32 s70, s70, 1
	s_cmp_eq_u32 s70, 3
	s_cselect_b32 s70, 0, s70
	s_mul_i32 s74, s70, 0x6000
	s_add_u32 s75, s74, s68
	s_mov_b32 m0, s75
	s_add_u32 s76, s74, 0x2000
	s_cmp_eq_u32 s70, 2
	s_cselect_b32 s76, 0x10000, s76
	global_load_lds_dwordx4 v176, s[64:65]
	s_add_u32 m0, s75, 0x400
	s_add_u32 s76, s76, s69
	global_load_lds_dwordx4 v177, s[64:65]
	s_mov_b32 m0, s76
	s_add_u32 s64, s64, 64
	s_addc_u32 s65, s65, 0
	global_load_lds_dwordx4 v178, s[66:67]
	global_load_lds_dwordx4 v178, s[66:67] offset:1024
	global_load_lds_dwordx4 v178, s[66:67] offset:2048
	global_load_lds_dwordx4 v178, s[66:67] offset:3072
	s_add_u32 s66, s66, 0x10000
	s_addc_u32 s67, s67, 0
	s_add_u32 s70, s70, 1
	s_cmp_eq_u32 s70, 3
	s_cselect_b32 s70, 0, s70
	v_mov_b32_e32 v112, 0
	v_mov_b32_e32 v113, 0
	v_mov_b32_e32 v114, 0
	v_mov_b32_e32 v115, 0
	v_mov_b32_e32 v116, 0
	v_mov_b32_e32 v117, 0
	v_mov_b32_e32 v118, 0
	v_mov_b32_e32 v119, 0
	v_mov_b32_e32 v120, 0
	v_mov_b32_e32 v121, 0
	v_mov_b32_e32 v122, 0
	v_mov_b32_e32 v123, 0
	v_mov_b32_e32 v124, 0
	v_mov_b32_e32 v125, 0
	v_mov_b32_e32 v126, 0
	v_mov_b32_e32 v127, 0
	v_mov_b32_e32 v96, 0
	v_mov_b32_e32 v97, 0
	v_mov_b32_e32 v98, 0
	v_mov_b32_e32 v99, 0
	v_mov_b32_e32 v100, 0
	v_mov_b32_e32 v101, 0
	v_mov_b32_e32 v102, 0
	v_mov_b32_e32 v103, 0
	v_mov_b32_e32 v104, 0
	v_mov_b32_e32 v105, 0
	v_mov_b32_e32 v106, 0
	v_mov_b32_e32 v107, 0
	v_mov_b32_e32 v108, 0
	v_mov_b32_e32 v109, 0
	v_mov_b32_e32 v110, 0
	v_mov_b32_e32 v111, 0
	v_mov_b32_e32 v80, 0
	v_mov_b32_e32 v81, 0
	v_mov_b32_e32 v82, 0
	v_mov_b32_e32 v83, 0
	v_mov_b32_e32 v84, 0
	v_mov_b32_e32 v85, 0
	v_mov_b32_e32 v86, 0
	v_mov_b32_e32 v87, 0
	v_mov_b32_e32 v88, 0
	v_mov_b32_e32 v89, 0
	v_mov_b32_e32 v90, 0
	v_mov_b32_e32 v91, 0
	v_mov_b32_e32 v92, 0
	v_mov_b32_e32 v93, 0
	v_mov_b32_e32 v94, 0
	v_mov_b32_e32 v95, 0
	v_mov_b32_e32 v64, 0
	v_mov_b32_e32 v65, 0
	v_mov_b32_e32 v66, 0
	v_mov_b32_e32 v67, 0
	v_mov_b32_e32 v68, 0
	v_mov_b32_e32 v69, 0
	v_mov_b32_e32 v70, 0
	v_mov_b32_e32 v71, 0
	v_mov_b32_e32 v72, 0
	v_mov_b32_e32 v73, 0
	v_mov_b32_e32 v74, 0
	v_mov_b32_e32 v75, 0
	v_mov_b32_e32 v76, 0
	v_mov_b32_e32 v77, 0
	v_mov_b32_e32 v78, 0
	v_mov_b32_e32 v79, 0
	v_mov_b32_e32 v48, 0
	v_mov_b32_e32 v49, 0
	v_mov_b32_e32 v50, 0
	v_mov_b32_e32 v51, 0
	v_mov_b32_e32 v52, 0
	v_mov_b32_e32 v53, 0
	v_mov_b32_e32 v54, 0
	v_mov_b32_e32 v55, 0
	v_mov_b32_e32 v56, 0
	v_mov_b32_e32 v57, 0
	v_mov_b32_e32 v58, 0
	v_mov_b32_e32 v59, 0
	v_mov_b32_e32 v60, 0
	v_mov_b32_e32 v61, 0
	v_mov_b32_e32 v62, 0
	v_mov_b32_e32 v63, 0
	v_mov_b32_e32 v32, 0
	v_mov_b32_e32 v33, 0
	v_mov_b32_e32 v34, 0
	v_mov_b32_e32 v35, 0
	v_mov_b32_e32 v36, 0
	v_mov_b32_e32 v37, 0
	v_mov_b32_e32 v38, 0
	v_mov_b32_e32 v39, 0
	v_mov_b32_e32 v40, 0
	v_mov_b32_e32 v41, 0
	v_mov_b32_e32 v42, 0
	v_mov_b32_e32 v43, 0
	v_mov_b32_e32 v44, 0
	v_mov_b32_e32 v45, 0
	v_mov_b32_e32 v46, 0
	v_mov_b32_e32 v47, 0
	v_mov_b32_e32 v16, 0
	v_mov_b32_e32 v17, 0
	v_mov_b32_e32 v18, 0
	v_mov_b32_e32 v19, 0
	v_mov_b32_e32 v20, 0
	v_mov_b32_e32 v21, 0
	v_mov_b32_e32 v22, 0
	v_mov_b32_e32 v23, 0
	v_mov_b32_e32 v24, 0
	v_mov_b32_e32 v25, 0
	v_mov_b32_e32 v26, 0
	v_mov_b32_e32 v27, 0
	v_mov_b32_e32 v28, 0
	v_mov_b32_e32 v29, 0
	v_mov_b32_e32 v30, 0
	v_mov_b32_e32 v31, 0
	v_mov_b32_e32 v0, 0
	v_mov_b32_e32 v1, 0
	v_mov_b32_e32 v2, 0
	v_mov_b32_e32 v3, 0
	v_mov_b32_e32 v4, 0
	v_mov_b32_e32 v5, 0
	v_mov_b32_e32 v6, 0
	v_mov_b32_e32 v7, 0
	v_mov_b32_e32 v8, 0
	v_mov_b32_e32 v9, 0
	v_mov_b32_e32 v10, 0
	v_mov_b32_e32 v11, 0
	v_mov_b32_e32 v12, 0
	v_mov_b32_e32 v13, 0
	v_mov_b32_e32 v14, 0
	v_mov_b32_e32 v15, 0
; #define MFMA32(a, b, c) __builtin_amdgcn_mfma_f32_32x32x16_bf16((a), (b), (c), 0, 0, 0)
; #define GA_LOAD(pr_) do { _Pragma("unroll") for (int i = 0; i < 4; ++i) ra[i] = *(const u32x4*)(Ab + (i * 32) * lda + (pr_) * 64); } while (0)
; #define GB_LOAD(kt_) do { const bfr* bk_ = Bb + (kt_) * NB * 32; \
;     _Pragma("unroll") for (int i = 0; i < 4; ++i) rb[i] = *(const u32x4*)(bk_ + (i * 64) * 32); } while (0)
; #define G_STORE(kt_) do { bfr* as_ = S0 + ((kt_) & 1) * GSTAGE; bfr* bs_ = as_ + 128 * 40; \
;     if (apar == ((kt_) & 1)) { _Pragma("unroll") for (int i = 0; i < 4; ++i) *(u32x4*)(as_ + asoff + i * 32 * 40) = ra[i]; } \
;     _Pragma("unroll") for (int i = 0; i < 4; ++i) *(u32x4*)(bs_ + bsoff + i * 64 * 40) = rb[i]; } while (0)
; template <int lda>
; DI void gemm_mainloop(const bfr* __restrict__ A, const bfr* __restrict__ Bt, int NB, int K, int m0, int n0, char* smem, f32x16 (&acc)[2][4]) {
;     ...
;   for (int kt = 0; kt < nk; ++kt) {
;     if (kt + 1 < nk) G_STORE(kt + 1);
;     if (kt + 2 < nk) {
;       GB_LOAD(kt + 2);
;       if ((kt & 1) == 0) GA_LOAD((kt >> 1) + 1);
;     }
;     const bfr* As = S0 + (kt & 1) * GSTAGE;
;     const bfr* Bs = As + 128 * 40;
; #pragma unroll
;     for (int ks = 0; ks < 2; ++ks) {
;       bf16x8 af[2], bfg[4];
; #pragma unroll
;       for (int i = 0; i < 2; ++i) af[i] = *(const bf16x8*)(As + (wr * 64 + i * 32 + r) * 40 + ks * 16 + hl * 8);
; #pragma unroll
;       for (int j = 0; j < 4; ++j) bfg[j] = *(const bf16x8*)(Bs + (wc * 128 + j * 32 + r) * 40 + ks * 16 + hl * 8);
; #pragma unroll
;       for (int i = 0; i < 2; ++i)
; #pragma unroll
;         for (int j = 0; j < 4; ++j) acc[i][j] = MFMA32(af[i], bfg[j], acc[i][j]);
;     }
;     __syncthreads();
.Lp10_loop:
	s_waitcnt vmcnt(6)
	s_barrier
	s_mul_i32 s74, s70, 0x6000
	s_add_u32 s75, s74, s68
	s_mov_b32 m0, s75
	s_add_u32 s76, s74, 0x2000
	s_cmp_eq_u32 s70, 2
	s_cselect_b32 s76, 0x10000, s76
	global_load_lds_dwordx4 v176, s[64:65]
	s_add_u32 m0, s75, 0x400
	s_add_u32 s76, s76, s69
	global_load_lds_dwordx4 v177, s[64:65]
	s_mov_b32 m0, s76
	s_add_u32 s64, s64, 64
	s_addc_u32 s65, s65, 0
	global_load_lds_dwordx4 v178, s[66:67]
	global_load_lds_dwordx4 v178, s[66:67] offset:1024
	global_load_lds_dwordx4 v178, s[66:67] offset:2048
	global_load_lds_dwordx4 v178, s[66:67] offset:3072
	s_add_u32 s66, s66, 0x10000
	s_addc_u32 s67, s67, 0
	s_add_u32 s70, s70, 1
	s_cmp_eq_u32 s70, 3
	s_cselect_b32 s70, 0, s70
	s_mul_i32 s74, s71, 0x6000
	s_add_u32 s75, s74, 0x2000
	s_cmp_eq_u32 s71, 2
	s_cselect_b32 s75, 0x10000, s75
	v_add_u32_e32 v183, s74, v179
	v_add_u32_e32 v185, s75, v181
	v_add_u32_e32 v184, s74, v180
	v_add_u32_e32 v186, s75, v182
	ds_read_b128 v[128:131], v183
	ds_read_b128 v[144:147], v185
	ds_read_b128 v[148:151], v185 offset:2048
	ds_read_b128 v[152:155], v185 offset:4096
	ds_read_b128 v[156:159], v185 offset:6144
	ds_read_b128 v[132:135], v183 offset:2048
	ds_read_b128 v[136:139], v184
	ds_read_b128 v[160:163], v186
	ds_read_b128 v[164:167], v186 offset:2048
	ds_read_b128 v[168:171], v186 offset:4096
	ds_read_b128 v[172:175], v186 offset:6144
	ds_read_b128 v[140:143], v184 offset:2048
	s_add_u32 s71, s71, 1
	s_cmp_eq_u32 s71, 3
	s_cselect_b32 s71, 0, s71
	s_waitcnt lgkmcnt(10)
	v_mfma_f32_32x32x16_bf16 v[112:127], v[128:131], v[144:147], v[112:127]
	s_waitcnt lgkmcnt(9)
	v_mfma_f32_32x32x16_bf16 v[96:111], v[128:131], v[148:151], v[96:111]
	s_waitcnt lgkmcnt(8)
	v_mfma_f32_32x32x16_bf16 v[80:95], v[128:131], v[152:155], v[80:95]
	s_waitcnt lgkmcnt(7)
	v_mfma_f32_32x32x16_bf16 v[64:79], v[128:131], v[156:159], v[64:79]
	s_waitcnt lgkmcnt(6)
	v_mfma_f32_32x32x16_bf16 v[48:63], v[132:135], v[144:147], v[48:63]
	v_mfma_f32_32x32x16_bf16 v[32:47], v[132:135], v[148:151], v[32:47]
	v_mfma_f32_32x32x16_bf16 v[16:31], v[132:135], v[152:155], v[16:31]
	v_mfma_f32_32x32x16_bf16 v[0:15], v[132:135], v[156:159], v[0:15]
	s_waitcnt lgkmcnt(4)
	v_mfma_f32_32x32x16_bf16 v[112:127], v[136:139], v[160:163], v[112:127]
	s_waitcnt lgkmcnt(3)
	v_mfma_f32_32x32x16_bf16 v[96:111], v[136:139], v[164:167], v[96:111]
	s_waitcnt lgkmcnt(2)
	v_mfma_f32_32x32x16_bf16 v[80:95], v[136:139], v[168:171], v[80:95]
	s_waitcnt lgkmcnt(1)
	v_mfma_f32_32x32x16_bf16 v[64:79], v[136:139], v[172:175], v[64:79]
	s_waitcnt lgkmcnt(0)
	v_mfma_f32_32x32x16_bf16 v[48:63], v[140:143], v[160:163], v[48:63]
	v_mfma_f32_32x32x16_bf16 v[32:47], v[140:143], v[164:167], v[32:47]
	v_mfma_f32_32x32x16_bf16 v[16:31], v[140:143], v[168:171], v[16:31]
	v_mfma_f32_32x32x16_bf16 v[0:15], v[140:143], v[172:175], v[0:15]
	s_add_u32 s72, s72, 1
	s_cmp_lt_u32 s72, 30
	s_cbranch_scc1 .Lp10_loop
	s_waitcnt vmcnt(6)
	s_barrier
	s_mul_i32 s74, s71, 0x6000
	s_add_u32 s75, s74, 0x2000
	s_cmp_eq_u32 s71, 2
	s_cselect_b32 s75, 0x10000, s75
	v_add_u32_e32 v183, s74, v179
	v_add_u32_e32 v185, s75, v181
	v_add_u32_e32 v184, s74, v180
	v_add_u32_e32 v186, s75, v182
	ds_read_b128 v[128:131], v183
	ds_read_b128 v[144:147], v185
	ds_read_b128 v[148:151], v185 offset:2048
	ds_read_b128 v[152:155], v185 offset:4096
	ds_read_b128 v[156:159], v185 offset:6144
	ds_read_b128 v[132:135], v183 offset:2048
	ds_read_b128 v[136:139], v184
	ds_read_b128 v[160:163], v186
	ds_read_b128 v[164:167], v186 offset:2048
	ds_read_b128 v[168:171], v186 offset:4096
	ds_read_b128 v[172:175], v186 offset:6144
	ds_read_b128 v[140:143], v184 offset:2048
	s_add_u32 s71, s71, 1
	s_cmp_eq_u32 s71, 3
	s_cselect_b32 s71, 0, s71
	s_waitcnt lgkmcnt(10)
	v_mfma_f32_32x32x16_bf16 v[112:127], v[128:131], v[144:147], v[112:127]
	s_waitcnt lgkmcnt(9)
	v_mfma_f32_32x32x16_bf16 v[96:111], v[128:131], v[148:151], v[96:111]
	s_waitcnt lgkmcnt(8)
	v_mfma_f32_32x32x16_bf16 v[80:95], v[128:131], v[152:155], v[80:95]
	s_waitcnt lgkmcnt(7)
	v_mfma_f32_32x32x16_bf16 v[64:79], v[128:131], v[156:159], v[64:79]
	s_waitcnt lgkmcnt(6)
	v_mfma_f32_32x32x16_bf16 v[48:63], v[132:135], v[144:147], v[48:63]
	v_mfma_f32_32x32x16_bf16 v[32:47], v[132:135], v[148:151], v[32:47]
	v_mfma_f32_32x32x16_bf16 v[16:31], v[132:135], v[152:155], v[16:31]
	v_mfma_f32_32x32x16_bf16 v[0:15], v[132:135], v[156:159], v[0:15]
	s_waitcnt lgkmcnt(4)
	v_mfma_f32_32x32x16_bf16 v[112:127], v[136:139], v[160:163], v[112:127]
	s_waitcnt lgkmcnt(3)
	v_mfma_f32_32x32x16_bf16 v[96:111], v[136:139], v[164:167], v[96:111]
	s_waitcnt lgkmcnt(2)
	v_mfma_f32_32x32x16_bf16 v[80:95], v[136:139], v[168:171], v[80:95]
	s_waitcnt lgkmcnt(1)
	v_mfma_f32_32x32x16_bf16 v[64:79], v[136:139], v[172:175], v[64:79]
	s_waitcnt lgkmcnt(0)
	v_mfma_f32_32x32x16_bf16 v[48:63], v[140:143], v[160:163], v[48:63]
	v_mfma_f32_32x32x16_bf16 v[32:47], v[140:143], v[164:167], v[32:47]
	v_mfma_f32_32x32x16_bf16 v[16:31], v[140:143], v[168:171], v[16:31]
	v_mfma_f32_32x32x16_bf16 v[0:15], v[140:143], v[172:175], v[0:15]
	s_waitcnt vmcnt(0)
	s_barrier
; #define MFMA32(a, b, c) __builtin_amdgcn_mfma_f32_32x32x16_bf16((a), (b), (c), 0, 0, 0)
; DI int crow(int reg, int h) { return (reg & 3) + 8 * (reg >> 2) + 4 * h; }
; #define GA_LOAD(pr_) do { _Pragma("unroll") for (int i = 0; i < 4; ++i) ra[i] = *(const u32x4*)(Ab + (i * 32) * lda + (pr_) * 64); } while (0)
; template <int lda>
; DI void gemm_mainloop(const bfr* __restrict__ A, const bfr* __restrict__ Bt, int NB, int K, int m0, int n0, char* smem, f32x16 (&acc)[2][4]) {
;     ...
;   for (int kt = 0; kt < nk; ++kt) {
;     if (kt + 1 < nk) G_STORE(kt + 1);
;     if (kt + 2 < nk) {
;       GB_LOAD(kt + 2);
;       if ((kt & 1) == 0) GA_LOAD((kt >> 1) + 1);
;     }
;     const bfr* As = S0 + (kt & 1) * GSTAGE;
;     const bfr* Bs = As + 128 * 40;
; #pragma unroll
;     for (int ks = 0; ks < 2; ++ks) {
;       bf16x8 af[2], bfg[4];
; #pragma unroll
;       for (int i = 0; i < 2; ++i) af[i] = *(const bf16x8*)(As + (wr * 64 + i * 32 + r) * 40 + ks * 16 + hl * 8);
; #pragma unroll
;       for (int j = 0; j < 4; ++j) bfg[j] = *(const bf16x8*)(Bs + (wc * 128 + j * 32 + r) * 40 + ks * 16 + hl * 8);
; #pragma unroll
;       for (int i = 0; i < 2; ++i)
; #pragma unroll
;         for (int j = 0; j < 4; ++j) acc[i][j] = MFMA32(af[i], bfg[j], acc[i][j]);
;     }
;     __syncthreads();
; template <bool FIRST, bool HAS_H>
; DI void phase_gemm_resid(const Params& p, const bfr* A, const bfr* Wt, const float* gnext, float* ss, char* smem) {
;     ...
;     int tid2 = threadIdx.x;
;     asm volatile("" : "+v"(tid2));
;     const int lane = tid2 & 63, wid = tid2 >> 6, wr = wid >> 1, wc = wid & 1, r = lane & 31, hl = lane >> 5;
;     const float* xsrc = FIRST ? p.x_prompt : X;
;     const int rbase = m0 + wr * 64 + 4 * hl, cbase = n0 + wc * 128 + r;
; #pragma unroll
;     for (int i = 0; i < 2; ++i) {
; #pragma unroll
;       for (int qh = 0; qh < 2; ++qh) {
;         float rs[8];
; #pragma unroll
;         for (int q = 0; q < 8; ++q) rs[q] = 0.f;
; #pragma unroll
;         for (int jh = 0; jh < 2; ++jh) {
;           float xo[2][8];
; #pragma unroll
;           for (int jj = 0; jj < 2; ++jj)
; #pragma unroll
;             for (int q = 0; q < 8; ++q)
;               xo[jj][q] = xsrc[(rbase + i * 32 + crow(qh * 8 + q, 0)) * 1024 + cbase + (jh * 2 + jj) * 32];
	s_mul_i32 s74, s71, 0x6000
	s_add_u32 s75, s74, 0x2000
	s_cmp_eq_u32 s71, 2
	s_cselect_b32 s75, 0x10000, s75
	v_add_u32_e32 v183, s74, v179
	v_add_u32_e32 v185, s75, v181
	v_add_u32_e32 v184, s74, v180
	v_add_u32_e32 v186, s75, v182
	ds_read_b128 v[128:131], v183
	ds_read_b128 v[144:147], v185
	ds_read_b128 v[148:151], v185 offset:2048
	ds_read_b128 v[152:155], v185 offset:4096
	ds_read_b128 v[156:159], v185 offset:6144
	ds_read_b128 v[132:135], v183 offset:2048
	ds_read_b128 v[136:139], v184
	ds_read_b128 v[160:163], v186
	ds_read_b128 v[164:167], v186 offset:2048
	ds_read_b128 v[168:171], v186 offset:4096
	ds_read_b128 v[172:175], v186 offset:6144
	ds_read_b128 v[140:143], v184 offset:2048
	s_add_u32 s71, s71, 1
	s_cmp_eq_u32 s71, 3
	s_cselect_b32 s71, 0, s71
	s_waitcnt lgkmcnt(10)
	v_mfma_f32_32x32x16_bf16 v[112:127], v[128:131], v[144:147], v[112:127]
	s_waitcnt lgkmcnt(9)
	v_mfma_f32_32x32x16_bf16 v[96:111], v[128:131], v[148:151], v[96:111]
	s_waitcnt lgkmcnt(8)
	v_mfma_f32_32x32x16_bf16 v[80:95], v[128:131], v[152:155], v[80:95]
	s_waitcnt lgkmcnt(7)
	v_mfma_f32_32x32x16_bf16 v[64:79], v[128:131], v[156:159], v[64:79]
	s_waitcnt lgkmcnt(6)
	v_mfma_f32_32x32x16_bf16 v[48:63], v[132:135], v[144:147], v[48:63]
	v_mfma_f32_32x32x16_bf16 v[32:47], v[132:135], v[148:151], v[32:47]
	v_mfma_f32_32x32x16_bf16 v[16:31], v[132:135], v[152:155], v[16:31]
	v_mfma_f32_32x32x16_bf16 v[0:15], v[132:135], v[156:159], v[0:15]
	s_waitcnt lgkmcnt(4)
	v_mfma_f32_32x32x16_bf16 v[112:127], v[136:139], v[160:163], v[112:127]
	s_waitcnt lgkmcnt(3)
	v_mfma_f32_32x32x16_bf16 v[96:111], v[136:139], v[164:167], v[96:111]
	s_waitcnt lgkmcnt(2)
	v_mfma_f32_32x32x16_bf16 v[80:95], v[136:139], v[168:171], v[80:95]
	s_waitcnt lgkmcnt(1)
	v_mfma_f32_32x32x16_bf16 v[64:79], v[136:139], v[172:175], v[64:79]
	s_waitcnt lgkmcnt(0)
	v_mfma_f32_32x32x16_bf16 v[48:63], v[140:143], v[160:163], v[48:63]
	v_mfma_f32_32x32x16_bf16 v[32:47], v[140:143], v[164:167], v[32:47]
	v_mfma_f32_32x32x16_bf16 v[16:31], v[140:143], v[168:171], v[16:31]
	v_mfma_f32_32x32x16_bf16 v[0:15], v[140:143], v[172:175], v[0:15]
	s_nop 7
	v_readlane_b32 s64, v187, 0
	v_readlane_b32 s65, v187, 1
	v_readlane_b32 s66, v187, 2
	v_readlane_b32 s67, v187, 3
	v_readlane_b32 s68, v187, 4
	v_readlane_b32 s69, v187, 5
	v_readlane_b32 s70, v187, 6
	v_readlane_b32 s71, v187, 7
	v_readlane_b32 s72, v187, 8
	v_readlane_b32 s73, v187, 9
	v_readlane_b32 s74, v187, 10
	v_readlane_b32 s75, v187, 11
	v_readlane_b32 s76, v187, 12
	v_readlane_b32 s77, v187, 13
	v_readlane_b32 s78, v187, 14
	v_readlane_b32 s79, v187, 15
	s_nop 7
	s_waitcnt vmcnt(1)
	s_nop 0
	s_nop 0
	s_nop 0
	s_waitcnt vmcnt(0)
	s_nop 0
	v_add_u32_e32 v132, v169, v171
	s_nop 0
	v_add_u32_e32 v133, v169, v170
	s_nop 0
	s_nop 0
	s_nop 0
	s_nop 0
	s_nop 0
	s_nop 0
	s_nop 0
	s_nop 0
	s_nop 0
	s_nop 0
	s_nop 0
	v_mov_b32_e32 v192, v196
	s_waitcnt lgkmcnt(0)
	s_nop 0
	s_nop 0
	s_nop 0
	s_nop 0
	s_nop 0
	s_nop 0
	s_nop 0
	s_nop 0
	s_nop 0
	s_nop 0
	s_nop 0
	s_nop 0
	s_nop 0
	s_nop 0
	s_nop 0
	s_nop 0
	s_nop 0
	s_waitcnt lgkmcnt(0)
	s_nop 0
	s_nop 0
	v_ashrrev_i32_e32 v194, 1, v192
	v_and_b32_e32 v194, 0xffffffc0, v194
	v_add_u32_e32 v194, s36, v194
	v_lshrrev_b32_e32 v195, 3, v192
	v_and_b32_e32 v229, 31, v192
	v_and_or_b32 v228, v195, 4, v194
	v_lshlrev_b32_e32 v192, 1, v192
	s_nop 0
	v_and_b32_e32 v192, 0x80, v192
	v_lshlrev_b32_e32 v204, 10, v228
	v_or3_b32 v202, s33, v192, v229
	v_or_b32_e32 v194, v204, v202
	v_ashrrev_i32_e32 v195, 31, v194
	v_or_b32_e32 v203, 32, v202
	v_or_b32_e32 v230, 0x2c00, v204
	s_nop 0
	v_or_b32_e32 v218, 0x400, v204
	v_or_b32_e32 v216, v218, v202
	v_ashrrev_i32_e32 v217, 31, v216
	v_lshl_add_u64 v[216:217], v[216:217], 2, s[10:11]
	global_load_dword v219, v[216:217], off
	v_or_b32_e32 v216, v218, v203
	v_ashrrev_i32_e32 v217, 31, v216
	s_nop 0
	v_ashrrev_i32_e32 v201, 31, v204
	v_mov_b32_e32 v200, v194
	v_lshl_add_u64 v[198:199], v[194:195], 2, s[10:11]
	v_lshl_add_u64 v[200:201], v[200:201], 2, s[10:11]
	global_load_dword v192, v[198:199], off
	global_load_dword v205, v[200:201], off offset:128
	v_lshl_add_u64 v[216:217], v[216:217], 2, s[10:11]
	s_nop 0
	v_or_b32_e32 v221, 0x800, v204
	global_load_dword v220, v[216:217], off
	v_or_b32_e32 v216, v221, v202
	v_ashrrev_i32_e32 v217, 31, v216
	v_lshl_add_u64 v[216:217], v[216:217], 2, s[10:11]
	global_load_dword v222, v[216:217], off
	v_or_b32_e32 v216, v221, v203
	v_ashrrev_i32_e32 v217, 31, v216
	v_lshl_add_u64 v[216:217], v[216:217], 2, s[10:11]
	global_load_dword v223, v[216:217], off
	s_nop 0
	v_or_b32_e32 v224, 0xc00, v204
	v_or_b32_e32 v225, 0x2000, v204
	v_or_b32_e32 v226, 0x2400, v204
	v_or_b32_e32 v227, 0x2800, v204
	v_or_b32_e32 v216, v224, v202
	v_ashrrev_i32_e32 v217, 31, v216
	v_lshl_add_u64 v[216:217], v[216:217], 2, s[10:11]
	s_nop 0
	v_cmp_eq_u32_e32 vcc, 31, v229
	v_ashrrev_i32_e32 v229, 31, v228
	s_nop 0
	s_nop 0
	s_nop 0
	s_nop 0
	s_nop 0
	s_waitcnt vmcnt(3)
; DI bfr f2bf(float a) { return (bfr)(pack2(a, 0.f) & 0xffffu); }
; DI int crow(int reg, int h) { return (reg & 3) + 8 * (reg >> 2) + 4 * h; }
; template <bool FIRST, bool HAS_H>
; DI void phase_gemm_resid(const Params& p, const bfr* A, const bfr* Wt, const float* gnext, float* ss, char* smem) {
;     ...
;         for (int jh = 0; jh < 2; ++jh) {
;           float xo[2][8];
; #pragma unroll
;           for (int jj = 0; jj < 2; ++jj)
; #pragma unroll
;             for (int q = 0; q < 8; ++q)
;               xo[jj][q] = xsrc[(rbase + i * 32 + crow(qh * 8 + q, 0)) * 1024 + cbase + (jh * 2 + jj) * 32];
; #pragma unroll
;           for (int q = 0; q < 8; ++q) {
;             const int o = (rbase + i * 32 + crow(qh * 8 + q, 0)) * 1024 + cbase;
; #pragma unroll
;             for (int jj = 0; jj < 2; ++jj) {
;               const int j = jh * 2 + jj;
;               const float xn = xo[jj][q] + acc[i][j][qh * 8 + q];
;               X[o + j * 32] = xn;
;               if (HAS_H) Hn[o + j * 32] = f2bf(xn * gnext[cbase + j * 32]);
;               rs[q] += xn * xn;
;             }
;           }
;         }
	s_nop 9
	v_add_f32_e32 v205, v96, v205
	s_nop 0
	v_or_b32_e32 v206, v225, v202
	v_or_b32_e32 v208, v226, v202
	v_ashrrev_i32_e32 v207, 31, v206
	v_ashrrev_i32_e32 v209, 31, v208
	v_lshl_add_u64 v[206:207], v[206:207], 2, s[10:11]
	v_lshl_add_u64 v[208:209], v[208:209], 2, s[10:11]
	v_or_b32_e32 v96, 0x420, v194
	s_nop 0
	v_or_b32_e32 v210, v227, v202
	v_ashrrev_i32_e32 v211, 31, v210
	v_or_b32_e32 v212, v230, v202
	v_lshl_add_u64 v[210:211], v[210:211], 2, s[10:11]
	v_ashrrev_i32_e32 v213, 31, v212
	v_lshl_add_u64 v[212:213], v[212:213], 2, s[10:11]
	global_load_dword v231, v[216:217], off
	global_load_dword v232, v[206:207], off
	global_load_dword v233, v[208:209], off
	global_load_dword v234, v[210:211], off
	global_load_dword v235, v[212:213], off
	v_or_b32_e32 v206, v224, v203
	v_or_b32_e32 v208, v225, v203
	v_or_b32_e32 v210, v226, v203
	v_ashrrev_i32_e32 v207, 31, v206
	v_ashrrev_i32_e32 v209, 31, v208
	v_ashrrev_i32_e32 v211, 31, v210
	v_or_b32_e32 v212, v227, v203
	v_or_b32_e32 v216, v230, v203
	v_lshl_add_u64 v[206:207], v[206:207], 2, s[10:11]
	v_lshl_add_u64 v[208:209], v[208:209], 2, s[10:11]
	v_lshl_add_u64 v[210:211], v[210:211], 2, s[10:11]
	v_ashrrev_i32_e32 v213, 31, v212
	v_ashrrev_i32_e32 v217, 31, v216
	v_lshl_add_u64 v[212:213], v[212:213], 2, s[10:11]
	v_lshl_add_u64 v[216:217], v[216:217], 2, s[10:11]
	global_load_dword v206, v[206:207], off
	s_nop 0
	global_load_dword v207, v[208:209], off
	s_nop 0
	global_load_dword v208, v[210:211], off
	global_load_dword v209, v[212:213], off
	s_nop 0
	global_load_dword v210, v[216:217], off
	v_add_f32_e32 v211, v112, v192
	v_or_b32_e32 v112, 0x400, v194
	global_store_dword v[198:199], v211, off
	v_lshlrev_b32_e32 v192, 2, v202
	s_nop 0
	v_add_f32_e32 v189, v113, v219
	v_ashrrev_i32_e32 v113, 31, v112
	global_load_dword v212, v192, s[12:13]
	v_lshl_add_u64 v[112:113], v[112:113], 2, s[10:11]
	global_store_dword v[198:199], v205, off offset:128
	global_load_dword v188, v192, s[12:13] offset:128
	s_waitcnt vmcnt(14)
	v_add_f32_e32 v98, v98, v223
	s_nop 0
	v_add_f32_e32 v185, v97, v220
	v_ashrrev_i32_e32 v97, 31, v96
	global_store_dword v[112:113], v189, off
	v_lshl_add_u64 v[96:97], v[96:97], 2, s[10:11]
	global_load_dword v184, v192, s[12:13]
	s_waitcnt vmcnt(15)
	v_add_f32_e32 v115, v115, v231
	s_nop 0
	v_or_b32_e32 v172, 0x800, v194
	v_ashrrev_i32_e32 v173, 31, v172
	global_store_dword v[96:97], v185, off
	v_add_f32_e32 v176, v114, v222
	v_lshl_add_u64 v[96:97], v[172:173], 2, s[10:11]
	v_or_b32_e32 v174, 0x820, v194
	global_load_dword v186, v192, s[12:13] offset:128
	v_ashrrev_i32_e32 v175, 31, v174
	global_store_dword v[96:97], v176, off
	global_load_dword v177, v192, s[12:13]
	v_lshl_add_u64 v[96:97], v[174:175], 2, s[10:11]
	global_store_dword v[96:97], v98, off
	global_load_dword v178, v192, s[12:13] offset:128
	s_nop 0
	v_lshl_add_u64 v[162:163], v[172:173], 1, s[6:7]
	v_lshl_add_u64 v[96:97], v[228:229], 2, s[14:15]
	s_waitcnt vmcnt(10)
	v_mul_f32_e32 v112, v211, v212
	s_nop 0
	v_cvt_pk_bf16_f32 v114, v112, s0
	v_lshl_add_u64 v[112:113], v[194:195], 1, s[6:7]
	global_store_short v[112:113], v114, off
	s_waitcnt vmcnt(9)
	v_mul_f32_e32 v114, v205, v188
	v_cvt_pk_bf16_f32 v114, v114, s0
	global_store_short v[112:113], v114, off offset:64
	v_mul_f32_e32 v114, v205, v205
	s_nop 0
	s_waitcnt vmcnt(8)
	v_mul_f32_e32 v160, v189, v184
	v_cvt_pk_bf16_f32 v160, v160, s0
	global_store_short v[112:113], v160, off offset:2048
	v_fmac_f32_e32 v114, v211, v211
	s_waitcnt vmcnt(7)
	v_mul_f32_e32 v160, v185, v186
	s_nop 0
	v_or_b32_e32 v152, 0xc00, v194
	v_ashrrev_i32_e32 v153, 31, v152
	v_lshl_add_u64 v[154:155], v[152:153], 2, s[10:11]
	global_store_dword v[154:155], v115, off
	s_waitcnt vmcnt(6)
	v_mul_f32_e32 v161, v176, v177
	v_cvt_pk_bf16_f32 v161, v161, s0
	global_store_short v[162:163], v161, off
	s_nop 0
	s_waitcnt vmcnt(5)
	v_mul_f32_e32 v161, v98, v178
	v_or_b32_e32 v154, 0xc20, v194
	v_cvt_pk_bf16_f32 v161, v161, s0
	v_lshl_add_u64 v[162:163], v[174:175], 1, s[6:7]
	v_ashrrev_i32_e32 v155, 31, v154
	global_store_short v[162:163], v161, off
	v_mul_f32_e32 v161, v98, v98
	s_nop 0
	global_load_dword v158, v192, s[12:13]
	v_add_f32_e32 v159, v99, v206
	v_lshl_add_u64 v[98:99], v[154:155], 2, s[10:11]
	global_store_dword v[98:99], v159, off
	global_load_dword v162, v192, s[12:13] offset:128
	v_or_b32_e32 v156, 0x2000, v194
	v_ashrrev_i32_e32 v157, 31, v156
	s_nop 0
	v_add_f32_e32 v163, v116, v232
	v_lshl_add_u64 v[98:99], v[156:157], 2, s[10:11]
	global_store_dword v[98:99], v163, off
	v_or_b32_e32 v116, 0x2400, v194
	v_add_f32_e32 v165, v117, v233
	v_ashrrev_i32_e32 v117, 31, v116
	v_add_f32_e32 v167, v102, v209
	s_nop 0
	v_or_b32_e32 v148, 0x2020, v194
	v_ashrrev_i32_e32 v149, 31, v148
	global_load_dword v150, v192, s[12:13]
	v_add_f32_e32 v151, v100, v207
	v_lshl_add_u64 v[98:99], v[148:149], 2, s[10:11]
	global_store_dword v[98:99], v151, off
	global_load_dword v164, v192, s[12:13] offset:128
	s_nop 0
	v_lshl_add_u64 v[98:99], v[116:117], 2, s[10:11]
	v_or_b32_e32 v140, 0x2420, v194
	global_store_dword v[98:99], v165, off
	v_ashrrev_i32_e32 v141, 31, v140
	v_lshl_add_u64 v[98:99], v[140:141], 2, s[10:11]
	v_add_f32_e32 v169, v119, v235
	v_add_f32_e32 v171, v103, v210
	s_nop 0
	global_load_dword v144, v192, s[12:13]
	v_add_f32_e32 v145, v101, v208
	global_store_dword v[98:99], v145, off
	global_load_dword v146, v192, s[12:13] offset:128
	v_add_f32_e32 v147, v118, v234
	v_cvt_pk_bf16_f32 v160, v160, s0
	global_store_short v[112:113], v160, off offset:2112
	s_nop 0
	v_or_b32_e32 v136, 0x2800, v194
	v_ashrrev_i32_e32 v137, 31, v136
	v_lshl_add_u64 v[98:99], v[136:137], 2, s[10:11]
; DI bfr f2bf(float a) { return (bfr)(pack2(a, 0.f) & 0xffffu); }
; DI int crow(int reg, int h) { return (reg & 3) + 8 * (reg >> 2) + 4 * h; }
; template <bool FIRST, bool HAS_H>
; DI void phase_gemm_resid(const Params& p, const bfr* A, const bfr* Wt, const float* gnext, float* ss, char* smem) {
;     ...
;         for (int jh = 0; jh < 2; ++jh) {
;           float xo[2][8];
; #pragma unroll
;           for (int jj = 0; jj < 2; ++jj)
; #pragma unroll
;             for (int q = 0; q < 8; ++q)
;               xo[jj][q] = xsrc[(rbase + i * 32 + crow(qh * 8 + q, 0)) * 1024 + cbase + (jh * 2 + jj) * 32];
; #pragma unroll
;           for (int q = 0; q < 8; ++q) {
;             const int o = (rbase + i * 32 + crow(qh * 8 + q, 0)) * 1024 + cbase;
; #pragma unroll
;             for (int jj = 0; jj < 2; ++jj) {
;               const int j = jh * 2 + jj;
;               const float xn = xo[jj][q] + acc[i][j][qh * 8 + q];
;               X[o + j * 32] = xn;
;               if (HAS_H) Hn[o + j * 32] = f2bf(xn * gnext[cbase + j * 32]);
;               rs[q] += xn * xn;
;             }
;           }
;         }
	global_store_dword v[98:99], v147, off
	global_load_dword v166, v192, s[12:13]
	v_lshl_add_u64 v[116:117], v[116:117], 1, s[6:7]
	v_mul_f32_e32 v160, v185, v185
	s_nop 0
	v_or_b32_e32 v128, 0x2820, v194
	v_ashrrev_i32_e32 v129, 31, v128
	v_lshl_add_u64 v[98:99], v[128:129], 2, s[10:11]
	global_store_dword v[98:99], v167, off
	global_load_dword v168, v192, s[12:13] offset:128
	v_or_b32_e32 v98, 0x2c00, v194
	v_ashrrev_i32_e32 v99, 31, v98
	v_lshl_add_u64 v[100:101], v[98:99], 2, s[10:11]
	global_store_dword v[100:101], v169, off
	global_load_dword v170, v192, s[12:13]
	v_or_b32_e32 v100, 0x2c20, v194
	v_ashrrev_i32_e32 v101, 31, v100
	v_lshl_add_u64 v[102:103], v[100:101], 2, s[10:11]
	global_store_dword v[102:103], v171, off
	v_or_b32_e32 v102, 64, v202
	v_or_b32_e32 v118, v218, v102
	v_or_b32_e32 v130, v221, v102
	v_or_b32_e32 v132, v224, v102
	v_or_b32_e32 v134, v225, v102
	v_ashrrev_i32_e32 v119, 31, v118
	v_ashrrev_i32_e32 v131, 31, v130
	v_ashrrev_i32_e32 v133, 31, v132
	v_ashrrev_i32_e32 v135, 31, v134
	v_or_b32_e32 v138, v226, v102
	v_or_b32_e32 v142, v227, v102
	v_lshl_add_u64 v[118:119], v[118:119], 2, s[10:11]
	v_lshl_add_u64 v[130:131], v[130:131], 2, s[10:11]
	v_lshl_add_u64 v[132:133], v[132:133], 2, s[10:11]
	v_lshl_add_u64 v[134:135], v[134:135], 2, s[10:11]
	v_ashrrev_i32_e32 v139, 31, v138
	v_ashrrev_i32_e32 v143, 31, v142
	v_lshl_add_u64 v[138:139], v[138:139], 2, s[10:11]
	s_waitcnt vmcnt(18)
	v_mul_f32_e32 v103, v115, v158
	v_lshl_add_u64 v[142:143], v[142:143], 2, s[10:11]
	global_load_dword v172, v[200:201], off offset:256
	global_load_dword v173, v[118:119], off
	s_nop 0
	global_load_dword v130, v[130:131], off
	s_nop 0
	global_load_dword v131, v[132:133], off
	s_nop 0
	global_load_dword v132, v[134:135], off
	global_load_dword v133, v[138:139], off
	s_nop 0
	global_load_dword v134, v[142:143], off
	global_load_dword v135, v[200:201], off offset:384
	v_cvt_pk_bf16_f32 v103, v103, s0
	v_lshl_add_u64 v[118:119], v[152:153], 1, s[6:7]
	global_store_short v[118:119], v103, off
	v_or_b32_e32 v103, 0x60, v202
	v_or_b32_e32 v118, v218, v103
	v_ashrrev_i32_e32 v119, 31, v118
	v_lshl_add_u64 v[118:119], v[118:119], 2, s[10:11]
	global_load_dword v138, v[118:119], off
	s_waitcnt vmcnt(26)
	v_mul_f32_e32 v118, v159, v162
	v_cvt_pk_bf16_f32 v139, v118, s0
	v_lshl_add_u64 v[118:119], v[154:155], 1, s[6:7]
	global_store_short v[118:119], v139, off
	v_or_b32_e32 v118, v221, v103
	v_mul_f32_e32 v139, v159, v159
	v_ashrrev_i32_e32 v119, 31, v118
	v_fmac_f32_e32 v139, v115, v115
	s_waitcnt vmcnt(25)
	v_mul_f32_e32 v115, v163, v150
	v_lshl_add_u64 v[118:119], v[118:119], 2, s[10:11]
	v_cvt_pk_bf16_f32 v115, v115, s0
	global_load_dword v142, v[118:119], off
	v_lshl_add_u64 v[118:119], v[156:157], 1, s[6:7]
	global_store_short v[118:119], v115, off
	s_waitcnt vmcnt(25)
	v_mul_f32_e32 v115, v151, v164
	v_cvt_pk_bf16_f32 v115, v115, s0
	v_lshl_add_u64 v[118:119], v[148:149], 1, s[6:7]
	global_store_short v[118:119], v115, off
	v_or_b32_e32 v118, v224, v103
	v_ashrrev_i32_e32 v119, 31, v118
	v_lshl_add_u64 v[118:119], v[118:119], 2, s[10:11]
	global_load_dword v143, v[118:119], off
	s_waitcnt vmcnt(25)
	v_mul_f32_e32 v118, v165, v144
	v_cvt_pk_bf16_f32 v118, v118, s0
	global_store_short v[116:117], v118, off
	s_waitcnt vmcnt(24)
	v_mul_f32_e32 v116, v145, v146
	v_cvt_pk_bf16_f32 v118, v116, s0
	v_lshl_add_u64 v[116:117], v[140:141], 1, s[6:7]
	global_store_short v[116:117], v118, off
	v_or_b32_e32 v116, v225, v103
	v_ashrrev_i32_e32 v117, 31, v116
	v_lshl_add_u64 v[116:117], v[116:117], 2, s[10:11]
	global_load_dword v140, v[116:117], off
	s_waitcnt vmcnt(23)
	v_mul_f32_e32 v116, v147, v166
	v_cvt_pk_bf16_f32 v118, v116, s0
	v_lshl_add_u64 v[116:117], v[136:137], 1, s[6:7]
	global_store_short v[116:117], v118, off
	v_mul_f32_e32 v137, v167, v167
	v_mul_f32_e32 v141, v145, v145
	v_fmac_f32_e32 v137, v147, v147
	global_load_dword v145, v192, s[12:13] offset:128
	s_waitcnt vmcnt(23)
	v_mul_f32_e32 v116, v167, v168
	v_cvt_pk_bf16_f32 v118, v116, s0
	v_or_b32_e32 v116, v226, v103
	v_ashrrev_i32_e32 v117, 31, v116
	v_lshl_add_u64 v[116:117], v[116:117], 2, s[10:11]
	global_load_dword v136, v[116:117], off
	v_lshl_add_u64 v[116:117], v[128:129], 1, s[6:7]
	global_store_short v[116:117], v118, off
	v_or_b32_e32 v118, v227, v103
	s_waitcnt vmcnt(23)
	v_mul_f32_e32 v116, v169, v170
	v_ashrrev_i32_e32 v119, 31, v118
	v_cvt_pk_bf16_f32 v144, v116, s0
	v_or_b32_e32 v116, v230, v102
	v_lshl_add_u64 v[118:119], v[118:119], 2, s[10:11]
	global_load_dword v146, v[118:119], off
	v_ashrrev_i32_e32 v117, 31, v116
	v_or_b32_e32 v118, v230, v103
	v_lshl_add_u64 v[116:117], v[116:117], 2, s[10:11]
	v_ashrrev_i32_e32 v119, 31, v118
	v_lshl_add_u64 v[118:119], v[118:119], 2, s[10:11]
	global_load_dword v147, v[116:117], off
	global_load_dword v148, v[118:119], off
	v_mul_f32_e32 v115, v151, v151
	v_fmac_f32_e32 v115, v163, v163
	s_waitcnt vmcnt(24)
	v_add_f32_e32 v149, v80, v172
	global_store_dword v[198:199], v149, off offset:256
	v_or_b32_e32 v80, 0x440, v194
	global_load_dword v150, v192, s[12:13] offset:256
	s_waitcnt vmcnt(25)
	v_add_f32_e32 v152, v81, v173
	v_ashrrev_i32_e32 v81, 31, v80
	v_lshl_add_u64 v[80:81], v[80:81], 2, s[10:11]
	s_waitcnt vmcnt(19)
	v_add_f32_e32 v135, v64, v135
	v_or_b32_e32 v64, 0x460, v194
	global_store_dword v[198:199], v135, off offset:384
	global_load_dword v151, v192, s[12:13] offset:384
	v_add_f32_e32 v155, v82, v130
	global_store_dword v[80:81], v152, off
	global_load_dword v153, v192, s[12:13] offset:256
	v_or_b32_e32 v82, 0xc40, v194
	s_waitcnt vmcnt(21)
; DI bfr f2bf(float a) { return (bfr)(pack2(a, 0.f) & 0xffffu); }
; DI int crow(int reg, int h) { return (reg & 3) + 8 * (reg >> 2) + 4 * h; }
; template <bool FIRST, bool HAS_H>
; DI void phase_gemm_resid(const Params& p, const bfr* A, const bfr* Wt, const float* gnext, float* ss, char* smem) {
;     ...
;         for (int jh = 0; jh < 2; ++jh) {
;           float xo[2][8];
; #pragma unroll
;           for (int jj = 0; jj < 2; ++jj)
; #pragma unroll
;             for (int q = 0; q < 8; ++q)
;               xo[jj][q] = xsrc[(rbase + i * 32 + crow(qh * 8 + q, 0)) * 1024 + cbase + (jh * 2 + jj) * 32];
; #pragma unroll
;           for (int q = 0; q < 8; ++q) {
;             const int o = (rbase + i * 32 + crow(qh * 8 + q, 0)) * 1024 + cbase;
; #pragma unroll
;             for (int jj = 0; jj < 2; ++jj) {
;               const int j = jh * 2 + jj;
;               const float xn = xo[jj][q] + acc[i][j][qh * 8 + q];
;               X[o + j * 32] = xn;
;               if (HAS_H) Hn[o + j * 32] = f2bf(xn * gnext[cbase + j * 32]);
;               rs[q] += xn * xn;
;             }
;           }
;         }
	v_add_f32_e32 v138, v65, v138
	v_ashrrev_i32_e32 v65, 31, v64
	v_lshl_add_u64 v[64:65], v[64:65], 2, s[10:11]
	global_store_dword v[64:65], v138, off
	v_or_b32_e32 v64, 0x840, v194
	v_ashrrev_i32_e32 v65, 31, v64
	v_lshl_add_u64 v[80:81], v[64:65], 2, s[10:11]
	global_load_dword v154, v192, s[12:13] offset:384
	v_add_f32_e32 v158, v83, v131
	global_store_dword v[80:81], v155, off
	v_or_b32_e32 v80, 0x860, v194
	v_ashrrev_i32_e32 v81, 31, v80
	global_load_dword v156, v192, s[12:13] offset:256
	s_waitcnt vmcnt(23)
	v_add_f32_e32 v142, v66, v142
	v_lshl_add_u64 v[116:117], v[80:81], 2, s[10:11]
	v_ashrrev_i32_e32 v83, 31, v82
	v_or_b32_e32 v66, 0xc60, v194
	global_store_dword v[116:117], v142, off
	v_lshl_add_u64 v[116:117], v[82:83], 2, s[10:11]
	global_load_dword v157, v192, s[12:13] offset:384
	v_add_f32_e32 v163, v84, v132
	global_store_dword v[116:117], v158, off
	s_waitcnt vmcnt(23)
	v_add_f32_e32 v143, v67, v143
	v_ashrrev_i32_e32 v67, 31, v66
	v_lshl_add_u64 v[116:117], v[66:67], 2, s[10:11]
	global_load_dword v159, v192, s[12:13] offset:256
	v_or_b32_e32 v84, 0x2440, v194
	global_store_dword v[116:117], v143, off
	v_or_b32_e32 v116, 0x2040, v194
	v_ashrrev_i32_e32 v117, 31, v116
	v_lshl_add_u64 v[118:119], v[116:117], 2, s[10:11]
	global_load_dword v162, v192, s[12:13] offset:384
	v_add_f32_e32 v166, v85, v133
	global_store_dword v[118:119], v163, off
	v_or_b32_e32 v118, 0x2060, v194
	v_ashrrev_i32_e32 v119, 31, v118
	global_load_dword v164, v192, s[12:13] offset:256
	s_waitcnt vmcnt(25)
	v_add_f32_e32 v140, v68, v140
	v_lshl_add_u64 v[128:129], v[118:119], 2, s[10:11]
	v_ashrrev_i32_e32 v85, 31, v84
	v_or_b32_e32 v68, 0x2460, v194
	global_store_dword v[128:129], v140, off
	v_lshl_add_u64 v[128:129], v[84:85], 2, s[10:11]
	v_fmac_f32_e32 v141, v165, v165
	global_load_dword v165, v192, s[12:13] offset:384
	v_add_f32_e32 v134, v86, v134
	global_store_dword v[128:129], v166, off
	s_waitcnt vmcnt(25)
	v_add_f32_e32 v136, v69, v136
	v_ashrrev_i32_e32 v69, 31, v68
	v_lshl_add_u64 v[128:129], v[68:69], 2, s[10:11]
	global_load_dword v167, v192, s[12:13] offset:256
	v_or_b32_e32 v86, 0x2c40, v194
	global_store_dword v[128:129], v136, off
	v_or_b32_e32 v128, 0x2840, v194
	v_ashrrev_i32_e32 v129, 31, v128
	v_lshl_add_u64 v[130:131], v[128:129], 2, s[10:11]
	global_load_dword v168, v192, s[12:13] offset:384
	s_waitcnt vmcnt(26)
	v_add_f32_e32 v146, v70, v146
	global_store_dword v[130:131], v134, off
	v_or_b32_e32 v130, 0x2860, v194
	v_ashrrev_i32_e32 v131, 31, v130
	global_load_dword v170, v192, s[12:13] offset:256
	v_lshl_add_u64 v[132:133], v[130:131], 2, s[10:11]
	global_store_dword v[132:133], v146, off
	s_waitcnt vmcnt(28)
	v_add_f32_e32 v147, v87, v147
	v_ashrrev_i32_e32 v87, 31, v86
	global_load_dword v172, v192, s[12:13] offset:384
	v_lshl_add_u64 v[132:133], v[86:87], 2, s[10:11]
	v_or_b32_e32 v70, 0x2c60, v194
	global_store_dword v[132:133], v147, off
	s_waitcnt vmcnt(29)
	v_add_f32_e32 v148, v71, v148
	v_ashrrev_i32_e32 v71, 31, v70
	global_load_dword v173, v192, s[12:13] offset:256
	v_lshl_add_u64 v[132:133], v[70:71], 2, s[10:11]
	global_store_dword v[132:133], v148, off
	global_load_dword v132, v192, s[12:13] offset:384
	v_lshl_add_u64 v[98:99], v[98:99], 1, s[6:7]
	global_store_short v[98:99], v144, off
	v_mul_f32_e32 v98, v171, v145
	v_cvt_pk_bf16_f32 v133, v98, s0
	v_lshl_add_u64 v[98:99], v[100:101], 1, s[6:7]
	global_store_short v[98:99], v133, off
	s_waitcnt vmcnt(32)
	v_mul_f32_e32 v99, v149, v150
	v_cvt_pk_bf16_f32 v99, v99, s0
	global_store_short v[112:113], v99, off offset:128
	s_waitcnt vmcnt(31)
	v_mul_f32_e32 v99, v135, v151
	v_cvt_pk_bf16_f32 v99, v99, s0
	global_store_short v[112:113], v99, off offset:192
	s_waitcnt vmcnt(30)
	v_mul_f32_e32 v99, v152, v153
	v_cvt_pk_bf16_f32 v99, v99, s0
	global_store_short v[112:113], v99, off offset:2176
	s_waitcnt vmcnt(29)
	v_mul_f32_e32 v99, v138, v154
	v_cvt_pk_bf16_f32 v99, v99, s0
	global_store_short v[112:113], v99, off offset:2240
	s_waitcnt vmcnt(28)
	v_mul_f32_e32 v99, v155, v156
	v_cvt_pk_bf16_f32 v99, v99, s0
	v_lshl_add_u64 v[64:65], v[64:65], 1, s[6:7]
	global_store_short v[64:65], v99, off
	v_mul_f32_e32 v98, v171, v171
	s_waitcnt vmcnt(27)
	v_mul_f32_e32 v64, v142, v157
	v_cvt_pk_bf16_f32 v99, v64, s0
	v_lshl_add_u64 v[64:65], v[80:81], 1, s[6:7]
	global_store_short v[64:65], v99, off
	v_fmac_f32_e32 v160, v189, v189
	v_fmac_f32_e32 v161, v176, v176
	s_waitcnt vmcnt(26)
	v_mul_f32_e32 v64, v158, v159
	v_cvt_pk_bf16_f32 v80, v64, s0
	v_lshl_add_u64 v[64:65], v[82:83], 1, s[6:7]
	global_store_short v[64:65], v80, off
	v_fmac_f32_e32 v98, v169, v169
	v_fmac_f32_e32 v114, v149, v149
	s_waitcnt vmcnt(25)
	v_mul_f32_e32 v64, v143, v162
	v_cvt_pk_bf16_f32 v80, v64, s0
	v_lshl_add_u64 v[64:65], v[66:67], 1, s[6:7]
	global_store_short v[64:65], v80, off
	v_fmac_f32_e32 v160, v152, v152
	s_waitcnt vmcnt(24)
	v_mul_f32_e32 v64, v163, v164
	v_cvt_pk_bf16_f32 v66, v64, s0
	v_lshl_add_u64 v[64:65], v[116:117], 1, s[6:7]
	global_store_short v[64:65], v66, off
	v_fmac_f32_e32 v161, v155, v155
	v_fmac_f32_e32 v139, v158, v158
	v_fmac_f32_e32 v115, v163, v163
	v_fmac_f32_e32 v141, v166, v166
	s_waitcnt vmcnt(23)
	v_mul_f32_e32 v64, v140, v165
	v_cvt_pk_bf16_f32 v66, v64, s0
	v_lshl_add_u64 v[64:65], v[118:119], 1, s[6:7]
	global_store_short v[64:65], v66, off
	v_fmac_f32_e32 v137, v134, v134
	v_fmac_f32_e32 v98, v147, v147
	s_waitcnt vmcnt(22)
; #define DPPF(v, ctrl, rmask) __builtin_bit_cast(float, __builtin_amdgcn_update_dpp(0, __builtin_bit_cast(int, (v)), (ctrl), (rmask), 0xf, false))
; DI int crow(int reg, int h) { return (reg & 3) + 8 * (reg >> 2) + 4 * h; }
; DI float row16_sum(float v) {
;   v += DPPF(v, 0xB1, 0xf);
;   v += DPPF(v, 0x4E, 0xf);
;   v += DPPF(v, 0x141, 0xf);
;   v += DPPF(v, 0x140, 0xf);
;   return v;
; }
; DI float half32_sum_hi(float v) {
;   v = row16_sum(v);
;   v += DPPF(v, 0x142, 0xa);
;   return v;
; }
; template <bool FIRST, bool HAS_H>
; DI void phase_gemm_resid(const Params& p, const bfr* A, const bfr* Wt, const float* gnext, float* ss, char* smem) {
;     ...
; #pragma unroll
;         for (int q = 0; q < 8; ++q) rs[q] = half32_sum_hi(rs[q]);
;         if (r == 31) {
; #pragma unroll
;           for (int q = 0; q < 8; ++q) unsafeAtomicAdd(ss + rbase + i * 32 + crow(qh * 8 + q, 0), rs[q]);
;         }
	v_mul_f32_e32 v64, v166, v167
	v_cvt_pk_bf16_f32 v66, v64, s0
	v_lshl_add_u64 v[64:65], v[84:85], 1, s[6:7]
	global_store_short v[64:65], v66, off
	v_fmac_f32_e32 v114, v135, v135
	v_fmac_f32_e32 v160, v138, v138
	s_waitcnt vmcnt(21)
	v_mul_f32_e32 v64, v136, v168
	v_cvt_pk_bf16_f32 v66, v64, s0
	v_lshl_add_u64 v[64:65], v[68:69], 1, s[6:7]
	global_store_short v[64:65], v66, off
	v_fmac_f32_e32 v161, v142, v142
	s_waitcnt vmcnt(20)
	v_mul_f32_e32 v64, v134, v170
	v_cvt_pk_bf16_f32 v66, v64, s0
	v_lshl_add_u64 v[64:65], v[128:129], 1, s[6:7]
	global_store_short v[64:65], v66, off
	v_fmac_f32_e32 v139, v143, v143
	s_waitcnt vmcnt(19)
	v_mul_f32_e32 v64, v146, v172
	v_cvt_pk_bf16_f32 v66, v64, s0
	v_lshl_add_u64 v[64:65], v[130:131], 1, s[6:7]
	global_store_short v[64:65], v66, off
	v_fmac_f32_e32 v115, v140, v140
	v_fmac_f32_e32 v141, v136, v136
	s_waitcnt vmcnt(18)
	v_mul_f32_e32 v64, v147, v173
	v_cvt_pk_bf16_f32 v66, v64, s0
	v_lshl_add_u64 v[64:65], v[86:87], 1, s[6:7]
	global_store_short v[64:65], v66, off
	s_waitcnt vmcnt(17)
	v_mul_f32_e32 v64, v148, v132
	v_fmac_f32_e32 v137, v146, v146
	v_cvt_pk_bf16_f32 v66, v64, s0
	v_lshl_add_u64 v[64:65], v[70:71], 1, s[6:7]
	v_fmac_f32_e32 v98, v148, v148
	global_store_short v[64:65], v66, off
	v_add_f32_dpp v64, v114, v114 quad_perm:[1,0,3,2] row_mask:0xf bank_mask:0xf bound_ctrl:1
	v_add_f32_dpp v66, v160, v160 quad_perm:[1,0,3,2] row_mask:0xf bank_mask:0xf bound_ctrl:1
	v_add_f32_dpp v68, v161, v161 quad_perm:[1,0,3,2] row_mask:0xf bank_mask:0xf bound_ctrl:1
	v_add_f32_dpp v70, v139, v139 quad_perm:[1,0,3,2] row_mask:0xf bank_mask:0xf bound_ctrl:1
	v_add_f32_dpp v80, v115, v115 quad_perm:[1,0,3,2] row_mask:0xf bank_mask:0xf bound_ctrl:1
	v_add_f32_dpp v82, v141, v141 quad_perm:[1,0,3,2] row_mask:0xf bank_mask:0xf bound_ctrl:1
	v_add_f32_dpp v84, v137, v137 quad_perm:[1,0,3,2] row_mask:0xf bank_mask:0xf bound_ctrl:1
	v_add_f32_dpp v86, v98, v98 quad_perm:[1,0,3,2] row_mask:0xf bank_mask:0xf bound_ctrl:1
	v_add_f32_dpp v64, v64, v64 quad_perm:[2,3,0,1] row_mask:0xf bank_mask:0xf bound_ctrl:1
	v_add_f32_dpp v66, v66, v66 quad_perm:[2,3,0,1] row_mask:0xf bank_mask:0xf bound_ctrl:1
	v_add_f32_dpp v68, v68, v68 quad_perm:[2,3,0,1] row_mask:0xf bank_mask:0xf bound_ctrl:1
	v_add_f32_dpp v70, v70, v70 quad_perm:[2,3,0,1] row_mask:0xf bank_mask:0xf bound_ctrl:1
	v_add_f32_dpp v80, v80, v80 quad_perm:[2,3,0,1] row_mask:0xf bank_mask:0xf bound_ctrl:1
	v_add_f32_dpp v82, v82, v82 quad_perm:[2,3,0,1] row_mask:0xf bank_mask:0xf bound_ctrl:1
	v_add_f32_dpp v84, v84, v84 quad_perm:[2,3,0,1] row_mask:0xf bank_mask:0xf bound_ctrl:1
	v_add_f32_dpp v86, v86, v86 quad_perm:[2,3,0,1] row_mask:0xf bank_mask:0xf bound_ctrl:1
	v_add_f32_dpp v64, v64, v64 row_half_mirror row_mask:0xf bank_mask:0xf bound_ctrl:1
	v_add_f32_dpp v66, v66, v66 row_half_mirror row_mask:0xf bank_mask:0xf bound_ctrl:1
	v_add_f32_dpp v68, v68, v68 row_half_mirror row_mask:0xf bank_mask:0xf bound_ctrl:1
	v_add_f32_dpp v70, v70, v70 row_half_mirror row_mask:0xf bank_mask:0xf bound_ctrl:1
	v_add_f32_dpp v80, v80, v80 row_half_mirror row_mask:0xf bank_mask:0xf bound_ctrl:1
	v_add_f32_dpp v82, v82, v82 row_half_mirror row_mask:0xf bank_mask:0xf bound_ctrl:1
	v_add_f32_dpp v84, v84, v84 row_half_mirror row_mask:0xf bank_mask:0xf bound_ctrl:1
	v_add_f32_dpp v86, v86, v86 row_half_mirror row_mask:0xf bank_mask:0xf bound_ctrl:1
	v_add_f32_dpp v64, v64, v64 row_mirror row_mask:0xf bank_mask:0xf bound_ctrl:1
	v_mov_b32_e32 v65, 0
	v_add_f32_dpp v66, v66, v66 row_mirror row_mask:0xf bank_mask:0xf bound_ctrl:1
	v_mov_b32_e32 v67, 0
	v_add_f32_dpp v68, v68, v68 row_mirror row_mask:0xf bank_mask:0xf bound_ctrl:1
	v_mov_b32_e32 v69, 0
	v_add_f32_dpp v70, v70, v70 row_mirror row_mask:0xf bank_mask:0xf bound_ctrl:1
	v_mov_b32_e32 v71, 0
	v_add_f32_dpp v80, v80, v80 row_mirror row_mask:0xf bank_mask:0xf bound_ctrl:1
	v_mov_b32_e32 v81, 0
	v_add_f32_dpp v82, v82, v82 row_mirror row_mask:0xf bank_mask:0xf bound_ctrl:1
	v_mov_b32_e32 v83, 0
	v_add_f32_dpp v84, v84, v84 row_mirror row_mask:0xf bank_mask:0xf bound_ctrl:1
	v_mov_b32_e32 v85, 0
	v_add_f32_dpp v86, v86, v86 row_mirror row_mask:0xf bank_mask:0xf bound_ctrl:1
	v_mov_b32_e32 v87, 0
	v_mov_b32_dpp v65, v64 row_bcast:15 row_mask:0xa bank_mask:0xf
	v_mov_b32_dpp v67, v66 row_bcast:15 row_mask:0xa bank_mask:0xf
	v_mov_b32_dpp v69, v68 row_bcast:15 row_mask:0xa bank_mask:0xf
	v_mov_b32_dpp v71, v70 row_bcast:15 row_mask:0xa bank_mask:0xf
	v_mov_b32_dpp v81, v80 row_bcast:15 row_mask:0xa bank_mask:0xf
	v_mov_b32_dpp v83, v82 row_bcast:15 row_mask:0xa bank_mask:0xf
	v_mov_b32_dpp v85, v84 row_bcast:15 row_mask:0xa bank_mask:0xf
	v_mov_b32_dpp v87, v86 row_bcast:15 row_mask:0xa bank_mask:0xf
	s_and_saveexec_b64 s[4:5], vcc
	s_cbranch_execz .LBB0_1112
	v_add_f32_e32 v64, v64, v65
	v_add_f32_e32 v86, v86, v87
	v_add_f32_e32 v84, v84, v85
	v_add_f32_e32 v82, v82, v83
	v_add_f32_e32 v80, v80, v81
	v_add_f32_e32 v70, v70, v71
	v_add_f32_e32 v68, v68, v69
	v_add_f32_e32 v66, v66, v67
	global_atomic_add_f32 v[96:97], v64, off
	global_atomic_add_f32 v[96:97], v66, off offset:4
	global_atomic_add_f32 v[96:97], v68, off offset:8
	global_atomic_add_f32 v[96:97], v70, off offset:12
	global_atomic_add_f32 v[96:97], v80, off offset:32
	global_atomic_add_f32 v[96:97], v82, off offset:36
	global_atomic_add_f32 v[96:97], v84, off offset:40
	global_atomic_add_f32 v[96:97], v86, off offset:44

; DI bfr f2bf(float a) { return (bfr)(pack2(a, 0.f) & 0xffffu); }
; DI int crow(int reg, int h) { return (reg & 3) + 8 * (reg >> 2) + 4 * h; }
; template <int lda, class Epi>
; DI void gemm_tile(const bfr* __restrict__ A, const bfr* __restrict__ Bt, int NB, int K, int m0, int n0, char* smem, Epi epi) {
;     ...
; #pragma unroll
;   for (int i = 0; i < 2; ++i)
; #pragma unroll
;     for (int j = 0; j < 4; ++j)
; #pragma unroll
;       for (int q = 0; q < 16; ++q) {
;         int row = m0 + wr * 64 + i * 32 + crow(q, hl);
;         int col = n0 + wc * 128 + j * 32 + r;
;         epi(row, col, acc[i][j][q]);
;       }
; DI void phase_gemm_bf16out(const Params& p, const bfr* A, const bfr* Wt, bfr* C, int N, const float* ss, char* smem) {
;     ...
;     gemm_tile<1024>(A, Wt, N, 1024, mt * 128, nt * 256, smem,
;               [=](int row, int col, float v) {
;                 float inv = rsqrtf(ss[row] * (1.0f / 1024.0f) + EPSF);
;                 C[(size_t)row * N + col] = f2bf(v * inv);
;               });
.LBB0_1178:
	s_nop 0
	s_waitcnt vmcnt(3)
	s_nop 0
	s_waitcnt vmcnt(2)
	s_nop 0
	s_waitcnt vmcnt(1)
	s_nop 0
	s_waitcnt vmcnt(0)
	s_nop 0
	v_add_u32_e32 v144, v169, v171
	s_nop 0
	v_add_u32_e32 v198, v169, v170
	s_nop 0
	s_nop 0
	s_nop 0
	s_nop 0
	s_nop 0
	s_nop 0
	s_nop 0
	s_nop 0
	s_nop 0
	s_nop 0
	s_nop 0
	s_waitcnt lgkmcnt(0)
	s_nop 0
	s_nop 0
	s_nop 0
	s_nop 0
	s_add_i32 s28, s28, s34
	s_cmpk_lt_i32 s28, 0x400
	s_nop 0
	s_nop 0
	s_nop 0
	s_nop 0
	s_nop 0
	s_nop 0
	s_nop 0
	s_nop 0
	s_nop 0
	s_nop 0
	s_nop 0
	s_nop 0
	s_nop 0
	s_nop 0
	v_mov_b32_e32 v198, v196
	s_waitcnt lgkmcnt(0)
	s_nop 0
	s_nop 0
	v_ashrrev_i32_e32 v200, 1, v198
	v_and_b32_e32 v200, 0xffffffc0, v200
	v_lshrrev_b32_e32 v201, 3, v198
	v_add_u32_e32 v200, s30, v200
	v_and_or_b32 v200, v201, 4, v200
	v_ashrrev_i32_e32 v201, 31, v200
	v_lshl_add_u64 v[202:203], v[200:201], 2, s[8:9]
	global_load_dwordx4 v[224:227], v[202:203], off
	v_or_b32_e32 v212, 8, v200
	v_ashrrev_i32_e32 v213, 31, v212
	v_lshl_add_u64 v[202:203], v[212:213], 2, s[8:9]
	s_nop 0
	global_load_dwordx4 v[220:223], v[202:203], off
	v_and_b32_e32 v202, 31, v198
	v_lshlrev_b32_e32 v198, 1, v198
	v_and_b32_e32 v198, 0x80, v198
	v_or3_b32 v202, v202, v198, s29
	v_ashrrev_i32_e32 v203, 31, v202
	v_lshl_add_u64 v[202:203], v[202:203], 1, s[2:3]
	s_nop 0
	s_nop 0
	s_nop 0
	v_mov_b64_e32 v[204:205], s[16:17]
	v_lshlrev_b64 v[206:207], 12, v[200:201]
	v_or_b32_e32 v208, 1, v200
	v_ashrrev_i32_e32 v209, 31, v208
	v_lshl_add_u64 v[206:207], v[202:203], 0, v[206:207]
	v_lshlrev_b64 v[208:209], 12, v[208:209]
	v_lshl_add_u64 v[208:209], v[202:203], 0, v[208:209]
	s_nop 0
	v_or_b32_e32 v210, 2, v200
	v_ashrrev_i32_e32 v211, 31, v210
	v_lshlrev_b64 v[210:211], 12, v[210:211]
	s_waitcnt vmcnt(1)
	v_fma_f32 v224, v224, s14, v204
	v_fma_f32 v225, v225, s14, v204
	v_mul_f32_e32 v198, 0x4b800000, v224
	v_cmp_gt_f32_e32 vcc, s27, v224
	v_mul_f32_e32 v201, 0x4b800000, v225
	v_cmp_gt_f32_e64 s[4:5], s27, v225
	v_cndmask_b32_e32 v198, v224, v198, vcc
	v_rsq_f32_e32 v198, v198
	v_cndmask_b32_e64 v201, v225, v201, s[4:5]
	v_rsq_f32_e32 v224, v201
	v_pk_fma_f32 v[226:227], v[226:227], s[14:15], v[204:205] op_sel_hi:[1,0,0]
	v_mul_f32_e32 v201, 0x45800000, v198
	v_cndmask_b32_e32 v201, v198, v201, vcc
	v_mul_f32_e32 v225, 0x45800000, v224
	v_cndmask_b32_e64 v198, v224, v225, s[4:5]
	v_mul_f32_e32 v112, v112, v201
	v_mul_f32_e32 v228, 0x4b800000, v226
	v_mul_f32_e32 v113, v113, v198
	v_cvt_pk_bf16_f32 v112, v112, s0
	v_cmp_gt_f32_e32 vcc, s27, v226
	v_cvt_pk_bf16_f32 v113, v113, s0
	global_store_short v[206:207], v112, off
	global_store_short v[208:209], v113, off
	v_cndmask_b32_e32 v112, v226, v228, vcc
	v_or_b32_e32 v228, 16, v200
	v_ashrrev_i32_e32 v229, 31, v228
	s_nop 0
	v_rsq_f32_e32 v226, v112
	v_lshl_add_u64 v[112:113], v[202:203], 0, v[210:211]
	v_mul_f32_e32 v211, 0x4b800000, v227
	v_or_b32_e32 v224, 3, v200
	v_mul_f32_e32 v210, 0x45800000, v226
	v_cndmask_b32_e32 v210, v226, v210, vcc
	v_cmp_gt_f32_e32 vcc, s27, v227
	s_nop 0
	v_mul_f32_e32 v114, v114, v210
	v_cndmask_b32_e32 v211, v227, v211, vcc
	v_cvt_pk_bf16_f32 v114, v114, s0
	global_store_short v[112:113], v114, off
	v_ashrrev_i32_e32 v225, 31, v224
	s_nop 0
	v_lshl_add_u64 v[216:217], v[228:229], 2, s[8:9]
	global_load_dwordx4 v[216:219], v[216:217], off
	s_nop 0
	v_rsq_f32_e32 v176, v211
	s_waitcnt vmcnt(4)
	v_pk_fma_f32 v[178:179], v[220:221], s[14:15], v[204:205] op_sel_hi:[1,0,0]
	v_mul_f32_e32 v114, 0x45800000, v176
	v_cndmask_b32_e32 v211, v176, v114, vcc
	v_cmp_gt_f32_e32 vcc, s27, v178
	s_nop 0
	v_or_b32_e32 v180, 24, v200
	v_ashrrev_i32_e32 v181, 31, v180
	v_lshl_add_u64 v[182:183], v[180:181], 2, s[8:9]
	v_mul_f32_e32 v114, v115, v211
	v_cvt_pk_bf16_f32 v176, v114, s0
	v_lshlrev_b64 v[114:115], 12, v[224:225]
	v_lshl_add_u64 v[114:115], v[202:203], 0, v[114:115]
	s_nop 0
	global_load_dwordx4 v[164:167], v[182:183], off
	s_nop 0
	global_store_short v[114:115], v176, off
	v_lshlrev_b64 v[176:177], 12, v[212:213]
	v_lshl_add_u64 v[176:177], v[202:203], 0, v[176:177]
	s_nop 0
	v_mul_f32_e32 v192, 0x4b800000, v178
	v_cndmask_b32_e32 v178, v178, v192, vcc
	v_rsq_f32_e32 v178, v178
	s_nop 0
	v_mul_f32_e32 v190, 0x45800000, v178
	v_cndmask_b32_e32 v190, v178, v190, vcc
	v_mul_f32_e32 v172, 0x4b800000, v179
	v_cmp_gt_f32_e32 vcc, s27, v179
	v_mul_f32_e32 v116, v116, v190
	v_cvt_pk_bf16_f32 v116, v116, s0
	v_cndmask_b32_e32 v172, v179, v172, vcc
	v_rsq_f32_e32 v172, v172
	global_store_short v[176:177], v116, off
	v_pk_fma_f32 v[178:179], v[222:223], s[14:15], v[204:205] op_sel_hi:[1,0,0]
	v_or_b32_e32 v188, 9, v200
	v_mul_f32_e32 v116, 0x45800000, v172
	v_cndmask_b32_e32 v191, v172, v116, vcc
	v_mul_f32_e32 v175, 0x4b800000, v178
	v_cmp_gt_f32_e32 vcc, s27, v178
	v_ashrrev_i32_e32 v189, 31, v188
	v_mul_f32_e32 v116, v117, v191
	v_cndmask_b32_e32 v175, v178, v175, vcc
	v_rsq_f32_e32 v178, v175
	v_cvt_pk_bf16_f32 v172, v116, s0
	v_lshlrev_b64 v[116:117], 12, v[188:189]
	v_lshl_add_u64 v[116:117], v[202:203], 0, v[116:117]
	v_mul_f32_e32 v182, 0x45800000, v178
	v_cndmask_b32_e32 v178, v178, v182, vcc
	v_mul_f32_e32 v182, 0x4b800000, v179
	v_cmp_gt_f32_e32 vcc, s27, v179
	s_nop 0
	global_store_short v[116:117], v172, off
	v_cndmask_b32_e32 v179, v179, v182, vcc
	v_or_b32_e32 v172, 10, v200
	v_ashrrev_i32_e32 v173, 31, v172
	v_lshlrev_b64 v[172:173], 12, v[172:173]
	v_mul_f32_e32 v118, v118, v178
	v_lshl_add_u64 v[172:173], v[202:203], 0, v[172:173]
	s_nop 0
	v_rsq_f32_e32 v168, v179
	v_cvt_pk_bf16_f32 v118, v118, s0
	global_store_short v[172:173], v118, off
	v_or_b32_e32 v174, 11, v200
	v_mul_f32_e32 v118, 0x45800000, v168
	v_cndmask_b32_e32 v168, v168, v118, vcc
	v_ashrrev_i32_e32 v175, 31, v174
	v_mul_f32_e32 v118, v119, v168
	s_nop 0
	s_nop 0
	v_cvt_pk_bf16_f32 v162, v118, s0
	v_lshlrev_b64 v[118:119], 12, v[174:175]
	v_lshl_add_u64 v[160:161], v[202:203], 0, v[118:119]
	global_store_short v[160:161], v162, off
	s_waitcnt vmcnt(6)
; DI bfr f2bf(float a) { return (bfr)(pack2(a, 0.f) & 0xffffu); }
; DI int crow(int reg, int h) { return (reg & 3) + 8 * (reg >> 2) + 4 * h; }
; template <int lda, class Epi>
; DI void gemm_tile(const bfr* __restrict__ A, const bfr* __restrict__ Bt, int NB, int K, int m0, int n0, char* smem, Epi epi) {
;     ...
; #pragma unroll
;   for (int i = 0; i < 2; ++i)
; #pragma unroll
;     for (int j = 0; j < 4; ++j)
; #pragma unroll
;       for (int q = 0; q < 16; ++q) {
;         int row = m0 + wr * 64 + i * 32 + crow(q, hl);
;         int col = n0 + wc * 128 + j * 32 + r;
;         epi(row, col, acc[i][j][q]);
;       }
; DI void phase_gemm_bf16out(const Params& p, const bfr* A, const bfr* Wt, bfr* C, int N, const float* ss, char* smem) {
;     ...
;     gemm_tile<1024>(A, Wt, N, 1024, mt * 128, nt * 256, smem,
;               [=](int row, int col, float v) {
;                 float inv = rsqrtf(ss[row] * (1.0f / 1024.0f) + EPSF);
;                 C[(size_t)row * N + col] = f2bf(v * inv);
;               });
	v_pk_fma_f32 v[162:163], v[216:217], s[14:15], v[204:205] op_sel_hi:[1,0,0]
	v_lshlrev_b64 v[118:119], 12, v[228:229]
	v_mul_f32_e32 v169, 0x4b800000, v162
	v_cmp_gt_f32_e32 vcc, s27, v162
	s_nop 0
	v_lshl_add_u64 v[118:119], v[202:203], 0, v[118:119]
	v_cndmask_b32_e32 v152, v162, v169, vcc
	v_rsq_f32_e32 v154, v152
	v_or_b32_e32 v152, 17, v200
	v_ashrrev_i32_e32 v153, 31, v152
	v_mul_f32_e32 v155, 0x45800000, v154
	s_nop 0
	v_cndmask_b32_e32 v154, v154, v155, vcc
	v_mul_f32_e32 v155, 0x4b800000, v163
	v_cmp_gt_f32_e32 vcc, s27, v163
	v_mul_f32_e32 v120, v120, v154
	v_cvt_pk_bf16_f32 v120, v120, s0
	v_cndmask_b32_e32 v155, v163, v155, vcc
	v_rsq_f32_e32 v155, v155
	global_store_short v[118:119], v120, off
	s_nop 0
	v_mul_f32_e32 v120, 0x45800000, v155
	v_cndmask_b32_e32 v155, v155, v120, vcc
	v_mul_f32_e32 v120, v121, v155
	v_cvt_pk_bf16_f32 v156, v120, s0
	v_lshlrev_b64 v[120:121], 12, v[152:153]
	v_lshl_add_u64 v[120:121], v[202:203], 0, v[120:121]
	s_nop 0
	s_nop 4
	v_mul_f32_e32 v96, v96, v201
	v_cvt_pk_bf16_f32 v96, v96, s0
	global_store_short v[206:207], v96, off offset:64
	v_mul_f32_e32 v96, v97, v198
	v_cvt_pk_bf16_f32 v96, v96, s0
	global_store_short v[208:209], v96, off offset:64
	v_mul_f32_e32 v96, v98, v210
	s_nop 0
	v_fma_f32 v142, v218, s14, v204
	v_fma_f32 v143, v219, s14, v204
	v_or_b32_e32 v140, 18, v200
	v_mul_f32_e32 v152, 0x4b800000, v142
	v_cmp_gt_f32_e32 vcc, s27, v142
	v_ashrrev_i32_e32 v141, 31, v140
	v_lshlrev_b64 v[140:141], 12, v[140:141]
	v_cndmask_b32_e32 v142, v142, v152, vcc
	v_rsq_f32_e32 v142, v142
	s_nop 0
	v_lshl_add_u64 v[136:137], v[202:203], 0, v[140:141]
	v_mul_f32_e32 v80, v80, v201
	v_mul_f32_e32 v140, 0x45800000, v142
	v_cndmask_b32_e32 v142, v142, v140, vcc
	v_mul_f32_e32 v140, 0x4b800000, v143
	v_cmp_gt_f32_e32 vcc, s27, v143
	v_mul_f32_e32 v122, v122, v142
	v_cvt_pk_bf16_f32 v122, v122, s0
	v_cndmask_b32_e32 v140, v143, v140, vcc
	v_rsq_f32_e32 v140, v140
	global_store_short v[136:137], v122, off
	v_or_b32_e32 v138, 19, v200
	v_cvt_pk_bf16_f32 v80, v80, s0
	v_mul_f32_e32 v122, 0x45800000, v140
	v_cndmask_b32_e32 v143, v140, v122, vcc
	v_ashrrev_i32_e32 v139, 31, v138
	v_mul_f32_e32 v122, v123, v143
	global_store_short v[206:207], v80, off offset:128
	v_mul_f32_e32 v80, v81, v198
	v_cvt_pk_bf16_f32 v140, v122, s0
	v_lshlrev_b64 v[122:123], 12, v[138:139]
	v_cvt_pk_bf16_f32 v80, v80, s0
	v_lshl_add_u64 v[122:123], v[202:203], 0, v[122:123]
	global_store_short v[208:209], v80, off offset:128
	v_mul_f32_e32 v80, v82, v210
	global_store_short v[122:123], v140, off
	s_waitcnt vmcnt(12)
	v_pk_fma_f32 v[140:141], v[164:165], s[14:15], v[204:205] op_sel_hi:[1,0,0]
	v_cvt_pk_bf16_f32 v80, v80, s0
	s_nop 0
	v_cmp_gt_f32_e32 vcc, s27, v140
	global_store_short v[112:113], v80, off offset:128
	v_mul_f32_e32 v80, v83, v211
	v_cvt_pk_bf16_f32 v80, v80, s0
	global_store_short v[114:115], v80, off offset:128
	v_mul_f32_e32 v80, v84, v190
	v_cvt_pk_bf16_f32 v80, v80, s0
	s_nop 0
	global_store_short v[176:177], v80, off offset:128
	v_mul_f32_e32 v80, v85, v191
	v_cvt_pk_bf16_f32 v80, v80, s0
	v_lshlrev_b64 v[138:139], 12, v[180:181]
	global_store_short v[116:117], v80, off offset:128
	v_mul_f32_e32 v80, v86, v178
	v_or_b32_e32 v84, 32, v200
	s_nop 0
	v_mul_f32_e32 v128, 0x4b800000, v140
	v_cndmask_b32_e32 v128, v140, v128, vcc
	v_rsq_f32_e32 v132, v128
	v_lshl_add_u64 v[128:129], v[202:203], 0, v[138:139]
	v_cvt_pk_bf16_f32 v80, v80, s0
	v_ashrrev_i32_e32 v85, 31, v84
	v_mul_f32_e32 v133, 0x45800000, v132
	v_cndmask_b32_e32 v138, v132, v133, vcc
	v_mul_f32_e32 v132, 0x4b800000, v141
	v_cmp_gt_f32_e32 vcc, s27, v141
	global_store_short v[172:173], v80, off offset:128
	v_lshl_add_u64 v[80:81], v[84:85], 2, s[8:9]
	v_cndmask_b32_e32 v132, v141, v132, vcc
	v_rsq_f32_e32 v132, v132
	global_load_dwordx4 v[80:83], v[80:81], off
	v_mul_f32_e32 v124, v124, v138
	v_cvt_pk_bf16_f32 v124, v124, s0
	global_store_short v[128:129], v124, off
	v_mul_f32_e32 v124, 0x45800000, v132
	v_or_b32_e32 v130, 25, v200
	v_cndmask_b32_e32 v139, v132, v124, vcc
	v_ashrrev_i32_e32 v131, 31, v130
	v_mul_f32_e32 v124, v125, v139
	v_cvt_pk_bf16_f32 v132, v124, s0
	v_lshlrev_b64 v[124:125], 12, v[130:131]
	v_lshl_add_u64 v[124:125], v[202:203], 0, v[124:125]
	global_store_short v[124:125], v132, off
	v_pk_fma_f32 v[132:133], v[166:167], s[14:15], v[204:205] op_sel_hi:[1,0,0]
	v_mul_f32_e32 v86, v87, v168
	v_mul_f32_e32 v134, 0x4b800000, v132
	v_cmp_gt_f32_e32 vcc, s27, v132
	v_cvt_pk_bf16_f32 v86, v86, s0
	global_store_short v[160:161], v86, off offset:128
	v_cndmask_b32_e32 v132, v132, v134, vcc
	v_rsq_f32_e32 v132, v132
	v_mul_f32_e32 v86, v88, v154
	v_cvt_pk_bf16_f32 v86, v86, s0
	v_mul_f32_e32 v64, v64, v201
	global_store_short v[118:119], v86, off offset:128
	v_mul_f32_e32 v86, v89, v155
	v_cvt_pk_bf16_f32 v64, v64, s0
	v_cvt_pk_bf16_f32 v86, v86, s0
	global_store_short v[206:207], v64, off offset:192
	v_mul_f32_e32 v64, v65, v198
	v_mul_f32_e32 v140, 0x45800000, v132
	global_store_short v[120:121], v86, off offset:128
	v_mul_f32_e32 v86, v90, v142
	v_cvt_pk_bf16_f32 v64, v64, s0
	v_cndmask_b32_e32 v132, v132, v140, vcc
	v_mul_f32_e32 v140, 0x4b800000, v133
	v_cmp_gt_f32_e32 vcc, s27, v133
	v_cvt_pk_bf16_f32 v86, v86, s0
	global_store_short v[208:209], v64, off offset:192
	v_mul_f32_e32 v64, v66, v210
	v_cndmask_b32_e32 v133, v133, v140, vcc
	global_store_short v[136:137], v86, off offset:128
	v_mul_f32_e32 v86, v91, v143
	v_cvt_pk_bf16_f32 v64, v64, s0
	v_or_b32_e32 v130, 26, v200
	v_rsq_f32_e32 v133, v133
	v_cvt_pk_bf16_f32 v86, v86, s0
	global_store_short v[112:113], v64, off offset:192
	v_mul_f32_e32 v64, v67, v211
; DI bfr f2bf(float a) { return (bfr)(pack2(a, 0.f) & 0xffffu); }
; DI int crow(int reg, int h) { return (reg & 3) + 8 * (reg >> 2) + 4 * h; }
; template <int lda, class Epi>
; DI void gemm_tile(const bfr* __restrict__ A, const bfr* __restrict__ Bt, int NB, int K, int m0, int n0, char* smem, Epi epi) {
;     ...
; #pragma unroll
;   for (int i = 0; i < 2; ++i)
; #pragma unroll
;     for (int j = 0; j < 4; ++j)
; #pragma unroll
;       for (int q = 0; q < 16; ++q) {
;         int row = m0 + wr * 64 + i * 32 + crow(q, hl);
;         int col = n0 + wc * 128 + j * 32 + r;
;         epi(row, col, acc[i][j][q]);
;       }
; DI void phase_gemm_bf16out(const Params& p, const bfr* A, const bfr* Wt, bfr* C, int N, const float* ss, char* smem) {
;     ...
;     gemm_tile<1024>(A, Wt, N, 1024, mt * 128, nt * 256, smem,
;               [=](int row, int col, float v) {
;                 float inv = rsqrtf(ss[row] * (1.0f / 1024.0f) + EPSF);
;                 C[(size_t)row * N + col] = f2bf(v * inv);
;               });
	v_ashrrev_i32_e32 v131, 31, v130
	global_store_short v[122:123], v86, off offset:128
	v_mul_f32_e32 v86, v92, v138
	v_cvt_pk_bf16_f32 v64, v64, s0
	v_lshlrev_b64 v[130:131], 12, v[130:131]
	v_mul_f32_e32 v126, v126, v132
	v_cvt_pk_bf16_f32 v86, v86, s0
	global_store_short v[114:115], v64, off offset:192
	v_mul_f32_e32 v64, v68, v190
	v_lshl_add_u64 v[130:131], v[202:203], 0, v[130:131]
	v_cvt_pk_bf16_f32 v126, v126, s0
	global_store_short v[128:129], v86, off offset:128
	v_mul_f32_e32 v86, v93, v139
	v_cvt_pk_bf16_f32 v64, v64, s0
	global_store_short v[130:131], v126, off
	v_mul_f32_e32 v126, 0x45800000, v133
	v_cvt_pk_bf16_f32 v86, v86, s0
	global_store_short v[176:177], v64, off offset:192
	v_mul_f32_e32 v64, v69, v191
	v_or_b32_e32 v134, 27, v200
	v_cndmask_b32_e32 v133, v133, v126, vcc
	global_store_short v[124:125], v86, off offset:128
	v_mul_f32_e32 v86, v94, v132
	v_cvt_pk_bf16_f32 v64, v64, s0
	v_ashrrev_i32_e32 v135, 31, v134
	v_mul_f32_e32 v126, v127, v133
	v_cvt_pk_bf16_f32 v86, v86, s0
	global_store_short v[116:117], v64, off offset:192
	v_mul_f32_e32 v64, v70, v178
	v_cvt_pk_bf16_f32 v140, v126, s0
	v_lshlrev_b64 v[126:127], 12, v[134:135]
	global_store_short v[130:131], v86, off offset:128
	v_mul_f32_e32 v86, v95, v133
	v_cvt_pk_bf16_f32 v64, v64, s0
	v_lshl_add_u64 v[126:127], v[202:203], 0, v[126:127]
	v_cvt_pk_bf16_f32 v86, v86, s0
	global_store_short v[172:173], v64, off offset:192
	v_mul_f32_e32 v64, v71, v168
	global_store_short v[126:127], v86, off offset:128
	v_cvt_pk_bf16_f32 v64, v64, s0
	v_or_b32_e32 v86, 40, v200
	global_store_short v[160:161], v64, off offset:192
	v_mul_f32_e32 v64, v72, v154
	v_ashrrev_i32_e32 v87, 31, v86
	v_cvt_pk_bf16_f32 v66, v64, s0
	v_lshl_add_u64 v[64:65], v[86:87], 2, s[8:9]
	global_load_dwordx4 v[68:71], v[64:65], off
	v_mul_f32_e32 v64, v73, v155
	v_cvt_pk_bf16_f32 v64, v64, s0
	global_store_short v[118:119], v66, off offset:192
	global_store_short v[120:121], v64, off offset:192
	v_mul_f32_e32 v64, v74, v142
	s_waitcnt vmcnt(23)
	v_pk_fma_f32 v[66:67], v[80:81], s[14:15], v[204:205] op_sel_hi:[1,0,0]
	v_cvt_pk_bf16_f32 v64, v64, s0
	v_mul_f32_e32 v72, 0x4b800000, v66
	v_cmp_gt_f32_e32 vcc, s27, v66
	global_store_short v[136:137], v64, off offset:192
	v_mul_f32_e32 v64, v75, v143
	v_cndmask_b32_e32 v66, v66, v72, vcc
	v_cvt_pk_bf16_f32 v64, v64, s0
	v_rsq_f32_e32 v66, v66
	global_store_short v[122:123], v64, off offset:192
	v_mul_f32_e32 v64, v76, v138
	v_cvt_pk_bf16_f32 v64, v64, s0
	global_store_short v[128:129], v64, off offset:192
	v_mul_f32_e32 v64, v77, v139
	v_cvt_pk_bf16_f32 v64, v64, s0
	v_mul_f32_e32 v74, 0x45800000, v66
	global_store_short v[124:125], v64, off offset:192
	v_mul_f32_e32 v64, v78, v132
	v_cndmask_b32_e32 v88, v66, v74, vcc
	v_mul_f32_e32 v66, 0x4b800000, v67
	v_cmp_gt_f32_e32 vcc, s27, v67
	v_cvt_pk_bf16_f32 v64, v64, s0
	global_store_short v[130:131], v64, off offset:192
	v_cndmask_b32_e32 v66, v67, v66, vcc
	v_mul_f32_e32 v64, v79, v133
	v_rsq_f32_e32 v66, v66
	v_cvt_pk_bf16_f32 v64, v64, s0
	global_store_short v[126:127], v64, off offset:192
	v_lshlrev_b64 v[64:65], 12, v[84:85]
	v_mul_f32_e32 v48, v48, v88
	v_lshl_add_u64 v[64:65], v[202:203], 0, v[64:65]
	v_cvt_pk_bf16_f32 v48, v48, s0
	global_store_short v[64:65], v48, off
	v_mul_f32_e32 v48, 0x45800000, v66
	v_pk_fma_f32 v[76:77], v[82:83], s[14:15], v[204:205] op_sel_hi:[1,0,0]
	v_or_b32_e32 v72, 33, v200
	v_cndmask_b32_e32 v89, v66, v48, vcc
	v_mul_f32_e32 v78, 0x4b800000, v76
	v_or_b32_e32 v80, 48, v200
	v_cmp_gt_f32_e32 vcc, s27, v76
	v_ashrrev_i32_e32 v73, 31, v72
	v_mul_f32_e32 v48, v49, v89
	v_ashrrev_i32_e32 v81, 31, v80
	v_cndmask_b32_e32 v76, v76, v78, vcc
	v_cvt_pk_bf16_f32 v66, v48, s0
	v_lshlrev_b64 v[48:49], 12, v[72:73]
	v_lshl_add_u64 v[72:73], v[80:81], 2, s[8:9]
	v_rsq_f32_e32 v76, v76
	global_load_dwordx4 v[72:75], v[72:73], off
	v_lshl_add_u64 v[48:49], v[202:203], 0, v[48:49]
	global_store_short v[48:49], v66, off
	v_mul_f32_e32 v82, 0x45800000, v76
	v_cndmask_b32_e32 v90, v76, v82, vcc
	v_mul_f32_e32 v76, 0x4b800000, v77
	v_cmp_gt_f32_e32 vcc, s27, v77
	v_or_b32_e32 v66, 34, v200
	v_ashrrev_i32_e32 v67, 31, v66
	v_cndmask_b32_e32 v76, v77, v76, vcc
	v_rsq_f32_e32 v76, v76
	v_lshlrev_b64 v[66:67], 12, v[66:67]
	v_mul_f32_e32 v50, v50, v90
	v_lshl_add_u64 v[66:67], v[202:203], 0, v[66:67]
	v_cvt_pk_bf16_f32 v50, v50, s0
	global_store_short v[66:67], v50, off
	v_mul_f32_e32 v50, 0x45800000, v76
	v_or_b32_e32 v78, 35, v200
	v_cndmask_b32_e32 v91, v76, v50, vcc
	v_ashrrev_i32_e32 v79, 31, v78
	v_mul_f32_e32 v50, v51, v91
	v_cvt_pk_bf16_f32 v76, v50, s0
	v_lshlrev_b64 v[50:51], 12, v[78:79]
	v_lshl_add_u64 v[50:51], v[202:203], 0, v[50:51]
	global_store_short v[50:51], v76, off
	v_lshlrev_b64 v[76:77], 12, v[86:87]
	s_waitcnt vmcnt(13)
; DI bfr f2bf(float a) { return (bfr)(pack2(a, 0.f) & 0xffffu); }
; DI int crow(int reg, int h) { return (reg & 3) + 8 * (reg >> 2) + 4 * h; }
; template <int lda, class Epi>
; DI void gemm_tile(const bfr* __restrict__ A, const bfr* __restrict__ Bt, int NB, int K, int m0, int n0, char* smem, Epi epi) {
;     ...
; #pragma unroll
;   for (int i = 0; i < 2; ++i)
; #pragma unroll
;     for (int j = 0; j < 4; ++j)
; #pragma unroll
;       for (int q = 0; q < 16; ++q) {
;         int row = m0 + wr * 64 + i * 32 + crow(q, hl);
;         int col = n0 + wc * 128 + j * 32 + r;
;         epi(row, col, acc[i][j][q]);
;       }
; DI void phase_gemm_bf16out(const Params& p, const bfr* A, const bfr* Wt, bfr* C, int N, const float* ss, char* smem) {
;     ...
;     gemm_tile<1024>(A, Wt, N, 1024, mt * 128, nt * 256, smem,
;               [=](int row, int col, float v) {
;                 float inv = rsqrtf(ss[row] * (1.0f / 1024.0f) + EPSF);
;                 C[(size_t)row * N + col] = f2bf(v * inv);
;               });
	v_pk_fma_f32 v[78:79], v[68:69], s[14:15], v[204:205] op_sel_hi:[1,0,0]
	v_or_b32_e32 v84, 56, v200
	v_mul_f32_e32 v68, 0x4b800000, v78
	v_cmp_gt_f32_e32 vcc, s27, v78
	v_ashrrev_i32_e32 v85, 31, v84
	v_pk_fma_f32 v[86:87], v[70:71], s[14:15], v[204:205] op_sel_hi:[1,0,0]
	v_cndmask_b32_e32 v68, v78, v68, vcc
	v_rsq_f32_e32 v78, v68
	v_lshl_add_u64 v[68:69], v[202:203], 0, v[76:77]
	v_or_b32_e32 v76, 41, v200
	v_ashrrev_i32_e32 v77, 31, v76
	v_mul_f32_e32 v82, 0x45800000, v78
	v_cndmask_b32_e32 v92, v78, v82, vcc
	v_mul_f32_e32 v78, 0x4b800000, v79
	v_cmp_gt_f32_e32 vcc, s27, v79
	v_mul_f32_e32 v52, v52, v92
	v_cvt_pk_bf16_f32 v52, v52, s0
	v_cndmask_b32_e32 v78, v79, v78, vcc
	v_rsq_f32_e32 v78, v78
	global_store_short v[68:69], v52, off
	v_mul_f32_e32 v70, 0x4b800000, v86
	v_or_b32_e32 v82, 42, v200
	v_mul_f32_e32 v52, 0x45800000, v78
	v_cndmask_b32_e32 v93, v78, v52, vcc
	v_mul_f32_e32 v52, v53, v93
	v_cvt_pk_bf16_f32 v78, v52, s0
	v_lshlrev_b64 v[52:53], 12, v[76:77]
	v_lshl_add_u64 v[52:53], v[202:203], 0, v[52:53]
	v_lshl_add_u64 v[76:77], v[84:85], 2, s[8:9]
	global_store_short v[52:53], v78, off
	global_load_dwordx4 v[76:79], v[76:77], off
	v_cmp_gt_f32_e32 vcc, s27, v86
	v_ashrrev_i32_e32 v83, 31, v82
	v_cvt_pk_bf16_f32 v96, v96, s0
	v_cndmask_b32_e32 v70, v86, v70, vcc
	v_rsq_f32_e32 v86, v70
	v_lshlrev_b64 v[82:83], 12, v[82:83]
	global_store_short v[112:113], v96, off offset:64
	v_mul_f32_e32 v96, v99, v211
	v_mul_f32_e32 v94, 0x45800000, v86
	v_cndmask_b32_e32 v86, v86, v94, vcc
	v_mul_f32_e32 v94, 0x4b800000, v87
	v_cmp_gt_f32_e32 vcc, s27, v87
	v_mul_f32_e32 v54, v54, v86
	v_lshl_add_u64 v[70:71], v[202:203], 0, v[82:83]
	v_cndmask_b32_e32 v87, v87, v94, vcc
	v_rsq_f32_e32 v87, v87
	v_cvt_pk_bf16_f32 v54, v54, s0
	v_cvt_pk_bf16_f32 v96, v96, s0
	global_store_short v[70:71], v54, off
	v_mul_f32_e32 v54, 0x45800000, v87
	global_store_short v[114:115], v96, off offset:64
	v_mul_f32_e32 v96, v100, v190
	v_or_b32_e32 v82, 43, v200
	v_cndmask_b32_e32 v87, v87, v54, vcc
	v_cvt_pk_bf16_f32 v96, v96, s0
	v_ashrrev_i32_e32 v83, 31, v82
	v_mul_f32_e32 v54, v55, v87
	s_waitcnt vmcnt(9)
	v_pk_fma_f32 v[72:73], v[72:73], s[14:15], v[204:205] op_sel_hi:[1,0,0]
	global_store_short v[176:177], v96, off offset:64
	v_mul_f32_e32 v96, v101, v191
	v_cvt_pk_bf16_f32 v94, v54, s0
	v_lshlrev_b64 v[54:55], 12, v[82:83]
	v_mul_f32_e32 v82, 0x4b800000, v72
	v_cmp_gt_f32_e32 vcc, s27, v72
	v_cvt_pk_bf16_f32 v96, v96, s0
	global_store_short v[116:117], v96, off offset:64
	v_cndmask_b32_e32 v72, v72, v82, vcc
	v_mul_f32_e32 v96, v102, v178
	v_rsq_f32_e32 v72, v72
	v_cvt_pk_bf16_f32 v96, v96, s0
	global_store_short v[172:173], v96, off offset:64
	v_mul_f32_e32 v96, v103, v168
	v_cvt_pk_bf16_f32 v96, v96, s0
	v_lshl_add_u64 v[54:55], v[202:203], 0, v[54:55]
	global_store_short v[160:161], v96, off offset:64
	v_mul_f32_e32 v96, v104, v154
	global_store_short v[54:55], v94, off
	v_mul_f32_e32 v94, 0x45800000, v72
	v_cvt_pk_bf16_f32 v96, v96, s0
	v_cndmask_b32_e32 v94, v72, v94, vcc
	v_mul_f32_e32 v72, 0x4b800000, v73
	v_cmp_gt_f32_e32 vcc, s27, v73
	global_store_short v[118:119], v96, off offset:64
	v_mul_f32_e32 v96, v105, v155
	v_cndmask_b32_e32 v72, v73, v72, vcc
	v_cvt_pk_bf16_f32 v96, v96, s0
	v_rsq_f32_e32 v72, v72
	global_store_short v[120:121], v96, off offset:64
	v_mul_f32_e32 v96, v106, v142
	v_cvt_pk_bf16_f32 v96, v96, s0
	v_lshlrev_b64 v[80:81], 12, v[80:81]
	v_mul_f32_e32 v56, v56, v94
	global_store_short v[136:137], v96, off offset:64
	v_mul_f32_e32 v96, v107, v143
	v_lshl_add_u64 v[80:81], v[202:203], 0, v[80:81]
	v_cvt_pk_bf16_f32 v56, v56, s0
	v_cvt_pk_bf16_f32 v96, v96, s0
	global_store_short v[80:81], v56, off
	v_mul_f32_e32 v56, 0x45800000, v72
	global_store_short v[122:123], v96, off offset:64
	v_mul_f32_e32 v96, v108, v138
	v_or_b32_e32 v82, 49, v200
	v_cndmask_b32_e32 v95, v72, v56, vcc
	v_cvt_pk_bf16_f32 v96, v96, s0
	v_ashrrev_i32_e32 v83, 31, v82
	v_mul_f32_e32 v56, v57, v95
	v_pk_fma_f32 v[74:75], v[74:75], s[14:15], v[204:205] op_sel_hi:[1,0,0]
	global_store_short v[128:129], v96, off offset:64
	v_mul_f32_e32 v96, v109, v139
	v_cvt_pk_bf16_f32 v72, v56, s0
	v_lshlrev_b64 v[56:57], 12, v[82:83]
	v_mul_f32_e32 v82, 0x4b800000, v74
	v_cmp_gt_f32_e32 vcc, s27, v74
	v_cvt_pk_bf16_f32 v96, v96, s0
	global_store_short v[124:125], v96, off offset:64
	v_cndmask_b32_e32 v74, v74, v82, vcc
	v_mul_f32_e32 v96, v110, v132
	v_rsq_f32_e32 v74, v74
	v_cvt_pk_bf16_f32 v96, v96, s0
	global_store_short v[130:131], v96, off offset:64
	v_mul_f32_e32 v96, v111, v133
	v_cvt_pk_bf16_f32 v96, v96, s0
	global_store_short v[126:127], v96, off offset:64
	v_mul_f32_e32 v96, 0x45800000, v74
	v_cndmask_b32_e32 v96, v74, v96, vcc
	v_mul_f32_e32 v74, 0x4b800000, v75
	v_cmp_gt_f32_e32 vcc, s27, v75
	v_lshl_add_u64 v[56:57], v[202:203], 0, v[56:57]
	global_store_short v[56:57], v72, off
	v_cndmask_b32_e32 v74, v75, v74, vcc
	v_or_b32_e32 v72, 50, v200
	v_rsq_f32_e32 v74, v74
	v_ashrrev_i32_e32 v73, 31, v72
	v_lshlrev_b64 v[72:73], 12, v[72:73]
	v_mul_f32_e32 v58, v58, v96
	v_lshl_add_u64 v[72:73], v[202:203], 0, v[72:73]
	v_cvt_pk_bf16_f32 v58, v58, s0
	global_store_short v[72:73], v58, off
	v_mul_f32_e32 v58, 0x45800000, v74
	v_or_b32_e32 v82, 51, v200
	v_cndmask_b32_e32 v97, v74, v58, vcc
	v_ashrrev_i32_e32 v83, 31, v82
	v_mul_f32_e32 v58, v59, v97
	s_waitcnt vmcnt(19)
; DI bfr f2bf(float a) { return (bfr)(pack2(a, 0.f) & 0xffffu); }
; DI int crow(int reg, int h) { return (reg & 3) + 8 * (reg >> 2) + 4 * h; }
; template <int lda, class Epi>
; DI void gemm_tile(const bfr* __restrict__ A, const bfr* __restrict__ Bt, int NB, int K, int m0, int n0, char* smem, Epi epi) {
;     ...
; #pragma unroll
;   for (int i = 0; i < 2; ++i)
; #pragma unroll
;     for (int j = 0; j < 4; ++j)
; #pragma unroll
;       for (int q = 0; q < 16; ++q) {
;         int row = m0 + wr * 64 + i * 32 + crow(q, hl);
;         int col = n0 + wc * 128 + j * 32 + r;
;         epi(row, col, acc[i][j][q]);
;       }
; DI void phase_gemm_bf16out(const Params& p, const bfr* A, const bfr* Wt, bfr* C, int N, const float* ss, char* smem) {
;     ...
;     gemm_tile<1024>(A, Wt, N, 1024, mt * 128, nt * 256, smem,
;               [=](int row, int col, float v) {
;                 float inv = rsqrtf(ss[row] * (1.0f / 1024.0f) + EPSF);
;                 C[(size_t)row * N + col] = f2bf(v * inv);
;               });
	v_pk_fma_f32 v[76:77], v[76:77], s[14:15], v[204:205] op_sel_hi:[1,0,0]
	v_cvt_pk_bf16_f32 v74, v58, s0
	v_lshlrev_b64 v[58:59], 12, v[82:83]
	v_mul_f32_e32 v82, 0x4b800000, v76
	v_cmp_gt_f32_e32 vcc, s27, v76
	v_mul_f32_e32 v32, v32, v88
	v_mul_f32_e32 v16, v16, v88
	v_cndmask_b32_e32 v76, v76, v82, vcc
	v_rsq_f32_e32 v76, v76
	v_mul_f32_e32 v0, v0, v88
	v_cvt_pk_bf16_f32 v32, v32, s0
	v_cvt_pk_bf16_f32 v16, v16, s0
	v_cvt_pk_bf16_f32 v0, v0, s0
	global_store_short v[64:65], v32, off offset:64
	v_mul_f32_e32 v32, v33, v89
	global_store_short v[64:65], v16, off offset:128
	v_mul_f32_e32 v16, v17, v89
	global_store_short v[64:65], v0, off offset:192
	v_mul_f32_e32 v0, v1, v89
	v_lshl_add_u64 v[58:59], v[202:203], 0, v[58:59]
	v_cvt_pk_bf16_f32 v32, v32, s0
	v_cvt_pk_bf16_f32 v16, v16, s0
	v_cvt_pk_bf16_f32 v0, v0, s0
	global_store_short v[58:59], v74, off
	v_lshlrev_b64 v[74:75], 12, v[84:85]
	v_mul_f32_e32 v84, 0x45800000, v76
	global_store_short v[48:49], v32, off offset:64
	v_mul_f32_e32 v32, v34, v90
	global_store_short v[48:49], v16, off offset:128
	v_mul_f32_e32 v16, v18, v90
	global_store_short v[48:49], v0, off offset:192
	v_mul_f32_e32 v0, v2, v90
	v_cndmask_b32_e32 v84, v76, v84, vcc
	v_mul_f32_e32 v76, 0x4b800000, v77
	v_cmp_gt_f32_e32 vcc, s27, v77
	v_cvt_pk_bf16_f32 v32, v32, s0
	v_cvt_pk_bf16_f32 v16, v16, s0
	v_cvt_pk_bf16_f32 v0, v0, s0
	v_cndmask_b32_e32 v76, v77, v76, vcc
	global_store_short v[66:67], v32, off offset:64
	v_mul_f32_e32 v32, v35, v91
	global_store_short v[66:67], v16, off offset:128
	v_mul_f32_e32 v16, v19, v91
	global_store_short v[66:67], v0, off offset:192
	v_mul_f32_e32 v0, v3, v91
	v_rsq_f32_e32 v76, v76
	v_cvt_pk_bf16_f32 v32, v32, s0
	v_cvt_pk_bf16_f32 v16, v16, s0
	v_cvt_pk_bf16_f32 v0, v0, s0
	global_store_short v[50:51], v32, off offset:64
	v_mul_f32_e32 v32, v36, v92
	global_store_short v[50:51], v16, off offset:128
	v_mul_f32_e32 v16, v20, v92
	global_store_short v[50:51], v0, off offset:192
	v_mul_f32_e32 v0, v4, v92
	v_mul_f32_e32 v60, v60, v84
	v_cvt_pk_bf16_f32 v32, v32, s0
	v_cvt_pk_bf16_f32 v16, v16, s0
	v_cvt_pk_bf16_f32 v0, v0, s0
	v_lshl_add_u64 v[74:75], v[202:203], 0, v[74:75]
	v_cvt_pk_bf16_f32 v60, v60, s0
	global_store_short v[68:69], v32, off offset:64
	v_mul_f32_e32 v32, v37, v93
	global_store_short v[68:69], v16, off offset:128
	v_mul_f32_e32 v16, v21, v93
	global_store_short v[68:69], v0, off offset:192
	v_mul_f32_e32 v0, v5, v93
	global_store_short v[74:75], v60, off
	v_mul_f32_e32 v60, 0x45800000, v76
	v_cvt_pk_bf16_f32 v32, v32, s0
	v_cvt_pk_bf16_f32 v16, v16, s0
	v_cvt_pk_bf16_f32 v0, v0, s0
	v_or_b32_e32 v82, 57, v200
	v_cndmask_b32_e32 v85, v76, v60, vcc
	global_store_short v[52:53], v32, off offset:64
	v_mul_f32_e32 v32, v38, v86
	global_store_short v[52:53], v16, off offset:128
	v_mul_f32_e32 v16, v22, v86
	global_store_short v[52:53], v0, off offset:192
	v_mul_f32_e32 v0, v6, v86
	v_ashrrev_i32_e32 v83, 31, v82
	v_mul_f32_e32 v60, v61, v85
	v_pk_fma_f32 v[78:79], v[78:79], s[14:15], v[204:205] op_sel_hi:[1,0,0]
	v_cvt_pk_bf16_f32 v32, v32, s0
	v_cvt_pk_bf16_f32 v16, v16, s0
	v_cvt_pk_bf16_f32 v0, v0, s0
	v_cvt_pk_bf16_f32 v76, v60, s0
	v_lshlrev_b64 v[60:61], 12, v[82:83]
	v_mul_f32_e32 v82, 0x4b800000, v78
	v_cmp_gt_f32_e32 vcc, s27, v78
	global_store_short v[70:71], v32, off offset:64
	v_mul_f32_e32 v32, v39, v87
	global_store_short v[70:71], v16, off offset:128
	v_mul_f32_e32 v16, v23, v87
	global_store_short v[70:71], v0, off offset:192
	v_mul_f32_e32 v0, v7, v87
	v_cndmask_b32_e32 v78, v78, v82, vcc
	v_cvt_pk_bf16_f32 v32, v32, s0
	v_cvt_pk_bf16_f32 v16, v16, s0
	v_cvt_pk_bf16_f32 v0, v0, s0
	v_rsq_f32_e32 v78, v78
	global_store_short v[54:55], v32, off offset:64
; DI bfr f2bf(float a) { return (bfr)(pack2(a, 0.f) & 0xffffu); }
; DI int crow(int reg, int h) { return (reg & 3) + 8 * (reg >> 2) + 4 * h; }
; template <int lda, class Epi>
; DI void gemm_tile(const bfr* __restrict__ A, const bfr* __restrict__ Bt, int NB, int K, int m0, int n0, char* smem, Epi epi) {
;     ...
; #pragma unroll
;   for (int i = 0; i < 2; ++i)
; #pragma unroll
;     for (int j = 0; j < 4; ++j)
; #pragma unroll
;       for (int q = 0; q < 16; ++q) {
;         int row = m0 + wr * 64 + i * 32 + crow(q, hl);
;         int col = n0 + wc * 128 + j * 32 + r;
;         epi(row, col, acc[i][j][q]);
;       }
; DI void phase_gemm_bf16out(const Params& p, const bfr* A, const bfr* Wt, bfr* C, int N, const float* ss, char* smem) {
;     ...
;     gemm_tile<1024>(A, Wt, N, 1024, mt * 128, nt * 256, smem,
;               [=](int row, int col, float v) {
;                 float inv = rsqrtf(ss[row] * (1.0f / 1024.0f) + EPSF);
;                 C[(size_t)row * N + col] = f2bf(v * inv);
;               });
	v_mul_f32_e32 v32, v40, v94
	global_store_short v[54:55], v16, off offset:128
	v_mul_f32_e32 v16, v24, v94
	global_store_short v[54:55], v0, off offset:192
	v_mul_f32_e32 v0, v8, v94
	v_cvt_pk_bf16_f32 v32, v32, s0
	v_cvt_pk_bf16_f32 v16, v16, s0
	v_cvt_pk_bf16_f32 v0, v0, s0
	global_store_short v[80:81], v32, off offset:64
	v_mul_f32_e32 v32, v41, v95
	global_store_short v[80:81], v16, off offset:128
	v_mul_f32_e32 v16, v25, v95
	global_store_short v[80:81], v0, off offset:192
	v_mul_f32_e32 v0, v9, v95
	v_cvt_pk_bf16_f32 v32, v32, s0
	v_cvt_pk_bf16_f32 v16, v16, s0
	v_cvt_pk_bf16_f32 v0, v0, s0
	v_mul_f32_e32 v98, 0x45800000, v78
	global_store_short v[56:57], v32, off offset:64
	v_mul_f32_e32 v32, v42, v96
	global_store_short v[56:57], v16, off offset:128
	v_mul_f32_e32 v16, v26, v96
	global_store_short v[56:57], v0, off offset:192
	v_mul_f32_e32 v0, v10, v96
	v_cndmask_b32_e32 v78, v78, v98, vcc
	v_mul_f32_e32 v98, 0x4b800000, v79
	v_cmp_gt_f32_e32 vcc, s27, v79
	v_cvt_pk_bf16_f32 v32, v32, s0
	v_cvt_pk_bf16_f32 v16, v16, s0
	v_cvt_pk_bf16_f32 v0, v0, s0
	v_lshl_add_u64 v[60:61], v[202:203], 0, v[60:61]
	v_cndmask_b32_e32 v79, v79, v98, vcc
	global_store_short v[72:73], v32, off offset:64
	v_mul_f32_e32 v32, v43, v97
	global_store_short v[72:73], v16, off offset:128
	v_mul_f32_e32 v16, v27, v97
	global_store_short v[72:73], v0, off offset:192
	v_mul_f32_e32 v0, v11, v97
	global_store_short v[60:61], v76, off
	v_or_b32_e32 v76, 58, v200
	v_rsq_f32_e32 v79, v79
	v_cvt_pk_bf16_f32 v32, v32, s0
	v_cvt_pk_bf16_f32 v16, v16, s0
	v_cvt_pk_bf16_f32 v0, v0, s0
	v_ashrrev_i32_e32 v77, 31, v76
	global_store_short v[58:59], v32, off offset:64
	v_mul_f32_e32 v32, v44, v84
	global_store_short v[58:59], v16, off offset:128
	v_mul_f32_e32 v16, v28, v84
	global_store_short v[58:59], v0, off offset:192
	v_mul_f32_e32 v0, v12, v84
	v_lshlrev_b64 v[76:77], 12, v[76:77]
	v_mul_f32_e32 v62, v62, v78
	v_cvt_pk_bf16_f32 v32, v32, s0
	v_cvt_pk_bf16_f32 v16, v16, s0
	v_cvt_pk_bf16_f32 v0, v0, s0
	v_lshl_add_u64 v[76:77], v[202:203], 0, v[76:77]
	v_cvt_pk_bf16_f32 v62, v62, s0
	global_store_short v[74:75], v32, off offset:64
	v_mul_f32_e32 v32, v45, v85
	global_store_short v[74:75], v16, off offset:128
	v_mul_f32_e32 v16, v29, v85
	global_store_short v[74:75], v0, off offset:192
	v_mul_f32_e32 v0, v13, v85
	global_store_short v[76:77], v62, off
	v_mul_f32_e32 v62, 0x45800000, v79
	v_cvt_pk_bf16_f32 v32, v32, s0
	v_cvt_pk_bf16_f32 v16, v16, s0
	v_cvt_pk_bf16_f32 v0, v0, s0
	v_or_b32_e32 v82, 59, v200
	v_cndmask_b32_e32 v79, v79, v62, vcc
	global_store_short v[60:61], v32, off offset:64
	v_mul_f32_e32 v32, v46, v78
	global_store_short v[60:61], v16, off offset:128
	v_mul_f32_e32 v16, v30, v78
	global_store_short v[60:61], v0, off offset:192
	v_mul_f32_e32 v0, v14, v78
	v_ashrrev_i32_e32 v83, 31, v82
	v_mul_f32_e32 v62, v63, v79
	v_cvt_pk_bf16_f32 v32, v32, s0
	v_cvt_pk_bf16_f32 v16, v16, s0
	v_cvt_pk_bf16_f32 v0, v0, s0
	v_cvt_pk_bf16_f32 v98, v62, s0
	v_lshlrev_b64 v[62:63], 12, v[82:83]
	global_store_short v[76:77], v32, off offset:64
	v_mul_f32_e32 v32, v47, v79
	global_store_short v[76:77], v16, off offset:128
	v_mul_f32_e32 v16, v31, v79
	global_store_short v[76:77], v0, off offset:192
	v_mul_f32_e32 v0, v15, v79
	v_lshl_add_u64 v[62:63], v[202:203], 0, v[62:63]
	v_cvt_pk_bf16_f32 v32, v32, s0
	v_cvt_pk_bf16_f32 v16, v16, s0
	v_cvt_pk_bf16_f32 v0, v0, s0
	global_store_short v[120:121], v156, off
	global_store_short v[126:127], v140, off
	global_store_short v[62:63], v98, off
	global_store_short v[62:63], v32, off offset:64
	global_store_short v[62:63], v16, off offset:128
	global_store_short v[62:63], v0, off offset:192
	s_cbranch_scc0 .LBB0_1192

; #define GA_LOAD(pr_) do { _Pragma("unroll") for (int i = 0; i < 4; ++i) ra[i] = *(const u32x4*)(Ab + (i * 32) * lda + (pr_) * 64); } while (0)
; #define GB_LOAD(kt_) do { const bfr* bk_ = Bb + (kt_) * NB * 32; \
;     _Pragma("unroll") for (int i = 0; i < 4; ++i) rb[i] = *(const u32x4*)(bk_ + (i * 64) * 32); } while (0)
; #define G_STORE(kt_) do { bfr* as_ = S0 + ((kt_) & 1) * GSTAGE; bfr* bs_ = as_ + 128 * 40; \
;     if (apar == ((kt_) & 1)) { _Pragma("unroll") for (int i = 0; i < 4; ++i) *(u32x4*)(as_ + asoff + i * 32 * 40) = ra[i]; } \
;     _Pragma("unroll") for (int i = 0; i < 4; ++i) *(u32x4*)(bs_ + bsoff + i * 64 * 40) = rb[i]; } while (0)
; template <int lda>
; DI void gemm_mainloop(const bfr* __restrict__ A, const bfr* __restrict__ Bt, int NB, int K, int m0, int n0, char* smem, f32x16 (&acc)[2][4]) {
;   bfr* S0 = (bfr*)smem;
;   int tid = threadIdx.x;
;   asm volatile("" : "+v"(tid));
;   const int lane = tid & 63, wid = tid >> 6, wr = wid >> 1, wc = wid & 1;
;   const int r = lane & 31, hl = lane >> 5;
; #pragma unroll
;   for (int i = 0; i < 2; ++i)
; #pragma unroll
;     for (int j = 0; j < 4; ++j)
; #pragma unroll
;       for (int q = 0; q < 16; ++q) acc[i][j][q] = 0.f;
;   u32x4 ra[4], rb[4];
;   const int nk = K >> 5;
;   const int arow = tid >> 3, ac8 = tid & 7, apar = ac8 >> 2;
;   const bfr* Ab = A + (m0 + arow) * lda + ac8 * 8;
;   const int asoff = arow * 40 + (ac8 & 3) * 8;
;   const int brow = tid >> 2, bc4 = tid & 3;
;   const bfr* Bb = Bt + (n0 + brow) * 32 + bc4 * 8;
;   const int bsoff = brow * 40 + bc4 * 8;
;     ...
;   GA_LOAD(0);
;   GB_LOAD(0);
;   G_STORE(0);
;   GB_LOAD(1);
;   __syncthreads();
; DI void phase_gemm_bf16out(const Params& p, const bfr* A, const bfr* Wt, bfr* C, int N, const float* ss, char* smem) {
;     ...
;   for (int t0 = blockIdx.x; t0 < 128 * ntn; t0 += gridDim.x) {
;     const int t = ((gridDim.x & 7) == 0) ? xcd_tile(t0, ntn) : t0;
;     int mt = t / ntn, nt = t % ntn;
;     gemm_tile<1024>(A, Wt, N, 1024, mt * 128, nt * 256, smem,
.LBB0_1181:
	s_ashr_i32 s5, s4, 31
	s_lshr_b32 s5, s5, 29
	s_add_i32 s5, s4, s5
	s_and_b32 s18, s5, 0xfffff8
	s_lshl_b32 s5, s5, 4
	s_and_b32 s30, s5, 0xffffff80
	s_sub_i32 s4, s4, s18
	s_lshl_b32 s29, s4, 8
	s_mov_b32 s31, 0
	s_mov_b64 s[18:19], 0
	s_lshl_b32 s98, s30, 11
	s_add_u32 s98, s10, s98
	s_addc_u32 s99, s11, 0
	s_lshl_b32 s100, s29, 6
	s_add_u32 s100, s12, s100
	s_addc_u32 s101, s13, 0
	v_writelane_b32 v187, s64, 0
	v_writelane_b32 v187, s65, 1
	v_writelane_b32 v187, s66, 2
	v_writelane_b32 v187, s67, 3
	v_writelane_b32 v187, s68, 4
	v_writelane_b32 v187, s69, 5
	v_writelane_b32 v187, s70, 6
	v_writelane_b32 v187, s71, 7
	v_writelane_b32 v187, s72, 8
	v_writelane_b32 v187, s73, 9
	v_writelane_b32 v187, s74, 10
	v_writelane_b32 v187, s75, 11
	v_writelane_b32 v187, s76, 12
	v_writelane_b32 v187, s77, 13
	v_writelane_b32 v187, s78, 14
	v_writelane_b32 v187, s79, 15
	v_lshrrev_b32_e32 v188, 6, v196
	v_and_b32_e32 v189, 63, v196
	v_readfirstlane_b32 s73, v188
	v_lshrrev_b32_e32 v190, 2, v189
	v_bfe_u32 v191, v189, 4, 2
	v_and_b32_e32 v188, 3, v189
	v_xor_b32_e32 v188, v188, v191
	v_lshlrev_b32_e32 v188, 4, v188
	v_lshl_add_u32 v176, v190, 11, v188
	v_add_u32_e32 v177, 0x8000, v176
	v_lshl_add_u32 v178, v190, 6, v188
	v_and_b32_e32 v190, 31, v189
	v_lshrrev_b32_e32 v191, 5, v189
	v_bfe_u32 v188, v189, 2, 2
	v_xor_b32_e32 v188, v188, v191
	v_lshlrev_b32_e32 v188, 4, v188
	v_lshl_add_u32 v179, v190, 6, v188
	s_lshr_b32 s74, s73, 1
	s_lshl_b32 s74, s74, 12
	s_and_b32 s75, s73, 1
	s_lshl_b32 s75, s75, 13
	v_add_u32_e32 v181, s75, v179
	v_add_u32_e32 v179, s74, v179
	v_xor_b32_e32 v182, 32, v181
	v_xor_b32_e32 v180, 32, v179
	s_lshl_b32 s74, s73, 16
	s_add_u32 s64, s98, s74
	s_addc_u32 s65, s99, 0
	s_lshl_b32 s74, s73, 12
	s_add_u32 s66, s100, s74
	s_addc_u32 s67, s101, 0
	s_lshl_b32 s68, s73, 11
	s_lshl_b32 s69, s73, 12
	s_mov_b32 s70, 0
	s_mov_b32 s71, 0
	s_mov_b32 s72, 0
	s_waitcnt lgkmcnt(0)
	s_barrier
	s_mul_i32 s74, s70, 0x6000
	s_add_u32 s75, s74, s68
	s_mov_b32 m0, s75
	s_add_u32 s76, s74, 0x2000
	s_cmp_eq_u32 s70, 2
	s_cselect_b32 s76, 0x10000, s76
	global_load_lds_dwordx4 v176, s[64:65]
	s_add_u32 m0, s75, 0x400
	s_add_u32 s76, s76, s69
	global_load_lds_dwordx4 v177, s[64:65]
	s_mov_b32 m0, s76
	s_add_u32 s64, s64, 64
	s_addc_u32 s65, s65, 0
	global_load_lds_dwordx4 v178, s[66:67]
	global_load_lds_dwordx4 v178, s[66:67] offset:1024
	global_load_lds_dwordx4 v178, s[66:67] offset:2048
	global_load_lds_dwordx4 v178, s[66:67] offset:3072
	s_add_u32 s66, s66, 0x20000
	s_addc_u32 s67, s67, 0
	s_add_u32 s70, s70, 1
	s_cmp_eq_u32 s70, 3
	s_cselect_b32 s70, 0, s70
	s_mul_i32 s74, s70, 0x6000
	s_add_u32 s75, s74, s68
	s_mov_b32 m0, s75
	s_add_u32 s76, s74, 0x2000
	s_cmp_eq_u32 s70, 2
	s_cselect_b32 s76, 0x10000, s76
	global_load_lds_dwordx4 v176, s[64:65]
	s_add_u32 m0, s75, 0x400
	s_add_u32 s76, s76, s69
	global_load_lds_dwordx4 v177, s[64:65]
	s_mov_b32 m0, s76
	s_add_u32 s64, s64, 64
	s_addc_u32 s65, s65, 0
	global_load_lds_dwordx4 v178, s[66:67]
	global_load_lds_dwordx4 v178, s[66:67] offset:1024
	global_load_lds_dwordx4 v178, s[66:67] offset:2048
	global_load_lds_dwordx4 v178, s[66:67] offset:3072
	s_add_u32 s66, s66, 0x20000
	s_addc_u32 s67, s67, 0
	s_add_u32 s70, s70, 1
	s_cmp_eq_u32 s70, 3
	s_cselect_b32 s70, 0, s70
	v_mov_b32_e32 v112, 0
	v_mov_b32_e32 v113, 0
	v_mov_b32_e32 v114, 0
	v_mov_b32_e32 v115, 0
	v_mov_b32_e32 v116, 0
	v_mov_b32_e32 v117, 0
	v_mov_b32_e32 v118, 0
	v_mov_b32_e32 v119, 0
	v_mov_b32_e32 v120, 0
	v_mov_b32_e32 v121, 0
	v_mov_b32_e32 v122, 0
	v_mov_b32_e32 v123, 0
	v_mov_b32_e32 v124, 0
	v_mov_b32_e32 v125, 0
	v_mov_b32_e32 v126, 0
	v_mov_b32_e32 v127, 0
	v_mov_b32_e32 v96, 0
	v_mov_b32_e32 v97, 0
	v_mov_b32_e32 v98, 0
	v_mov_b32_e32 v99, 0
	v_mov_b32_e32 v100, 0
	v_mov_b32_e32 v101, 0
	v_mov_b32_e32 v102, 0
	v_mov_b32_e32 v103, 0
	v_mov_b32_e32 v104, 0
	v_mov_b32_e32 v105, 0
	v_mov_b32_e32 v106, 0
	v_mov_b32_e32 v107, 0
	v_mov_b32_e32 v108, 0
	v_mov_b32_e32 v109, 0
	v_mov_b32_e32 v110, 0
	v_mov_b32_e32 v111, 0
	v_mov_b32_e32 v80, 0
	v_mov_b32_e32 v81, 0
	v_mov_b32_e32 v82, 0
	v_mov_b32_e32 v83, 0
	v_mov_b32_e32 v84, 0
	v_mov_b32_e32 v85, 0
	v_mov_b32_e32 v86, 0
	v_mov_b32_e32 v87, 0
	v_mov_b32_e32 v88, 0
	v_mov_b32_e32 v89, 0
	v_mov_b32_e32 v90, 0
	v_mov_b32_e32 v91, 0
	v_mov_b32_e32 v92, 0
	v_mov_b32_e32 v93, 0
	v_mov_b32_e32 v94, 0
	v_mov_b32_e32 v95, 0
	v_mov_b32_e32 v64, 0
	v_mov_b32_e32 v65, 0
	v_mov_b32_e32 v66, 0
	v_mov_b32_e32 v67, 0
	v_mov_b32_e32 v68, 0
	v_mov_b32_e32 v69, 0
	v_mov_b32_e32 v70, 0
	v_mov_b32_e32 v71, 0
	v_mov_b32_e32 v72, 0
	v_mov_b32_e32 v73, 0
	v_mov_b32_e32 v74, 0
	v_mov_b32_e32 v75, 0
	v_mov_b32_e32 v76, 0
	v_mov_b32_e32 v77, 0
	v_mov_b32_e32 v78, 0
	v_mov_b32_e32 v79, 0
	v_mov_b32_e32 v48, 0
	v_mov_b32_e32 v49, 0
	v_mov_b32_e32 v50, 0
	v_mov_b32_e32 v51, 0
	v_mov_b32_e32 v52, 0
	v_mov_b32_e32 v53, 0
	v_mov_b32_e32 v54, 0
	v_mov_b32_e32 v55, 0
	v_mov_b32_e32 v56, 0
	v_mov_b32_e32 v57, 0
	v_mov_b32_e32 v58, 0
	v_mov_b32_e32 v59, 0
	v_mov_b32_e32 v60, 0
	v_mov_b32_e32 v61, 0
	v_mov_b32_e32 v62, 0
	v_mov_b32_e32 v63, 0
	v_mov_b32_e32 v32, 0
	v_mov_b32_e32 v33, 0
	v_mov_b32_e32 v34, 0
	v_mov_b32_e32 v35, 0
	v_mov_b32_e32 v36, 0
	v_mov_b32_e32 v37, 0
	v_mov_b32_e32 v38, 0
	v_mov_b32_e32 v39, 0
	v_mov_b32_e32 v40, 0
	v_mov_b32_e32 v41, 0
	v_mov_b32_e32 v42, 0
	v_mov_b32_e32 v43, 0
	v_mov_b32_e32 v44, 0
	v_mov_b32_e32 v45, 0
	v_mov_b32_e32 v46, 0
	v_mov_b32_e32 v47, 0
	v_mov_b32_e32 v16, 0
	v_mov_b32_e32 v17, 0
	v_mov_b32_e32 v18, 0
	v_mov_b32_e32 v19, 0
	v_mov_b32_e32 v20, 0
	v_mov_b32_e32 v21, 0
	v_mov_b32_e32 v22, 0
	v_mov_b32_e32 v23, 0
	v_mov_b32_e32 v24, 0
	v_mov_b32_e32 v25, 0
	v_mov_b32_e32 v26, 0
	v_mov_b32_e32 v27, 0
	v_mov_b32_e32 v28, 0
	v_mov_b32_e32 v29, 0
	v_mov_b32_e32 v30, 0
	v_mov_b32_e32 v31, 0
	v_mov_b32_e32 v0, 0
	v_mov_b32_e32 v1, 0
	v_mov_b32_e32 v2, 0
	v_mov_b32_e32 v3, 0
	v_mov_b32_e32 v4, 0
	v_mov_b32_e32 v5, 0
	v_mov_b32_e32 v6, 0
	v_mov_b32_e32 v7, 0
	v_mov_b32_e32 v8, 0
	v_mov_b32_e32 v9, 0
	v_mov_b32_e32 v10, 0
	v_mov_b32_e32 v11, 0
	v_mov_b32_e32 v12, 0
	v_mov_b32_e32 v13, 0
	v_mov_b32_e32 v14, 0
	v_mov_b32_e32 v15, 0
; #define MFMA32(a, b, c) __builtin_amdgcn_mfma_f32_32x32x16_bf16((a), (b), (c), 0, 0, 0)
; #define GA_LOAD(pr_) do { _Pragma("unroll") for (int i = 0; i < 4; ++i) ra[i] = *(const u32x4*)(Ab + (i * 32) * lda + (pr_) * 64); } while (0)
; #define GB_LOAD(kt_) do { const bfr* bk_ = Bb + (kt_) * NB * 32; \
;     _Pragma("unroll") for (int i = 0; i < 4; ++i) rb[i] = *(const u32x4*)(bk_ + (i * 64) * 32); } while (0)
; #define G_STORE(kt_) do { bfr* as_ = S0 + ((kt_) & 1) * GSTAGE; bfr* bs_ = as_ + 128 * 40; \
;     if (apar == ((kt_) & 1)) { _Pragma("unroll") for (int i = 0; i < 4; ++i) *(u32x4*)(as_ + asoff + i * 32 * 40) = ra[i]; } \
;     _Pragma("unroll") for (int i = 0; i < 4; ++i) *(u32x4*)(bs_ + bsoff + i * 64 * 40) = rb[i]; } while (0)
; template <int lda>
; DI void gemm_mainloop(const bfr* __restrict__ A, const bfr* __restrict__ Bt, int NB, int K, int m0, int n0, char* smem, f32x16 (&acc)[2][4]) {
;     ...
;   for (int kt = 0; kt < nk; ++kt) {
;     if (kt + 1 < nk) G_STORE(kt + 1);
;     if (kt + 2 < nk) {
;       GB_LOAD(kt + 2);
;       if ((kt & 1) == 0) GA_LOAD((kt >> 1) + 1);
;     }
;     const bfr* As = S0 + (kt & 1) * GSTAGE;
;     const bfr* Bs = As + 128 * 40;
; #pragma unroll
;     for (int ks = 0; ks < 2; ++ks) {
;       bf16x8 af[2], bfg[4];
; #pragma unroll
;       for (int i = 0; i < 2; ++i) af[i] = *(const bf16x8*)(As + (wr * 64 + i * 32 + r) * 40 + ks * 16 + hl * 8);
; #pragma unroll
;       for (int j = 0; j < 4; ++j) bfg[j] = *(const bf16x8*)(Bs + (wc * 128 + j * 32 + r) * 40 + ks * 16 + hl * 8);
; #pragma unroll
;       for (int i = 0; i < 2; ++i)
; #pragma unroll
;         for (int j = 0; j < 4; ++j) acc[i][j] = MFMA32(af[i], bfg[j], acc[i][j]);
;     }
;     __syncthreads();
.Lp12_loop:
	s_waitcnt vmcnt(6)
	s_barrier
	s_mul_i32 s74, s70, 0x6000
	s_add_u32 s75, s74, s68
	s_mov_b32 m0, s75
	s_add_u32 s76, s74, 0x2000
	s_cmp_eq_u32 s70, 2
	s_cselect_b32 s76, 0x10000, s76
	global_load_lds_dwordx4 v176, s[64:65]
	s_add_u32 m0, s75, 0x400
	s_add_u32 s76, s76, s69
	global_load_lds_dwordx4 v177, s[64:65]
	s_mov_b32 m0, s76
	s_add_u32 s64, s64, 64
	s_addc_u32 s65, s65, 0
	global_load_lds_dwordx4 v178, s[66:67]
	global_load_lds_dwordx4 v178, s[66:67] offset:1024
	global_load_lds_dwordx4 v178, s[66:67] offset:2048
	global_load_lds_dwordx4 v178, s[66:67] offset:3072
	s_add_u32 s66, s66, 0x20000
	s_addc_u32 s67, s67, 0
	s_add_u32 s70, s70, 1
	s_cmp_eq_u32 s70, 3
	s_cselect_b32 s70, 0, s70
	s_mul_i32 s74, s71, 0x6000
	s_add_u32 s75, s74, 0x2000
	s_cmp_eq_u32 s71, 2
	s_cselect_b32 s75, 0x10000, s75
	v_add_u32_e32 v183, s74, v179
	v_add_u32_e32 v185, s75, v181
	v_add_u32_e32 v184, s74, v180
	v_add_u32_e32 v186, s75, v182
	ds_read_b128 v[128:131], v183
	ds_read_b128 v[144:147], v185
	ds_read_b128 v[148:151], v185 offset:2048
	ds_read_b128 v[152:155], v185 offset:4096
	ds_read_b128 v[156:159], v185 offset:6144
	ds_read_b128 v[132:135], v183 offset:2048
	ds_read_b128 v[136:139], v184
	ds_read_b128 v[160:163], v186
	ds_read_b128 v[164:167], v186 offset:2048
	ds_read_b128 v[168:171], v186 offset:4096
	ds_read_b128 v[172:175], v186 offset:6144
	ds_read_b128 v[140:143], v184 offset:2048
	s_add_u32 s71, s71, 1
	s_cmp_eq_u32 s71, 3
	s_cselect_b32 s71, 0, s71
	s_waitcnt lgkmcnt(10)
	v_mfma_f32_32x32x16_bf16 v[112:127], v[128:131], v[144:147], v[112:127]
	s_waitcnt lgkmcnt(9)
	v_mfma_f32_32x32x16_bf16 v[96:111], v[128:131], v[148:151], v[96:111]
	s_waitcnt lgkmcnt(8)
	v_mfma_f32_32x32x16_bf16 v[80:95], v[128:131], v[152:155], v[80:95]
	s_waitcnt lgkmcnt(7)
	v_mfma_f32_32x32x16_bf16 v[64:79], v[128:131], v[156:159], v[64:79]
	s_waitcnt lgkmcnt(6)
	v_mfma_f32_32x32x16_bf16 v[48:63], v[132:135], v[144:147], v[48:63]
	v_mfma_f32_32x32x16_bf16 v[32:47], v[132:135], v[148:151], v[32:47]
	v_mfma_f32_32x32x16_bf16 v[16:31], v[132:135], v[152:155], v[16:31]
	v_mfma_f32_32x32x16_bf16 v[0:15], v[132:135], v[156:159], v[0:15]
	s_waitcnt lgkmcnt(4)
	v_mfma_f32_32x32x16_bf16 v[112:127], v[136:139], v[160:163], v[112:127]
	s_waitcnt lgkmcnt(3)
	v_mfma_f32_32x32x16_bf16 v[96:111], v[136:139], v[164:167], v[96:111]
	s_waitcnt lgkmcnt(2)
	v_mfma_f32_32x32x16_bf16 v[80:95], v[136:139], v[168:171], v[80:95]
	s_waitcnt lgkmcnt(1)
	v_mfma_f32_32x32x16_bf16 v[64:79], v[136:139], v[172:175], v[64:79]
	s_waitcnt lgkmcnt(0)
	v_mfma_f32_32x32x16_bf16 v[48:63], v[140:143], v[160:163], v[48:63]
	v_mfma_f32_32x32x16_bf16 v[32:47], v[140:143], v[164:167], v[32:47]
	v_mfma_f32_32x32x16_bf16 v[16:31], v[140:143], v[168:171], v[16:31]
	v_mfma_f32_32x32x16_bf16 v[0:15], v[140:143], v[172:175], v[0:15]
	s_add_u32 s72, s72, 1
	s_cmp_lt_u32 s72, 30
	s_cbranch_scc1 .Lp12_loop
	s_waitcnt vmcnt(6)
	s_barrier
; #define MFMA32(a, b, c) __builtin_amdgcn_mfma_f32_32x32x16_bf16((a), (b), (c), 0, 0, 0)
; #define GA_LOAD(pr_) do { _Pragma("unroll") for (int i = 0; i < 4; ++i) ra[i] = *(const u32x4*)(Ab + (i * 32) * lda + (pr_) * 64); } while (0)
; #define GB_LOAD(kt_) do { const bfr* bk_ = Bb + (kt_) * NB * 32; \
;     _Pragma("unroll") for (int i = 0; i < 4; ++i) rb[i] = *(const u32x4*)(bk_ + (i * 64) * 32); } while (0)
; #define G_STORE(kt_) do { bfr* as_ = S0 + ((kt_) & 1) * GSTAGE; bfr* bs_ = as_ + 128 * 40; \
;     if (apar == ((kt_) & 1)) { _Pragma("unroll") for (int i = 0; i < 4; ++i) *(u32x4*)(as_ + asoff + i * 32 * 40) = ra[i]; } \
;     _Pragma("unroll") for (int i = 0; i < 4; ++i) *(u32x4*)(bs_ + bsoff + i * 64 * 40) = rb[i]; } while (0)
; template <int lda>
; DI void gemm_mainloop(const bfr* __restrict__ A, const bfr* __restrict__ Bt, int NB, int K, int m0, int n0, char* smem, f32x16 (&acc)[2][4]) {
;     ...
;   for (int kt = 0; kt < nk; ++kt) {
;     if (kt + 1 < nk) G_STORE(kt + 1);
;     if (kt + 2 < nk) {
;       GB_LOAD(kt + 2);
;       if ((kt & 1) == 0) GA_LOAD((kt >> 1) + 1);
;     }
;     const bfr* As = S0 + (kt & 1) * GSTAGE;
;     const bfr* Bs = As + 128 * 40;
; #pragma unroll
;     for (int ks = 0; ks < 2; ++ks) {
;       bf16x8 af[2], bfg[4];
; #pragma unroll
;       for (int i = 0; i < 2; ++i) af[i] = *(const bf16x8*)(As + (wr * 64 + i * 32 + r) * 40 + ks * 16 + hl * 8);
; #pragma unroll
;       for (int j = 0; j < 4; ++j) bfg[j] = *(const bf16x8*)(Bs + (wc * 128 + j * 32 + r) * 40 + ks * 16 + hl * 8);
; #pragma unroll
;       for (int i = 0; i < 2; ++i)
; #pragma unroll
;         for (int j = 0; j < 4; ++j) acc[i][j] = MFMA32(af[i], bfg[j], acc[i][j]);
;     }
;     __syncthreads();
	s_mul_i32 s74, s71, 0x6000
	s_add_u32 s75, s74, 0x2000
	s_cmp_eq_u32 s71, 2
	s_cselect_b32 s75, 0x10000, s75
	v_add_u32_e32 v183, s74, v179
	v_add_u32_e32 v185, s75, v181
	v_add_u32_e32 v184, s74, v180
	v_add_u32_e32 v186, s75, v182
	ds_read_b128 v[128:131], v183
	ds_read_b128 v[144:147], v185
	ds_read_b128 v[148:151], v185 offset:2048
	ds_read_b128 v[152:155], v185 offset:4096
	ds_read_b128 v[156:159], v185 offset:6144
	ds_read_b128 v[132:135], v183 offset:2048
	ds_read_b128 v[136:139], v184
	ds_read_b128 v[160:163], v186
	ds_read_b128 v[164:167], v186 offset:2048
	ds_read_b128 v[168:171], v186 offset:4096
	ds_read_b128 v[172:175], v186 offset:6144
	ds_read_b128 v[140:143], v184 offset:2048
	s_add_u32 s71, s71, 1
	s_cmp_eq_u32 s71, 3
	s_cselect_b32 s71, 0, s71
	s_waitcnt lgkmcnt(10)
	v_mfma_f32_32x32x16_bf16 v[112:127], v[128:131], v[144:147], v[112:127]
	s_waitcnt lgkmcnt(9)
	v_mfma_f32_32x32x16_bf16 v[96:111], v[128:131], v[148:151], v[96:111]
	s_waitcnt lgkmcnt(8)
	v_mfma_f32_32x32x16_bf16 v[80:95], v[128:131], v[152:155], v[80:95]
	s_waitcnt lgkmcnt(7)
	v_mfma_f32_32x32x16_bf16 v[64:79], v[128:131], v[156:159], v[64:79]
	s_waitcnt lgkmcnt(6)
	v_mfma_f32_32x32x16_bf16 v[48:63], v[132:135], v[144:147], v[48:63]
	v_mfma_f32_32x32x16_bf16 v[32:47], v[132:135], v[148:151], v[32:47]
	v_mfma_f32_32x32x16_bf16 v[16:31], v[132:135], v[152:155], v[16:31]
	v_mfma_f32_32x32x16_bf16 v[0:15], v[132:135], v[156:159], v[0:15]
	s_waitcnt lgkmcnt(4)
	v_mfma_f32_32x32x16_bf16 v[112:127], v[136:139], v[160:163], v[112:127]
	s_waitcnt lgkmcnt(3)
	v_mfma_f32_32x32x16_bf16 v[96:111], v[136:139], v[164:167], v[96:111]
	s_waitcnt lgkmcnt(2)
	v_mfma_f32_32x32x16_bf16 v[80:95], v[136:139], v[168:171], v[80:95]
	s_waitcnt lgkmcnt(1)
	v_mfma_f32_32x32x16_bf16 v[64:79], v[136:139], v[172:175], v[64:79]
	s_waitcnt lgkmcnt(0)
	v_mfma_f32_32x32x16_bf16 v[48:63], v[140:143], v[160:163], v[48:63]
	v_mfma_f32_32x32x16_bf16 v[32:47], v[140:143], v[164:167], v[32:47]
	v_mfma_f32_32x32x16_bf16 v[16:31], v[140:143], v[168:171], v[16:31]
	v_mfma_f32_32x32x16_bf16 v[0:15], v[140:143], v[172:175], v[0:15]
	s_waitcnt vmcnt(0)
	s_barrier
	s_mul_i32 s74, s71, 0x6000
	s_add_u32 s75, s74, 0x2000
	s_cmp_eq_u32 s71, 2
	s_cselect_b32 s75, 0x10000, s75
	v_add_u32_e32 v183, s74, v179
	v_add_u32_e32 v185, s75, v181
	v_add_u32_e32 v184, s74, v180
	v_add_u32_e32 v186, s75, v182
	ds_read_b128 v[128:131], v183
	ds_read_b128 v[144:147], v185
	ds_read_b128 v[148:151], v185 offset:2048
	ds_read_b128 v[152:155], v185 offset:4096
	ds_read_b128 v[156:159], v185 offset:6144
	ds_read_b128 v[132:135], v183 offset:2048
	ds_read_b128 v[136:139], v184
	ds_read_b128 v[160:163], v186
	ds_read_b128 v[164:167], v186 offset:2048
	ds_read_b128 v[168:171], v186 offset:4096
	ds_read_b128 v[172:175], v186 offset:6144
	ds_read_b128 v[140:143], v184 offset:2048
	s_add_u32 s71, s71, 1
	s_cmp_eq_u32 s71, 3
	s_cselect_b32 s71, 0, s71
	s_waitcnt lgkmcnt(10)
	v_mfma_f32_32x32x16_bf16 v[112:127], v[128:131], v[144:147], v[112:127]
	s_waitcnt lgkmcnt(9)
	v_mfma_f32_32x32x16_bf16 v[96:111], v[128:131], v[148:151], v[96:111]
	s_waitcnt lgkmcnt(8)
	v_mfma_f32_32x32x16_bf16 v[80:95], v[128:131], v[152:155], v[80:95]
	s_waitcnt lgkmcnt(7)
	v_mfma_f32_32x32x16_bf16 v[64:79], v[128:131], v[156:159], v[64:79]
	s_waitcnt lgkmcnt(6)
	v_mfma_f32_32x32x16_bf16 v[48:63], v[132:135], v[144:147], v[48:63]
	v_mfma_f32_32x32x16_bf16 v[32:47], v[132:135], v[148:151], v[32:47]
	v_mfma_f32_32x32x16_bf16 v[16:31], v[132:135], v[152:155], v[16:31]
	v_mfma_f32_32x32x16_bf16 v[0:15], v[132:135], v[156:159], v[0:15]
	s_waitcnt lgkmcnt(4)
	v_mfma_f32_32x32x16_bf16 v[112:127], v[136:139], v[160:163], v[112:127]
	s_waitcnt lgkmcnt(3)
	v_mfma_f32_32x32x16_bf16 v[96:111], v[136:139], v[164:167], v[96:111]
	s_waitcnt lgkmcnt(2)
	v_mfma_f32_32x32x16_bf16 v[80:95], v[136:139], v[168:171], v[80:95]
	s_waitcnt lgkmcnt(1)
	v_mfma_f32_32x32x16_bf16 v[64:79], v[136:139], v[172:175], v[64:79]
	s_waitcnt lgkmcnt(0)
	v_mfma_f32_32x32x16_bf16 v[48:63], v[140:143], v[160:163], v[48:63]
	v_mfma_f32_32x32x16_bf16 v[32:47], v[140:143], v[164:167], v[32:47]
	v_mfma_f32_32x32x16_bf16 v[16:31], v[140:143], v[168:171], v[16:31]
	v_mfma_f32_32x32x16_bf16 v[0:15], v[140:143], v[172:175], v[0:15]
	s_nop 7
	v_readlane_b32 s64, v187, 0
	v_readlane_b32 s65, v187, 1
	v_readlane_b32 s66, v187, 2
	v_readlane_b32 s67, v187, 3
	v_readlane_b32 s68, v187, 4
	v_readlane_b32 s69, v187, 5
	v_readlane_b32 s70, v187, 6
	v_readlane_b32 s71, v187, 7
	v_readlane_b32 s72, v187, 8
	v_readlane_b32 s73, v187, 9
	v_readlane_b32 s74, v187, 10
	v_readlane_b32 s75, v187, 11
	v_readlane_b32 s76, v187, 12
	v_readlane_b32 s77, v187, 13
	v_readlane_b32 s78, v187, 14
	v_readlane_b32 s79, v187, 15
	s_nop 7
	s_branch .LBB0_1178

; #define MFMA32(a, b, c) __builtin_amdgcn_mfma_f32_32x32x16_bf16((a), (b), (c), 0, 0, 0)
; #define GA_LOAD(pr_) do { _Pragma("unroll") for (int i = 0; i < 4; ++i) ra[i] = *(const u32x4*)(Ab + (i * 32) * lda + (pr_) * 64); } while (0)
; #define GB_LOAD(kt_) do { const bfr* bk_ = Bb + (kt_) * NB * 32; \
;     _Pragma("unroll") for (int i = 0; i < 4; ++i) rb[i] = *(const u32x4*)(bk_ + (i * 64) * 32); } while (0)
; #define G_STORE(kt_) do { bfr* as_ = S0 + ((kt_) & 1) * GSTAGE; bfr* bs_ = as_ + 128 * 40; \
;     if (apar == ((kt_) & 1)) { _Pragma("unroll") for (int i = 0; i < 4; ++i) *(u32x4*)(as_ + asoff + i * 32 * 40) = ra[i]; } \
;     _Pragma("unroll") for (int i = 0; i < 4; ++i) *(u32x4*)(bs_ + bsoff + i * 64 * 40) = rb[i]; } while (0)
; template <int lda>
; DI void gemm_mainloop(const bfr* __restrict__ A, const bfr* __restrict__ Bt, int NB, int K, int m0, int n0, char* smem, f32x16 (&acc)[2][4]) {
;     ...
;   for (int kt = 0; kt < nk; ++kt) {
;     if (kt + 1 < nk) G_STORE(kt + 1);
;     if (kt + 2 < nk) {
;       GB_LOAD(kt + 2);
;       if ((kt & 1) == 0) GA_LOAD((kt >> 1) + 1);
;     }
;     const bfr* As = S0 + (kt & 1) * GSTAGE;
;     const bfr* Bs = As + 128 * 40;
; #pragma unroll
;     for (int ks = 0; ks < 2; ++ks) {
;       bf16x8 af[2], bfg[4];
; #pragma unroll
;       for (int i = 0; i < 2; ++i) af[i] = *(const bf16x8*)(As + (wr * 64 + i * 32 + r) * 40 + ks * 16 + hl * 8);
; #pragma unroll
;       for (int j = 0; j < 4; ++j) bfg[j] = *(const bf16x8*)(Bs + (wc * 128 + j * 32 + r) * 40 + ks * 16 + hl * 8);
; #pragma unroll
;       for (int i = 0; i < 2; ++i)
; #pragma unroll
;         for (int j = 0; j < 4; ++j) acc[i][j] = MFMA32(af[i], bfg[j], acc[i][j]);
;     }
;     __syncthreads();
.Lp15_loop:
	s_waitcnt vmcnt(6)
	s_barrier
	s_mul_i32 s74, s70, 0x6000
	s_add_u32 s75, s74, s68
	s_mov_b32 m0, s75
	s_add_u32 s76, s74, 0x2000
	s_cmp_eq_u32 s70, 2
	s_cselect_b32 s76, 0x10000, s76
	global_load_lds_dwordx4 v176, s[64:65]
	s_add_u32 m0, s75, 0x400
	s_add_u32 s76, s76, s69
	global_load_lds_dwordx4 v177, s[64:65]
	s_mov_b32 m0, s76
	s_add_u32 s64, s64, 64
	s_addc_u32 s65, s65, 0
	global_load_lds_dwordx4 v178, s[66:67]
	global_load_lds_dwordx4 v178, s[66:67] offset:1024
	global_load_lds_dwordx4 v178, s[66:67] offset:2048
	global_load_lds_dwordx4 v178, s[66:67] offset:3072
	s_add_u32 s66, s66, 0x10000
	s_addc_u32 s67, s67, 0
	s_add_u32 s70, s70, 1
	s_cmp_eq_u32 s70, 3
	s_cselect_b32 s70, 0, s70
	s_mul_i32 s74, s71, 0x6000
	s_add_u32 s75, s74, 0x2000
	s_cmp_eq_u32 s71, 2
	s_cselect_b32 s75, 0x10000, s75
	v_add_u32_e32 v183, s74, v179
	v_add_u32_e32 v185, s75, v181
	v_add_u32_e32 v184, s74, v180
	v_add_u32_e32 v186, s75, v182
	ds_read_b128 v[128:131], v183
	ds_read_b128 v[144:147], v185
	ds_read_b128 v[148:151], v185 offset:2048
	ds_read_b128 v[152:155], v185 offset:4096
	ds_read_b128 v[156:159], v185 offset:6144
	ds_read_b128 v[132:135], v183 offset:2048
	ds_read_b128 v[136:139], v184
	ds_read_b128 v[160:163], v186
	ds_read_b128 v[164:167], v186 offset:2048
	ds_read_b128 v[168:171], v186 offset:4096
	ds_read_b128 v[172:175], v186 offset:6144
	ds_read_b128 v[140:143], v184 offset:2048
	s_add_u32 s71, s71, 1
	s_cmp_eq_u32 s71, 3
	s_cselect_b32 s71, 0, s71
	s_waitcnt lgkmcnt(10)
	v_mfma_f32_32x32x16_bf16 v[112:127], v[128:131], v[144:147], v[112:127]
	s_waitcnt lgkmcnt(9)
	v_mfma_f32_32x32x16_bf16 v[96:111], v[128:131], v[148:151], v[96:111]
	s_waitcnt lgkmcnt(8)
	v_mfma_f32_32x32x16_bf16 v[80:95], v[128:131], v[152:155], v[80:95]
	s_waitcnt lgkmcnt(7)
	v_mfma_f32_32x32x16_bf16 v[64:79], v[128:131], v[156:159], v[64:79]
	s_waitcnt lgkmcnt(6)
	v_mfma_f32_32x32x16_bf16 v[48:63], v[132:135], v[144:147], v[48:63]
	v_mfma_f32_32x32x16_bf16 v[32:47], v[132:135], v[148:151], v[32:47]
	v_mfma_f32_32x32x16_bf16 v[16:31], v[132:135], v[152:155], v[16:31]
	v_mfma_f32_32x32x16_bf16 v[0:15], v[132:135], v[156:159], v[0:15]
	s_waitcnt lgkmcnt(4)
	v_mfma_f32_32x32x16_bf16 v[112:127], v[136:139], v[160:163], v[112:127]
	s_waitcnt lgkmcnt(3)
	v_mfma_f32_32x32x16_bf16 v[96:111], v[136:139], v[164:167], v[96:111]
	s_waitcnt lgkmcnt(2)
	v_mfma_f32_32x32x16_bf16 v[80:95], v[136:139], v[168:171], v[80:95]
	s_waitcnt lgkmcnt(1)
	v_mfma_f32_32x32x16_bf16 v[64:79], v[136:139], v[172:175], v[64:79]
	s_waitcnt lgkmcnt(0)
	v_mfma_f32_32x32x16_bf16 v[48:63], v[140:143], v[160:163], v[48:63]
	v_mfma_f32_32x32x16_bf16 v[32:47], v[140:143], v[164:167], v[32:47]
	v_mfma_f32_32x32x16_bf16 v[16:31], v[140:143], v[168:171], v[16:31]
	v_mfma_f32_32x32x16_bf16 v[0:15], v[140:143], v[172:175], v[0:15]
	s_add_u32 s72, s72, 1
	s_cmp_lt_u32 s72, 30
	s_cbranch_scc1 .Lp15_loop
	s_waitcnt vmcnt(6)
	s_barrier
	s_mul_i32 s74, s71, 0x6000
	s_add_u32 s75, s74, 0x2000
	s_cmp_eq_u32 s71, 2
	s_cselect_b32 s75, 0x10000, s75
	v_add_u32_e32 v183, s74, v179
	v_add_u32_e32 v185, s75, v181
	v_add_u32_e32 v184, s74, v180
	v_add_u32_e32 v186, s75, v182
	ds_read_b128 v[128:131], v183
	ds_read_b128 v[144:147], v185
	ds_read_b128 v[148:151], v185 offset:2048
	ds_read_b128 v[152:155], v185 offset:4096
	ds_read_b128 v[156:159], v185 offset:6144
	ds_read_b128 v[132:135], v183 offset:2048
	ds_read_b128 v[136:139], v184
	ds_read_b128 v[160:163], v186
	ds_read_b128 v[164:167], v186 offset:2048
	ds_read_b128 v[168:171], v186 offset:4096
	ds_read_b128 v[172:175], v186 offset:6144
	ds_read_b128 v[140:143], v184 offset:2048
	s_add_u32 s71, s71, 1
	s_cmp_eq_u32 s71, 3
	s_cselect_b32 s71, 0, s71
	s_waitcnt lgkmcnt(10)
	v_mfma_f32_32x32x16_bf16 v[112:127], v[128:131], v[144:147], v[112:127]
	s_waitcnt lgkmcnt(9)
	v_mfma_f32_32x32x16_bf16 v[96:111], v[128:131], v[148:151], v[96:111]
	s_waitcnt lgkmcnt(8)
	v_mfma_f32_32x32x16_bf16 v[80:95], v[128:131], v[152:155], v[80:95]
	s_waitcnt lgkmcnt(7)
	v_mfma_f32_32x32x16_bf16 v[64:79], v[128:131], v[156:159], v[64:79]
	s_waitcnt lgkmcnt(6)
	v_mfma_f32_32x32x16_bf16 v[48:63], v[132:135], v[144:147], v[48:63]
	v_mfma_f32_32x32x16_bf16 v[32:47], v[132:135], v[148:151], v[32:47]
	v_mfma_f32_32x32x16_bf16 v[16:31], v[132:135], v[152:155], v[16:31]
	v_mfma_f32_32x32x16_bf16 v[0:15], v[132:135], v[156:159], v[0:15]
	s_waitcnt lgkmcnt(4)
	v_mfma_f32_32x32x16_bf16 v[112:127], v[136:139], v[160:163], v[112:127]
	s_waitcnt lgkmcnt(3)
	v_mfma_f32_32x32x16_bf16 v[96:111], v[136:139], v[164:167], v[96:111]
	s_waitcnt lgkmcnt(2)
	v_mfma_f32_32x32x16_bf16 v[80:95], v[136:139], v[168:171], v[80:95]
	s_waitcnt lgkmcnt(1)
	v_mfma_f32_32x32x16_bf16 v[64:79], v[136:139], v[172:175], v[64:79]
	s_waitcnt lgkmcnt(0)
	v_mfma_f32_32x32x16_bf16 v[48:63], v[140:143], v[160:163], v[48:63]
	v_mfma_f32_32x32x16_bf16 v[32:47], v[140:143], v[164:167], v[32:47]
	v_mfma_f32_32x32x16_bf16 v[16:31], v[140:143], v[168:171], v[16:31]
	v_mfma_f32_32x32x16_bf16 v[0:15], v[140:143], v[172:175], v[0:15]
	s_waitcnt vmcnt(0)
	s_barrier
; #define MFMA32(a, b, c) __builtin_amdgcn_mfma_f32_32x32x16_bf16((a), (b), (c), 0, 0, 0)
; DI int crow(int reg, int h) { return (reg & 3) + 8 * (reg >> 2) + 4 * h; }
; template <int lda>
; DI void gemm_mainloop(const bfr* __restrict__ A, const bfr* __restrict__ Bt, int NB, int K, int m0, int n0, char* smem, f32x16 (&acc)[2][4]) {
;     ...
; #pragma unroll
;     for (int ks = 0; ks < 2; ++ks) {
;       bf16x8 af[2], bfg[4];
; #pragma unroll
;       for (int i = 0; i < 2; ++i) af[i] = *(const bf16x8*)(As + (wr * 64 + i * 32 + r) * 40 + ks * 16 + hl * 8);
; #pragma unroll
;       for (int j = 0; j < 4; ++j) bfg[j] = *(const bf16x8*)(Bs + (wc * 128 + j * 32 + r) * 40 + ks * 16 + hl * 8);
; #pragma unroll
;       for (int i = 0; i < 2; ++i)
; #pragma unroll
;         for (int j = 0; j < 4; ++j) acc[i][j] = MFMA32(af[i], bfg[j], acc[i][j]);
;     }
; template <bool FIRST, bool HAS_H>
; DI void phase_gemm_resid(const Params& p, const bfr* A, const bfr* Wt, const float* gnext, float* ss, char* smem) {
;     ...
;     int tid2 = threadIdx.x;
;     asm volatile("" : "+v"(tid2));
;     const int lane = tid2 & 63, wid = tid2 >> 6, wr = wid >> 1, wc = wid & 1, r = lane & 31, hl = lane >> 5;
;     const float* xsrc = FIRST ? p.x_prompt : X;
;     const int rbase = m0 + wr * 64 + 4 * hl, cbase = n0 + wc * 128 + r;
; #pragma unroll
;     for (int i = 0; i < 2; ++i) {
; #pragma unroll
;       for (int qh = 0; qh < 2; ++qh) {
;         float rs[8];
; #pragma unroll
;         for (int q = 0; q < 8; ++q) rs[q] = 0.f;
; #pragma unroll
;         for (int jh = 0; jh < 2; ++jh) {
;           float xo[2][8];
; #pragma unroll
;           for (int jj = 0; jj < 2; ++jj)
; #pragma unroll
;             for (int q = 0; q < 8; ++q)
;               xo[jj][q] = xsrc[(rbase + i * 32 + crow(qh * 8 + q, 0)) * 1024 + cbase + (jh * 2 + jj) * 32];
	s_mul_i32 s74, s71, 0x6000
	s_add_u32 s75, s74, 0x2000
	s_cmp_eq_u32 s71, 2
	s_cselect_b32 s75, 0x10000, s75
	v_add_u32_e32 v183, s74, v179
	v_add_u32_e32 v185, s75, v181
	v_add_u32_e32 v184, s74, v180
	v_add_u32_e32 v186, s75, v182
	ds_read_b128 v[128:131], v183
	ds_read_b128 v[144:147], v185
	ds_read_b128 v[148:151], v185 offset:2048
	ds_read_b128 v[152:155], v185 offset:4096
	ds_read_b128 v[156:159], v185 offset:6144
	ds_read_b128 v[132:135], v183 offset:2048
	ds_read_b128 v[136:139], v184
	ds_read_b128 v[160:163], v186
	ds_read_b128 v[164:167], v186 offset:2048
	ds_read_b128 v[168:171], v186 offset:4096
	ds_read_b128 v[172:175], v186 offset:6144
	ds_read_b128 v[140:143], v184 offset:2048
	s_add_u32 s71, s71, 1
	s_cmp_eq_u32 s71, 3
	s_cselect_b32 s71, 0, s71
	s_waitcnt lgkmcnt(10)
	v_mfma_f32_32x32x16_bf16 v[112:127], v[128:131], v[144:147], v[112:127]
	s_waitcnt lgkmcnt(9)
	v_mfma_f32_32x32x16_bf16 v[96:111], v[128:131], v[148:151], v[96:111]
	s_waitcnt lgkmcnt(8)
	v_mfma_f32_32x32x16_bf16 v[80:95], v[128:131], v[152:155], v[80:95]
	s_waitcnt lgkmcnt(7)
	v_mfma_f32_32x32x16_bf16 v[64:79], v[128:131], v[156:159], v[64:79]
	s_waitcnt lgkmcnt(6)
	v_mfma_f32_32x32x16_bf16 v[48:63], v[132:135], v[144:147], v[48:63]
	v_mfma_f32_32x32x16_bf16 v[32:47], v[132:135], v[148:151], v[32:47]
	v_mfma_f32_32x32x16_bf16 v[16:31], v[132:135], v[152:155], v[16:31]
	v_mfma_f32_32x32x16_bf16 v[0:15], v[132:135], v[156:159], v[0:15]
	s_waitcnt lgkmcnt(4)
	v_mfma_f32_32x32x16_bf16 v[112:127], v[136:139], v[160:163], v[112:127]
	s_waitcnt lgkmcnt(3)
	v_mfma_f32_32x32x16_bf16 v[96:111], v[136:139], v[164:167], v[96:111]
	s_waitcnt lgkmcnt(2)
	v_mfma_f32_32x32x16_bf16 v[80:95], v[136:139], v[168:171], v[80:95]
	s_waitcnt lgkmcnt(1)
	v_mfma_f32_32x32x16_bf16 v[64:79], v[136:139], v[172:175], v[64:79]
	s_waitcnt lgkmcnt(0)
	v_mfma_f32_32x32x16_bf16 v[48:63], v[140:143], v[160:163], v[48:63]
	v_mfma_f32_32x32x16_bf16 v[32:47], v[140:143], v[164:167], v[32:47]
	v_mfma_f32_32x32x16_bf16 v[16:31], v[140:143], v[168:171], v[16:31]
	v_mfma_f32_32x32x16_bf16 v[0:15], v[140:143], v[172:175], v[0:15]
	s_nop 7
	v_readlane_b32 s64, v187, 0
	v_readlane_b32 s65, v187, 1
	v_readlane_b32 s66, v187, 2
	v_readlane_b32 s67, v187, 3
	v_readlane_b32 s68, v187, 4
	v_readlane_b32 s69, v187, 5
	v_readlane_b32 s70, v187, 6
	v_readlane_b32 s71, v187, 7
	v_readlane_b32 s72, v187, 8
	v_readlane_b32 s73, v187, 9
	v_readlane_b32 s74, v187, 10
	v_readlane_b32 s75, v187, 11
	v_readlane_b32 s76, v187, 12
	v_readlane_b32 s77, v187, 13
	v_readlane_b32 s78, v187, 14
	v_readlane_b32 s79, v187, 15
	s_nop 7
	s_waitcnt vmcnt(1)
	s_nop 0
	s_nop 0
	s_nop 0
	s_waitcnt vmcnt(0)
	s_nop 0
	v_add_u32_e32 v132, v169, v171
	s_nop 0
	v_add_u32_e32 v133, v169, v170
	s_nop 0
	s_nop 0
	s_nop 0
	s_nop 0
	s_nop 0
	s_nop 0
	s_nop 0
	s_nop 0
	s_nop 0
	s_nop 0
	s_nop 0
	v_mov_b32_e32 v192, v196
	s_waitcnt lgkmcnt(0)
	s_nop 0
	s_nop 0
	s_nop 0
	s_nop 0
	s_nop 0
	s_nop 0
	s_nop 0
	s_nop 0
	s_nop 0
	s_nop 0
	s_nop 0
	s_nop 0
	s_nop 0
	s_nop 0
	s_nop 0
	s_nop 0
	s_nop 0
	s_waitcnt lgkmcnt(0)
	s_nop 0
	s_nop 0
	v_ashrrev_i32_e32 v194, 1, v192
	v_and_b32_e32 v194, 0xffffffc0, v194
	v_add_u32_e32 v194, s36, v194
	v_lshrrev_b32_e32 v195, 3, v192
	v_and_b32_e32 v232, 31, v192
	s_nop 0
	v_and_or_b32 v216, v195, 4, v194
	v_lshlrev_b32_e32 v192, 1, v192
	v_and_b32_e32 v192, 0x80, v192
	v_lshlrev_b32_e32 v205, 10, v216
	v_or3_b32 v199, s33, v192, v232
	v_or_b32_e32 v194, v205, v199
	v_ashrrev_i32_e32 v195, 31, v194
	s_nop 0
	v_or_b32_e32 v220, 0x400, v205
	v_or_b32_e32 v218, v220, v199
	v_ashrrev_i32_e32 v219, 31, v218
	v_lshl_add_u64 v[218:219], v[218:219], 2, s[10:11]
	v_or_b32_e32 v204, 32, v199
	global_load_dword v221, v[218:219], off
	v_or_b32_e32 v218, v220, v204
	s_nop 0
	v_ashrrev_i32_e32 v203, 31, v205
	v_mov_b32_e32 v202, v194
	v_lshl_add_u64 v[200:201], v[194:195], 2, s[10:11]
	v_lshl_add_u64 v[202:203], v[202:203], 2, s[10:11]
	global_load_dword v192, v[200:201], off
	global_load_dword v217, v[202:203], off offset:128
	v_ashrrev_i32_e32 v219, 31, v218
	v_lshl_add_u64 v[218:219], v[218:219], 2, s[10:11]
	v_or_b32_e32 v223, 0x800, v205
	global_load_dword v222, v[218:219], off
	v_or_b32_e32 v218, v223, v199
	v_ashrrev_i32_e32 v219, 31, v218
	v_lshl_add_u64 v[218:219], v[218:219], 2, s[10:11]
	s_nop 0
	global_load_dword v224, v[218:219], off
	v_or_b32_e32 v218, v223, v204
	v_ashrrev_i32_e32 v219, 31, v218
	v_lshl_add_u64 v[218:219], v[218:219], 2, s[10:11]
	global_load_dword v225, v[218:219], off
	v_or_b32_e32 v226, 0xc00, v205
	v_or_b32_e32 v227, 0x2000, v205
	s_nop 0
	v_or_b32_e32 v228, 0x2400, v205
	v_or_b32_e32 v229, 0x2800, v205
	v_or_b32_e32 v218, v226, v199
	v_or_b32_e32 v230, 0x2c00, v205
	v_ashrrev_i32_e32 v219, 31, v218
	v_lshl_add_u64 v[218:219], v[218:219], 2, s[10:11]
	v_cmp_eq_u32_e32 vcc, 31, v232
	s_nop 0
	s_nop 0
	s_nop 0
	s_nop 0
	s_nop 0
	s_nop 0
	s_waitcnt vmcnt(0)
; DI bfr f2bf(float a) { return (bfr)(pack2(a, 0.f) & 0xffffu); }
; DI int crow(int reg, int h) { return (reg & 3) + 8 * (reg >> 2) + 4 * h; }
; template <bool FIRST, bool HAS_H>
; DI void phase_gemm_resid(const Params& p, const bfr* A, const bfr* Wt, const float* gnext, float* ss, char* smem) {
;     ...
; #pragma unroll
;     for (int i = 0; i < 2; ++i) {
; #pragma unroll
;       for (int qh = 0; qh < 2; ++qh) {
;         float rs[8];
; #pragma unroll
;         for (int q = 0; q < 8; ++q) rs[q] = 0.f;
; #pragma unroll
;         for (int jh = 0; jh < 2; ++jh) {
;           float xo[2][8];
; #pragma unroll
;           for (int jj = 0; jj < 2; ++jj)
; #pragma unroll
;             for (int q = 0; q < 8; ++q)
;               xo[jj][q] = xsrc[(rbase + i * 32 + crow(qh * 8 + q, 0)) * 1024 + cbase + (jh * 2 + jj) * 32];
; #pragma unroll
;           for (int q = 0; q < 8; ++q) {
;             const int o = (rbase + i * 32 + crow(qh * 8 + q, 0)) * 1024 + cbase;
; #pragma unroll
;             for (int jj = 0; jj < 2; ++jj) {
;               const int j = jh * 2 + jj;
;               const float xn = xo[jj][q] + acc[i][j][qh * 8 + q];
;               X[o + j * 32] = xn;
;               if (HAS_H) Hn[o + j * 32] = f2bf(xn * gnext[cbase + j * 32]);
;               rs[q] += xn * xn;
;             }
;           }
;         }
	s_nop 9
	v_add_f32_e32 v98, v98, v225
	s_nop 0
	v_or_b32_e32 v206, v227, v199
	v_or_b32_e32 v208, v228, v199
	v_ashrrev_i32_e32 v207, 31, v206
	v_ashrrev_i32_e32 v209, 31, v208
	v_lshl_add_u64 v[206:207], v[206:207], 2, s[10:11]
	v_lshl_add_u64 v[208:209], v[208:209], 2, s[10:11]
	s_nop 0
	v_or_b32_e32 v210, v229, v199
	v_ashrrev_i32_e32 v211, 31, v210
	v_or_b32_e32 v212, v230, v199
	v_lshl_add_u64 v[210:211], v[210:211], 2, s[10:11]
	v_ashrrev_i32_e32 v213, 31, v212
	v_lshl_add_u64 v[212:213], v[212:213], 2, s[10:11]
	global_load_dword v231, v[218:219], off
	global_load_dword v233, v[206:207], off
	global_load_dword v234, v[208:209], off
	global_load_dword v235, v[210:211], off
	global_load_dword v236, v[212:213], off
	v_or_b32_e32 v206, v226, v204
	v_or_b32_e32 v208, v227, v204
	v_or_b32_e32 v210, v228, v204
	v_ashrrev_i32_e32 v207, 31, v206
	v_ashrrev_i32_e32 v209, 31, v208
	v_ashrrev_i32_e32 v211, 31, v210
	v_or_b32_e32 v212, v229, v204
	v_or_b32_e32 v218, v230, v204
	v_lshl_add_u64 v[206:207], v[206:207], 2, s[10:11]
	v_lshl_add_u64 v[208:209], v[208:209], 2, s[10:11]
	v_lshl_add_u64 v[210:211], v[210:211], 2, s[10:11]
	v_ashrrev_i32_e32 v213, 31, v212
	v_ashrrev_i32_e32 v219, 31, v218
	v_lshl_add_u64 v[212:213], v[212:213], 2, s[10:11]
	v_lshl_add_u64 v[218:219], v[218:219], 2, s[10:11]
	global_load_dword v206, v[206:207], off
	s_nop 0
	global_load_dword v207, v[208:209], off
	s_nop 0
	global_load_dword v208, v[210:211], off
	global_load_dword v209, v[212:213], off
	s_nop 0
	global_load_dword v210, v[218:219], off
	v_add_f32_e32 v211, v112, v192
	v_or_b32_e32 v112, 0x400, v194
	global_store_dword v[200:201], v211, off
	v_lshlrev_b32_e32 v192, 2, v199
	v_add_f32_e32 v213, v96, v217
	s_nop 0
	v_add_f32_e32 v189, v113, v221
	v_ashrrev_i32_e32 v113, 31, v112
	v_or_b32_e32 v96, 0x420, v194
	global_load_dword v212, v192, s[12:13]
	v_lshl_add_u64 v[112:113], v[112:113], 2, s[10:11]
	global_store_dword v[200:201], v213, off offset:128
	global_load_dword v188, v192, s[12:13] offset:128
	s_nop 0
	v_add_f32_e32 v185, v97, v222
	v_ashrrev_i32_e32 v97, 31, v96
	global_store_dword v[112:113], v189, off
	v_lshl_add_u64 v[96:97], v[96:97], 2, s[10:11]
	global_load_dword v184, v192, s[12:13]
	v_ashrrev_i32_e32 v217, 31, v216
	global_store_dword v[96:97], v185, off
	s_nop 0
	v_or_b32_e32 v172, 0x800, v194
	v_ashrrev_i32_e32 v173, 31, v172
	v_add_f32_e32 v176, v114, v224
	v_lshl_add_u64 v[96:97], v[172:173], 2, s[10:11]
	v_or_b32_e32 v174, 0x820, v194
	global_load_dword v186, v192, s[12:13] offset:128
	v_ashrrev_i32_e32 v175, 31, v174
	global_store_dword v[96:97], v176, off
	global_load_dword v177, v192, s[12:13]
	v_lshl_add_u64 v[96:97], v[174:175], 2, s[10:11]
	global_store_dword v[96:97], v98, off
	global_load_dword v178, v192, s[12:13] offset:128
	s_nop 0
	v_lshl_add_u64 v[162:163], v[172:173], 1, s[6:7]
	v_lshl_add_u64 v[96:97], v[216:217], 2, s[14:15]
	s_waitcnt vmcnt(21)
	v_add_f32_e32 v115, v115, v231
	s_nop 0
	s_waitcnt vmcnt(10)
	v_mul_f32_e32 v112, v211, v212
	s_nop 0
	v_cvt_pk_bf16_f32 v114, v112, s0
	v_lshl_add_u64 v[112:113], v[194:195], 1, s[6:7]
	global_store_short v[112:113], v114, off
	s_waitcnt vmcnt(9)
	v_mul_f32_e32 v114, v213, v188
	v_cvt_pk_bf16_f32 v114, v114, s0
	global_store_short v[112:113], v114, off offset:64
	v_mul_f32_e32 v114, v213, v213
	s_nop 0
	v_or_b32_e32 v152, 0xc00, v194
	v_ashrrev_i32_e32 v153, 31, v152
	v_lshl_add_u64 v[154:155], v[152:153], 2, s[10:11]
	global_store_dword v[154:155], v115, off
	v_or_b32_e32 v154, 0xc20, v194
	v_ashrrev_i32_e32 v155, 31, v154
	s_waitcnt vmcnt(9)
	v_mul_f32_e32 v160, v189, v184
	s_nop 0
	v_add_f32_e32 v169, v119, v236
	v_add_f32_e32 v171, v103, v210
	v_cvt_pk_bf16_f32 v160, v160, s0
	s_waitcnt vmcnt(5)
	v_mul_f32_e32 v161, v176, v177
	v_cvt_pk_bf16_f32 v161, v161, s0
	global_store_short v[162:163], v161, off
	s_waitcnt vmcnt(4)
	v_mul_f32_e32 v161, v98, v178
	s_nop 0
	global_load_dword v158, v192, s[12:13]
	v_cvt_pk_bf16_f32 v161, v161, s0
	v_lshl_add_u64 v[162:163], v[174:175], 1, s[6:7]
	global_store_short v[162:163], v161, off
	v_mul_f32_e32 v161, v98, v98
	v_add_f32_e32 v159, v99, v206
	v_lshl_add_u64 v[98:99], v[154:155], 2, s[10:11]
	global_store_dword v[98:99], v159, off
	global_load_dword v162, v192, s[12:13] offset:128
	v_or_b32_e32 v156, 0x2000, v194
	v_ashrrev_i32_e32 v157, 31, v156
	s_nop 0
	v_add_f32_e32 v163, v116, v233
	v_lshl_add_u64 v[98:99], v[156:157], 2, s[10:11]
	global_store_dword v[98:99], v163, off
	v_or_b32_e32 v116, 0x2400, v194
	v_add_f32_e32 v165, v117, v234
	v_ashrrev_i32_e32 v117, 31, v116
	v_add_f32_e32 v167, v102, v209
	s_nop 0
	v_or_b32_e32 v148, 0x2020, v194
	v_ashrrev_i32_e32 v149, 31, v148
	global_load_dword v150, v192, s[12:13]
	v_add_f32_e32 v151, v100, v207
	v_lshl_add_u64 v[98:99], v[148:149], 2, s[10:11]
	global_store_dword v[98:99], v151, off
	global_load_dword v164, v192, s[12:13] offset:128
	s_nop 0
	v_lshl_add_u64 v[98:99], v[116:117], 2, s[10:11]
	v_or_b32_e32 v140, 0x2420, v194
	global_store_dword v[98:99], v165, off
	v_ashrrev_i32_e32 v141, 31, v140
	v_lshl_add_u64 v[98:99], v[140:141], 2, s[10:11]
	global_store_short v[112:113], v160, off offset:2048
	v_mul_f32_e32 v160, v185, v186
	s_nop 0
	global_load_dword v144, v192, s[12:13]
	v_add_f32_e32 v145, v101, v208
	global_store_dword v[98:99], v145, off
	global_load_dword v146, v192, s[12:13] offset:128
	v_add_f32_e32 v147, v118, v235
	v_cvt_pk_bf16_f32 v160, v160, s0
	global_store_short v[112:113], v160, off offset:2112
	s_nop 0
	v_or_b32_e32 v136, 0x2800, v194
	v_ashrrev_i32_e32 v137, 31, v136
	v_lshl_add_u64 v[98:99], v[136:137], 2, s[10:11]
	global_store_dword v[98:99], v147, off
	global_load_dword v166, v192, s[12:13]
	v_lshl_add_u64 v[116:117], v[116:117], 1, s[6:7]
	v_mul_f32_e32 v160, v185, v185
	s_nop 0
	v_or_b32_e32 v128, 0x2820, v194
	v_ashrrev_i32_e32 v129, 31, v128
	v_lshl_add_u64 v[98:99], v[128:129], 2, s[10:11]
	global_store_dword v[98:99], v167, off
	global_load_dword v168, v192, s[12:13] offset:128
	v_or_b32_e32 v98, 0x2c00, v194
	v_ashrrev_i32_e32 v99, 31, v98
	v_lshl_add_u64 v[100:101], v[98:99], 2, s[10:11]
	global_store_dword v[100:101], v169, off
	global_load_dword v170, v192, s[12:13]
	v_or_b32_e32 v100, 0x2c20, v194
	v_ashrrev_i32_e32 v101, 31, v100
	v_lshl_add_u64 v[102:103], v[100:101], 2, s[10:11]
	global_store_dword v[102:103], v171, off
	v_or_b32_e32 v102, 64, v199
	v_or_b32_e32 v118, v220, v102
	v_or_b32_e32 v130, v223, v102
	v_or_b32_e32 v132, v226, v102
	v_or_b32_e32 v134, v227, v102
	v_ashrrev_i32_e32 v119, 31, v118
	v_ashrrev_i32_e32 v131, 31, v130
	v_ashrrev_i32_e32 v133, 31, v132
	v_ashrrev_i32_e32 v135, 31, v134
	v_or_b32_e32 v138, v228, v102
	v_or_b32_e32 v142, v229, v102
	v_lshl_add_u64 v[118:119], v[118:119], 2, s[10:11]
	v_lshl_add_u64 v[130:131], v[130:131], 2, s[10:11]
	v_lshl_add_u64 v[132:133], v[132:133], 2, s[10:11]
	v_lshl_add_u64 v[134:135], v[134:135], 2, s[10:11]
	v_ashrrev_i32_e32 v139, 31, v138
	v_ashrrev_i32_e32 v143, 31, v142
	s_waitcnt vmcnt(20)
; DI bfr f2bf(float a) { return (bfr)(pack2(a, 0.f) & 0xffffu); }
; DI int crow(int reg, int h) { return (reg & 3) + 8 * (reg >> 2) + 4 * h; }
; template <bool FIRST, bool HAS_H>
; DI void phase_gemm_resid(const Params& p, const bfr* A, const bfr* Wt, const float* gnext, float* ss, char* smem) {
;     ...
;         for (int jh = 0; jh < 2; ++jh) {
;           float xo[2][8];
; #pragma unroll
;           for (int jj = 0; jj < 2; ++jj)
; #pragma unroll
;             for (int q = 0; q < 8; ++q)
;               xo[jj][q] = xsrc[(rbase + i * 32 + crow(qh * 8 + q, 0)) * 1024 + cbase + (jh * 2 + jj) * 32];
; #pragma unroll
;           for (int q = 0; q < 8; ++q) {
;             const int o = (rbase + i * 32 + crow(qh * 8 + q, 0)) * 1024 + cbase;
; #pragma unroll
;             for (int jj = 0; jj < 2; ++jj) {
;               const int j = jh * 2 + jj;
;               const float xn = xo[jj][q] + acc[i][j][qh * 8 + q];
;               X[o + j * 32] = xn;
;               if (HAS_H) Hn[o + j * 32] = f2bf(xn * gnext[cbase + j * 32]);
;               rs[q] += xn * xn;
;             }
;           }
;         }
	v_mul_f32_e32 v103, v115, v158
	v_lshl_add_u64 v[138:139], v[138:139], 2, s[10:11]
	v_lshl_add_u64 v[142:143], v[142:143], 2, s[10:11]
	global_load_dword v172, v[202:203], off offset:256
	global_load_dword v173, v[118:119], off
	s_nop 0
	global_load_dword v130, v[130:131], off
	s_nop 0
	global_load_dword v131, v[132:133], off
	s_nop 0
	global_load_dword v132, v[134:135], off
	global_load_dword v133, v[138:139], off
	s_nop 0
	global_load_dword v134, v[142:143], off
	global_load_dword v135, v[202:203], off offset:384
	v_cvt_pk_bf16_f32 v103, v103, s0
	v_lshl_add_u64 v[118:119], v[152:153], 1, s[6:7]
	global_store_short v[118:119], v103, off
	v_or_b32_e32 v103, 0x60, v199
	v_or_b32_e32 v118, v220, v103
	v_ashrrev_i32_e32 v119, 31, v118
	v_lshl_add_u64 v[118:119], v[118:119], 2, s[10:11]
	global_load_dword v138, v[118:119], off
	s_waitcnt vmcnt(27)
	v_mul_f32_e32 v118, v159, v162
	v_cvt_pk_bf16_f32 v139, v118, s0
	v_lshl_add_u64 v[118:119], v[154:155], 1, s[6:7]
	global_store_short v[118:119], v139, off
	v_or_b32_e32 v118, v223, v103
	v_mul_f32_e32 v139, v159, v159
	v_ashrrev_i32_e32 v119, 31, v118
	v_fmac_f32_e32 v139, v115, v115
	s_waitcnt vmcnt(26)
	v_mul_f32_e32 v115, v163, v150
	v_lshl_add_u64 v[118:119], v[118:119], 2, s[10:11]
	v_cvt_pk_bf16_f32 v115, v115, s0
	global_load_dword v142, v[118:119], off
	v_lshl_add_u64 v[118:119], v[156:157], 1, s[6:7]
	global_store_short v[118:119], v115, off
	s_waitcnt vmcnt(26)
	v_mul_f32_e32 v115, v151, v164
	v_cvt_pk_bf16_f32 v115, v115, s0
	v_lshl_add_u64 v[118:119], v[148:149], 1, s[6:7]
	global_store_short v[118:119], v115, off
	v_or_b32_e32 v118, v226, v103
	v_ashrrev_i32_e32 v119, 31, v118
	v_lshl_add_u64 v[118:119], v[118:119], 2, s[10:11]
	global_load_dword v143, v[118:119], off
	s_waitcnt vmcnt(25)
	v_mul_f32_e32 v118, v165, v144
	v_cvt_pk_bf16_f32 v118, v118, s0
	global_store_short v[116:117], v118, off
	s_waitcnt vmcnt(24)
	v_mul_f32_e32 v116, v145, v146
	v_cvt_pk_bf16_f32 v118, v116, s0
	v_lshl_add_u64 v[116:117], v[140:141], 1, s[6:7]
	global_store_short v[116:117], v118, off
	v_or_b32_e32 v116, v227, v103
	v_ashrrev_i32_e32 v117, 31, v116
	v_lshl_add_u64 v[116:117], v[116:117], 2, s[10:11]
	global_load_dword v140, v[116:117], off
	s_waitcnt vmcnt(23)
	v_mul_f32_e32 v116, v147, v166
	v_cvt_pk_bf16_f32 v118, v116, s0
	v_lshl_add_u64 v[116:117], v[136:137], 1, s[6:7]
	global_store_short v[116:117], v118, off
	v_mul_f32_e32 v137, v167, v167
	v_mul_f32_e32 v141, v145, v145
	v_fmac_f32_e32 v137, v147, v147
	global_load_dword v145, v192, s[12:13] offset:128
	s_waitcnt vmcnt(23)
	v_mul_f32_e32 v116, v167, v168
	v_cvt_pk_bf16_f32 v118, v116, s0
	v_or_b32_e32 v116, v228, v103
	v_ashrrev_i32_e32 v117, 31, v116
	v_lshl_add_u64 v[116:117], v[116:117], 2, s[10:11]
	global_load_dword v136, v[116:117], off
	v_lshl_add_u64 v[116:117], v[128:129], 1, s[6:7]
	global_store_short v[116:117], v118, off
	v_or_b32_e32 v118, v229, v103
	s_waitcnt vmcnt(23)
	v_mul_f32_e32 v116, v169, v170
	v_ashrrev_i32_e32 v119, 31, v118
	v_cvt_pk_bf16_f32 v144, v116, s0
	v_or_b32_e32 v116, v230, v102
	v_lshl_add_u64 v[118:119], v[118:119], 2, s[10:11]
	global_load_dword v146, v[118:119], off
	v_ashrrev_i32_e32 v117, 31, v116
	v_or_b32_e32 v118, v230, v103
	v_lshl_add_u64 v[116:117], v[116:117], 2, s[10:11]
	v_ashrrev_i32_e32 v119, 31, v118
	v_lshl_add_u64 v[118:119], v[118:119], 2, s[10:11]
	global_load_dword v147, v[116:117], off
	global_load_dword v148, v[118:119], off
	v_mul_f32_e32 v115, v151, v151
	v_fmac_f32_e32 v115, v163, v163
	s_waitcnt vmcnt(24)
	v_add_f32_e32 v149, v80, v172
	global_store_dword v[200:201], v149, off offset:256
	v_or_b32_e32 v80, 0x440, v194
	global_load_dword v150, v192, s[12:13] offset:256
	s_waitcnt vmcnt(25)
	v_add_f32_e32 v152, v81, v173
	v_ashrrev_i32_e32 v81, 31, v80
	v_lshl_add_u64 v[80:81], v[80:81], 2, s[10:11]
	s_waitcnt vmcnt(19)
	v_add_f32_e32 v135, v64, v135
	v_or_b32_e32 v64, 0x460, v194
	global_store_dword v[200:201], v135, off offset:384
	global_load_dword v151, v192, s[12:13] offset:384
	v_add_f32_e32 v155, v82, v130
	global_store_dword v[80:81], v152, off
	global_load_dword v153, v192, s[12:13] offset:256
	v_or_b32_e32 v82, 0xc40, v194
	s_waitcnt vmcnt(21)
	v_add_f32_e32 v138, v65, v138
	v_ashrrev_i32_e32 v65, 31, v64
	v_lshl_add_u64 v[64:65], v[64:65], 2, s[10:11]
	global_store_dword v[64:65], v138, off
	v_or_b32_e32 v64, 0x840, v194
	v_ashrrev_i32_e32 v65, 31, v64
	v_lshl_add_u64 v[80:81], v[64:65], 2, s[10:11]
	global_load_dword v154, v192, s[12:13] offset:384
	v_add_f32_e32 v158, v83, v131
	global_store_dword v[80:81], v155, off
	v_or_b32_e32 v80, 0x860, v194
	v_ashrrev_i32_e32 v81, 31, v80
	global_load_dword v156, v192, s[12:13] offset:256
	s_waitcnt vmcnt(23)
	v_add_f32_e32 v142, v66, v142
	v_lshl_add_u64 v[116:117], v[80:81], 2, s[10:11]
	v_ashrrev_i32_e32 v83, 31, v82
	v_or_b32_e32 v66, 0xc60, v194
	global_store_dword v[116:117], v142, off
	v_lshl_add_u64 v[116:117], v[82:83], 2, s[10:11]
	global_load_dword v157, v192, s[12:13] offset:384
	v_add_f32_e32 v163, v84, v132
	global_store_dword v[116:117], v158, off
	s_waitcnt vmcnt(23)
	v_add_f32_e32 v143, v67, v143
	v_ashrrev_i32_e32 v67, 31, v66
	v_lshl_add_u64 v[116:117], v[66:67], 2, s[10:11]
	global_load_dword v159, v192, s[12:13] offset:256
	v_or_b32_e32 v84, 0x2440, v194
	global_store_dword v[116:117], v143, off
	v_or_b32_e32 v116, 0x2040, v194
	v_ashrrev_i32_e32 v117, 31, v116
	v_lshl_add_u64 v[118:119], v[116:117], 2, s[10:11]
	global_load_dword v162, v192, s[12:13] offset:384
	v_add_f32_e32 v166, v85, v133
	global_store_dword v[118:119], v163, off
	v_or_b32_e32 v118, 0x2060, v194
	v_ashrrev_i32_e32 v119, 31, v118
	global_load_dword v164, v192, s[12:13] offset:256
	s_waitcnt vmcnt(25)
; DI bfr f2bf(float a) { return (bfr)(pack2(a, 0.f) & 0xffffu); }
; DI int crow(int reg, int h) { return (reg & 3) + 8 * (reg >> 2) + 4 * h; }
; template <bool FIRST, bool HAS_H>
; DI void phase_gemm_resid(const Params& p, const bfr* A, const bfr* Wt, const float* gnext, float* ss, char* smem) {
;     ...
;         for (int jh = 0; jh < 2; ++jh) {
;           float xo[2][8];
; #pragma unroll
;           for (int jj = 0; jj < 2; ++jj)
; #pragma unroll
;             for (int q = 0; q < 8; ++q)
;               xo[jj][q] = xsrc[(rbase + i * 32 + crow(qh * 8 + q, 0)) * 1024 + cbase + (jh * 2 + jj) * 32];
; #pragma unroll
;           for (int q = 0; q < 8; ++q) {
;             const int o = (rbase + i * 32 + crow(qh * 8 + q, 0)) * 1024 + cbase;
; #pragma unroll
;             for (int jj = 0; jj < 2; ++jj) {
;               const int j = jh * 2 + jj;
;               const float xn = xo[jj][q] + acc[i][j][qh * 8 + q];
;               X[o + j * 32] = xn;
;               if (HAS_H) Hn[o + j * 32] = f2bf(xn * gnext[cbase + j * 32]);
;               rs[q] += xn * xn;
;             }
;           }
;         }
	v_add_f32_e32 v140, v68, v140
	v_lshl_add_u64 v[128:129], v[118:119], 2, s[10:11]
	v_ashrrev_i32_e32 v85, 31, v84
	v_or_b32_e32 v68, 0x2460, v194
	global_store_dword v[128:129], v140, off
	v_lshl_add_u64 v[128:129], v[84:85], 2, s[10:11]
	v_fmac_f32_e32 v141, v165, v165
	global_load_dword v165, v192, s[12:13] offset:384
	v_add_f32_e32 v134, v86, v134
	global_store_dword v[128:129], v166, off
	s_waitcnt vmcnt(25)
	v_add_f32_e32 v136, v69, v136
	v_ashrrev_i32_e32 v69, 31, v68
	v_lshl_add_u64 v[128:129], v[68:69], 2, s[10:11]
	global_load_dword v167, v192, s[12:13] offset:256
	v_or_b32_e32 v86, 0x2c40, v194
	global_store_dword v[128:129], v136, off
	v_or_b32_e32 v128, 0x2840, v194
	v_ashrrev_i32_e32 v129, 31, v128
	v_lshl_add_u64 v[130:131], v[128:129], 2, s[10:11]
	global_load_dword v168, v192, s[12:13] offset:384
	s_waitcnt vmcnt(26)
	v_add_f32_e32 v146, v70, v146
	global_store_dword v[130:131], v134, off
	v_or_b32_e32 v130, 0x2860, v194
	v_ashrrev_i32_e32 v131, 31, v130
	global_load_dword v170, v192, s[12:13] offset:256
	v_lshl_add_u64 v[132:133], v[130:131], 2, s[10:11]
	global_store_dword v[132:133], v146, off
	s_waitcnt vmcnt(28)
	v_add_f32_e32 v147, v87, v147
	v_ashrrev_i32_e32 v87, 31, v86
	global_load_dword v172, v192, s[12:13] offset:384
	v_lshl_add_u64 v[132:133], v[86:87], 2, s[10:11]
	v_or_b32_e32 v70, 0x2c60, v194
	global_store_dword v[132:133], v147, off
	s_waitcnt vmcnt(29)
	v_add_f32_e32 v148, v71, v148
	v_ashrrev_i32_e32 v71, 31, v70
	global_load_dword v173, v192, s[12:13] offset:256
	v_lshl_add_u64 v[132:133], v[70:71], 2, s[10:11]
	global_store_dword v[132:133], v148, off
	global_load_dword v132, v192, s[12:13] offset:384
	v_lshl_add_u64 v[98:99], v[98:99], 1, s[6:7]
	global_store_short v[98:99], v144, off
	v_mul_f32_e32 v98, v171, v145
	v_cvt_pk_bf16_f32 v133, v98, s0
	v_lshl_add_u64 v[98:99], v[100:101], 1, s[6:7]
	global_store_short v[98:99], v133, off
	s_waitcnt vmcnt(32)
	v_mul_f32_e32 v99, v149, v150
	v_cvt_pk_bf16_f32 v99, v99, s0
	global_store_short v[112:113], v99, off offset:128
	s_waitcnt vmcnt(31)
	v_mul_f32_e32 v99, v135, v151
	v_cvt_pk_bf16_f32 v99, v99, s0
	global_store_short v[112:113], v99, off offset:192
	s_waitcnt vmcnt(30)
	v_mul_f32_e32 v99, v152, v153
	v_cvt_pk_bf16_f32 v99, v99, s0
	global_store_short v[112:113], v99, off offset:2176
	s_waitcnt vmcnt(29)
	v_mul_f32_e32 v99, v138, v154
	v_cvt_pk_bf16_f32 v99, v99, s0
	global_store_short v[112:113], v99, off offset:2240
	s_waitcnt vmcnt(28)
	v_mul_f32_e32 v99, v155, v156
	v_cvt_pk_bf16_f32 v99, v99, s0
	v_lshl_add_u64 v[64:65], v[64:65], 1, s[6:7]
	global_store_short v[64:65], v99, off
	v_mul_f32_e32 v98, v171, v171
	s_waitcnt vmcnt(27)
	v_mul_f32_e32 v64, v142, v157
	v_cvt_pk_bf16_f32 v99, v64, s0
	v_lshl_add_u64 v[64:65], v[80:81], 1, s[6:7]
	global_store_short v[64:65], v99, off
	v_fmac_f32_e32 v114, v211, v211
	v_fmac_f32_e32 v160, v189, v189
	s_waitcnt vmcnt(26)
	v_mul_f32_e32 v64, v158, v159
	v_cvt_pk_bf16_f32 v80, v64, s0
	v_lshl_add_u64 v[64:65], v[82:83], 1, s[6:7]
	global_store_short v[64:65], v80, off
	v_fmac_f32_e32 v161, v176, v176
	v_fmac_f32_e32 v98, v169, v169
	s_waitcnt vmcnt(25)
	v_mul_f32_e32 v64, v143, v162
	v_cvt_pk_bf16_f32 v80, v64, s0
	v_lshl_add_u64 v[64:65], v[66:67], 1, s[6:7]
	global_store_short v[64:65], v80, off
	v_fmac_f32_e32 v114, v149, v149
	s_waitcnt vmcnt(24)
	v_mul_f32_e32 v64, v163, v164
	v_cvt_pk_bf16_f32 v66, v64, s0
	v_lshl_add_u64 v[64:65], v[116:117], 1, s[6:7]
	global_store_short v[64:65], v66, off
	v_fmac_f32_e32 v160, v152, v152
	v_fmac_f32_e32 v161, v155, v155
	v_fmac_f32_e32 v139, v158, v158
	v_fmac_f32_e32 v115, v163, v163
	s_waitcnt vmcnt(23)
	v_mul_f32_e32 v64, v140, v165
	v_cvt_pk_bf16_f32 v66, v64, s0
	v_lshl_add_u64 v[64:65], v[118:119], 1, s[6:7]
	global_store_short v[64:65], v66, off
	v_fmac_f32_e32 v141, v166, v166
	v_fmac_f32_e32 v137, v134, v134
	s_waitcnt vmcnt(22)
	v_mul_f32_e32 v64, v166, v167
	v_cvt_pk_bf16_f32 v66, v64, s0
	v_lshl_add_u64 v[64:65], v[84:85], 1, s[6:7]
	global_store_short v[64:65], v66, off
	v_fmac_f32_e32 v98, v147, v147
	v_fmac_f32_e32 v114, v135, v135
	s_waitcnt vmcnt(21)
	v_mul_f32_e32 v64, v136, v168
	v_cvt_pk_bf16_f32 v66, v64, s0
	v_lshl_add_u64 v[64:65], v[68:69], 1, s[6:7]
	global_store_short v[64:65], v66, off
	v_fmac_f32_e32 v160, v138, v138
	s_waitcnt vmcnt(20)
	v_mul_f32_e32 v64, v134, v170
	v_cvt_pk_bf16_f32 v66, v64, s0
	v_lshl_add_u64 v[64:65], v[128:129], 1, s[6:7]
	global_store_short v[64:65], v66, off
	v_fmac_f32_e32 v161, v142, v142
	s_waitcnt vmcnt(19)
	v_mul_f32_e32 v64, v146, v172
	v_cvt_pk_bf16_f32 v66, v64, s0
	v_lshl_add_u64 v[64:65], v[130:131], 1, s[6:7]
	global_store_short v[64:65], v66, off
	v_fmac_f32_e32 v139, v143, v143
	v_fmac_f32_e32 v115, v140, v140
	s_waitcnt vmcnt(18)
; #define DPPF(v, ctrl, rmask) __builtin_bit_cast(float, __builtin_amdgcn_update_dpp(0, __builtin_bit_cast(int, (v)), (ctrl), (rmask), 0xf, false))
; DI int crow(int reg, int h) { return (reg & 3) + 8 * (reg >> 2) + 4 * h; }
; DI float row16_sum(float v) {
;   v += DPPF(v, 0xB1, 0xf);
;   v += DPPF(v, 0x4E, 0xf);
;   v += DPPF(v, 0x141, 0xf);
;   v += DPPF(v, 0x140, 0xf);
;   return v;
; }
; DI float half32_sum_hi(float v) {
;   v = row16_sum(v);
;   v += DPPF(v, 0x142, 0xa);
;   return v;
; template <bool FIRST, bool HAS_H>
; DI void phase_gemm_resid(const Params& p, const bfr* A, const bfr* Wt, const float* gnext, float* ss, char* smem) {
;     ...
; #pragma unroll
;         for (int q = 0; q < 8; ++q) rs[q] = half32_sum_hi(rs[q]);
;         if (r == 31) {
; #pragma unroll
;           for (int q = 0; q < 8; ++q) unsafeAtomicAdd(ss + rbase + i * 32 + crow(qh * 8 + q, 0), rs[q]);
;         }
	v_mul_f32_e32 v64, v147, v173
	v_cvt_pk_bf16_f32 v66, v64, s0
	v_lshl_add_u64 v[64:65], v[86:87], 1, s[6:7]
	global_store_short v[64:65], v66, off
	s_waitcnt vmcnt(17)
	v_mul_f32_e32 v64, v148, v132
	v_fmac_f32_e32 v141, v136, v136
	v_fmac_f32_e32 v137, v146, v146
	v_cvt_pk_bf16_f32 v66, v64, s0
	v_lshl_add_u64 v[64:65], v[70:71], 1, s[6:7]
	v_fmac_f32_e32 v98, v148, v148
	global_store_short v[64:65], v66, off
	v_add_f32_dpp v64, v114, v114 quad_perm:[1,0,3,2] row_mask:0xf bank_mask:0xf bound_ctrl:1
	v_add_f32_dpp v66, v160, v160 quad_perm:[1,0,3,2] row_mask:0xf bank_mask:0xf bound_ctrl:1
	v_add_f32_dpp v68, v161, v161 quad_perm:[1,0,3,2] row_mask:0xf bank_mask:0xf bound_ctrl:1
	v_add_f32_dpp v70, v139, v139 quad_perm:[1,0,3,2] row_mask:0xf bank_mask:0xf bound_ctrl:1
	v_add_f32_dpp v80, v115, v115 quad_perm:[1,0,3,2] row_mask:0xf bank_mask:0xf bound_ctrl:1
	v_add_f32_dpp v82, v141, v141 quad_perm:[1,0,3,2] row_mask:0xf bank_mask:0xf bound_ctrl:1
	v_add_f32_dpp v84, v137, v137 quad_perm:[1,0,3,2] row_mask:0xf bank_mask:0xf bound_ctrl:1
	v_add_f32_dpp v86, v98, v98 quad_perm:[1,0,3,2] row_mask:0xf bank_mask:0xf bound_ctrl:1
	v_add_f32_dpp v64, v64, v64 quad_perm:[2,3,0,1] row_mask:0xf bank_mask:0xf bound_ctrl:1
	v_add_f32_dpp v66, v66, v66 quad_perm:[2,3,0,1] row_mask:0xf bank_mask:0xf bound_ctrl:1
	v_add_f32_dpp v68, v68, v68 quad_perm:[2,3,0,1] row_mask:0xf bank_mask:0xf bound_ctrl:1
	v_add_f32_dpp v70, v70, v70 quad_perm:[2,3,0,1] row_mask:0xf bank_mask:0xf bound_ctrl:1
	v_add_f32_dpp v80, v80, v80 quad_perm:[2,3,0,1] row_mask:0xf bank_mask:0xf bound_ctrl:1
	v_add_f32_dpp v82, v82, v82 quad_perm:[2,3,0,1] row_mask:0xf bank_mask:0xf bound_ctrl:1
	v_add_f32_dpp v84, v84, v84 quad_perm:[2,3,0,1] row_mask:0xf bank_mask:0xf bound_ctrl:1
	v_add_f32_dpp v86, v86, v86 quad_perm:[2,3,0,1] row_mask:0xf bank_mask:0xf bound_ctrl:1
	v_add_f32_dpp v64, v64, v64 row_half_mirror row_mask:0xf bank_mask:0xf bound_ctrl:1
	v_add_f32_dpp v66, v66, v66 row_half_mirror row_mask:0xf bank_mask:0xf bound_ctrl:1
	v_add_f32_dpp v68, v68, v68 row_half_mirror row_mask:0xf bank_mask:0xf bound_ctrl:1
	v_add_f32_dpp v70, v70, v70 row_half_mirror row_mask:0xf bank_mask:0xf bound_ctrl:1
	v_add_f32_dpp v80, v80, v80 row_half_mirror row_mask:0xf bank_mask:0xf bound_ctrl:1
	v_add_f32_dpp v82, v82, v82 row_half_mirror row_mask:0xf bank_mask:0xf bound_ctrl:1
	v_add_f32_dpp v84, v84, v84 row_half_mirror row_mask:0xf bank_mask:0xf bound_ctrl:1
	v_add_f32_dpp v86, v86, v86 row_half_mirror row_mask:0xf bank_mask:0xf bound_ctrl:1
	v_add_f32_dpp v64, v64, v64 row_mirror row_mask:0xf bank_mask:0xf bound_ctrl:1
	v_mov_b32_e32 v65, 0
	v_add_f32_dpp v66, v66, v66 row_mirror row_mask:0xf bank_mask:0xf bound_ctrl:1
	v_mov_b32_e32 v67, 0
	v_add_f32_dpp v68, v68, v68 row_mirror row_mask:0xf bank_mask:0xf bound_ctrl:1
	v_mov_b32_e32 v69, 0
	v_add_f32_dpp v70, v70, v70 row_mirror row_mask:0xf bank_mask:0xf bound_ctrl:1
	v_mov_b32_e32 v71, 0
	v_add_f32_dpp v80, v80, v80 row_mirror row_mask:0xf bank_mask:0xf bound_ctrl:1
	v_mov_b32_e32 v81, 0
	v_add_f32_dpp v82, v82, v82 row_mirror row_mask:0xf bank_mask:0xf bound_ctrl:1
	v_mov_b32_e32 v83, 0
	v_add_f32_dpp v84, v84, v84 row_mirror row_mask:0xf bank_mask:0xf bound_ctrl:1
	v_mov_b32_e32 v85, 0
	v_add_f32_dpp v86, v86, v86 row_mirror row_mask:0xf bank_mask:0xf bound_ctrl:1
	v_mov_b32_e32 v87, 0
	v_mov_b32_dpp v65, v64 row_bcast:15 row_mask:0xa bank_mask:0xf
	v_mov_b32_dpp v67, v66 row_bcast:15 row_mask:0xa bank_mask:0xf
	v_mov_b32_dpp v69, v68 row_bcast:15 row_mask:0xa bank_mask:0xf
	v_mov_b32_dpp v71, v70 row_bcast:15 row_mask:0xa bank_mask:0xf
	v_mov_b32_dpp v81, v80 row_bcast:15 row_mask:0xa bank_mask:0xf
	v_mov_b32_dpp v83, v82 row_bcast:15 row_mask:0xa bank_mask:0xf
	v_mov_b32_dpp v85, v84 row_bcast:15 row_mask:0xa bank_mask:0xf
	v_mov_b32_dpp v87, v86 row_bcast:15 row_mask:0xa bank_mask:0xf
	s_and_saveexec_b64 s[4:5], vcc
	s_cbranch_execz .LBB0_1479
	v_add_f32_e32 v64, v64, v65
	v_add_f32_e32 v86, v86, v87
	v_add_f32_e32 v84, v84, v85
	v_add_f32_e32 v82, v82, v83
	v_add_f32_e32 v80, v80, v81
	v_add_f32_e32 v70, v70, v71
	v_add_f32_e32 v68, v68, v69
	v_add_f32_e32 v66, v66, v67
	global_atomic_add_f32 v[96:97], v64, off
	global_atomic_add_f32 v[96:97], v66, off offset:4
	global_atomic_add_f32 v[96:97], v68, off offset:8
	global_atomic_add_f32 v[96:97], v70, off offset:12
	global_atomic_add_f32 v[96:97], v80, off offset:32
	global_atomic_add_f32 v[96:97], v82, off offset:36
	global_atomic_add_f32 v[96:97], v84, off offset:40
	global_atomic_add_f32 v[96:97], v86, off offset:44

; DI bfr f2bf(float a) { return (bfr)(pack2(a, 0.f) & 0xffffu); }
; DI int crow(int reg, int h) { return (reg & 3) + 8 * (reg >> 2) + 4 * h; }
; template <int lda, class Epi>
; DI void gemm_tile(const bfr* __restrict__ A, const bfr* __restrict__ Bt, int NB, int K, int m0, int n0, char* smem, Epi epi) {
;     ...
; #pragma unroll
;   for (int i = 0; i < 2; ++i)
; #pragma unroll
;     for (int j = 0; j < 4; ++j)
; #pragma unroll
;       for (int q = 0; q < 16; ++q) {
;         int row = m0 + wr * 64 + i * 32 + crow(q, hl);
;         int col = n0 + wc * 128 + j * 32 + r;
;         epi(row, col, acc[i][j][q]);
;       }
; DI void phase_gemm_bf16out(const Params& p, const bfr* A, const bfr* Wt, bfr* C, int N, const float* ss, char* smem) {
;     ...
;   for (int t0 = blockIdx.x; t0 < 128 * ntn; t0 += gridDim.x) {
;     const int t = ((gridDim.x & 7) == 0) ? xcd_tile(t0, ntn) : t0;
;     int mt = t / ntn, nt = t % ntn;
;     gemm_tile<1024>(A, Wt, N, 1024, mt * 128, nt * 256, smem,
;               [=](int row, int col, float v) {
;                 float inv = rsqrtf(ss[row] * (1.0f / 1024.0f) + EPSF);
;                 C[(size_t)row * N + col] = f2bf(v * inv);
;               });
.LBB0_1545:
	s_nop 0
	s_waitcnt vmcnt(3)
	s_nop 0
	s_waitcnt vmcnt(2)
	s_nop 0
	s_waitcnt vmcnt(1)
	s_nop 0
	s_waitcnt vmcnt(0)
	s_nop 0
	v_add_u32_e32 v144, v169, v171
	s_nop 0
	v_add_u32_e32 v199, v169, v170
	s_nop 0
	s_nop 0
	s_nop 0
	s_nop 0
	s_nop 0
	s_nop 0
	s_nop 0
	s_nop 0
	s_nop 0
	s_nop 0
	s_nop 0
	s_waitcnt lgkmcnt(0)
	s_nop 0
	s_nop 0
	s_nop 0
	s_nop 0
	s_add_i32 s30, s30, s34
	s_cmpk_lt_i32 s30, 0x200
	s_nop 0
	s_nop 0
	s_nop 0
	s_nop 0
	s_nop 0
	s_nop 0
	s_nop 0
	s_nop 0
	s_nop 0
	s_nop 0
	s_nop 0
	s_nop 0
	s_nop 0
	s_nop 0
	v_mov_b32_e32 v199, v196
	s_waitcnt lgkmcnt(0)
	s_nop 0
	s_nop 0
	v_ashrrev_i32_e32 v200, 1, v199
	v_and_b32_e32 v200, 0xffffffc0, v200
	s_nop 0
	v_lshrrev_b32_e32 v202, 3, v199
	v_add_u32_e32 v200, s33, v200
	v_and_or_b32 v202, v202, 4, v200
	v_ashrrev_i32_e32 v203, 31, v202
	v_lshl_add_u64 v[204:205], v[202:203], 2, s[8:9]
	global_load_dwordx4 v[224:227], v[204:205], off
	v_or_b32_e32 v228, 8, v202
	v_ashrrev_i32_e32 v229, 31, v228
	s_nop 0
	v_lshl_add_u64 v[204:205], v[228:229], 2, s[8:9]
	v_and_b32_e32 v200, 31, v199
	v_lshlrev_b32_e32 v199, 1, v199
	v_and_b32_e32 v199, 0x80, v199
	s_nop 0
	global_load_dwordx4 v[220:223], v[204:205], off
	v_or3_b32 v204, v200, v199, s31
	v_ashrrev_i32_e32 v205, 31, v204
	v_lshl_add_u64 v[204:205], v[204:205], 1, s[12:13]
	s_nop 0
	s_nop 0
	v_mov_b64_e32 v[206:207], s[18:19]
	v_or_b32_e32 v210, 1, v202
	v_lshlrev_b64 v[208:209], 11, v[202:203]
	v_ashrrev_i32_e32 v211, 31, v210
	v_lshl_add_u64 v[208:209], v[204:205], 0, v[208:209]
	v_lshlrev_b64 v[210:211], 11, v[210:211]
	v_lshl_add_u64 v[210:211], v[204:205], 0, v[210:211]
	s_nop 0
	v_or_b32_e32 v212, 2, v202
	v_ashrrev_i32_e32 v213, 31, v212
	v_lshlrev_b64 v[212:213], 11, v[212:213]
	s_waitcnt vmcnt(1)
	v_fma_f32 v224, v224, s16, v206
	v_fma_f32 v225, v225, s16, v206
	v_mul_f32_e32 v199, 0x4b800000, v224
	v_cmp_gt_f32_e32 vcc, s29, v224
	v_mul_f32_e32 v200, 0x4b800000, v225
	v_cmp_gt_f32_e64 s[4:5], s29, v225
	v_cndmask_b32_e32 v199, v224, v199, vcc
	v_rsq_f32_e32 v199, v199
	v_cndmask_b32_e64 v200, v225, v200, s[4:5]
	v_rsq_f32_e32 v224, v200
	v_pk_fma_f32 v[226:227], v[226:227], s[16:17], v[206:207] op_sel_hi:[1,0,0]
	v_mul_f32_e32 v200, 0x45800000, v199
	v_cndmask_b32_e32 v200, v199, v200, vcc
	v_mul_f32_e32 v225, 0x45800000, v224
	v_cndmask_b32_e64 v199, v224, v225, s[4:5]
	v_mul_f32_e32 v112, v112, v200
	v_mul_f32_e32 v203, 0x4b800000, v226
	v_mul_f32_e32 v113, v113, v199
	v_cvt_pk_bf16_f32 v112, v112, s0
	v_cmp_gt_f32_e32 vcc, s29, v226
	v_cvt_pk_bf16_f32 v113, v113, s0
	global_store_short v[208:209], v112, off
	global_store_short v[210:211], v113, off
	v_cndmask_b32_e32 v112, v226, v203, vcc
	v_rsq_f32_e32 v203, v112
	s_nop 0
	v_mul_f32_e32 v226, 0x4b800000, v227
	v_lshl_add_u64 v[112:113], v[204:205], 0, v[212:213]
	v_mul_f32_e32 v224, 0x45800000, v203
	v_cndmask_b32_e32 v203, v203, v224, vcc
	v_or_b32_e32 v224, 16, v202
	v_ashrrev_i32_e32 v225, 31, v224
	v_cmp_gt_f32_e32 vcc, s29, v227
	s_nop 0
	v_mul_f32_e32 v114, v114, v203
	v_cndmask_b32_e32 v226, v227, v226, vcc
	v_cvt_pk_bf16_f32 v114, v114, s0
	global_store_short v[112:113], v114, off
	v_or_b32_e32 v212, 3, v202
	v_ashrrev_i32_e32 v213, 31, v212
	s_nop 0
	v_lshl_add_u64 v[216:217], v[224:225], 2, s[8:9]
	global_load_dwordx4 v[216:219], v[216:217], off
	s_nop 0
	v_rsq_f32_e32 v176, v226
	s_waitcnt vmcnt(4)
	v_pk_fma_f32 v[178:179], v[220:221], s[16:17], v[206:207] op_sel_hi:[1,0,0]
	v_mul_f32_e32 v114, 0x45800000, v176
	v_cndmask_b32_e32 v226, v176, v114, vcc
	v_cmp_gt_f32_e32 vcc, s29, v178
	s_nop 0
	v_or_b32_e32 v180, 24, v202
	v_ashrrev_i32_e32 v181, 31, v180
	v_lshl_add_u64 v[182:183], v[180:181], 2, s[8:9]
	v_mul_f32_e32 v114, v115, v226
	v_cvt_pk_bf16_f32 v176, v114, s0
	v_lshlrev_b64 v[114:115], 11, v[212:213]
	v_lshl_add_u64 v[114:115], v[204:205], 0, v[114:115]
	s_nop 0
	global_load_dwordx4 v[164:167], v[182:183], off
	s_nop 0
	global_store_short v[114:115], v176, off
	v_lshlrev_b64 v[176:177], 11, v[228:229]
	v_lshl_add_u64 v[176:177], v[204:205], 0, v[176:177]
	s_nop 0
	v_mul_f32_e32 v192, 0x4b800000, v178
	v_cndmask_b32_e32 v178, v178, v192, vcc
	v_rsq_f32_e32 v178, v178
	s_nop 0
	v_mul_f32_e32 v190, 0x45800000, v178
	v_cndmask_b32_e32 v190, v178, v190, vcc
	v_mul_f32_e32 v172, 0x4b800000, v179
	v_cmp_gt_f32_e32 vcc, s29, v179
	v_mul_f32_e32 v116, v116, v190
	v_cvt_pk_bf16_f32 v116, v116, s0
	v_cndmask_b32_e32 v172, v179, v172, vcc
	v_rsq_f32_e32 v172, v172
	global_store_short v[176:177], v116, off
	v_pk_fma_f32 v[178:179], v[222:223], s[16:17], v[206:207] op_sel_hi:[1,0,0]
	v_or_b32_e32 v188, 9, v202
	v_mul_f32_e32 v116, 0x45800000, v172
	v_cndmask_b32_e32 v191, v172, v116, vcc
	v_mul_f32_e32 v175, 0x4b800000, v178
	v_cmp_gt_f32_e32 vcc, s29, v178
	v_ashrrev_i32_e32 v189, 31, v188
	v_mul_f32_e32 v116, v117, v191
	v_cndmask_b32_e32 v175, v178, v175, vcc
	v_rsq_f32_e32 v178, v175
	v_cvt_pk_bf16_f32 v172, v116, s0
	v_lshlrev_b64 v[116:117], 11, v[188:189]
	v_lshl_add_u64 v[116:117], v[204:205], 0, v[116:117]
	v_mul_f32_e32 v182, 0x45800000, v178
	v_cndmask_b32_e32 v178, v178, v182, vcc
	v_mul_f32_e32 v182, 0x4b800000, v179
	v_cmp_gt_f32_e32 vcc, s29, v179
	s_nop 0
	global_store_short v[116:117], v172, off
	v_cndmask_b32_e32 v179, v179, v182, vcc
	v_or_b32_e32 v172, 10, v202
	v_ashrrev_i32_e32 v173, 31, v172
	v_lshlrev_b64 v[172:173], 11, v[172:173]
	v_mul_f32_e32 v118, v118, v178
	v_lshl_add_u64 v[172:173], v[204:205], 0, v[172:173]
	s_nop 0
	v_rsq_f32_e32 v168, v179
	v_cvt_pk_bf16_f32 v118, v118, s0
	global_store_short v[172:173], v118, off
	v_or_b32_e32 v174, 11, v202
	v_mul_f32_e32 v118, 0x45800000, v168
	v_cndmask_b32_e32 v168, v168, v118, vcc
	v_ashrrev_i32_e32 v175, 31, v174
	v_mul_f32_e32 v118, v119, v168
	s_nop 0
	s_nop 0
	v_cvt_pk_bf16_f32 v162, v118, s0
	v_lshlrev_b64 v[118:119], 11, v[174:175]
	v_lshl_add_u64 v[160:161], v[204:205], 0, v[118:119]
	global_store_short v[160:161], v162, off
	s_waitcnt vmcnt(6)
; DI bfr f2bf(float a) { return (bfr)(pack2(a, 0.f) & 0xffffu); }
; DI int crow(int reg, int h) { return (reg & 3) + 8 * (reg >> 2) + 4 * h; }
; template <int lda, class Epi>
; DI void gemm_tile(const bfr* __restrict__ A, const bfr* __restrict__ Bt, int NB, int K, int m0, int n0, char* smem, Epi epi) {
;     ...
; #pragma unroll
;   for (int i = 0; i < 2; ++i)
; #pragma unroll
;     for (int j = 0; j < 4; ++j)
; #pragma unroll
;       for (int q = 0; q < 16; ++q) {
;         int row = m0 + wr * 64 + i * 32 + crow(q, hl);
;         int col = n0 + wc * 128 + j * 32 + r;
;         epi(row, col, acc[i][j][q]);
;       }
; DI void phase_gemm_bf16out(const Params& p, const bfr* A, const bfr* Wt, bfr* C, int N, const float* ss, char* smem) {
;     ...
;     gemm_tile<1024>(A, Wt, N, 1024, mt * 128, nt * 256, smem,
;               [=](int row, int col, float v) {
;                 float inv = rsqrtf(ss[row] * (1.0f / 1024.0f) + EPSF);
;                 C[(size_t)row * N + col] = f2bf(v * inv);
;               });
	v_pk_fma_f32 v[162:163], v[216:217], s[16:17], v[206:207] op_sel_hi:[1,0,0]
	v_lshlrev_b64 v[118:119], 11, v[224:225]
	v_mul_f32_e32 v169, 0x4b800000, v162
	v_cmp_gt_f32_e32 vcc, s29, v162
	s_nop 0
	v_lshl_add_u64 v[118:119], v[204:205], 0, v[118:119]
	v_cndmask_b32_e32 v152, v162, v169, vcc
	v_rsq_f32_e32 v154, v152
	v_or_b32_e32 v152, 17, v202
	v_ashrrev_i32_e32 v153, 31, v152
	v_mul_f32_e32 v155, 0x45800000, v154
	s_nop 0
	v_cndmask_b32_e32 v154, v154, v155, vcc
	v_mul_f32_e32 v155, 0x4b800000, v163
	v_cmp_gt_f32_e32 vcc, s29, v163
	v_mul_f32_e32 v120, v120, v154
	v_cvt_pk_bf16_f32 v120, v120, s0
	v_cndmask_b32_e32 v155, v163, v155, vcc
	v_rsq_f32_e32 v155, v155
	global_store_short v[118:119], v120, off
	s_nop 0
	v_mul_f32_e32 v120, 0x45800000, v155
	v_cndmask_b32_e32 v155, v155, v120, vcc
	v_mul_f32_e32 v120, v121, v155
	v_cvt_pk_bf16_f32 v156, v120, s0
	v_lshlrev_b64 v[120:121], 11, v[152:153]
	v_lshl_add_u64 v[120:121], v[204:205], 0, v[120:121]
	s_nop 0
	s_nop 4
	v_mul_f32_e32 v96, v96, v200
	v_cvt_pk_bf16_f32 v96, v96, s0
	global_store_short v[208:209], v96, off offset:64
	v_mul_f32_e32 v96, v97, v199
	v_cvt_pk_bf16_f32 v96, v96, s0
	global_store_short v[210:211], v96, off offset:64
	v_mul_f32_e32 v96, v98, v203
	s_nop 0
	v_fma_f32 v142, v218, s16, v206
	v_fma_f32 v143, v219, s16, v206
	v_or_b32_e32 v140, 18, v202
	v_mul_f32_e32 v152, 0x4b800000, v142
	v_cmp_gt_f32_e32 vcc, s29, v142
	v_ashrrev_i32_e32 v141, 31, v140
	v_lshlrev_b64 v[140:141], 11, v[140:141]
	v_cndmask_b32_e32 v142, v142, v152, vcc
	v_rsq_f32_e32 v142, v142
	s_nop 0
	v_lshl_add_u64 v[136:137], v[204:205], 0, v[140:141]
	v_mul_f32_e32 v80, v80, v200
	v_mul_f32_e32 v140, 0x45800000, v142
	v_cndmask_b32_e32 v142, v142, v140, vcc
	v_mul_f32_e32 v140, 0x4b800000, v143
	v_cmp_gt_f32_e32 vcc, s29, v143
	v_mul_f32_e32 v122, v122, v142
	v_cvt_pk_bf16_f32 v122, v122, s0
	v_cndmask_b32_e32 v140, v143, v140, vcc
	v_rsq_f32_e32 v140, v140
	global_store_short v[136:137], v122, off
	v_or_b32_e32 v138, 19, v202
	v_cvt_pk_bf16_f32 v80, v80, s0
	v_mul_f32_e32 v122, 0x45800000, v140
	v_cndmask_b32_e32 v143, v140, v122, vcc
	v_ashrrev_i32_e32 v139, 31, v138
	v_mul_f32_e32 v122, v123, v143
	global_store_short v[208:209], v80, off offset:128
	v_mul_f32_e32 v80, v81, v199
	v_cvt_pk_bf16_f32 v140, v122, s0
	v_lshlrev_b64 v[122:123], 11, v[138:139]
	v_cvt_pk_bf16_f32 v80, v80, s0
	v_lshl_add_u64 v[122:123], v[204:205], 0, v[122:123]
	global_store_short v[210:211], v80, off offset:128
	v_mul_f32_e32 v80, v82, v203
	global_store_short v[122:123], v140, off
	s_waitcnt vmcnt(12)
	v_pk_fma_f32 v[140:141], v[164:165], s[16:17], v[206:207] op_sel_hi:[1,0,0]
	v_cvt_pk_bf16_f32 v80, v80, s0
	s_nop 0
	v_cmp_gt_f32_e32 vcc, s29, v140
	global_store_short v[112:113], v80, off offset:128
	v_mul_f32_e32 v80, v83, v226
	v_cvt_pk_bf16_f32 v80, v80, s0
	global_store_short v[114:115], v80, off offset:128
	v_mul_f32_e32 v80, v84, v190
	v_cvt_pk_bf16_f32 v80, v80, s0
	s_nop 0
	global_store_short v[176:177], v80, off offset:128
	v_mul_f32_e32 v80, v85, v191
	v_cvt_pk_bf16_f32 v80, v80, s0
	v_lshlrev_b64 v[138:139], 11, v[180:181]
	global_store_short v[116:117], v80, off offset:128
	v_mul_f32_e32 v80, v86, v178
	v_or_b32_e32 v84, 32, v202
	s_nop 0
	v_mul_f32_e32 v128, 0x4b800000, v140
	v_cndmask_b32_e32 v128, v140, v128, vcc
	v_rsq_f32_e32 v132, v128
	v_lshl_add_u64 v[128:129], v[204:205], 0, v[138:139]
	v_cvt_pk_bf16_f32 v80, v80, s0
	v_ashrrev_i32_e32 v85, 31, v84
	v_mul_f32_e32 v133, 0x45800000, v132
	v_cndmask_b32_e32 v138, v132, v133, vcc
	v_mul_f32_e32 v132, 0x4b800000, v141
	v_cmp_gt_f32_e32 vcc, s29, v141
	global_store_short v[172:173], v80, off offset:128
	v_lshl_add_u64 v[80:81], v[84:85], 2, s[8:9]
	v_cndmask_b32_e32 v132, v141, v132, vcc
	v_rsq_f32_e32 v132, v132
	global_load_dwordx4 v[80:83], v[80:81], off
	v_mul_f32_e32 v124, v124, v138
	v_cvt_pk_bf16_f32 v124, v124, s0
	global_store_short v[128:129], v124, off
	v_mul_f32_e32 v124, 0x45800000, v132
	v_or_b32_e32 v130, 25, v202
	v_cndmask_b32_e32 v139, v132, v124, vcc
	v_ashrrev_i32_e32 v131, 31, v130
	v_mul_f32_e32 v124, v125, v139
	v_cvt_pk_bf16_f32 v132, v124, s0
	v_lshlrev_b64 v[124:125], 11, v[130:131]
	v_lshl_add_u64 v[124:125], v[204:205], 0, v[124:125]
	global_store_short v[124:125], v132, off
	v_pk_fma_f32 v[132:133], v[166:167], s[16:17], v[206:207] op_sel_hi:[1,0,0]
	v_mul_f32_e32 v86, v87, v168
	v_mul_f32_e32 v134, 0x4b800000, v132
	v_cmp_gt_f32_e32 vcc, s29, v132
	v_cvt_pk_bf16_f32 v86, v86, s0
	global_store_short v[160:161], v86, off offset:128
	v_cndmask_b32_e32 v132, v132, v134, vcc
	v_rsq_f32_e32 v132, v132
	v_mul_f32_e32 v86, v88, v154
	v_cvt_pk_bf16_f32 v86, v86, s0
	v_mul_f32_e32 v64, v64, v200
	global_store_short v[118:119], v86, off offset:128
	v_mul_f32_e32 v86, v89, v155
	v_cvt_pk_bf16_f32 v64, v64, s0
	v_cvt_pk_bf16_f32 v86, v86, s0
	global_store_short v[208:209], v64, off offset:192
	v_mul_f32_e32 v64, v65, v199
	v_mul_f32_e32 v140, 0x45800000, v132
	global_store_short v[120:121], v86, off offset:128
	v_mul_f32_e32 v86, v90, v142
	v_cvt_pk_bf16_f32 v64, v64, s0
	v_cndmask_b32_e32 v132, v132, v140, vcc
	v_mul_f32_e32 v140, 0x4b800000, v133
	v_cmp_gt_f32_e32 vcc, s29, v133
	v_cvt_pk_bf16_f32 v86, v86, s0
	global_store_short v[210:211], v64, off offset:192
	v_mul_f32_e32 v64, v66, v203
	v_cndmask_b32_e32 v133, v133, v140, vcc
	global_store_short v[136:137], v86, off offset:128
	v_mul_f32_e32 v86, v91, v143
	v_cvt_pk_bf16_f32 v64, v64, s0
	v_or_b32_e32 v130, 26, v202
	v_rsq_f32_e32 v133, v133
	v_cvt_pk_bf16_f32 v86, v86, s0
	global_store_short v[112:113], v64, off offset:192
	v_mul_f32_e32 v64, v67, v226
; DI bfr f2bf(float a) { return (bfr)(pack2(a, 0.f) & 0xffffu); }
; DI int crow(int reg, int h) { return (reg & 3) + 8 * (reg >> 2) + 4 * h; }
; template <int lda, class Epi>
; DI void gemm_tile(const bfr* __restrict__ A, const bfr* __restrict__ Bt, int NB, int K, int m0, int n0, char* smem, Epi epi) {
;     ...
; #pragma unroll
;   for (int i = 0; i < 2; ++i)
; #pragma unroll
;     for (int j = 0; j < 4; ++j)
; #pragma unroll
;       for (int q = 0; q < 16; ++q) {
;         int row = m0 + wr * 64 + i * 32 + crow(q, hl);
;         int col = n0 + wc * 128 + j * 32 + r;
;         epi(row, col, acc[i][j][q]);
;       }
; DI void phase_gemm_bf16out(const Params& p, const bfr* A, const bfr* Wt, bfr* C, int N, const float* ss, char* smem) {
;     ...
;     gemm_tile<1024>(A, Wt, N, 1024, mt * 128, nt * 256, smem,
;               [=](int row, int col, float v) {
;                 float inv = rsqrtf(ss[row] * (1.0f / 1024.0f) + EPSF);
;                 C[(size_t)row * N + col] = f2bf(v * inv);
;               });
	v_ashrrev_i32_e32 v131, 31, v130
	global_store_short v[122:123], v86, off offset:128
	v_mul_f32_e32 v86, v92, v138
	v_cvt_pk_bf16_f32 v64, v64, s0
	v_lshlrev_b64 v[130:131], 11, v[130:131]
	v_mul_f32_e32 v126, v126, v132
	v_cvt_pk_bf16_f32 v86, v86, s0
	global_store_short v[114:115], v64, off offset:192
	v_mul_f32_e32 v64, v68, v190
	v_lshl_add_u64 v[130:131], v[204:205], 0, v[130:131]
	v_cvt_pk_bf16_f32 v126, v126, s0
	global_store_short v[128:129], v86, off offset:128
	v_mul_f32_e32 v86, v93, v139
	v_cvt_pk_bf16_f32 v64, v64, s0
	global_store_short v[130:131], v126, off
	v_mul_f32_e32 v126, 0x45800000, v133
	v_cvt_pk_bf16_f32 v86, v86, s0
	global_store_short v[176:177], v64, off offset:192
	v_mul_f32_e32 v64, v69, v191
	v_or_b32_e32 v134, 27, v202
	v_cndmask_b32_e32 v133, v133, v126, vcc
	global_store_short v[124:125], v86, off offset:128
	v_mul_f32_e32 v86, v94, v132
	v_cvt_pk_bf16_f32 v64, v64, s0
	v_ashrrev_i32_e32 v135, 31, v134
	v_mul_f32_e32 v126, v127, v133
	v_cvt_pk_bf16_f32 v86, v86, s0
	global_store_short v[116:117], v64, off offset:192
	v_mul_f32_e32 v64, v70, v178
	v_cvt_pk_bf16_f32 v140, v126, s0
	v_lshlrev_b64 v[126:127], 11, v[134:135]
	global_store_short v[130:131], v86, off offset:128
	v_mul_f32_e32 v86, v95, v133
	v_cvt_pk_bf16_f32 v64, v64, s0
	v_lshl_add_u64 v[126:127], v[204:205], 0, v[126:127]
	v_cvt_pk_bf16_f32 v86, v86, s0
	global_store_short v[172:173], v64, off offset:192
	v_mul_f32_e32 v64, v71, v168
	global_store_short v[126:127], v86, off offset:128
	v_cvt_pk_bf16_f32 v64, v64, s0
	v_or_b32_e32 v86, 40, v202
	global_store_short v[160:161], v64, off offset:192
	v_mul_f32_e32 v64, v72, v154
	v_ashrrev_i32_e32 v87, 31, v86
	v_cvt_pk_bf16_f32 v66, v64, s0
	v_lshl_add_u64 v[64:65], v[86:87], 2, s[8:9]
	global_load_dwordx4 v[68:71], v[64:65], off
	v_mul_f32_e32 v64, v73, v155
	v_cvt_pk_bf16_f32 v64, v64, s0
	global_store_short v[118:119], v66, off offset:192
	global_store_short v[120:121], v64, off offset:192
	v_mul_f32_e32 v64, v74, v142
	s_waitcnt vmcnt(23)
	v_pk_fma_f32 v[66:67], v[80:81], s[16:17], v[206:207] op_sel_hi:[1,0,0]
	v_cvt_pk_bf16_f32 v64, v64, s0
	v_mul_f32_e32 v72, 0x4b800000, v66
	v_cmp_gt_f32_e32 vcc, s29, v66
	global_store_short v[136:137], v64, off offset:192
	v_mul_f32_e32 v64, v75, v143
	v_cndmask_b32_e32 v66, v66, v72, vcc
	v_cvt_pk_bf16_f32 v64, v64, s0
	v_rsq_f32_e32 v66, v66
	global_store_short v[122:123], v64, off offset:192
	v_mul_f32_e32 v64, v76, v138
	v_cvt_pk_bf16_f32 v64, v64, s0
	global_store_short v[128:129], v64, off offset:192
	v_mul_f32_e32 v64, v77, v139
	v_cvt_pk_bf16_f32 v64, v64, s0
	v_mul_f32_e32 v74, 0x45800000, v66
	global_store_short v[124:125], v64, off offset:192
	v_mul_f32_e32 v64, v78, v132
	v_cndmask_b32_e32 v88, v66, v74, vcc
	v_mul_f32_e32 v66, 0x4b800000, v67
	v_cmp_gt_f32_e32 vcc, s29, v67
	v_cvt_pk_bf16_f32 v64, v64, s0
	global_store_short v[130:131], v64, off offset:192
	v_cndmask_b32_e32 v66, v67, v66, vcc
	v_mul_f32_e32 v64, v79, v133
	v_rsq_f32_e32 v66, v66
	v_cvt_pk_bf16_f32 v64, v64, s0
	global_store_short v[126:127], v64, off offset:192
	v_lshlrev_b64 v[64:65], 11, v[84:85]
	v_mul_f32_e32 v48, v48, v88
	v_lshl_add_u64 v[64:65], v[204:205], 0, v[64:65]
	v_cvt_pk_bf16_f32 v48, v48, s0
	global_store_short v[64:65], v48, off
	v_mul_f32_e32 v48, 0x45800000, v66
	v_pk_fma_f32 v[76:77], v[82:83], s[16:17], v[206:207] op_sel_hi:[1,0,0]
	v_or_b32_e32 v72, 33, v202
	v_cndmask_b32_e32 v89, v66, v48, vcc
	v_mul_f32_e32 v78, 0x4b800000, v76
	v_or_b32_e32 v80, 48, v202
	v_cmp_gt_f32_e32 vcc, s29, v76
	v_ashrrev_i32_e32 v73, 31, v72
	v_mul_f32_e32 v48, v49, v89
	v_ashrrev_i32_e32 v81, 31, v80
	v_cndmask_b32_e32 v76, v76, v78, vcc
	v_cvt_pk_bf16_f32 v66, v48, s0
	v_lshlrev_b64 v[48:49], 11, v[72:73]
	v_lshl_add_u64 v[72:73], v[80:81], 2, s[8:9]
	v_rsq_f32_e32 v76, v76
	global_load_dwordx4 v[72:75], v[72:73], off
	v_lshl_add_u64 v[48:49], v[204:205], 0, v[48:49]
	global_store_short v[48:49], v66, off
	v_mul_f32_e32 v82, 0x45800000, v76
	v_cndmask_b32_e32 v90, v76, v82, vcc
	v_mul_f32_e32 v76, 0x4b800000, v77
	v_cmp_gt_f32_e32 vcc, s29, v77
	v_or_b32_e32 v66, 34, v202
	v_ashrrev_i32_e32 v67, 31, v66
	v_cndmask_b32_e32 v76, v77, v76, vcc
	v_rsq_f32_e32 v76, v76
	v_lshlrev_b64 v[66:67], 11, v[66:67]
	v_mul_f32_e32 v50, v50, v90
	v_lshl_add_u64 v[66:67], v[204:205], 0, v[66:67]
	v_cvt_pk_bf16_f32 v50, v50, s0
	global_store_short v[66:67], v50, off
	v_mul_f32_e32 v50, 0x45800000, v76
	v_or_b32_e32 v78, 35, v202
	v_cndmask_b32_e32 v91, v76, v50, vcc
	v_ashrrev_i32_e32 v79, 31, v78
	v_mul_f32_e32 v50, v51, v91
	v_cvt_pk_bf16_f32 v76, v50, s0
	v_lshlrev_b64 v[50:51], 11, v[78:79]
	v_lshl_add_u64 v[50:51], v[204:205], 0, v[50:51]
	global_store_short v[50:51], v76, off
	v_lshlrev_b64 v[76:77], 11, v[86:87]
	s_waitcnt vmcnt(13)
; DI bfr f2bf(float a) { return (bfr)(pack2(a, 0.f) & 0xffffu); }
; DI int crow(int reg, int h) { return (reg & 3) + 8 * (reg >> 2) + 4 * h; }
; template <int lda, class Epi>
; DI void gemm_tile(const bfr* __restrict__ A, const bfr* __restrict__ Bt, int NB, int K, int m0, int n0, char* smem, Epi epi) {
;     ...
; #pragma unroll
;   for (int i = 0; i < 2; ++i)
; #pragma unroll
;     for (int j = 0; j < 4; ++j)
; #pragma unroll
;       for (int q = 0; q < 16; ++q) {
;         int row = m0 + wr * 64 + i * 32 + crow(q, hl);
;         int col = n0 + wc * 128 + j * 32 + r;
;         epi(row, col, acc[i][j][q]);
;       }
; DI void phase_gemm_bf16out(const Params& p, const bfr* A, const bfr* Wt, bfr* C, int N, const float* ss, char* smem) {
;     ...
;     gemm_tile<1024>(A, Wt, N, 1024, mt * 128, nt * 256, smem,
;               [=](int row, int col, float v) {
;                 float inv = rsqrtf(ss[row] * (1.0f / 1024.0f) + EPSF);
;                 C[(size_t)row * N + col] = f2bf(v * inv);
;               });
	v_pk_fma_f32 v[78:79], v[68:69], s[16:17], v[206:207] op_sel_hi:[1,0,0]
	v_or_b32_e32 v84, 56, v202
	v_mul_f32_e32 v68, 0x4b800000, v78
	v_cmp_gt_f32_e32 vcc, s29, v78
	v_ashrrev_i32_e32 v85, 31, v84
	v_pk_fma_f32 v[86:87], v[70:71], s[16:17], v[206:207] op_sel_hi:[1,0,0]
	v_cndmask_b32_e32 v68, v78, v68, vcc
	v_rsq_f32_e32 v78, v68
	v_lshl_add_u64 v[68:69], v[204:205], 0, v[76:77]
	v_or_b32_e32 v76, 41, v202
	v_ashrrev_i32_e32 v77, 31, v76
	v_mul_f32_e32 v82, 0x45800000, v78
	v_cndmask_b32_e32 v92, v78, v82, vcc
	v_mul_f32_e32 v78, 0x4b800000, v79
	v_cmp_gt_f32_e32 vcc, s29, v79
	v_mul_f32_e32 v52, v52, v92
	v_cvt_pk_bf16_f32 v52, v52, s0
	v_cndmask_b32_e32 v78, v79, v78, vcc
	v_rsq_f32_e32 v78, v78
	global_store_short v[68:69], v52, off
	v_mul_f32_e32 v70, 0x4b800000, v86
	v_or_b32_e32 v82, 42, v202
	v_mul_f32_e32 v52, 0x45800000, v78
	v_cndmask_b32_e32 v93, v78, v52, vcc
	v_mul_f32_e32 v52, v53, v93
	v_cvt_pk_bf16_f32 v78, v52, s0
	v_lshlrev_b64 v[52:53], 11, v[76:77]
	v_lshl_add_u64 v[52:53], v[204:205], 0, v[52:53]
	v_lshl_add_u64 v[76:77], v[84:85], 2, s[8:9]
	global_store_short v[52:53], v78, off
	global_load_dwordx4 v[76:79], v[76:77], off
	v_cmp_gt_f32_e32 vcc, s29, v86
	v_ashrrev_i32_e32 v83, 31, v82
	v_cvt_pk_bf16_f32 v96, v96, s0
	v_cndmask_b32_e32 v70, v86, v70, vcc
	v_rsq_f32_e32 v86, v70
	v_lshlrev_b64 v[82:83], 11, v[82:83]
	global_store_short v[112:113], v96, off offset:64
	v_mul_f32_e32 v96, v99, v226
	v_mul_f32_e32 v94, 0x45800000, v86
	v_cndmask_b32_e32 v86, v86, v94, vcc
	v_mul_f32_e32 v94, 0x4b800000, v87
	v_cmp_gt_f32_e32 vcc, s29, v87
	v_mul_f32_e32 v54, v54, v86
	v_lshl_add_u64 v[70:71], v[204:205], 0, v[82:83]
	v_cndmask_b32_e32 v87, v87, v94, vcc
	v_rsq_f32_e32 v87, v87
	v_cvt_pk_bf16_f32 v54, v54, s0
	v_cvt_pk_bf16_f32 v96, v96, s0
	global_store_short v[70:71], v54, off
	v_mul_f32_e32 v54, 0x45800000, v87
	global_store_short v[114:115], v96, off offset:64
	v_mul_f32_e32 v96, v100, v190
	v_or_b32_e32 v82, 43, v202
	v_cndmask_b32_e32 v87, v87, v54, vcc
	v_cvt_pk_bf16_f32 v96, v96, s0
	v_ashrrev_i32_e32 v83, 31, v82
	v_mul_f32_e32 v54, v55, v87
	s_waitcnt vmcnt(9)
	v_pk_fma_f32 v[72:73], v[72:73], s[16:17], v[206:207] op_sel_hi:[1,0,0]
	global_store_short v[176:177], v96, off offset:64
	v_mul_f32_e32 v96, v101, v191
	v_cvt_pk_bf16_f32 v94, v54, s0
	v_lshlrev_b64 v[54:55], 11, v[82:83]
	v_mul_f32_e32 v82, 0x4b800000, v72
	v_cmp_gt_f32_e32 vcc, s29, v72
	v_cvt_pk_bf16_f32 v96, v96, s0
	global_store_short v[116:117], v96, off offset:64
	v_cndmask_b32_e32 v72, v72, v82, vcc
	v_mul_f32_e32 v96, v102, v178
	v_rsq_f32_e32 v72, v72
	v_cvt_pk_bf16_f32 v96, v96, s0
	global_store_short v[172:173], v96, off offset:64
	v_mul_f32_e32 v96, v103, v168
	v_cvt_pk_bf16_f32 v96, v96, s0
	v_lshl_add_u64 v[54:55], v[204:205], 0, v[54:55]
	global_store_short v[160:161], v96, off offset:64
	v_mul_f32_e32 v96, v104, v154
	global_store_short v[54:55], v94, off
	v_mul_f32_e32 v94, 0x45800000, v72
	v_cvt_pk_bf16_f32 v96, v96, s0
	v_cndmask_b32_e32 v94, v72, v94, vcc
	v_mul_f32_e32 v72, 0x4b800000, v73
	v_cmp_gt_f32_e32 vcc, s29, v73
	global_store_short v[118:119], v96, off offset:64
	v_mul_f32_e32 v96, v105, v155
	v_cndmask_b32_e32 v72, v73, v72, vcc
	v_cvt_pk_bf16_f32 v96, v96, s0
	v_rsq_f32_e32 v72, v72
	global_store_short v[120:121], v96, off offset:64
	v_mul_f32_e32 v96, v106, v142
	v_cvt_pk_bf16_f32 v96, v96, s0
	v_lshlrev_b64 v[80:81], 11, v[80:81]
	v_mul_f32_e32 v56, v56, v94
	global_store_short v[136:137], v96, off offset:64
	v_mul_f32_e32 v96, v107, v143
	v_lshl_add_u64 v[80:81], v[204:205], 0, v[80:81]
	v_cvt_pk_bf16_f32 v56, v56, s0
	v_cvt_pk_bf16_f32 v96, v96, s0
	global_store_short v[80:81], v56, off
	v_mul_f32_e32 v56, 0x45800000, v72
	global_store_short v[122:123], v96, off offset:64
	v_mul_f32_e32 v96, v108, v138
	v_or_b32_e32 v82, 49, v202
	v_cndmask_b32_e32 v95, v72, v56, vcc
	v_cvt_pk_bf16_f32 v96, v96, s0
	v_ashrrev_i32_e32 v83, 31, v82
	v_mul_f32_e32 v56, v57, v95
	v_pk_fma_f32 v[74:75], v[74:75], s[16:17], v[206:207] op_sel_hi:[1,0,0]
	global_store_short v[128:129], v96, off offset:64
	v_mul_f32_e32 v96, v109, v139
	v_cvt_pk_bf16_f32 v72, v56, s0
	v_lshlrev_b64 v[56:57], 11, v[82:83]
	v_mul_f32_e32 v82, 0x4b800000, v74
	v_cmp_gt_f32_e32 vcc, s29, v74
	v_cvt_pk_bf16_f32 v96, v96, s0
	global_store_short v[124:125], v96, off offset:64
	v_cndmask_b32_e32 v74, v74, v82, vcc
	v_mul_f32_e32 v96, v110, v132
	v_rsq_f32_e32 v74, v74
	v_cvt_pk_bf16_f32 v96, v96, s0
	global_store_short v[130:131], v96, off offset:64
	v_mul_f32_e32 v96, v111, v133
	v_cvt_pk_bf16_f32 v96, v96, s0
	global_store_short v[126:127], v96, off offset:64
	v_mul_f32_e32 v96, 0x45800000, v74
	v_cndmask_b32_e32 v96, v74, v96, vcc
	v_mul_f32_e32 v74, 0x4b800000, v75
	v_cmp_gt_f32_e32 vcc, s29, v75
	v_lshl_add_u64 v[56:57], v[204:205], 0, v[56:57]
	global_store_short v[56:57], v72, off
	v_cndmask_b32_e32 v74, v75, v74, vcc
	v_or_b32_e32 v72, 50, v202
	v_rsq_f32_e32 v74, v74
	v_ashrrev_i32_e32 v73, 31, v72
	v_lshlrev_b64 v[72:73], 11, v[72:73]
	v_mul_f32_e32 v58, v58, v96
	v_lshl_add_u64 v[72:73], v[204:205], 0, v[72:73]
	v_cvt_pk_bf16_f32 v58, v58, s0
	global_store_short v[72:73], v58, off
	v_mul_f32_e32 v58, 0x45800000, v74
	v_or_b32_e32 v82, 51, v202
	v_cndmask_b32_e32 v97, v74, v58, vcc
	v_ashrrev_i32_e32 v83, 31, v82
	v_mul_f32_e32 v58, v59, v97
	s_waitcnt vmcnt(19)
; DI bfr f2bf(float a) { return (bfr)(pack2(a, 0.f) & 0xffffu); }
; DI int crow(int reg, int h) { return (reg & 3) + 8 * (reg >> 2) + 4 * h; }
; template <int lda, class Epi>
; DI void gemm_tile(const bfr* __restrict__ A, const bfr* __restrict__ Bt, int NB, int K, int m0, int n0, char* smem, Epi epi) {
;     ...
; #pragma unroll
;   for (int i = 0; i < 2; ++i)
; #pragma unroll
;     for (int j = 0; j < 4; ++j)
; #pragma unroll
;       for (int q = 0; q < 16; ++q) {
;         int row = m0 + wr * 64 + i * 32 + crow(q, hl);
;         int col = n0 + wc * 128 + j * 32 + r;
;         epi(row, col, acc[i][j][q]);
;       }
; DI void phase_gemm_bf16out(const Params& p, const bfr* A, const bfr* Wt, bfr* C, int N, const float* ss, char* smem) {
;     ...
;     gemm_tile<1024>(A, Wt, N, 1024, mt * 128, nt * 256, smem,
;               [=](int row, int col, float v) {
;                 float inv = rsqrtf(ss[row] * (1.0f / 1024.0f) + EPSF);
;                 C[(size_t)row * N + col] = f2bf(v * inv);
;               });
	v_pk_fma_f32 v[76:77], v[76:77], s[16:17], v[206:207] op_sel_hi:[1,0,0]
	v_cvt_pk_bf16_f32 v74, v58, s0
	v_lshlrev_b64 v[58:59], 11, v[82:83]
	v_mul_f32_e32 v82, 0x4b800000, v76
	v_cmp_gt_f32_e32 vcc, s29, v76
	v_mul_f32_e32 v32, v32, v88
	v_mul_f32_e32 v16, v16, v88
	v_cndmask_b32_e32 v76, v76, v82, vcc
	v_rsq_f32_e32 v76, v76
	v_mul_f32_e32 v0, v0, v88
	v_cvt_pk_bf16_f32 v32, v32, s0
	v_cvt_pk_bf16_f32 v16, v16, s0
	v_cvt_pk_bf16_f32 v0, v0, s0
	global_store_short v[64:65], v32, off offset:64
	v_mul_f32_e32 v32, v33, v89
	global_store_short v[64:65], v16, off offset:128
	v_mul_f32_e32 v16, v17, v89
	global_store_short v[64:65], v0, off offset:192
	v_mul_f32_e32 v0, v1, v89
	v_lshl_add_u64 v[58:59], v[204:205], 0, v[58:59]
	v_cvt_pk_bf16_f32 v32, v32, s0
	v_cvt_pk_bf16_f32 v16, v16, s0
	v_cvt_pk_bf16_f32 v0, v0, s0
	global_store_short v[58:59], v74, off
	v_lshlrev_b64 v[74:75], 11, v[84:85]
	v_mul_f32_e32 v84, 0x45800000, v76
	global_store_short v[48:49], v32, off offset:64
	v_mul_f32_e32 v32, v34, v90
	global_store_short v[48:49], v16, off offset:128
	v_mul_f32_e32 v16, v18, v90
	global_store_short v[48:49], v0, off offset:192
	v_mul_f32_e32 v0, v2, v90
	v_cndmask_b32_e32 v84, v76, v84, vcc
	v_mul_f32_e32 v76, 0x4b800000, v77
	v_cmp_gt_f32_e32 vcc, s29, v77
	v_cvt_pk_bf16_f32 v32, v32, s0
	v_cvt_pk_bf16_f32 v16, v16, s0
	v_cvt_pk_bf16_f32 v0, v0, s0
	v_cndmask_b32_e32 v76, v77, v76, vcc
	global_store_short v[66:67], v32, off offset:64
	v_mul_f32_e32 v32, v35, v91
	global_store_short v[66:67], v16, off offset:128
	v_mul_f32_e32 v16, v19, v91
	global_store_short v[66:67], v0, off offset:192
	v_mul_f32_e32 v0, v3, v91
	v_rsq_f32_e32 v76, v76
	v_cvt_pk_bf16_f32 v32, v32, s0
	v_cvt_pk_bf16_f32 v16, v16, s0
	v_cvt_pk_bf16_f32 v0, v0, s0
	global_store_short v[50:51], v32, off offset:64
	v_mul_f32_e32 v32, v36, v92
	global_store_short v[50:51], v16, off offset:128
	v_mul_f32_e32 v16, v20, v92
	global_store_short v[50:51], v0, off offset:192
	v_mul_f32_e32 v0, v4, v92
	v_mul_f32_e32 v60, v60, v84
	v_cvt_pk_bf16_f32 v32, v32, s0
	v_cvt_pk_bf16_f32 v16, v16, s0
	v_cvt_pk_bf16_f32 v0, v0, s0
	v_lshl_add_u64 v[74:75], v[204:205], 0, v[74:75]
	v_cvt_pk_bf16_f32 v60, v60, s0
	global_store_short v[68:69], v32, off offset:64
	v_mul_f32_e32 v32, v37, v93
	global_store_short v[68:69], v16, off offset:128
	v_mul_f32_e32 v16, v21, v93
	global_store_short v[68:69], v0, off offset:192
	v_mul_f32_e32 v0, v5, v93
	global_store_short v[74:75], v60, off
	v_mul_f32_e32 v60, 0x45800000, v76
	v_cvt_pk_bf16_f32 v32, v32, s0
	v_cvt_pk_bf16_f32 v16, v16, s0
	v_cvt_pk_bf16_f32 v0, v0, s0
	v_or_b32_e32 v82, 57, v202
	v_cndmask_b32_e32 v85, v76, v60, vcc
	global_store_short v[52:53], v32, off offset:64
	v_mul_f32_e32 v32, v38, v86
	global_store_short v[52:53], v16, off offset:128
	v_mul_f32_e32 v16, v22, v86
	global_store_short v[52:53], v0, off offset:192
	v_mul_f32_e32 v0, v6, v86
	v_ashrrev_i32_e32 v83, 31, v82
	v_mul_f32_e32 v60, v61, v85
	v_pk_fma_f32 v[78:79], v[78:79], s[16:17], v[206:207] op_sel_hi:[1,0,0]
	v_cvt_pk_bf16_f32 v32, v32, s0
	v_cvt_pk_bf16_f32 v16, v16, s0
	v_cvt_pk_bf16_f32 v0, v0, s0
	v_cvt_pk_bf16_f32 v76, v60, s0
	v_lshlrev_b64 v[60:61], 11, v[82:83]
	v_mul_f32_e32 v82, 0x4b800000, v78
	v_cmp_gt_f32_e32 vcc, s29, v78
	global_store_short v[70:71], v32, off offset:64
	v_mul_f32_e32 v32, v39, v87
	global_store_short v[70:71], v16, off offset:128
	v_mul_f32_e32 v16, v23, v87
	global_store_short v[70:71], v0, off offset:192
	v_mul_f32_e32 v0, v7, v87
	v_cndmask_b32_e32 v78, v78, v82, vcc
	v_cvt_pk_bf16_f32 v32, v32, s0
	v_cvt_pk_bf16_f32 v16, v16, s0
	v_cvt_pk_bf16_f32 v0, v0, s0
	v_rsq_f32_e32 v78, v78
	global_store_short v[54:55], v32, off offset:64
; DI bfr f2bf(float a) { return (bfr)(pack2(a, 0.f) & 0xffffu); }
; DI int crow(int reg, int h) { return (reg & 3) + 8 * (reg >> 2) + 4 * h; }
; template <int lda, class Epi>
; DI void gemm_tile(const bfr* __restrict__ A, const bfr* __restrict__ Bt, int NB, int K, int m0, int n0, char* smem, Epi epi) {
;     ...
; #pragma unroll
;   for (int i = 0; i < 2; ++i)
; #pragma unroll
;     for (int j = 0; j < 4; ++j)
; #pragma unroll
;       for (int q = 0; q < 16; ++q) {
;         int row = m0 + wr * 64 + i * 32 + crow(q, hl);
;         int col = n0 + wc * 128 + j * 32 + r;
;         epi(row, col, acc[i][j][q]);
;       }
; DI void phase_gemm_bf16out(const Params& p, const bfr* A, const bfr* Wt, bfr* C, int N, const float* ss, char* smem) {
;     ...
;     gemm_tile<1024>(A, Wt, N, 1024, mt * 128, nt * 256, smem,
;               [=](int row, int col, float v) {
;                 float inv = rsqrtf(ss[row] * (1.0f / 1024.0f) + EPSF);
;                 C[(size_t)row * N + col] = f2bf(v * inv);
;               });
	v_mul_f32_e32 v32, v40, v94
	global_store_short v[54:55], v16, off offset:128
	v_mul_f32_e32 v16, v24, v94
	global_store_short v[54:55], v0, off offset:192
	v_mul_f32_e32 v0, v8, v94
	v_cvt_pk_bf16_f32 v32, v32, s0
	v_cvt_pk_bf16_f32 v16, v16, s0
	v_cvt_pk_bf16_f32 v0, v0, s0
	global_store_short v[80:81], v32, off offset:64
	v_mul_f32_e32 v32, v41, v95
	global_store_short v[80:81], v16, off offset:128
	v_mul_f32_e32 v16, v25, v95
	global_store_short v[80:81], v0, off offset:192
	v_mul_f32_e32 v0, v9, v95
	v_cvt_pk_bf16_f32 v32, v32, s0
	v_cvt_pk_bf16_f32 v16, v16, s0
	v_cvt_pk_bf16_f32 v0, v0, s0
	v_mul_f32_e32 v98, 0x45800000, v78
	global_store_short v[56:57], v32, off offset:64
	v_mul_f32_e32 v32, v42, v96
	global_store_short v[56:57], v16, off offset:128
	v_mul_f32_e32 v16, v26, v96
	global_store_short v[56:57], v0, off offset:192
	v_mul_f32_e32 v0, v10, v96
	v_cndmask_b32_e32 v78, v78, v98, vcc
	v_mul_f32_e32 v98, 0x4b800000, v79
	v_cmp_gt_f32_e32 vcc, s29, v79
	v_cvt_pk_bf16_f32 v32, v32, s0
	v_cvt_pk_bf16_f32 v16, v16, s0
	v_cvt_pk_bf16_f32 v0, v0, s0
	v_lshl_add_u64 v[60:61], v[204:205], 0, v[60:61]
	v_cndmask_b32_e32 v79, v79, v98, vcc
	global_store_short v[72:73], v32, off offset:64
	v_mul_f32_e32 v32, v43, v97
	global_store_short v[72:73], v16, off offset:128
	v_mul_f32_e32 v16, v27, v97
	global_store_short v[72:73], v0, off offset:192
	v_mul_f32_e32 v0, v11, v97
	global_store_short v[60:61], v76, off
	v_or_b32_e32 v76, 58, v202
	v_rsq_f32_e32 v79, v79
	v_cvt_pk_bf16_f32 v32, v32, s0
	v_cvt_pk_bf16_f32 v16, v16, s0
	v_cvt_pk_bf16_f32 v0, v0, s0
	v_ashrrev_i32_e32 v77, 31, v76
	global_store_short v[58:59], v32, off offset:64
	v_mul_f32_e32 v32, v44, v84
	global_store_short v[58:59], v16, off offset:128
	v_mul_f32_e32 v16, v28, v84
	global_store_short v[58:59], v0, off offset:192
	v_mul_f32_e32 v0, v12, v84
	v_lshlrev_b64 v[76:77], 11, v[76:77]
	v_mul_f32_e32 v62, v62, v78
	v_cvt_pk_bf16_f32 v32, v32, s0
	v_cvt_pk_bf16_f32 v16, v16, s0
	v_cvt_pk_bf16_f32 v0, v0, s0
	v_lshl_add_u64 v[76:77], v[204:205], 0, v[76:77]
	v_cvt_pk_bf16_f32 v62, v62, s0
	global_store_short v[74:75], v32, off offset:64
	v_mul_f32_e32 v32, v45, v85
	global_store_short v[74:75], v16, off offset:128
	v_mul_f32_e32 v16, v29, v85
	global_store_short v[74:75], v0, off offset:192
	v_mul_f32_e32 v0, v13, v85
	global_store_short v[76:77], v62, off
	v_mul_f32_e32 v62, 0x45800000, v79
	v_cvt_pk_bf16_f32 v32, v32, s0
	v_cvt_pk_bf16_f32 v16, v16, s0
	v_cvt_pk_bf16_f32 v0, v0, s0
	v_or_b32_e32 v82, 59, v202
	v_cndmask_b32_e32 v79, v79, v62, vcc
	global_store_short v[60:61], v32, off offset:64
	v_mul_f32_e32 v32, v46, v78
	global_store_short v[60:61], v16, off offset:128
	v_mul_f32_e32 v16, v30, v78
	global_store_short v[60:61], v0, off offset:192
	v_mul_f32_e32 v0, v14, v78
	v_ashrrev_i32_e32 v83, 31, v82
	v_mul_f32_e32 v62, v63, v79
	v_cvt_pk_bf16_f32 v32, v32, s0
	v_cvt_pk_bf16_f32 v16, v16, s0
	v_cvt_pk_bf16_f32 v0, v0, s0
	v_cvt_pk_bf16_f32 v98, v62, s0
	v_lshlrev_b64 v[62:63], 11, v[82:83]
	global_store_short v[76:77], v32, off offset:64
	v_mul_f32_e32 v32, v47, v79
	global_store_short v[76:77], v16, off offset:128
	v_mul_f32_e32 v16, v31, v79
	global_store_short v[76:77], v0, off offset:192
	v_mul_f32_e32 v0, v15, v79
	v_lshl_add_u64 v[62:63], v[204:205], 0, v[62:63]
	v_cvt_pk_bf16_f32 v32, v32, s0
	v_cvt_pk_bf16_f32 v16, v16, s0
	v_cvt_pk_bf16_f32 v0, v0, s0
	global_store_short v[120:121], v156, off
	global_store_short v[126:127], v140, off
	global_store_short v[62:63], v98, off
	global_store_short v[62:63], v32, off offset:64
	global_store_short v[62:63], v16, off offset:128
	global_store_short v[62:63], v0, off offset:192
	s_cbranch_scc0 .LBB0_1559

; #define GA_LOAD(pr_) do { _Pragma("unroll") for (int i = 0; i < 4; ++i) ra[i] = *(const u32x4*)(Ab + (i * 32) * lda + (pr_) * 64); } while (0)
; #define GB_LOAD(kt_) do { const bfr* bk_ = Bb + (kt_) * NB * 32; \
;     _Pragma("unroll") for (int i = 0; i < 4; ++i) rb[i] = *(const u32x4*)(bk_ + (i * 64) * 32); } while (0)
; #define G_STORE(kt_) do { bfr* as_ = S0 + ((kt_) & 1) * GSTAGE; bfr* bs_ = as_ + 128 * 40; \
;     if (apar == ((kt_) & 1)) { _Pragma("unroll") for (int i = 0; i < 4; ++i) *(u32x4*)(as_ + asoff + i * 32 * 40) = ra[i]; } \
;     _Pragma("unroll") for (int i = 0; i < 4; ++i) *(u32x4*)(bs_ + bsoff + i * 64 * 40) = rb[i]; } while (0)
; template <int lda>
; DI void gemm_mainloop(const bfr* __restrict__ A, const bfr* __restrict__ Bt, int NB, int K, int m0, int n0, char* smem, f32x16 (&acc)[2][4]) {
;   bfr* S0 = (bfr*)smem;
;   int tid = threadIdx.x;
;   asm volatile("" : "+v"(tid));
;   const int lane = tid & 63, wid = tid >> 6, wr = wid >> 1, wc = wid & 1;
;   const int r = lane & 31, hl = lane >> 5;
; #pragma unroll
;   for (int i = 0; i < 2; ++i)
; #pragma unroll
;     for (int j = 0; j < 4; ++j)
; #pragma unroll
;       for (int q = 0; q < 16; ++q) acc[i][j][q] = 0.f;
;   u32x4 ra[4], rb[4];
;   const int nk = K >> 5;
;   const int arow = tid >> 3, ac8 = tid & 7, apar = ac8 >> 2;
;   const bfr* Ab = A + (m0 + arow) * lda + ac8 * 8;
;   const int asoff = arow * 40 + (ac8 & 3) * 8;
;   const int brow = tid >> 2, bc4 = tid & 3;
;   const bfr* Bb = Bt + (n0 + brow) * 32 + bc4 * 8;
;   const int bsoff = brow * 40 + bc4 * 8;
;     ...
;   GA_LOAD(0);
;   GB_LOAD(0);
;   G_STORE(0);
;   GB_LOAD(1);
;   __syncthreads();
; DI void phase_gemm_bf16out(const Params& p, const bfr* A, const bfr* Wt, bfr* C, int N, const float* ss, char* smem) {
;     ...
;   for (int t0 = blockIdx.x; t0 < 128 * ntn; t0 += gridDim.x) {
;     const int t = ((gridDim.x & 7) == 0) ? xcd_tile(t0, ntn) : t0;
;     int mt = t / ntn, nt = t % ntn;
.LBB0_1548:
	s_ashr_i32 s5, s4, 31
	s_lshr_b32 s5, s5, 30
	s_add_i32 s5, s4, s5
	s_and_b32 s20, s5, 0xfffffc
	s_lshl_b32 s5, s5, 5
	s_and_b32 s33, s5, 0xffffff80
	s_sub_i32 s4, s4, s20
	s_lshl_b32 s31, s4, 8
	s_mov_b32 s36, 0
	s_mov_b64 s[20:21], 0
	s_lshl_b32 s98, s33, 11
	s_add_u32 s98, s10, s98
	s_addc_u32 s99, s11, 0
	s_lshl_b32 s100, s31, 6
	s_add_u32 s100, s14, s100
	s_addc_u32 s101, s15, 0
	v_writelane_b32 v187, s64, 0
	v_writelane_b32 v187, s65, 1
	v_writelane_b32 v187, s66, 2
	v_writelane_b32 v187, s67, 3
	v_writelane_b32 v187, s68, 4
	v_writelane_b32 v187, s69, 5
	v_writelane_b32 v187, s70, 6
	v_writelane_b32 v187, s71, 7
	v_writelane_b32 v187, s72, 8
	v_writelane_b32 v187, s73, 9
	v_writelane_b32 v187, s74, 10
	v_writelane_b32 v187, s75, 11
	v_writelane_b32 v187, s76, 12
	v_writelane_b32 v187, s77, 13
	v_writelane_b32 v187, s78, 14
	v_writelane_b32 v187, s79, 15
	v_lshrrev_b32_e32 v188, 6, v196
	v_and_b32_e32 v189, 63, v196
	v_readfirstlane_b32 s73, v188
	v_lshrrev_b32_e32 v190, 2, v189
	v_bfe_u32 v191, v189, 4, 2
	v_and_b32_e32 v188, 3, v189
	v_xor_b32_e32 v188, v188, v191
	v_lshlrev_b32_e32 v188, 4, v188
	v_lshl_add_u32 v176, v190, 11, v188
	v_add_u32_e32 v177, 0x8000, v176
	v_lshl_add_u32 v178, v190, 6, v188
	v_and_b32_e32 v190, 31, v189
	v_lshrrev_b32_e32 v191, 5, v189
	v_bfe_u32 v188, v189, 2, 2
	v_xor_b32_e32 v188, v188, v191
	v_lshlrev_b32_e32 v188, 4, v188
	v_lshl_add_u32 v179, v190, 6, v188
	s_lshr_b32 s74, s73, 1
	s_lshl_b32 s74, s74, 12
	s_and_b32 s75, s73, 1
	s_lshl_b32 s75, s75, 13
	v_add_u32_e32 v181, s75, v179
	v_add_u32_e32 v179, s74, v179
	v_xor_b32_e32 v182, 32, v181
	v_xor_b32_e32 v180, 32, v179
	s_lshl_b32 s74, s73, 16
	s_add_u32 s64, s98, s74
	s_addc_u32 s65, s99, 0
	s_lshl_b32 s74, s73, 12
	s_add_u32 s66, s100, s74
	s_addc_u32 s67, s101, 0
	s_lshl_b32 s68, s73, 11
	s_lshl_b32 s69, s73, 12
	s_mov_b32 s70, 0
	s_mov_b32 s71, 0
	s_mov_b32 s72, 0
	s_waitcnt lgkmcnt(0)
	s_barrier
	s_mul_i32 s74, s70, 0x6000
	s_add_u32 s75, s74, s68
	s_mov_b32 m0, s75
	s_add_u32 s76, s74, 0x2000
	s_cmp_eq_u32 s70, 2
	s_cselect_b32 s76, 0x10000, s76
	global_load_lds_dwordx4 v176, s[64:65]
	s_add_u32 m0, s75, 0x400
	s_add_u32 s76, s76, s69
	global_load_lds_dwordx4 v177, s[64:65]
	s_mov_b32 m0, s76
	s_add_u32 s64, s64, 64
	s_addc_u32 s65, s65, 0
	global_load_lds_dwordx4 v178, s[66:67]
	global_load_lds_dwordx4 v178, s[66:67] offset:1024
	global_load_lds_dwordx4 v178, s[66:67] offset:2048
	global_load_lds_dwordx4 v178, s[66:67] offset:3072
	s_add_u32 s66, s66, 0x10000
	s_addc_u32 s67, s67, 0
	s_add_u32 s70, s70, 1
	s_cmp_eq_u32 s70, 3
	s_cselect_b32 s70, 0, s70
	s_mul_i32 s74, s70, 0x6000
	s_add_u32 s75, s74, s68
	s_mov_b32 m0, s75
	s_add_u32 s76, s74, 0x2000
	s_cmp_eq_u32 s70, 2
	s_cselect_b32 s76, 0x10000, s76
	global_load_lds_dwordx4 v176, s[64:65]
	s_add_u32 m0, s75, 0x400
	s_add_u32 s76, s76, s69
	global_load_lds_dwordx4 v177, s[64:65]
	s_mov_b32 m0, s76
	s_add_u32 s64, s64, 64
	s_addc_u32 s65, s65, 0
	global_load_lds_dwordx4 v178, s[66:67]
	global_load_lds_dwordx4 v178, s[66:67] offset:1024
	global_load_lds_dwordx4 v178, s[66:67] offset:2048
	global_load_lds_dwordx4 v178, s[66:67] offset:3072
	s_add_u32 s66, s66, 0x10000
	s_addc_u32 s67, s67, 0
	s_add_u32 s70, s70, 1
	s_cmp_eq_u32 s70, 3
	s_cselect_b32 s70, 0, s70
	v_mov_b32_e32 v112, 0
	v_mov_b32_e32 v113, 0
	v_mov_b32_e32 v114, 0
	v_mov_b32_e32 v115, 0
	v_mov_b32_e32 v116, 0
	v_mov_b32_e32 v117, 0
	v_mov_b32_e32 v118, 0
	v_mov_b32_e32 v119, 0
	v_mov_b32_e32 v120, 0
	v_mov_b32_e32 v121, 0
	v_mov_b32_e32 v122, 0
	v_mov_b32_e32 v123, 0
	v_mov_b32_e32 v124, 0
	v_mov_b32_e32 v125, 0
	v_mov_b32_e32 v126, 0
	v_mov_b32_e32 v127, 0
	v_mov_b32_e32 v96, 0
	v_mov_b32_e32 v97, 0
	v_mov_b32_e32 v98, 0
	v_mov_b32_e32 v99, 0
	v_mov_b32_e32 v100, 0
	v_mov_b32_e32 v101, 0
	v_mov_b32_e32 v102, 0
	v_mov_b32_e32 v103, 0
	v_mov_b32_e32 v104, 0
	v_mov_b32_e32 v105, 0
	v_mov_b32_e32 v106, 0
	v_mov_b32_e32 v107, 0
	v_mov_b32_e32 v108, 0
	v_mov_b32_e32 v109, 0
	v_mov_b32_e32 v110, 0
	v_mov_b32_e32 v111, 0
	v_mov_b32_e32 v80, 0
	v_mov_b32_e32 v81, 0
	v_mov_b32_e32 v82, 0
	v_mov_b32_e32 v83, 0
	v_mov_b32_e32 v84, 0
	v_mov_b32_e32 v85, 0
	v_mov_b32_e32 v86, 0
	v_mov_b32_e32 v87, 0
	v_mov_b32_e32 v88, 0
	v_mov_b32_e32 v89, 0
	v_mov_b32_e32 v90, 0
	v_mov_b32_e32 v91, 0
	v_mov_b32_e32 v92, 0
	v_mov_b32_e32 v93, 0
	v_mov_b32_e32 v94, 0
	v_mov_b32_e32 v95, 0
	v_mov_b32_e32 v64, 0
	v_mov_b32_e32 v65, 0
	v_mov_b32_e32 v66, 0
	v_mov_b32_e32 v67, 0
	v_mov_b32_e32 v68, 0
	v_mov_b32_e32 v69, 0
	v_mov_b32_e32 v70, 0
	v_mov_b32_e32 v71, 0
	v_mov_b32_e32 v72, 0
	v_mov_b32_e32 v73, 0
	v_mov_b32_e32 v74, 0
	v_mov_b32_e32 v75, 0
	v_mov_b32_e32 v76, 0
	v_mov_b32_e32 v77, 0
	v_mov_b32_e32 v78, 0
	v_mov_b32_e32 v79, 0
	v_mov_b32_e32 v48, 0
	v_mov_b32_e32 v49, 0
	v_mov_b32_e32 v50, 0
	v_mov_b32_e32 v51, 0
	v_mov_b32_e32 v52, 0
	v_mov_b32_e32 v53, 0
	v_mov_b32_e32 v54, 0
	v_mov_b32_e32 v55, 0
	v_mov_b32_e32 v56, 0
	v_mov_b32_e32 v57, 0
	v_mov_b32_e32 v58, 0
	v_mov_b32_e32 v59, 0
	v_mov_b32_e32 v60, 0
	v_mov_b32_e32 v61, 0
	v_mov_b32_e32 v62, 0
	v_mov_b32_e32 v63, 0
	v_mov_b32_e32 v32, 0
	v_mov_b32_e32 v33, 0
	v_mov_b32_e32 v34, 0
	v_mov_b32_e32 v35, 0
	v_mov_b32_e32 v36, 0
	v_mov_b32_e32 v37, 0
	v_mov_b32_e32 v38, 0
	v_mov_b32_e32 v39, 0
	v_mov_b32_e32 v40, 0
	v_mov_b32_e32 v41, 0
	v_mov_b32_e32 v42, 0
	v_mov_b32_e32 v43, 0
	v_mov_b32_e32 v44, 0
	v_mov_b32_e32 v45, 0
	v_mov_b32_e32 v46, 0
	v_mov_b32_e32 v47, 0
	v_mov_b32_e32 v16, 0
	v_mov_b32_e32 v17, 0
	v_mov_b32_e32 v18, 0
	v_mov_b32_e32 v19, 0
	v_mov_b32_e32 v20, 0
	v_mov_b32_e32 v21, 0
	v_mov_b32_e32 v22, 0
	v_mov_b32_e32 v23, 0
	v_mov_b32_e32 v24, 0
	v_mov_b32_e32 v25, 0
	v_mov_b32_e32 v26, 0
	v_mov_b32_e32 v27, 0
	v_mov_b32_e32 v28, 0
	v_mov_b32_e32 v29, 0
	v_mov_b32_e32 v30, 0
	v_mov_b32_e32 v31, 0
	v_mov_b32_e32 v0, 0
	v_mov_b32_e32 v1, 0
	v_mov_b32_e32 v2, 0
	v_mov_b32_e32 v3, 0
	v_mov_b32_e32 v4, 0
	v_mov_b32_e32 v5, 0
	v_mov_b32_e32 v6, 0
	v_mov_b32_e32 v7, 0
	v_mov_b32_e32 v8, 0
	v_mov_b32_e32 v9, 0
	v_mov_b32_e32 v10, 0
	v_mov_b32_e32 v11, 0
	v_mov_b32_e32 v12, 0
	v_mov_b32_e32 v13, 0
	v_mov_b32_e32 v14, 0
	v_mov_b32_e32 v15, 0
; #define MFMA32(a, b, c) __builtin_amdgcn_mfma_f32_32x32x16_bf16((a), (b), (c), 0, 0, 0)
; #define GA_LOAD(pr_) do { _Pragma("unroll") for (int i = 0; i < 4; ++i) ra[i] = *(const u32x4*)(Ab + (i * 32) * lda + (pr_) * 64); } while (0)
; #define GB_LOAD(kt_) do { const bfr* bk_ = Bb + (kt_) * NB * 32; \
;     _Pragma("unroll") for (int i = 0; i < 4; ++i) rb[i] = *(const u32x4*)(bk_ + (i * 64) * 32); } while (0)
; #define G_STORE(kt_) do { bfr* as_ = S0 + ((kt_) & 1) * GSTAGE; bfr* bs_ = as_ + 128 * 40; \
;     if (apar == ((kt_) & 1)) { _Pragma("unroll") for (int i = 0; i < 4; ++i) *(u32x4*)(as_ + asoff + i * 32 * 40) = ra[i]; } \
;     _Pragma("unroll") for (int i = 0; i < 4; ++i) *(u32x4*)(bs_ + bsoff + i * 64 * 40) = rb[i]; } while (0)
; template <int lda>
; DI void gemm_mainloop(const bfr* __restrict__ A, const bfr* __restrict__ Bt, int NB, int K, int m0, int n0, char* smem, f32x16 (&acc)[2][4]) {
;     ...
;   for (int kt = 0; kt < nk; ++kt) {
;     if (kt + 1 < nk) G_STORE(kt + 1);
;     if (kt + 2 < nk) {
;       GB_LOAD(kt + 2);
;       if ((kt & 1) == 0) GA_LOAD((kt >> 1) + 1);
;     }
;     const bfr* As = S0 + (kt & 1) * GSTAGE;
;     const bfr* Bs = As + 128 * 40;
; #pragma unroll
;     for (int ks = 0; ks < 2; ++ks) {
;       bf16x8 af[2], bfg[4];
; #pragma unroll
;       for (int i = 0; i < 2; ++i) af[i] = *(const bf16x8*)(As + (wr * 64 + i * 32 + r) * 40 + ks * 16 + hl * 8);
; #pragma unroll
;       for (int j = 0; j < 4; ++j) bfg[j] = *(const bf16x8*)(Bs + (wc * 128 + j * 32 + r) * 40 + ks * 16 + hl * 8);
; #pragma unroll
;       for (int i = 0; i < 2; ++i)
; #pragma unroll
;         for (int j = 0; j < 4; ++j) acc[i][j] = MFMA32(af[i], bfg[j], acc[i][j]);
;     }
;     __syncthreads();
;   }
.Lp17_loop:
	s_waitcnt vmcnt(6)
	s_barrier
	s_mul_i32 s74, s70, 0x6000
	s_add_u32 s75, s74, s68
	s_mov_b32 m0, s75
	s_add_u32 s76, s74, 0x2000
	s_cmp_eq_u32 s70, 2
	s_cselect_b32 s76, 0x10000, s76
	global_load_lds_dwordx4 v176, s[64:65]
	s_add_u32 m0, s75, 0x400
	s_add_u32 s76, s76, s69
	global_load_lds_dwordx4 v177, s[64:65]
	s_mov_b32 m0, s76
	s_add_u32 s64, s64, 64
	s_addc_u32 s65, s65, 0
	global_load_lds_dwordx4 v178, s[66:67]
	global_load_lds_dwordx4 v178, s[66:67] offset:1024
	global_load_lds_dwordx4 v178, s[66:67] offset:2048
	global_load_lds_dwordx4 v178, s[66:67] offset:3072
	s_add_u32 s66, s66, 0x10000
	s_addc_u32 s67, s67, 0
	s_add_u32 s70, s70, 1
	s_cmp_eq_u32 s70, 3
	s_cselect_b32 s70, 0, s70
	s_mul_i32 s74, s71, 0x6000
	s_add_u32 s75, s74, 0x2000
	s_cmp_eq_u32 s71, 2
	s_cselect_b32 s75, 0x10000, s75
	v_add_u32_e32 v183, s74, v179
	v_add_u32_e32 v185, s75, v181
	v_add_u32_e32 v184, s74, v180
	v_add_u32_e32 v186, s75, v182
	ds_read_b128 v[128:131], v183
	ds_read_b128 v[144:147], v185
	ds_read_b128 v[148:151], v185 offset:2048
	ds_read_b128 v[152:155], v185 offset:4096
	ds_read_b128 v[156:159], v185 offset:6144
	ds_read_b128 v[132:135], v183 offset:2048
	ds_read_b128 v[136:139], v184
	ds_read_b128 v[160:163], v186
	ds_read_b128 v[164:167], v186 offset:2048
	ds_read_b128 v[168:171], v186 offset:4096
	ds_read_b128 v[172:175], v186 offset:6144
	ds_read_b128 v[140:143], v184 offset:2048
	s_add_u32 s71, s71, 1
	s_cmp_eq_u32 s71, 3
	s_cselect_b32 s71, 0, s71
	s_waitcnt lgkmcnt(10)
	v_mfma_f32_32x32x16_bf16 v[112:127], v[128:131], v[144:147], v[112:127]
	s_waitcnt lgkmcnt(9)
	v_mfma_f32_32x32x16_bf16 v[96:111], v[128:131], v[148:151], v[96:111]
	s_waitcnt lgkmcnt(8)
	v_mfma_f32_32x32x16_bf16 v[80:95], v[128:131], v[152:155], v[80:95]
	s_waitcnt lgkmcnt(7)
	v_mfma_f32_32x32x16_bf16 v[64:79], v[128:131], v[156:159], v[64:79]
	s_waitcnt lgkmcnt(6)
	v_mfma_f32_32x32x16_bf16 v[48:63], v[132:135], v[144:147], v[48:63]
	v_mfma_f32_32x32x16_bf16 v[32:47], v[132:135], v[148:151], v[32:47]
	v_mfma_f32_32x32x16_bf16 v[16:31], v[132:135], v[152:155], v[16:31]
	v_mfma_f32_32x32x16_bf16 v[0:15], v[132:135], v[156:159], v[0:15]
	s_waitcnt lgkmcnt(4)
	v_mfma_f32_32x32x16_bf16 v[112:127], v[136:139], v[160:163], v[112:127]
	s_waitcnt lgkmcnt(3)
	v_mfma_f32_32x32x16_bf16 v[96:111], v[136:139], v[164:167], v[96:111]
	s_waitcnt lgkmcnt(2)
	v_mfma_f32_32x32x16_bf16 v[80:95], v[136:139], v[168:171], v[80:95]
	s_waitcnt lgkmcnt(1)
	v_mfma_f32_32x32x16_bf16 v[64:79], v[136:139], v[172:175], v[64:79]
	s_waitcnt lgkmcnt(0)
	v_mfma_f32_32x32x16_bf16 v[48:63], v[140:143], v[160:163], v[48:63]
	v_mfma_f32_32x32x16_bf16 v[32:47], v[140:143], v[164:167], v[32:47]
	v_mfma_f32_32x32x16_bf16 v[16:31], v[140:143], v[168:171], v[16:31]
	v_mfma_f32_32x32x16_bf16 v[0:15], v[140:143], v[172:175], v[0:15]
	s_add_u32 s72, s72, 1
	s_cmp_lt_u32 s72, 30
	s_cbranch_scc1 .Lp17_loop
	s_waitcnt vmcnt(6)
	s_barrier
	s_mul_i32 s74, s71, 0x6000
	s_add_u32 s75, s74, 0x2000
	s_cmp_eq_u32 s71, 2
	s_cselect_b32 s75, 0x10000, s75
	v_add_u32_e32 v183, s74, v179
	v_add_u32_e32 v185, s75, v181
	v_add_u32_e32 v184, s74, v180
	v_add_u32_e32 v186, s75, v182
	ds_read_b128 v[128:131], v183
	ds_read_b128 v[144:147], v185
	ds_read_b128 v[148:151], v185 offset:2048
	ds_read_b128 v[152:155], v185 offset:4096
	ds_read_b128 v[156:159], v185 offset:6144
	ds_read_b128 v[132:135], v183 offset:2048
	ds_read_b128 v[136:139], v184
	ds_read_b128 v[160:163], v186
	ds_read_b128 v[164:167], v186 offset:2048
	ds_read_b128 v[168:171], v186 offset:4096
	ds_read_b128 v[172:175], v186 offset:6144
	ds_read_b128 v[140:143], v184 offset:2048
	s_add_u32 s71, s71, 1
	s_cmp_eq_u32 s71, 3
	s_cselect_b32 s71, 0, s71
	s_waitcnt lgkmcnt(10)
	v_mfma_f32_32x32x16_bf16 v[112:127], v[128:131], v[144:147], v[112:127]
	s_waitcnt lgkmcnt(9)
	v_mfma_f32_32x32x16_bf16 v[96:111], v[128:131], v[148:151], v[96:111]
	s_waitcnt lgkmcnt(8)
	v_mfma_f32_32x32x16_bf16 v[80:95], v[128:131], v[152:155], v[80:95]
	s_waitcnt lgkmcnt(7)
	v_mfma_f32_32x32x16_bf16 v[64:79], v[128:131], v[156:159], v[64:79]
	s_waitcnt lgkmcnt(6)
	v_mfma_f32_32x32x16_bf16 v[48:63], v[132:135], v[144:147], v[48:63]
	v_mfma_f32_32x32x16_bf16 v[32:47], v[132:135], v[148:151], v[32:47]
	v_mfma_f32_32x32x16_bf16 v[16:31], v[132:135], v[152:155], v[16:31]
	v_mfma_f32_32x32x16_bf16 v[0:15], v[132:135], v[156:159], v[0:15]
	s_waitcnt lgkmcnt(4)
	v_mfma_f32_32x32x16_bf16 v[112:127], v[136:139], v[160:163], v[112:127]
	s_waitcnt lgkmcnt(3)
	v_mfma_f32_32x32x16_bf16 v[96:111], v[136:139], v[164:167], v[96:111]
	s_waitcnt lgkmcnt(2)
	v_mfma_f32_32x32x16_bf16 v[80:95], v[136:139], v[168:171], v[80:95]
	s_waitcnt lgkmcnt(1)
	v_mfma_f32_32x32x16_bf16 v[64:79], v[136:139], v[172:175], v[64:79]
	s_waitcnt lgkmcnt(0)
	v_mfma_f32_32x32x16_bf16 v[48:63], v[140:143], v[160:163], v[48:63]
	v_mfma_f32_32x32x16_bf16 v[32:47], v[140:143], v[164:167], v[32:47]
	v_mfma_f32_32x32x16_bf16 v[16:31], v[140:143], v[168:171], v[16:31]
	v_mfma_f32_32x32x16_bf16 v[0:15], v[140:143], v[172:175], v[0:15]
	s_waitcnt vmcnt(0)
	s_barrier
; #define MFMA32(a, b, c) __builtin_amdgcn_mfma_f32_32x32x16_bf16((a), (b), (c), 0, 0, 0)
; DI void xcd_barrier(const XcdBarrier& b) {
;   asm volatile("s_waitcnt vmcnt(0)" ::: "memory");
;   __syncthreads();
;   if (threadIdx.x == 0) {
;     unsigned* bar = b.bar;
;     __builtin_amdgcn_s_waitcnt(0);
;     unsigned nloc = b.st[0], nx = b.st[1];
;     if (nloc == 0u) { xcd_barrier_complete(bar, b.x, nloc, nx); b.st[0] = nloc; b.st[1] = nx; }
; template <int lda>
; DI void gemm_mainloop(const bfr* __restrict__ A, const bfr* __restrict__ Bt, int NB, int K, int m0, int n0, char* smem, f32x16 (&acc)[2][4]) {
;     ...
; #pragma unroll
;     for (int ks = 0; ks < 2; ++ks) {
;       bf16x8 af[2], bfg[4];
; #pragma unroll
;       for (int i = 0; i < 2; ++i) af[i] = *(const bf16x8*)(As + (wr * 64 + i * 32 + r) * 40 + ks * 16 + hl * 8);
; #pragma unroll
;       for (int j = 0; j < 4; ++j) bfg[j] = *(const bf16x8*)(Bs + (wc * 128 + j * 32 + r) * 40 + ks * 16 + hl * 8);
; #pragma unroll
;       for (int i = 0; i < 2; ++i)
; #pragma unroll
;         for (int j = 0; j < 4; ++j) acc[i][j] = MFMA32(af[i], bfg[j], acc[i][j]);
;     }
;     __syncthreads();
;   }
	s_mul_i32 s74, s71, 0x6000
	s_add_u32 s75, s74, 0x2000
	s_cmp_eq_u32 s71, 2
	s_cselect_b32 s75, 0x10000, s75
	v_add_u32_e32 v183, s74, v179
	v_add_u32_e32 v185, s75, v181
	v_add_u32_e32 v184, s74, v180
	v_add_u32_e32 v186, s75, v182
	ds_read_b128 v[128:131], v183
	ds_read_b128 v[144:147], v185
	ds_read_b128 v[148:151], v185 offset:2048
	ds_read_b128 v[152:155], v185 offset:4096
	ds_read_b128 v[156:159], v185 offset:6144
	ds_read_b128 v[132:135], v183 offset:2048
	ds_read_b128 v[136:139], v184
	ds_read_b128 v[160:163], v186
	ds_read_b128 v[164:167], v186 offset:2048
	ds_read_b128 v[168:171], v186 offset:4096
	ds_read_b128 v[172:175], v186 offset:6144
	ds_read_b128 v[140:143], v184 offset:2048
	s_add_u32 s71, s71, 1
	s_cmp_eq_u32 s71, 3
	s_cselect_b32 s71, 0, s71
	s_waitcnt lgkmcnt(10)
	v_mfma_f32_32x32x16_bf16 v[112:127], v[128:131], v[144:147], v[112:127]
	s_waitcnt lgkmcnt(9)
	v_mfma_f32_32x32x16_bf16 v[96:111], v[128:131], v[148:151], v[96:111]
	s_waitcnt lgkmcnt(8)
	v_mfma_f32_32x32x16_bf16 v[80:95], v[128:131], v[152:155], v[80:95]
	s_waitcnt lgkmcnt(7)
	v_mfma_f32_32x32x16_bf16 v[64:79], v[128:131], v[156:159], v[64:79]
	s_waitcnt lgkmcnt(6)
	v_mfma_f32_32x32x16_bf16 v[48:63], v[132:135], v[144:147], v[48:63]
	v_mfma_f32_32x32x16_bf16 v[32:47], v[132:135], v[148:151], v[32:47]
	v_mfma_f32_32x32x16_bf16 v[16:31], v[132:135], v[152:155], v[16:31]
	v_mfma_f32_32x32x16_bf16 v[0:15], v[132:135], v[156:159], v[0:15]
	s_waitcnt lgkmcnt(4)
	v_mfma_f32_32x32x16_bf16 v[112:127], v[136:139], v[160:163], v[112:127]
	s_waitcnt lgkmcnt(3)
	v_mfma_f32_32x32x16_bf16 v[96:111], v[136:139], v[164:167], v[96:111]
	s_waitcnt lgkmcnt(2)
	v_mfma_f32_32x32x16_bf16 v[80:95], v[136:139], v[168:171], v[80:95]
	s_waitcnt lgkmcnt(1)
	v_mfma_f32_32x32x16_bf16 v[64:79], v[136:139], v[172:175], v[64:79]
	s_waitcnt lgkmcnt(0)
	v_mfma_f32_32x32x16_bf16 v[48:63], v[140:143], v[160:163], v[48:63]
	v_mfma_f32_32x32x16_bf16 v[32:47], v[140:143], v[164:167], v[32:47]
	v_mfma_f32_32x32x16_bf16 v[16:31], v[140:143], v[168:171], v[16:31]
	v_mfma_f32_32x32x16_bf16 v[0:15], v[140:143], v[172:175], v[0:15]
	s_nop 7
	v_readlane_b32 s64, v187, 0
	v_readlane_b32 s65, v187, 1
	v_readlane_b32 s66, v187, 2
	v_readlane_b32 s67, v187, 3
	v_readlane_b32 s68, v187, 4
	v_readlane_b32 s69, v187, 5
	v_readlane_b32 s70, v187, 6
	v_readlane_b32 s71, v187, 7
	v_readlane_b32 s72, v187, 8
	v_readlane_b32 s73, v187, 9
	v_readlane_b32 s74, v187, 10
	v_readlane_b32 s75, v187, 11
	v_readlane_b32 s76, v187, 12
	v_readlane_b32 s77, v187, 13
	v_readlane_b32 s78, v187, 14
	v_readlane_b32 s79, v187, 15
	s_nop 7
	s_branch .LBB0_1545
.LBB0_1559:
	v_readlane_b32 s2, v254, 2
	v_readlane_b32 s3, v254, 3
	s_cmp_lt_i32 s2, 18
	s_cselect_b64 s[0:1], -1, 0
	s_cmp_gt_i32 s3, 17
	s_cselect_b64 s[2:3], -1, 0
	s_and_b64 s[0:1], s[0:1], s[2:3]
	s_andn2_b64 vcc, exec, s[0:1]
	s_cbranch_vccnz .LBB0_1613
	s_getreg_b32 s4, hwreg(HW_REG_XCC_ID, 0, 4)
	s_waitcnt vmcnt(0)
	s_waitcnt lgkmcnt(0)
	s_barrier
	s_and_saveexec_b64 s[0:1], s[50:51]
	s_cbranch_execz .LBB0_1612
	v_mov_b32_e32 v16, 0
	s_waitcnt vmcnt(0) expcnt(0) lgkmcnt(0)
	ds_read_b32 v2, v16 offset:65520
	s_load_dwordx2 s[2:3], s[92:93], 0x1f0
	ds_read_b32 v0, v16 offset:65524
	s_and_b32 s18, s4, 15
	s_waitcnt lgkmcnt(0)
	v_cmp_ne_u32_e32 vcc, 0, v2
	s_cbranch_vccnz .LBB0_1576
	s_add_u32 s4, s2, 0x1000
	s_addc_u32 s5, s3, 0
	s_add_u32 s6, s2, 0x1100
	s_addc_u32 s7, s3, 0
	s_add_u32 s8, s2, 0x1200
	s_addc_u32 s9, s3, 0
	s_mul_i32 s19, s35, s94
	s_add_u32 s10, s2, 0x1300
	s_mul_i32 s19, s19, s34
	s_addc_u32 s11, s3, 0
	s_mov_b32 s20, 1
	s_branch .LBB0_1564

; #define GA_LOAD(pr_) do { _Pragma("unroll") for (int i = 0; i < 4; ++i) ra[i] = *(const u32x4*)(Ab + (i * 32) * lda + (pr_) * 64); } while (0)
; #define GB_LOAD(kt_) do { const bfr* bk_ = Bb + (kt_) * NB * 32; \
;     _Pragma("unroll") for (int i = 0; i < 4; ++i) rb[i] = *(const u32x4*)(bk_ + (i * 64) * 32); } while (0)
; #define G_STORE(kt_) do { bfr* as_ = S0 + ((kt_) & 1) * GSTAGE; bfr* bs_ = as_ + 128 * 40; \
;     if (apar == ((kt_) & 1)) { _Pragma("unroll") for (int i = 0; i < 4; ++i) *(u32x4*)(as_ + asoff + i * 32 * 40) = ra[i]; } \
;     _Pragma("unroll") for (int i = 0; i < 4; ++i) *(u32x4*)(bs_ + bsoff + i * 64 * 40) = rb[i]; } while (0)
; template <int lda>
; DI void gemm_mainloop(const bfr* __restrict__ A, const bfr* __restrict__ Bt, int NB, int K, int m0, int n0, char* smem, f32x16 (&acc)[2][4]) {
;   bfr* S0 = (bfr*)smem;
;   int tid = threadIdx.x;
;   asm volatile("" : "+v"(tid));
;   const int lane = tid & 63, wid = tid >> 6, wr = wid >> 1, wc = wid & 1;
;   const int r = lane & 31, hl = lane >> 5;
; #pragma unroll
;   for (int i = 0; i < 2; ++i)
; #pragma unroll
;     for (int j = 0; j < 4; ++j)
; #pragma unroll
;       for (int q = 0; q < 16; ++q) acc[i][j][q] = 0.f;
;   u32x4 ra[4], rb[4];
;   const int nk = K >> 5;
;   const int arow = tid >> 3, ac8 = tid & 7, apar = ac8 >> 2;
;   const bfr* Ab = A + (m0 + arow) * lda + ac8 * 8;
;   const int asoff = arow * 40 + (ac8 & 3) * 8;
;   const int brow = tid >> 2, bc4 = tid & 3;
;   const bfr* Bb = Bt + (n0 + brow) * 32 + bc4 * 8;
;   const int bsoff = brow * 40 + bc4 * 8;
;     ...
;   GA_LOAD(0);
;   GB_LOAD(0);
;   G_STORE(0);
;   GB_LOAD(1);
;   __syncthreads();
; template <bool FIRST, bool HAS_H>
; DI void phase_gemm_resid(const Params& p, const bfr* A, const bfr* Wt, const float* gnext, float* ss, char* smem) {
;     ...
;   for (int t0 = blockIdx.x; t0 < 128 * 4; t0 += gridDim.x) {
;     const int t = ((gridDim.x & 7) == 0) ? xcd_tile(t0, 4) : t0;
;     const int mt = t >> 2, nt = t & 3, m0 = mt * 128, n0 = nt * 256;
;     f32x16 acc[2][4];
;     gemm_mainloop<1024>(A, Wt, 1024, 1024, m0, n0, smem, acc);
.LBB0_1721:
	s_lshl_b32 s5, s4, 5
	s_and_b32 s59, s5, 0xffffff80
	s_lshl_b32 s4, s4, 8
	s_and_b32 s58, s4, 0x300
	s_mov_b32 s60, 0
	s_mov_b64 s[16:17], 0
	s_lshl_b32 s98, s59, 11
	s_add_u32 s98, s6, s98
	s_addc_u32 s99, s7, 0
	s_lshl_b32 s100, s58, 6
	s_add_u32 s100, s2, s100
	s_addc_u32 s101, s3, 0
	v_writelane_b32 v188, s64, 0
	v_writelane_b32 v188, s65, 1
	v_writelane_b32 v188, s66, 2
	v_writelane_b32 v188, s67, 3
	v_writelane_b32 v188, s68, 4
	v_writelane_b32 v188, s69, 5
	v_writelane_b32 v188, s70, 6
	v_writelane_b32 v188, s71, 7
	v_writelane_b32 v188, s72, 8
	v_writelane_b32 v188, s73, 9
	v_writelane_b32 v188, s74, 10
	v_writelane_b32 v188, s75, 11
	v_writelane_b32 v188, s76, 12
	v_writelane_b32 v188, s77, 13
	v_writelane_b32 v188, s78, 14
	v_writelane_b32 v188, s79, 15
	v_lshrrev_b32_e32 v189, 6, v196
	v_and_b32_e32 v190, 63, v196
	v_readfirstlane_b32 s73, v189
	v_lshrrev_b32_e32 v191, 2, v190
	v_bfe_u32 v192, v190, 4, 2
	v_and_b32_e32 v189, 3, v190
	v_xor_b32_e32 v189, v189, v192
	v_lshlrev_b32_e32 v189, 4, v189
	v_lshl_add_u32 v176, v191, 11, v189
	v_add_u32_e32 v177, 0x8000, v176
	v_lshl_add_u32 v178, v191, 6, v189
	v_and_b32_e32 v191, 31, v190
	v_lshrrev_b32_e32 v192, 5, v190
	v_bfe_u32 v189, v190, 2, 2
	v_xor_b32_e32 v189, v189, v192
	v_lshlrev_b32_e32 v189, 4, v189
	v_lshl_add_u32 v179, v191, 6, v189
	s_lshr_b32 s74, s73, 1
	s_lshl_b32 s74, s74, 12
	s_and_b32 s75, s73, 1
	s_lshl_b32 s75, s75, 13
	v_add_u32_e32 v182, s75, v179
	v_add_u32_e32 v179, s74, v179
	v_xor_b32_e32 v183, 32, v182
	v_xor_b32_e32 v180, 32, v179
	s_lshl_b32 s74, s73, 16
	s_add_u32 s64, s98, s74
	s_addc_u32 s65, s99, 0
	s_lshl_b32 s74, s73, 12
	s_add_u32 s66, s100, s74
	s_addc_u32 s67, s101, 0
	s_lshl_b32 s68, s73, 11
	s_lshl_b32 s69, s73, 12
	s_mov_b32 s70, 0
	s_mov_b32 s71, 0
	s_mov_b32 s72, 0
	s_waitcnt lgkmcnt(0)
	s_barrier
	s_mul_i32 s74, s70, 0x6000
	s_add_u32 s75, s74, s68
	s_mov_b32 m0, s75
	s_add_u32 s76, s74, 0x2000
	s_cmp_eq_u32 s70, 2
	s_cselect_b32 s76, 0x10000, s76
	global_load_lds_dwordx4 v176, s[64:65]
	s_add_u32 m0, s75, 0x400
	s_add_u32 s76, s76, s69
	global_load_lds_dwordx4 v177, s[64:65]
	s_mov_b32 m0, s76
	s_add_u32 s64, s64, 64
	s_addc_u32 s65, s65, 0
	global_load_lds_dwordx4 v178, s[66:67]
	global_load_lds_dwordx4 v178, s[66:67] offset:1024
	global_load_lds_dwordx4 v178, s[66:67] offset:2048
	global_load_lds_dwordx4 v178, s[66:67] offset:3072
	s_add_u32 s66, s66, 0x10000
	s_addc_u32 s67, s67, 0
	s_add_u32 s70, s70, 1
	s_cmp_eq_u32 s70, 3
	s_cselect_b32 s70, 0, s70
	s_mul_i32 s74, s70, 0x6000
	s_add_u32 s75, s74, s68
	s_mov_b32 m0, s75
	s_add_u32 s76, s74, 0x2000
	s_cmp_eq_u32 s70, 2
	s_cselect_b32 s76, 0x10000, s76
	global_load_lds_dwordx4 v176, s[64:65]
	s_add_u32 m0, s75, 0x400
	s_add_u32 s76, s76, s69
	global_load_lds_dwordx4 v177, s[64:65]
	s_mov_b32 m0, s76
	s_add_u32 s64, s64, 64
	s_addc_u32 s65, s65, 0
	global_load_lds_dwordx4 v178, s[66:67]
	global_load_lds_dwordx4 v178, s[66:67] offset:1024
	global_load_lds_dwordx4 v178, s[66:67] offset:2048
	global_load_lds_dwordx4 v178, s[66:67] offset:3072
	s_add_u32 s66, s66, 0x10000
	s_addc_u32 s67, s67, 0
	s_add_u32 s70, s70, 1
	s_cmp_eq_u32 s70, 3
	s_cselect_b32 s70, 0, s70
	v_mov_b32_e32 v112, 0
	v_mov_b32_e32 v113, 0
	v_mov_b32_e32 v114, 0
	v_mov_b32_e32 v115, 0
	v_mov_b32_e32 v116, 0
	v_mov_b32_e32 v117, 0
	v_mov_b32_e32 v118, 0
	v_mov_b32_e32 v119, 0
	v_mov_b32_e32 v120, 0
	v_mov_b32_e32 v121, 0
	v_mov_b32_e32 v122, 0
	v_mov_b32_e32 v123, 0
	v_mov_b32_e32 v124, 0
	v_mov_b32_e32 v125, 0
	v_mov_b32_e32 v126, 0
	v_mov_b32_e32 v127, 0
	v_mov_b32_e32 v96, 0
	v_mov_b32_e32 v97, 0
	v_mov_b32_e32 v98, 0
	v_mov_b32_e32 v99, 0
	v_mov_b32_e32 v100, 0
	v_mov_b32_e32 v101, 0
	v_mov_b32_e32 v102, 0
	v_mov_b32_e32 v103, 0
	v_mov_b32_e32 v104, 0
	v_mov_b32_e32 v105, 0
	v_mov_b32_e32 v106, 0
	v_mov_b32_e32 v107, 0
	v_mov_b32_e32 v108, 0
	v_mov_b32_e32 v109, 0
	v_mov_b32_e32 v110, 0
	v_mov_b32_e32 v111, 0
	v_mov_b32_e32 v80, 0
	v_mov_b32_e32 v81, 0
	v_mov_b32_e32 v82, 0
	v_mov_b32_e32 v83, 0
	v_mov_b32_e32 v84, 0
	v_mov_b32_e32 v85, 0
	v_mov_b32_e32 v86, 0
	v_mov_b32_e32 v87, 0
	v_mov_b32_e32 v88, 0
	v_mov_b32_e32 v89, 0
	v_mov_b32_e32 v90, 0
	v_mov_b32_e32 v91, 0
	v_mov_b32_e32 v92, 0
	v_mov_b32_e32 v93, 0
	v_mov_b32_e32 v94, 0
	v_mov_b32_e32 v95, 0
	v_mov_b32_e32 v64, 0
	v_mov_b32_e32 v65, 0
	v_mov_b32_e32 v66, 0
	v_mov_b32_e32 v67, 0
	v_mov_b32_e32 v68, 0
	v_mov_b32_e32 v69, 0
	v_mov_b32_e32 v70, 0
	v_mov_b32_e32 v71, 0
	v_mov_b32_e32 v72, 0
	v_mov_b32_e32 v73, 0
	v_mov_b32_e32 v74, 0
	v_mov_b32_e32 v75, 0
	v_mov_b32_e32 v76, 0
	v_mov_b32_e32 v77, 0
	v_mov_b32_e32 v78, 0
	v_mov_b32_e32 v79, 0
	v_mov_b32_e32 v48, 0
	v_mov_b32_e32 v49, 0
	v_mov_b32_e32 v50, 0
	v_mov_b32_e32 v51, 0
	v_mov_b32_e32 v52, 0
	v_mov_b32_e32 v53, 0
	v_mov_b32_e32 v54, 0
	v_mov_b32_e32 v55, 0
	v_mov_b32_e32 v56, 0
	v_mov_b32_e32 v57, 0
	v_mov_b32_e32 v58, 0
	v_mov_b32_e32 v59, 0
	v_mov_b32_e32 v60, 0
	v_mov_b32_e32 v61, 0
	v_mov_b32_e32 v62, 0
	v_mov_b32_e32 v63, 0
	v_mov_b32_e32 v32, 0
	v_mov_b32_e32 v33, 0
	v_mov_b32_e32 v34, 0
	v_mov_b32_e32 v35, 0
	v_mov_b32_e32 v36, 0
	v_mov_b32_e32 v37, 0
	v_mov_b32_e32 v38, 0
	v_mov_b32_e32 v39, 0
	v_mov_b32_e32 v40, 0
	v_mov_b32_e32 v41, 0
	v_mov_b32_e32 v42, 0
	v_mov_b32_e32 v43, 0
	v_mov_b32_e32 v44, 0
	v_mov_b32_e32 v45, 0
	v_mov_b32_e32 v46, 0
	v_mov_b32_e32 v47, 0
	v_mov_b32_e32 v16, 0
	v_mov_b32_e32 v17, 0
	v_mov_b32_e32 v18, 0
	v_mov_b32_e32 v19, 0
	v_mov_b32_e32 v20, 0
	v_mov_b32_e32 v21, 0
	v_mov_b32_e32 v22, 0
	v_mov_b32_e32 v23, 0
	v_mov_b32_e32 v24, 0
	v_mov_b32_e32 v25, 0
	v_mov_b32_e32 v26, 0
	v_mov_b32_e32 v27, 0
	v_mov_b32_e32 v28, 0
	v_mov_b32_e32 v29, 0
	v_mov_b32_e32 v30, 0
	v_mov_b32_e32 v31, 0
	v_mov_b32_e32 v0, 0
	v_mov_b32_e32 v1, 0
	v_mov_b32_e32 v2, 0
	v_mov_b32_e32 v3, 0
	v_mov_b32_e32 v4, 0
	v_mov_b32_e32 v5, 0
	v_mov_b32_e32 v6, 0
	v_mov_b32_e32 v7, 0
	v_mov_b32_e32 v8, 0
	v_mov_b32_e32 v9, 0
	v_mov_b32_e32 v10, 0
	v_mov_b32_e32 v11, 0
	v_mov_b32_e32 v12, 0
	v_mov_b32_e32 v13, 0
	v_mov_b32_e32 v14, 0
	v_mov_b32_e32 v15, 0
; #define MFMA32(a, b, c) __builtin_amdgcn_mfma_f32_32x32x16_bf16((a), (b), (c), 0, 0, 0)
; #define GA_LOAD(pr_) do { _Pragma("unroll") for (int i = 0; i < 4; ++i) ra[i] = *(const u32x4*)(Ab + (i * 32) * lda + (pr_) * 64); } while (0)
; #define GB_LOAD(kt_) do { const bfr* bk_ = Bb + (kt_) * NB * 32; \
;     _Pragma("unroll") for (int i = 0; i < 4; ++i) rb[i] = *(const u32x4*)(bk_ + (i * 64) * 32); } while (0)
; #define G_STORE(kt_) do { bfr* as_ = S0 + ((kt_) & 1) * GSTAGE; bfr* bs_ = as_ + 128 * 40; \
;     if (apar == ((kt_) & 1)) { _Pragma("unroll") for (int i = 0; i < 4; ++i) *(u32x4*)(as_ + asoff + i * 32 * 40) = ra[i]; } \
;     _Pragma("unroll") for (int i = 0; i < 4; ++i) *(u32x4*)(bs_ + bsoff + i * 64 * 40) = rb[i]; } while (0)
; template <int lda>
; DI void gemm_mainloop(const bfr* __restrict__ A, const bfr* __restrict__ Bt, int NB, int K, int m0, int n0, char* smem, f32x16 (&acc)[2][4]) {
;     ...
;   for (int kt = 0; kt < nk; ++kt) {
;     if (kt + 1 < nk) G_STORE(kt + 1);
;     if (kt + 2 < nk) {
;       GB_LOAD(kt + 2);
;       if ((kt & 1) == 0) GA_LOAD((kt >> 1) + 1);
;     }
;     const bfr* As = S0 + (kt & 1) * GSTAGE;
;     const bfr* Bs = As + 128 * 40;
; #pragma unroll
;     for (int ks = 0; ks < 2; ++ks) {
;       bf16x8 af[2], bfg[4];
; #pragma unroll
;       for (int i = 0; i < 2; ++i) af[i] = *(const bf16x8*)(As + (wr * 64 + i * 32 + r) * 40 + ks * 16 + hl * 8);
; #pragma unroll
;       for (int j = 0; j < 4; ++j) bfg[j] = *(const bf16x8*)(Bs + (wc * 128 + j * 32 + r) * 40 + ks * 16 + hl * 8);
; #pragma unroll
;       for (int i = 0; i < 2; ++i)
; #pragma unroll
;         for (int j = 0; j < 4; ++j) acc[i][j] = MFMA32(af[i], bfg[j], acc[i][j]);
;     }
;     __syncthreads();
;   }
.Lp19_loop:
	s_waitcnt vmcnt(6)
	s_barrier
	s_mul_i32 s74, s70, 0x6000
	s_add_u32 s75, s74, s68
	s_mov_b32 m0, s75
	s_add_u32 s76, s74, 0x2000
	s_cmp_eq_u32 s70, 2
	s_cselect_b32 s76, 0x10000, s76
	global_load_lds_dwordx4 v176, s[64:65]
	s_add_u32 m0, s75, 0x400
	s_add_u32 s76, s76, s69
	global_load_lds_dwordx4 v177, s[64:65]
	s_mov_b32 m0, s76
	s_add_u32 s64, s64, 64
	s_addc_u32 s65, s65, 0
	global_load_lds_dwordx4 v178, s[66:67]
	global_load_lds_dwordx4 v178, s[66:67] offset:1024
	global_load_lds_dwordx4 v178, s[66:67] offset:2048
	global_load_lds_dwordx4 v178, s[66:67] offset:3072
	s_add_u32 s66, s66, 0x10000
	s_addc_u32 s67, s67, 0
	s_add_u32 s70, s70, 1
	s_cmp_eq_u32 s70, 3
	s_cselect_b32 s70, 0, s70
	s_mul_i32 s74, s71, 0x6000
	s_add_u32 s75, s74, 0x2000
	s_cmp_eq_u32 s71, 2
	s_cselect_b32 s75, 0x10000, s75
	v_add_u32_e32 v184, s74, v179
	v_add_u32_e32 v186, s75, v182
	v_add_u32_e32 v185, s74, v180
	v_add_u32_e32 v187, s75, v183
	ds_read_b128 v[128:131], v184
	ds_read_b128 v[144:147], v186
	ds_read_b128 v[148:151], v186 offset:2048
	ds_read_b128 v[152:155], v186 offset:4096
	ds_read_b128 v[156:159], v186 offset:6144
	ds_read_b128 v[132:135], v184 offset:2048
	ds_read_b128 v[136:139], v185
	ds_read_b128 v[160:163], v187
	ds_read_b128 v[164:167], v187 offset:2048
	ds_read_b128 v[168:171], v187 offset:4096
	ds_read_b128 v[172:175], v187 offset:6144
	ds_read_b128 v[140:143], v185 offset:2048
	s_add_u32 s71, s71, 1
	s_cmp_eq_u32 s71, 3
	s_cselect_b32 s71, 0, s71
	s_waitcnt lgkmcnt(10)
	v_mfma_f32_32x32x16_bf16 v[112:127], v[128:131], v[144:147], v[112:127]
	s_waitcnt lgkmcnt(9)
	v_mfma_f32_32x32x16_bf16 v[96:111], v[128:131], v[148:151], v[96:111]
	s_waitcnt lgkmcnt(8)
	v_mfma_f32_32x32x16_bf16 v[80:95], v[128:131], v[152:155], v[80:95]
	s_waitcnt lgkmcnt(7)
	v_mfma_f32_32x32x16_bf16 v[64:79], v[128:131], v[156:159], v[64:79]
	s_waitcnt lgkmcnt(6)
	v_mfma_f32_32x32x16_bf16 v[48:63], v[132:135], v[144:147], v[48:63]
	v_mfma_f32_32x32x16_bf16 v[32:47], v[132:135], v[148:151], v[32:47]
	v_mfma_f32_32x32x16_bf16 v[16:31], v[132:135], v[152:155], v[16:31]
	v_mfma_f32_32x32x16_bf16 v[0:15], v[132:135], v[156:159], v[0:15]
	s_waitcnt lgkmcnt(4)
	v_mfma_f32_32x32x16_bf16 v[112:127], v[136:139], v[160:163], v[112:127]
	s_waitcnt lgkmcnt(3)
	v_mfma_f32_32x32x16_bf16 v[96:111], v[136:139], v[164:167], v[96:111]
	s_waitcnt lgkmcnt(2)
	v_mfma_f32_32x32x16_bf16 v[80:95], v[136:139], v[168:171], v[80:95]
	s_waitcnt lgkmcnt(1)
	v_mfma_f32_32x32x16_bf16 v[64:79], v[136:139], v[172:175], v[64:79]
	s_waitcnt lgkmcnt(0)
	v_mfma_f32_32x32x16_bf16 v[48:63], v[140:143], v[160:163], v[48:63]
	v_mfma_f32_32x32x16_bf16 v[32:47], v[140:143], v[164:167], v[32:47]
	v_mfma_f32_32x32x16_bf16 v[16:31], v[140:143], v[168:171], v[16:31]
	v_mfma_f32_32x32x16_bf16 v[0:15], v[140:143], v[172:175], v[0:15]
	s_add_u32 s72, s72, 1
	s_cmp_lt_u32 s72, 30
	s_cbranch_scc1 .Lp19_loop
	s_waitcnt vmcnt(6)
	s_barrier
	s_mul_i32 s74, s71, 0x6000
	s_add_u32 s75, s74, 0x2000
	s_cmp_eq_u32 s71, 2
	s_cselect_b32 s75, 0x10000, s75
	v_add_u32_e32 v184, s74, v179
	v_add_u32_e32 v186, s75, v182
	v_add_u32_e32 v185, s74, v180
	v_add_u32_e32 v187, s75, v183
	ds_read_b128 v[128:131], v184
	ds_read_b128 v[144:147], v186
	ds_read_b128 v[148:151], v186 offset:2048
	ds_read_b128 v[152:155], v186 offset:4096
	ds_read_b128 v[156:159], v186 offset:6144
	ds_read_b128 v[132:135], v184 offset:2048
	ds_read_b128 v[136:139], v185
	ds_read_b128 v[160:163], v187
	ds_read_b128 v[164:167], v187 offset:2048
	ds_read_b128 v[168:171], v187 offset:4096
	ds_read_b128 v[172:175], v187 offset:6144
	ds_read_b128 v[140:143], v185 offset:2048
	s_add_u32 s71, s71, 1
	s_cmp_eq_u32 s71, 3
	s_cselect_b32 s71, 0, s71
	s_waitcnt lgkmcnt(10)
	v_mfma_f32_32x32x16_bf16 v[112:127], v[128:131], v[144:147], v[112:127]
	s_waitcnt lgkmcnt(9)
	v_mfma_f32_32x32x16_bf16 v[96:111], v[128:131], v[148:151], v[96:111]
	s_waitcnt lgkmcnt(8)
	v_mfma_f32_32x32x16_bf16 v[80:95], v[128:131], v[152:155], v[80:95]
	s_waitcnt lgkmcnt(7)
	v_mfma_f32_32x32x16_bf16 v[64:79], v[128:131], v[156:159], v[64:79]
	s_waitcnt lgkmcnt(6)
	v_mfma_f32_32x32x16_bf16 v[48:63], v[132:135], v[144:147], v[48:63]
	v_mfma_f32_32x32x16_bf16 v[32:47], v[132:135], v[148:151], v[32:47]
	v_mfma_f32_32x32x16_bf16 v[16:31], v[132:135], v[152:155], v[16:31]
	v_mfma_f32_32x32x16_bf16 v[0:15], v[132:135], v[156:159], v[0:15]
	s_waitcnt lgkmcnt(4)
	v_mfma_f32_32x32x16_bf16 v[112:127], v[136:139], v[160:163], v[112:127]
	s_waitcnt lgkmcnt(3)
	v_mfma_f32_32x32x16_bf16 v[96:111], v[136:139], v[164:167], v[96:111]
	s_waitcnt lgkmcnt(2)
	v_mfma_f32_32x32x16_bf16 v[80:95], v[136:139], v[168:171], v[80:95]
	s_waitcnt lgkmcnt(1)
	v_mfma_f32_32x32x16_bf16 v[64:79], v[136:139], v[172:175], v[64:79]
	s_waitcnt lgkmcnt(0)
	v_mfma_f32_32x32x16_bf16 v[48:63], v[140:143], v[160:163], v[48:63]
	v_mfma_f32_32x32x16_bf16 v[32:47], v[140:143], v[164:167], v[32:47]
	v_mfma_f32_32x32x16_bf16 v[16:31], v[140:143], v[168:171], v[16:31]
	v_mfma_f32_32x32x16_bf16 v[0:15], v[140:143], v[172:175], v[0:15]
	s_waitcnt vmcnt(0)
	s_barrier
; #define MFMA32(a, b, c) __builtin_amdgcn_mfma_f32_32x32x16_bf16((a), (b), (c), 0, 0, 0)
; DI int crow(int reg, int h) { return (reg & 3) + 8 * (reg >> 2) + 4 * h; }
; template <int lda>
; DI void gemm_mainloop(const bfr* __restrict__ A, const bfr* __restrict__ Bt, int NB, int K, int m0, int n0, char* smem, f32x16 (&acc)[2][4]) {
;     ...
; #pragma unroll
;     for (int ks = 0; ks < 2; ++ks) {
;       bf16x8 af[2], bfg[4];
; #pragma unroll
;       for (int i = 0; i < 2; ++i) af[i] = *(const bf16x8*)(As + (wr * 64 + i * 32 + r) * 40 + ks * 16 + hl * 8);
; #pragma unroll
;       for (int j = 0; j < 4; ++j) bfg[j] = *(const bf16x8*)(Bs + (wc * 128 + j * 32 + r) * 40 + ks * 16 + hl * 8);
; #pragma unroll
;       for (int i = 0; i < 2; ++i)
; #pragma unroll
;         for (int j = 0; j < 4; ++j) acc[i][j] = MFMA32(af[i], bfg[j], acc[i][j]);
;     }
;     __syncthreads();
;   }
; template <bool FIRST, bool HAS_H>
; DI void phase_gemm_resid(const Params& p, const bfr* A, const bfr* Wt, const float* gnext, float* ss, char* smem) {
;     ...
;     int tid2 = threadIdx.x;
;     asm volatile("" : "+v"(tid2));
;     const int lane = tid2 & 63, wid = tid2 >> 6, wr = wid >> 1, wc = wid & 1, r = lane & 31, hl = lane >> 5;
;     const float* xsrc = FIRST ? p.x_prompt : X;
;     const int rbase = m0 + wr * 64 + 4 * hl, cbase = n0 + wc * 128 + r;
; #pragma unroll
;     for (int i = 0; i < 2; ++i) {
; #pragma unroll
;       for (int qh = 0; qh < 2; ++qh) {
;         float rs[8];
; #pragma unroll
;         for (int q = 0; q < 8; ++q) rs[q] = 0.f;
; #pragma unroll
;         for (int jh = 0; jh < 2; ++jh) {
;           float xo[2][8];
; #pragma unroll
;           for (int jj = 0; jj < 2; ++jj)
; #pragma unroll
;             for (int q = 0; q < 8; ++q)
;               xo[jj][q] = xsrc[(rbase + i * 32 + crow(qh * 8 + q, 0)) * 1024 + cbase + (jh * 2 + jj) * 32];
	s_mul_i32 s74, s71, 0x6000
	s_add_u32 s75, s74, 0x2000
	s_cmp_eq_u32 s71, 2
	s_cselect_b32 s75, 0x10000, s75
	v_add_u32_e32 v184, s74, v179
	v_add_u32_e32 v186, s75, v182
	v_add_u32_e32 v185, s74, v180
	v_add_u32_e32 v187, s75, v183
	ds_read_b128 v[128:131], v184
	ds_read_b128 v[144:147], v186
	ds_read_b128 v[148:151], v186 offset:2048
	ds_read_b128 v[152:155], v186 offset:4096
	ds_read_b128 v[156:159], v186 offset:6144
	ds_read_b128 v[132:135], v184 offset:2048
	ds_read_b128 v[136:139], v185
	ds_read_b128 v[160:163], v187
	ds_read_b128 v[164:167], v187 offset:2048
	ds_read_b128 v[168:171], v187 offset:4096
	ds_read_b128 v[172:175], v187 offset:6144
	ds_read_b128 v[140:143], v185 offset:2048
	s_add_u32 s71, s71, 1
	s_cmp_eq_u32 s71, 3
	s_cselect_b32 s71, 0, s71
	s_waitcnt lgkmcnt(10)
	v_mfma_f32_32x32x16_bf16 v[112:127], v[128:131], v[144:147], v[112:127]
	s_waitcnt lgkmcnt(9)
	v_mfma_f32_32x32x16_bf16 v[96:111], v[128:131], v[148:151], v[96:111]
	s_waitcnt lgkmcnt(8)
	v_mfma_f32_32x32x16_bf16 v[80:95], v[128:131], v[152:155], v[80:95]
	s_waitcnt lgkmcnt(7)
	v_mfma_f32_32x32x16_bf16 v[64:79], v[128:131], v[156:159], v[64:79]
	s_waitcnt lgkmcnt(6)
	v_mfma_f32_32x32x16_bf16 v[48:63], v[132:135], v[144:147], v[48:63]
	v_mfma_f32_32x32x16_bf16 v[32:47], v[132:135], v[148:151], v[32:47]
	v_mfma_f32_32x32x16_bf16 v[16:31], v[132:135], v[152:155], v[16:31]
	v_mfma_f32_32x32x16_bf16 v[0:15], v[132:135], v[156:159], v[0:15]
	s_waitcnt lgkmcnt(4)
	v_mfma_f32_32x32x16_bf16 v[112:127], v[136:139], v[160:163], v[112:127]
	s_waitcnt lgkmcnt(3)
	v_mfma_f32_32x32x16_bf16 v[96:111], v[136:139], v[164:167], v[96:111]
	s_waitcnt lgkmcnt(2)
	v_mfma_f32_32x32x16_bf16 v[80:95], v[136:139], v[168:171], v[80:95]
	s_waitcnt lgkmcnt(1)
	v_mfma_f32_32x32x16_bf16 v[64:79], v[136:139], v[172:175], v[64:79]
	s_waitcnt lgkmcnt(0)
	v_mfma_f32_32x32x16_bf16 v[48:63], v[140:143], v[160:163], v[48:63]
	v_mfma_f32_32x32x16_bf16 v[32:47], v[140:143], v[164:167], v[32:47]
	v_mfma_f32_32x32x16_bf16 v[16:31], v[140:143], v[168:171], v[16:31]
	v_mfma_f32_32x32x16_bf16 v[0:15], v[140:143], v[172:175], v[0:15]
	s_nop 7
	v_readlane_b32 s64, v188, 0
	v_readlane_b32 s65, v188, 1
	v_readlane_b32 s66, v188, 2
	v_readlane_b32 s67, v188, 3
	v_readlane_b32 s68, v188, 4
	v_readlane_b32 s69, v188, 5
	v_readlane_b32 s70, v188, 6
	v_readlane_b32 s71, v188, 7
	v_readlane_b32 s72, v188, 8
	v_readlane_b32 s73, v188, 9
	v_readlane_b32 s74, v188, 10
	v_readlane_b32 s75, v188, 11
	v_readlane_b32 s76, v188, 12
	v_readlane_b32 s77, v188, 13
	v_readlane_b32 s78, v188, 14
	v_readlane_b32 s79, v188, 15
	s_nop 7
	s_waitcnt vmcnt(1)
	s_nop 0
	s_nop 0
	s_nop 0
	s_waitcnt vmcnt(0)
	s_nop 0
	v_add_u32_e32 v136, v169, v171
	s_nop 0
	v_add_u32_e32 v180, v169, v170
	s_nop 0
	s_nop 0
	s_nop 0
	s_nop 0
	s_nop 0
	s_nop 0
	s_nop 0
	s_nop 0
	s_nop 0
	s_nop 0
	s_nop 0
	s_waitcnt lgkmcnt(0)
	s_nop 0
	s_nop 0
	s_nop 0
	s_nop 0
	s_nop 0
	s_nop 0
	s_nop 0
	s_nop 0
	s_nop 0
	s_nop 0
	s_nop 0
	s_nop 0
	s_nop 0
	s_nop 0
	s_nop 0
	s_nop 0
	s_nop 0
	s_nop 0
	v_mov_b32_e32 v180, v196
	s_waitcnt lgkmcnt(0)
	s_nop 0
	s_nop 0
	v_ashrrev_i32_e32 v182, 1, v180
	v_and_b32_e32 v182, 0xffffffc0, v182
	v_add_u32_e32 v182, s59, v182
	v_lshrrev_b32_e32 v183, 3, v180
	v_and_b32_e32 v185, 31, v180
	v_and_or_b32 v184, v183, 4, v182
	v_lshlrev_b32_e32 v180, 1, v180
	v_and_b32_e32 v180, 0x80, v180
	v_lshlrev_b32_e32 v186, 10, v184
	v_or3_b32 v180, s58, v180, v185
	v_or_b32_e32 v197, 0x400, v186
	v_or_b32_e32 v199, 0x800, v186
	s_nop 0
	v_or_b32_e32 v204, v186, v180
	v_or_b32_e32 v206, v197, v180
	v_ashrrev_i32_e32 v205, 31, v204
	v_ashrrev_i32_e32 v207, 31, v206
	v_or_b32_e32 v187, 32, v180
	v_lshl_add_u64 v[182:183], v[204:205], 2, s[8:9]
	v_lshl_add_u64 v[206:207], v[206:207], 2, s[8:9]
	s_nop 0
	v_or_b32_e32 v212, v199, v180
	v_ashrrev_i32_e32 v213, 31, v212
	v_lshl_add_u64 v[212:213], v[212:213], 2, s[8:9]
	v_or_b32_e32 v224, 0xc00, v186
	v_or_b32_e32 v225, 0x2000, v186
	v_or_b32_e32 v214, v197, v187
	global_load_dword v216, v[182:183], off
	global_load_dword v217, v[206:207], off
	global_load_dword v218, v[212:213], off
	s_nop 0
	v_ashrrev_i32_e32 v205, 31, v186
	v_or_b32_e32 v206, v224, v180
	v_or_b32_e32 v212, v225, v180
	v_ashrrev_i32_e32 v215, 31, v214
	v_lshl_add_u64 v[204:205], v[204:205], 2, s[8:9]
	v_ashrrev_i32_e32 v207, 31, v206
	v_ashrrev_i32_e32 v213, 31, v212
	s_nop 0
	v_lshl_add_u64 v[214:215], v[214:215], 2, s[8:9]
	global_load_dword v219, v[204:205], off offset:128
	v_lshl_add_u64 v[206:207], v[206:207], 2, s[8:9]
	global_load_dword v214, v[214:215], off
	s_nop 0
	s_nop 0
	v_or_b32_e32 v188, v199, v187
	v_ashrrev_i32_e32 v189, 31, v188
	v_lshl_add_u64 v[188:189], v[188:189], 2, s[8:9]
	global_load_dword v215, v[188:189], off
	v_lshl_add_u64 v[188:189], v[212:213], 2, s[8:9]
	global_load_dword v206, v[206:207], off
	s_nop 0
	global_load_dword v207, v[188:189], off
	v_or_b32_e32 v188, v224, v187
	v_or_b32_e32 v190, v225, v187
	v_ashrrev_i32_e32 v189, 31, v188
	v_ashrrev_i32_e32 v191, 31, v190
	s_nop 0
	v_or_b32_e32 v192, 0x2400, v186
	v_lshl_add_u64 v[188:189], v[188:189], 2, s[8:9]
	v_lshl_add_u64 v[190:191], v[190:191], 2, s[8:9]
	global_load_dword v193, v[188:189], off
	v_or_b32_e32 v195, 0x2800, v186
	s_nop 0
	global_load_dword v200, v[190:191], off
	v_or_b32_e32 v188, v192, v180
	v_or_b32_e32 v190, v192, v187
	v_ashrrev_i32_e32 v189, 31, v188
	v_ashrrev_i32_e32 v191, 31, v190
	v_lshl_add_u64 v[188:189], v[188:189], 2, s[8:9]
	v_lshl_add_u64 v[190:191], v[190:191], 2, s[8:9]
	global_load_dword v194, v[188:189], off
	v_or_b32_e32 v201, 0x2c00, v186
	global_load_dword v190, v[190:191], off
	v_or_b32_e32 v188, v195, v180
	v_ashrrev_i32_e32 v189, 31, v188
	v_lshl_add_u64 v[188:189], v[188:189], 2, s[8:9]
	global_load_dword v191, v[188:189], off
	v_or_b32_e32 v188, v201, v180
	v_ashrrev_i32_e32 v189, 31, v188
	v_lshl_add_u64 v[188:189], v[188:189], 2, s[8:9]
	global_load_dword v202, v[188:189], off
	v_or_b32_e32 v188, v195, v187
	v_ashrrev_i32_e32 v189, 31, v188
	v_lshl_add_u64 v[188:189], v[188:189], 2, s[8:9]
	global_load_dword v203, v[188:189], off
	v_or_b32_e32 v188, v201, v187
	v_ashrrev_i32_e32 v189, 31, v188
	v_lshl_add_u64 v[188:189], v[188:189], 2, s[8:9]
	global_load_dword v212, v[188:189], off
	s_nop 0
	s_nop 0
	s_nop 0
	s_waitcnt vmcnt(15)
; DI bfr f2bf(float a) { return (bfr)(pack2(a, 0.f) & 0xffffu); }
; DI int crow(int reg, int h) { return (reg & 3) + 8 * (reg >> 2) + 4 * h; }
; template <bool FIRST, bool HAS_H>
; DI void phase_gemm_resid(const Params& p, const bfr* A, const bfr* Wt, const float* gnext, float* ss, char* smem) {
;     ...
; #pragma unroll
;     for (int i = 0; i < 2; ++i) {
; #pragma unroll
;       for (int qh = 0; qh < 2; ++qh) {
;         float rs[8];
; #pragma unroll
;         for (int q = 0; q < 8; ++q) rs[q] = 0.f;
; #pragma unroll
;         for (int jh = 0; jh < 2; ++jh) {
;           float xo[2][8];
; #pragma unroll
;           for (int jj = 0; jj < 2; ++jj)
; #pragma unroll
;             for (int q = 0; q < 8; ++q)
;               xo[jj][q] = xsrc[(rbase + i * 32 + crow(qh * 8 + q, 0)) * 1024 + cbase + (jh * 2 + jj) * 32];
; #pragma unroll
;           for (int q = 0; q < 8; ++q) {
;             const int o = (rbase + i * 32 + crow(qh * 8 + q, 0)) * 1024 + cbase;
; #pragma unroll
;             for (int jj = 0; jj < 2; ++jj) {
;               const int j = jh * 2 + jj;
;               const float xn = xo[jj][q] + acc[i][j][qh * 8 + q];
;               X[o + j * 32] = xn;
;               if (HAS_H) Hn[o + j * 32] = f2bf(xn * gnext[cbase + j * 32]);
;               rs[q] += xn * xn;
;             }
;           }
;         }
	s_nop 9
	v_add_f32_e32 v213, v112, v216
	v_add_co_u32_e32 v112, vcc, s23, v182
	s_waitcnt vmcnt(14)
	v_add_f32_e32 v217, v113, v217
	v_addc_co_u32_e32 v113, vcc, 0, v183, vcc
	v_add_co_u32_e32 v188, vcc, s24, v182
	s_nop 0
	s_nop 0
	v_addc_co_u32_e32 v189, vcc, 0, v183, vcc
	global_store_dword v[182:183], v213, off
	global_store_dword v[188:189], v217, off offset:-4096
	s_waitcnt vmcnt(11)
	v_add_f32_e32 v206, v115, v206
	s_nop 0
	v_add_f32_e32 v209, v114, v218
	v_add_co_u32_e32 v114, vcc, s25, v182
	s_nop 2
	v_add_f32_e32 v210, v98, v215
	v_addc_co_u32_e32 v115, vcc, 0, v183, vcc
	v_or_b32_e32 v98, 64, v180
	s_nop 0
	v_add_co_u32_e32 v172, vcc, s33, v182
	v_add_f32_e32 v216, v96, v219
	s_nop 0
	v_addc_co_u32_e32 v173, vcc, 0, v183, vcc
	v_add_co_u32_e32 v174, vcc, s36, v182
	s_nop 0
	s_nop 0
	v_addc_co_u32_e32 v175, vcc, 0, v183, vcc
	s_waitcnt vmcnt(10)
	v_add_f32_e32 v207, v116, v207
	v_or_b32_e32 v96, v197, v98
	v_add_f32_e32 v208, v97, v214
	s_waitcnt vmcnt(9)
	v_add_f32_e32 v193, v99, v193
	v_ashrrev_i32_e32 v97, 31, v96
	s_nop 0
	global_store_dword v[182:183], v216, off offset:128
	global_store_dword v[112:113], v208, off offset:128
	global_store_dword v[188:189], v209, off
	global_store_dword v[188:189], v210, off offset:128
	global_store_dword v[114:115], v206, off
	global_store_dword v[114:115], v193, off offset:128
	global_store_dword v[174:175], v207, off offset:-4096
	s_nop 0
	s_waitcnt vmcnt(15)
	v_add_f32_e32 v164, v100, v200
	v_add_co_u32_e32 v100, vcc, s37, v182
	s_waitcnt vmcnt(13)
	v_add_f32_e32 v166, v101, v190
	v_addc_co_u32_e32 v101, vcc, 0, v183, vcc
	s_waitcnt vmcnt(12)
	v_add_f32_e32 v167, v118, v191
	s_nop 0
	v_add_co_u32_e32 v116, vcc, s38, v182
	s_waitcnt vmcnt(10)
	v_add_f32_e32 v168, v102, v203
	v_or_b32_e32 v102, v199, v98
	v_or_b32_e32 v118, v224, v98
	v_add_f32_e32 v165, v117, v194
	v_addc_co_u32_e32 v117, vcc, 0, v183, vcc
	s_nop 0
	v_add_f32_e32 v160, v119, v202
	s_waitcnt vmcnt(9)
	v_add_f32_e32 v161, v103, v212
	v_ashrrev_i32_e32 v103, 31, v102
	v_ashrrev_i32_e32 v119, 31, v118
	global_store_dword v[172:173], v164, off offset:128
	global_store_dword v[174:175], v165, off
	global_store_dword v[174:175], v166, off offset:128
	s_nop 0
	v_or_b32_e32 v152, v225, v98
	v_or_b32_e32 v154, v192, v98
	v_ashrrev_i32_e32 v153, 31, v152
	v_ashrrev_i32_e32 v155, 31, v154
	v_or_b32_e32 v156, v195, v98
	global_store_dword v[116:117], v167, off offset:-4096
	global_store_dword v[100:101], v168, off offset:128
	global_store_dword v[116:117], v160, off
	global_store_dword v[116:117], v161, off offset:128
	v_lshl_add_u64 v[96:97], v[96:97], 2, s[8:9]
	v_lshl_add_u64 v[102:103], v[102:103], 2, s[8:9]
	v_lshl_add_u64 v[118:119], v[118:119], 2, s[8:9]
	v_lshl_add_u64 v[152:153], v[152:153], 2, s[8:9]
	v_lshl_add_u64 v[154:155], v[154:155], 2, s[8:9]
	v_ashrrev_i32_e32 v157, 31, v156
	v_or_b32_e32 v99, 0x60, v180
	v_lshl_add_u64 v[156:157], v[156:157], 2, s[8:9]
	global_load_dword v158, v[204:205], off offset:256
	global_load_dword v159, v[96:97], off
	global_load_dword v162, v[102:103], off
	s_nop 0
	global_load_dword v118, v[118:119], off
	s_nop 0
	global_load_dword v119, v[152:153], off
	s_nop 0
	global_load_dword v152, v[154:155], off
	global_load_dword v153, v[156:157], off
	s_nop 0
	global_load_dword v154, v[204:205], off offset:384
	v_or_b32_e32 v96, v197, v99
	v_or_b32_e32 v102, v192, v99
	v_ashrrev_i32_e32 v97, 31, v96
	v_ashrrev_i32_e32 v103, 31, v102
	v_lshl_add_u64 v[96:97], v[96:97], 2, s[8:9]
	v_lshl_add_u64 v[102:103], v[102:103], 2, s[8:9]
	s_nop 0
	v_cmp_eq_u32_e32 vcc, 31, v185
	v_ashrrev_i32_e32 v185, 31, v184
	s_nop 0
	global_load_dword v148, v[96:97], off
	s_waitcnt vmcnt(8)
	s_nop 6
	v_add_f32_e32 v80, v80, v158
	s_nop 0
	global_load_dword v142, v[102:103], off
	v_or_b32_e32 v96, v199, v99
	v_ashrrev_i32_e32 v97, 31, v96
	v_lshl_add_u64 v[96:97], v[96:97], 2, s[8:9]
	global_load_dword v149, v[96:97], off
	v_or_b32_e32 v96, v224, v99
	v_ashrrev_i32_e32 v97, 31, v96
	v_lshl_add_u64 v[96:97], v[96:97], 2, s[8:9]
	global_load_dword v140, v[96:97], off
	v_or_b32_e32 v96, v225, v99
	v_ashrrev_i32_e32 v97, 31, v96
	v_lshl_add_u64 v[96:97], v[96:97], 2, s[8:9]
	global_load_dword v141, v[96:97], off
	v_or_b32_e32 v96, v201, v98
	v_or_b32_e32 v102, v195, v99
	v_ashrrev_i32_e32 v97, 31, v96
	v_ashrrev_i32_e32 v103, 31, v102
	v_lshl_add_u64 v[96:97], v[96:97], 2, s[8:9]
	v_lshl_add_u64 v[102:103], v[102:103], 2, s[8:9]
	global_load_dword v102, v[102:103], off
	s_nop 0
	global_load_dword v103, v[96:97], off
	v_or_b32_e32 v96, v201, v99
	v_ashrrev_i32_e32 v97, 31, v96
	v_lshl_add_u64 v[96:97], v[96:97], 2, s[8:9]
	s_nop 0
	global_load_dword v136, v[96:97], off
	s_waitcnt vmcnt(8)
	v_add_f32_e32 v64, v64, v154
	global_store_dword v[182:183], v64, off offset:384
	global_store_dword v[182:183], v80, off offset:256
	v_lshl_add_u64 v[96:97], v[184:185], 2, s[10:11]
	s_nop 0
	s_nop 0
	v_mul_f32_e32 v128, v216, v216
	v_fmac_f32_e32 v128, v213, v213
	v_mul_f32_e32 v129, v208, v208
	v_fmac_f32_e32 v128, v80, v80
	v_fmac_f32_e32 v129, v217, v217
	v_fmac_f32_e32 v128, v64, v64
	v_add_f32_e32 v64, v81, v159
	v_mul_f32_e32 v130, v210, v210
	global_store_dword v[112:113], v64, off offset:256
	v_fmac_f32_e32 v129, v64, v64
	s_waitcnt vmcnt(10)
	v_add_f32_e32 v64, v65, v148
	v_fmac_f32_e32 v130, v209, v209
	global_store_dword v[112:113], v64, off offset:384
	v_fmac_f32_e32 v129, v64, v64
	v_add_f32_e32 v64, v82, v162
	v_mul_f32_e32 v131, v193, v193
	global_store_dword v[188:189], v64, off offset:256
	v_fmac_f32_e32 v130, v64, v64
	v_fmac_f32_e32 v131, v206, v206
	v_mul_f32_e32 v132, v164, v164
	v_fmac_f32_e32 v132, v207, v207
	v_mul_f32_e32 v133, v166, v166
	v_fmac_f32_e32 v133, v165, v165
	v_mul_f32_e32 v134, v168, v168
	v_fmac_f32_e32 v134, v167, v167
	v_mul_f32_e32 v135, v161, v161
	v_fmac_f32_e32 v135, v160, v160
	v_mov_b32_e32 v65, 0
	v_mov_b32_e32 v81, 0
	s_waitcnt vmcnt(10)
; DI bfr f2bf(float a) { return (bfr)(pack2(a, 0.f) & 0xffffu); }
; DI int crow(int reg, int h) { return (reg & 3) + 8 * (reg >> 2) + 4 * h; }
; template <bool FIRST, bool HAS_H>
; DI void phase_gemm_resid(const Params& p, const bfr* A, const bfr* Wt, const float* gnext, float* ss, char* smem) {
;     ...
;         for (int jh = 0; jh < 2; ++jh) {
;           float xo[2][8];
; #pragma unroll
;           for (int jj = 0; jj < 2; ++jj)
; #pragma unroll
;             for (int q = 0; q < 8; ++q)
;               xo[jj][q] = xsrc[(rbase + i * 32 + crow(qh * 8 + q, 0)) * 1024 + cbase + (jh * 2 + jj) * 32];
; #pragma unroll
;           for (int q = 0; q < 8; ++q) {
;             const int o = (rbase + i * 32 + crow(qh * 8 + q, 0)) * 1024 + cbase;
; #pragma unroll
;             for (int jj = 0; jj < 2; ++jj) {
;               const int j = jh * 2 + jj;
;               const float xn = xo[jj][q] + acc[i][j][qh * 8 + q];
;               X[o + j * 32] = xn;
;               if (HAS_H) Hn[o + j * 32] = f2bf(xn * gnext[cbase + j * 32]);
;               rs[q] += xn * xn;
;             }
;           }
;         }
; #pragma unroll
;         for (int q = 0; q < 8; ++q) rs[q] = half32_sum_hi(rs[q]);
;         if (r == 31) {
; #pragma unroll
;           for (int q = 0; q < 8; ++q) unsafeAtomicAdd(ss + rbase + i * 32 + crow(qh * 8 + q, 0), rs[q]);
;         }
;       }
;     }
;   }
	v_add_f32_e32 v64, v66, v149
	global_store_dword v[188:189], v64, off offset:384
	v_fmac_f32_e32 v130, v64, v64
	v_add_f32_e32 v64, v83, v118
	global_store_dword v[114:115], v64, off offset:256
	v_fmac_f32_e32 v131, v64, v64
	s_waitcnt vmcnt(11)
	v_add_f32_e32 v64, v67, v140
	global_store_dword v[114:115], v64, off offset:384
	v_fmac_f32_e32 v131, v64, v64
	v_add_f32_e32 v64, v84, v119
	global_store_dword v[172:173], v64, off offset:256
	v_fmac_f32_e32 v132, v64, v64
	s_waitcnt vmcnt(12)
	v_add_f32_e32 v64, v68, v141
	global_store_dword v[172:173], v64, off offset:384
	v_fmac_f32_e32 v132, v64, v64
	v_add_f32_e32 v64, v85, v152
	global_store_dword v[174:175], v64, off offset:256
	v_fmac_f32_e32 v133, v64, v64
	v_add_f32_e32 v64, v69, v142
	global_store_dword v[174:175], v64, off offset:384
	v_fmac_f32_e32 v133, v64, v64
	v_add_f32_e32 v64, v86, v153
	global_store_dword v[100:101], v64, off offset:256
	v_fmac_f32_e32 v134, v64, v64
	s_waitcnt vmcnt(15)
	v_add_f32_e32 v64, v70, v102
	global_store_dword v[100:101], v64, off offset:384
	v_fmac_f32_e32 v134, v64, v64
	s_waitcnt vmcnt(15)
	v_add_f32_e32 v64, v87, v103
	global_store_dword v[116:117], v64, off offset:256
	v_fmac_f32_e32 v135, v64, v64
	s_waitcnt vmcnt(15)
	v_add_f32_e32 v64, v71, v136
	v_fmac_f32_e32 v135, v64, v64
	global_store_dword v[116:117], v64, off offset:384
	v_add_f32_dpp v64, v128, v128 quad_perm:[1,0,3,2] row_mask:0xf bank_mask:0xf bound_ctrl:1
	v_add_f32_dpp v66, v129, v129 quad_perm:[1,0,3,2] row_mask:0xf bank_mask:0xf bound_ctrl:1
	v_add_f32_dpp v68, v130, v130 quad_perm:[1,0,3,2] row_mask:0xf bank_mask:0xf bound_ctrl:1
	v_add_f32_dpp v70, v131, v131 quad_perm:[1,0,3,2] row_mask:0xf bank_mask:0xf bound_ctrl:1
	v_add_f32_dpp v80, v132, v132 quad_perm:[1,0,3,2] row_mask:0xf bank_mask:0xf bound_ctrl:1
	v_add_f32_dpp v82, v133, v133 quad_perm:[1,0,3,2] row_mask:0xf bank_mask:0xf bound_ctrl:1
	v_add_f32_dpp v84, v134, v134 quad_perm:[1,0,3,2] row_mask:0xf bank_mask:0xf bound_ctrl:1
	v_add_f32_dpp v86, v135, v135 quad_perm:[1,0,3,2] row_mask:0xf bank_mask:0xf bound_ctrl:1
	v_add_f32_dpp v64, v64, v64 quad_perm:[2,3,0,1] row_mask:0xf bank_mask:0xf bound_ctrl:1
	v_add_f32_dpp v66, v66, v66 quad_perm:[2,3,0,1] row_mask:0xf bank_mask:0xf bound_ctrl:1
	v_add_f32_dpp v68, v68, v68 quad_perm:[2,3,0,1] row_mask:0xf bank_mask:0xf bound_ctrl:1
	v_add_f32_dpp v70, v70, v70 quad_perm:[2,3,0,1] row_mask:0xf bank_mask:0xf bound_ctrl:1
	v_add_f32_dpp v80, v80, v80 quad_perm:[2,3,0,1] row_mask:0xf bank_mask:0xf bound_ctrl:1
	v_add_f32_dpp v82, v82, v82 quad_perm:[2,3,0,1] row_mask:0xf bank_mask:0xf bound_ctrl:1
	v_add_f32_dpp v84, v84, v84 quad_perm:[2,3,0,1] row_mask:0xf bank_mask:0xf bound_ctrl:1
	v_add_f32_dpp v86, v86, v86 quad_perm:[2,3,0,1] row_mask:0xf bank_mask:0xf bound_ctrl:1
	v_add_f32_dpp v64, v64, v64 row_half_mirror row_mask:0xf bank_mask:0xf bound_ctrl:1
	v_add_f32_dpp v66, v66, v66 row_half_mirror row_mask:0xf bank_mask:0xf bound_ctrl:1
	v_add_f32_dpp v68, v68, v68 row_half_mirror row_mask:0xf bank_mask:0xf bound_ctrl:1
	v_add_f32_dpp v70, v70, v70 row_half_mirror row_mask:0xf bank_mask:0xf bound_ctrl:1
	v_add_f32_dpp v80, v80, v80 row_half_mirror row_mask:0xf bank_mask:0xf bound_ctrl:1
	v_add_f32_dpp v82, v82, v82 row_half_mirror row_mask:0xf bank_mask:0xf bound_ctrl:1
	v_add_f32_dpp v84, v84, v84 row_half_mirror row_mask:0xf bank_mask:0xf bound_ctrl:1
	v_add_f32_dpp v86, v86, v86 row_half_mirror row_mask:0xf bank_mask:0xf bound_ctrl:1
	v_add_f32_dpp v64, v64, v64 row_mirror row_mask:0xf bank_mask:0xf bound_ctrl:1
	v_add_f32_dpp v66, v66, v66 row_mirror row_mask:0xf bank_mask:0xf bound_ctrl:1
	v_mov_b32_e32 v67, 0
	v_add_f32_dpp v68, v68, v68 row_mirror row_mask:0xf bank_mask:0xf bound_ctrl:1
	v_mov_b32_e32 v69, 0
	v_add_f32_dpp v70, v70, v70 row_mirror row_mask:0xf bank_mask:0xf bound_ctrl:1
	v_mov_b32_e32 v71, 0
	v_add_f32_dpp v80, v80, v80 row_mirror row_mask:0xf bank_mask:0xf bound_ctrl:1
	v_add_f32_dpp v82, v82, v82 row_mirror row_mask:0xf bank_mask:0xf bound_ctrl:1
	v_mov_b32_e32 v83, 0
	v_add_f32_dpp v84, v84, v84 row_mirror row_mask:0xf bank_mask:0xf bound_ctrl:1
	v_mov_b32_e32 v85, 0
	v_add_f32_dpp v86, v86, v86 row_mirror row_mask:0xf bank_mask:0xf bound_ctrl:1
	v_mov_b32_e32 v87, 0
	v_mov_b32_dpp v65, v64 row_bcast:15 row_mask:0xa bank_mask:0xf
	v_mov_b32_dpp v67, v66 row_bcast:15 row_mask:0xa bank_mask:0xf
	v_mov_b32_dpp v69, v68 row_bcast:15 row_mask:0xa bank_mask:0xf
	v_mov_b32_dpp v71, v70 row_bcast:15 row_mask:0xa bank_mask:0xf
	v_mov_b32_dpp v81, v80 row_bcast:15 row_mask:0xa bank_mask:0xf
	v_mov_b32_dpp v83, v82 row_bcast:15 row_mask:0xa bank_mask:0xf
	v_mov_b32_dpp v85, v84 row_bcast:15 row_mask:0xa bank_mask:0xf
	v_mov_b32_dpp v87, v86 row_bcast:15 row_mask:0xa bank_mask:0xf
	s_and_saveexec_b64 s[4:5], vcc
	s_cbranch_execz .LBB0_1734
	v_add_f32_e32 v64, v64, v65
	v_add_f32_e32 v86, v86, v87
	v_add_f32_e32 v84, v84, v85
	v_add_f32_e32 v82, v82, v83
	v_add_f32_e32 v80, v80, v81
	v_add_f32_e32 v70, v70, v71
	v_add_f32_e32 v68, v68, v69
	v_add_f32_e32 v66, v66, v67
	global_atomic_add_f32 v[96:97], v64, off
	global_atomic_add_f32 v[96:97], v66, off offset:4
	global_atomic_add_f32 v[96:97], v68, off offset:8
	global_atomic_add_f32 v[96:97], v70, off offset:12
	global_atomic_add_f32 v[96:97], v80, off offset:32
	global_atomic_add_f32 v[96:97], v82, off offset:36
	global_atomic_add_f32 v[96:97], v84, off offset:40
	global_atomic_add_f32 v[96:97], v86, off offset:44
